# nt (non-temporal) cache policy on GEMM epilogue global stores
# speedup vs baseline: 1.0061x; 1.0061x over previous
.LBB0_281:
	s_add_u32 s24, s22, 0xfffc0080
	s_addc_u32 s25, s23, -1
	s_add_i32 s57, 0, 0x10000
	s_cmp_eq_u32 s45, 12
	s_cselect_b32 s27, s3, s25
	s_cselect_b32 s26, s13, s24
	v_add_u32_e32 v160, s57, v183
	s_cselect_b32 s25, s11, s44
	s_cselect_b32 s24, s19, s21
	s_add_i32 s59, 0, 0x14000
	ds_read_b128 v[148:151], v160
	ds_read_b128 v[152:155], v160 offset:1024
	ds_read_b128 v[156:159], v160 offset:2048
	ds_read_b128 v[168:171], v160 offset:3072
	v_add_u32_e32 v160, s59, v183
	ds_read_b128 v[172:175], v160
	ds_read_b128 v[176:179], v160 offset:1024
	ds_read_b128 v[186:189], v160 offset:2048
	ds_read_b128 v[190:193], v160 offset:3072
	v_lshl_add_u64 v[164:165], s[22:23], 0, v[140:141]
	s_add_i32 m0, s52, 0xc000
	ds_read_b128 v[194:197], v212
	ds_read_b128 v[198:201], v212 offset:1024
	ds_read_b128 v[214:217], v212 offset:2048
	ds_read_b128 v[218:221], v212 offset:3072
	ds_read_b128 v[222:225], v212 offset:4096
	ds_read_b128 v[240:243], v212 offset:5120
	ds_read_b128 v[244:247], v212 offset:6144
	ds_read_b128 v[248:251], v212 offset:7168
	global_load_lds_dwordx4 v[164:165], off
	v_lshl_add_u64 v[164:165], s[22:23], 0, v[142:143]
	s_add_i32 m0, s52, 0xe000
	s_nop 0
	global_load_lds_dwordx4 v[164:165], off
	s_waitcnt vmcnt(8)
	s_waitcnt lgkmcnt(0)
	s_barrier
	s_setprio 1
	s_waitcnt lgkmcnt(0)
	v_mfma_i32_16x16x64_i8 v[128:131], v[148:151], v[194:197], v[128:131]
	v_mfma_i32_16x16x64_i8 v[124:127], v[156:159], v[194:197], v[124:127]
	v_mfma_i32_16x16x64_i8 v[120:123], v[148:151], v[214:217], v[120:123]
	v_mfma_i32_16x16x64_i8 v[116:119], v[156:159], v[214:217], v[116:119]
	v_mfma_i32_16x16x64_i8 v[110:113], v[148:151], v[222:225], v[110:113]
	v_mfma_i32_16x16x64_i8 v[106:109], v[156:159], v[222:225], v[106:109]
	v_mfma_i32_16x16x64_i8 v[102:105], v[148:151], v[244:247], v[102:105]
	v_mfma_i32_16x16x64_i8 v[98:101], v[156:159], v[244:247], v[98:101]
	v_mfma_i32_16x16x64_i8 v[128:131], v[152:155], v[198:201], v[128:131]
	v_mfma_i32_16x16x64_i8 v[124:127], v[168:171], v[198:201], v[124:127]
	v_mfma_i32_16x16x64_i8 v[120:123], v[152:155], v[218:221], v[120:123]
	v_mfma_i32_16x16x64_i8 v[116:119], v[168:171], v[218:221], v[116:119]
	v_mfma_i32_16x16x64_i8 v[110:113], v[152:155], v[240:243], v[110:113]
	v_mfma_i32_16x16x64_i8 v[106:109], v[168:171], v[240:243], v[106:109]
	v_mfma_i32_16x16x64_i8 v[102:105], v[152:155], v[248:251], v[102:105]
	v_mfma_i32_16x16x64_i8 v[98:101], v[168:171], v[248:251], v[98:101]
	s_setprio 0
	s_setprio 1
	v_mfma_i32_16x16x64_i8 v[94:97], v[172:175], v[194:197], v[94:97]
	v_mfma_i32_16x16x64_i8 v[90:93], v[186:189], v[194:197], v[90:93]
	v_mfma_i32_16x16x64_i8 v[86:89], v[172:175], v[214:217], v[86:89]
	v_mfma_i32_16x16x64_i8 v[82:85], v[186:189], v[214:217], v[82:85]
	v_mfma_i32_16x16x64_i8 v[78:81], v[172:175], v[222:225], v[78:81]
	v_mfma_i32_16x16x64_i8 v[74:77], v[186:189], v[222:225], v[74:77]
	v_mfma_i32_16x16x64_i8 v[70:73], v[172:175], v[244:247], v[70:73]
	v_mfma_i32_16x16x64_i8 v[66:69], v[186:189], v[244:247], v[66:69]
	v_mfma_i32_16x16x64_i8 v[94:97], v[176:179], v[198:201], v[94:97]
	v_mfma_i32_16x16x64_i8 v[90:93], v[190:193], v[198:201], v[90:93]
	v_mfma_i32_16x16x64_i8 v[86:89], v[176:179], v[218:221], v[86:89]
	v_mfma_i32_16x16x64_i8 v[82:85], v[190:193], v[218:221], v[82:85]
	v_mfma_i32_16x16x64_i8 v[78:81], v[176:179], v[240:243], v[78:81]
	v_mfma_i32_16x16x64_i8 v[74:77], v[190:193], v[240:243], v[74:77]
	v_mfma_i32_16x16x64_i8 v[70:73], v[176:179], v[248:251], v[70:73]
	v_mfma_i32_16x16x64_i8 v[66:69], v[190:193], v[248:251], v[66:69]
	s_setprio 0
	s_barrier
	s_add_i32 s57, s57, s51
	v_lshl_add_u64 v[164:165], s[24:25], 0, v[114:115]
	s_mov_b32 m0, s57
	ds_read_b128 v[194:197], v212 offset:16384
	ds_read_b128 v[198:201], v212 offset:17408
	ds_read_b128 v[214:217], v212 offset:18432
	ds_read_b128 v[218:221], v212 offset:19456
	ds_read_b128 v[222:225], v212 offset:20480
	ds_read_b128 v[240:243], v212 offset:21504
	ds_read_b128 v[244:247], v212 offset:22528
	ds_read_b128 v[248:251], v212 offset:23552
	global_load_lds_dwordx4 v[164:165], off
	s_add_i32 m0, s57, 0x2000
	s_add_u32 s62, s24, 0x10000
	v_lshl_add_u64 v[180:181], s[24:25], 0, v[136:137]
	s_addc_u32 s63, s25, 0
	s_add_i32 s57, s59, s51
	global_load_lds_dwordx4 v[180:181], off
	v_lshl_add_u64 v[202:203], s[62:63], 0, v[114:115]
	s_mov_b32 m0, s57
	v_lshl_add_u64 v[236:237], s[26:27], 0, v[134:135]
	global_load_lds_dwordx4 v[202:203], off
	v_lshl_add_u64 v[202:203], s[62:63], 0, v[136:137]
	s_add_i32 m0, s57, 0x2000
	s_nop 0
	global_load_lds_dwordx4 v[202:203], off
	v_lshl_add_u64 v[202:203], s[26:27], 0, v[132:133]
	s_mov_b32 m0, s52
	s_nop 0
	global_load_lds_dwordx4 v[202:203], off
	s_mov_b32 m0, s53
	s_nop 0
	global_load_lds_dwordx4 v[236:237], off
	s_waitcnt vmcnt(8)
	s_waitcnt lgkmcnt(0)
	s_barrier
	s_setprio 1
	s_waitcnt lgkmcnt(0)
	v_mfma_i32_16x16x64_i8 v[62:65], v[148:151], v[194:197], v[62:65]
	v_mfma_i32_16x16x64_i8 v[58:61], v[156:159], v[194:197], v[58:61]
	v_mfma_i32_16x16x64_i8 v[54:57], v[148:151], v[214:217], v[54:57]
	v_mfma_i32_16x16x64_i8 v[50:53], v[156:159], v[214:217], v[50:53]
	v_mfma_i32_16x16x64_i8 v[46:49], v[148:151], v[222:225], v[46:49]
	v_mfma_i32_16x16x64_i8 v[42:45], v[156:159], v[222:225], v[42:45]
	v_mfma_i32_16x16x64_i8 v[38:41], v[148:151], v[244:247], v[38:41]
	v_mfma_i32_16x16x64_i8 v[34:37], v[156:159], v[244:247], v[34:37]
	v_mfma_i32_16x16x64_i8 v[62:65], v[152:155], v[198:201], v[62:65]
	v_mfma_i32_16x16x64_i8 v[58:61], v[168:171], v[198:201], v[58:61]
	v_mfma_i32_16x16x64_i8 v[54:57], v[152:155], v[218:221], v[54:57]
	v_mfma_i32_16x16x64_i8 v[50:53], v[168:171], v[218:221], v[50:53]
	v_mfma_i32_16x16x64_i8 v[46:49], v[152:155], v[240:243], v[46:49]
	v_mfma_i32_16x16x64_i8 v[42:45], v[168:171], v[240:243], v[42:45]
	v_mfma_i32_16x16x64_i8 v[38:41], v[152:155], v[248:251], v[38:41]
	v_mfma_i32_16x16x64_i8 v[34:37], v[168:171], v[248:251], v[34:37]
	s_setprio 0
	s_setprio 1
	v_mfma_i32_16x16x64_i8 v[30:33], v[172:175], v[194:197], v[30:33]
	v_mfma_i32_16x16x64_i8 v[26:29], v[186:189], v[194:197], v[26:29]
	v_mfma_i32_16x16x64_i8 v[22:25], v[172:175], v[214:217], v[22:25]
	v_mfma_i32_16x16x64_i8 v[18:21], v[186:189], v[214:217], v[18:21]
	v_mfma_i32_16x16x64_i8 v[14:17], v[172:175], v[222:225], v[14:17]
	v_mfma_i32_16x16x64_i8 v[10:13], v[186:189], v[222:225], v[10:13]
	v_mfma_i32_16x16x64_i8 v[6:9], v[172:175], v[244:247], v[6:9]
	v_mfma_i32_16x16x64_i8 v[2:5], v[186:189], v[244:247], v[2:5]
	v_mfma_i32_16x16x64_i8 v[30:33], v[176:179], v[198:201], v[30:33]
	v_mfma_i32_16x16x64_i8 v[26:29], v[190:193], v[198:201], v[26:29]
	v_mfma_i32_16x16x64_i8 v[22:25], v[176:179], v[218:221], v[22:25]
	v_mfma_i32_16x16x64_i8 v[18:21], v[190:193], v[218:221], v[18:21]
	v_mfma_i32_16x16x64_i8 v[14:17], v[176:179], v[240:243], v[14:17]
	v_mfma_i32_16x16x64_i8 v[10:13], v[190:193], v[240:243], v[10:13]
	v_mfma_i32_16x16x64_i8 v[6:9], v[176:179], v[248:251], v[6:9]
	v_mfma_i32_16x16x64_i8 v[2:5], v[190:193], v[248:251], v[2:5]
	s_setprio 0
	s_barrier
	s_add_i32 s57, 0, 0x18000
	v_add_u32_e32 v160, s57, v183
	s_add_i32 s59, 0, 0x1c000
	ds_read_b128 v[148:151], v160
	ds_read_b128 v[152:155], v160 offset:1024
	ds_read_b128 v[156:159], v160 offset:2048
	ds_read_b128 v[168:171], v160 offset:3072
	v_add_u32_e32 v160, s59, v183
	ds_read_b128 v[172:175], v160
	ds_read_b128 v[176:179], v160 offset:1024
	ds_read_b128 v[186:189], v160 offset:2048
	ds_read_b128 v[190:193], v160 offset:3072
	s_add_u32 s26, s26, 0x40000
	s_addc_u32 s27, s27, 0
	s_mov_b32 m0, s54
	v_lshl_add_u64 v[238:239], s[26:27], 0, v[132:133]
	ds_read_b128 v[194:197], v212 offset:32768
	ds_read_b128 v[198:201], v212 offset:33792
	ds_read_b128 v[214:217], v212 offset:34816
	ds_read_b128 v[218:221], v212 offset:35840
	ds_read_b128 v[222:225], v212 offset:36864
	ds_read_b128 v[240:243], v212 offset:37888
	ds_read_b128 v[244:247], v212 offset:38912
	ds_read_b128 v[248:251], v212 offset:39936
	global_load_lds_dwordx4 v[238:239], off
	v_lshl_add_u64 v[238:239], s[26:27], 0, v[134:135]
	s_mov_b32 m0, s55
	s_nop 0
	global_load_lds_dwordx4 v[238:239], off
	s_waitcnt vmcnt(8)
	s_waitcnt lgkmcnt(0)
	s_barrier
	s_setprio 1
	s_waitcnt lgkmcnt(0)
	v_mfma_i32_16x16x64_i8 v[128:131], v[148:151], v[194:197], v[128:131]
	v_mfma_i32_16x16x64_i8 v[124:127], v[156:159], v[194:197], v[124:127]
	v_mfma_i32_16x16x64_i8 v[120:123], v[148:151], v[214:217], v[120:123]
	v_mfma_i32_16x16x64_i8 v[116:119], v[156:159], v[214:217], v[116:119]
	v_mfma_i32_16x16x64_i8 v[110:113], v[148:151], v[222:225], v[110:113]
	v_mfma_i32_16x16x64_i8 v[106:109], v[156:159], v[222:225], v[106:109]
	v_mfma_i32_16x16x64_i8 v[102:105], v[148:151], v[244:247], v[102:105]
	v_mfma_i32_16x16x64_i8 v[98:101], v[156:159], v[244:247], v[98:101]
	v_mfma_i32_16x16x64_i8 v[128:131], v[152:155], v[198:201], v[128:131]
	v_mfma_i32_16x16x64_i8 v[124:127], v[168:171], v[198:201], v[124:127]
	v_mfma_i32_16x16x64_i8 v[120:123], v[152:155], v[218:221], v[120:123]
	v_mfma_i32_16x16x64_i8 v[116:119], v[168:171], v[218:221], v[116:119]
	v_mfma_i32_16x16x64_i8 v[110:113], v[152:155], v[240:243], v[110:113]
	v_mfma_i32_16x16x64_i8 v[106:109], v[168:171], v[240:243], v[106:109]
	v_mfma_i32_16x16x64_i8 v[102:105], v[152:155], v[248:251], v[102:105]
	v_mfma_i32_16x16x64_i8 v[98:101], v[168:171], v[248:251], v[98:101]
	s_setprio 0
	s_setprio 1
	v_mfma_i32_16x16x64_i8 v[94:97], v[172:175], v[194:197], v[94:97]
	v_mfma_i32_16x16x64_i8 v[90:93], v[186:189], v[194:197], v[90:93]
	v_mfma_i32_16x16x64_i8 v[86:89], v[172:175], v[214:217], v[86:89]
	v_mfma_i32_16x16x64_i8 v[82:85], v[186:189], v[214:217], v[82:85]
	v_mfma_i32_16x16x64_i8 v[78:81], v[172:175], v[222:225], v[78:81]
	v_mfma_i32_16x16x64_i8 v[74:77], v[186:189], v[222:225], v[74:77]
	v_mfma_i32_16x16x64_i8 v[70:73], v[172:175], v[244:247], v[70:73]
	v_mfma_i32_16x16x64_i8 v[66:69], v[186:189], v[244:247], v[66:69]
	v_mfma_i32_16x16x64_i8 v[94:97], v[176:179], v[198:201], v[94:97]
	v_mfma_i32_16x16x64_i8 v[90:93], v[190:193], v[198:201], v[90:93]
	v_mfma_i32_16x16x64_i8 v[86:89], v[176:179], v[218:221], v[86:89]
	v_mfma_i32_16x16x64_i8 v[82:85], v[190:193], v[218:221], v[82:85]
	v_mfma_i32_16x16x64_i8 v[78:81], v[176:179], v[240:243], v[78:81]
	v_mfma_i32_16x16x64_i8 v[74:77], v[190:193], v[240:243], v[74:77]
	v_mfma_i32_16x16x64_i8 v[70:73], v[176:179], v[248:251], v[70:73]
	v_mfma_i32_16x16x64_i8 v[66:69], v[190:193], v[248:251], v[66:69]
	s_setprio 0
	s_barrier
	s_add_i32 s26, s57, s51
	v_lshl_add_u64 v[164:165], v[164:165], 0, s[28:29]
	s_mov_b32 m0, s26
	ds_read_b128 v[194:197], v212 offset:49152
	ds_read_b128 v[198:201], v212 offset:50176
	ds_read_b128 v[214:217], v212 offset:51200
	ds_read_b128 v[218:221], v212 offset:52224
	ds_read_b128 v[222:225], v212 offset:53248
	ds_read_b128 v[240:243], v212 offset:54272
	ds_read_b128 v[244:247], v212 offset:55296
	ds_read_b128 v[248:251], v212 offset:56320
	global_load_lds_dwordx4 v[164:165], off
	s_add_i32 m0, s26, 0x2000
	s_add_u32 s24, s24, 0x10080
	v_lshl_add_u64 v[164:165], v[180:181], 0, s[28:29]
	s_addc_u32 s25, s25, 0
	s_add_i32 s26, s59, s51
	global_load_lds_dwordx4 v[164:165], off
	v_lshl_add_u64 v[164:165], s[24:25], 0, v[114:115]
	s_mov_b32 m0, s26
	s_nop 0
	global_load_lds_dwordx4 v[164:165], off
	v_lshl_add_u64 v[164:165], s[24:25], 0, v[136:137]
	s_add_i32 m0, s26, 0x2000
	s_nop 0
	global_load_lds_dwordx4 v[164:165], off
	v_lshl_add_u64 v[164:165], v[202:203], 0, s[28:29]
	s_mov_b32 m0, s73
	s_nop 0
	global_load_lds_dwordx4 v[164:165], off
	v_lshl_add_u64 v[164:165], v[236:237], 0, s[28:29]
	s_mov_b32 m0, s74
	s_nop 0
	global_load_lds_dwordx4 v[164:165], off
	s_waitcnt vmcnt(8)
	s_waitcnt lgkmcnt(0)
	s_barrier
	s_setprio 1
	s_waitcnt lgkmcnt(0)
	v_mfma_i32_16x16x64_i8 v[62:65], v[148:151], v[194:197], v[62:65]
	v_mfma_i32_16x16x64_i8 v[58:61], v[156:159], v[194:197], v[58:61]
	v_mfma_i32_16x16x64_i8 v[54:57], v[148:151], v[214:217], v[54:57]
	v_mfma_i32_16x16x64_i8 v[50:53], v[156:159], v[214:217], v[50:53]
	v_mfma_i32_16x16x64_i8 v[46:49], v[148:151], v[222:225], v[46:49]
	v_mfma_i32_16x16x64_i8 v[42:45], v[156:159], v[222:225], v[42:45]
	v_mfma_i32_16x16x64_i8 v[38:41], v[148:151], v[244:247], v[38:41]
	v_mfma_i32_16x16x64_i8 v[34:37], v[156:159], v[244:247], v[34:37]
	v_mfma_i32_16x16x64_i8 v[62:65], v[152:155], v[198:201], v[62:65]
	v_mfma_i32_16x16x64_i8 v[58:61], v[168:171], v[198:201], v[58:61]
	v_mfma_i32_16x16x64_i8 v[54:57], v[152:155], v[218:221], v[54:57]
	v_mfma_i32_16x16x64_i8 v[50:53], v[168:171], v[218:221], v[50:53]
	v_mfma_i32_16x16x64_i8 v[46:49], v[152:155], v[240:243], v[46:49]
	v_mfma_i32_16x16x64_i8 v[42:45], v[168:171], v[240:243], v[42:45]
	v_mfma_i32_16x16x64_i8 v[38:41], v[152:155], v[248:251], v[38:41]
	v_mfma_i32_16x16x64_i8 v[34:37], v[168:171], v[248:251], v[34:37]
	s_setprio 0
	s_setprio 1
	v_mfma_i32_16x16x64_i8 v[30:33], v[172:175], v[194:197], v[30:33]
	v_mfma_i32_16x16x64_i8 v[26:29], v[186:189], v[194:197], v[26:29]
	v_mfma_i32_16x16x64_i8 v[22:25], v[172:175], v[214:217], v[22:25]
	v_mfma_i32_16x16x64_i8 v[18:21], v[186:189], v[214:217], v[18:21]
	v_mfma_i32_16x16x64_i8 v[14:17], v[172:175], v[222:225], v[14:17]
	v_mfma_i32_16x16x64_i8 v[10:13], v[186:189], v[222:225], v[10:13]
	v_mfma_i32_16x16x64_i8 v[6:9], v[172:175], v[244:247], v[6:9]
	v_mfma_i32_16x16x64_i8 v[2:5], v[186:189], v[244:247], v[2:5]
	v_mfma_i32_16x16x64_i8 v[30:33], v[176:179], v[198:201], v[30:33]
	v_mfma_i32_16x16x64_i8 v[26:29], v[190:193], v[198:201], v[26:29]
	v_mfma_i32_16x16x64_i8 v[22:25], v[176:179], v[218:221], v[22:25]
	v_mfma_i32_16x16x64_i8 v[18:21], v[190:193], v[218:221], v[18:21]
	v_mfma_i32_16x16x64_i8 v[14:17], v[176:179], v[240:243], v[14:17]
	v_mfma_i32_16x16x64_i8 v[10:13], v[190:193], v[240:243], v[10:13]
	v_mfma_i32_16x16x64_i8 v[6:9], v[176:179], v[248:251], v[6:9]
	v_mfma_i32_16x16x64_i8 v[2:5], v[190:193], v[248:251], v[2:5]
	s_setprio 0
	s_barrier
	s_add_i32 s45, s45, 2
	s_add_u32 s22, s22, 0x100
	s_addc_u32 s23, s23, 0
	s_add_u32 s21, s21, 0x100
	s_addc_u32 s44, s44, 0
	s_cmp_gt_u32 s45, 13
	s_cbranch_scc0 .LBB0_281
	s_and_b64 vcc, exec, s[8:9]
	s_cbranch_vccz .LBB0_284
	s_barrier

.LBB0_320:
	s_add_u32 s44, s42, 0xfff80080
	s_addc_u32 s45, s43, -1
	s_add_i32 s59, 0, 0x10000
	s_cmp_eq_u32 s57, 28
	s_cselect_b32 s47, s3, s45
	s_cselect_b32 s46, s4, s44
	s_waitcnt vmcnt(0) lgkmcnt(0)
	v_add_u32_e32 v146, s59, v149
	s_cselect_b32 s45, s17, s27
	s_cselect_b32 s44, s19, s25
	s_add_i32 s64, 0, 0x14000
	ds_read_b128 v[164:167], v146
	ds_read_b128 v[168:171], v146 offset:1024
	ds_read_b128 v[172:175], v146 offset:2048
	ds_read_b128 v[176:179], v146 offset:3072
	v_add_u32_e32 v146, s64, v149
	ds_read_b128 v[180:183], v146
	ds_read_b128 v[190:193], v146 offset:1024
	ds_read_b128 v[194:197], v146 offset:2048
	ds_read_b128 v[198:201], v146 offset:3072
	v_lshl_add_u64 v[236:237], s[42:43], 0, v[142:143]
	s_add_i32 m0, s51, 0xc000
	ds_read_b128 v[202:205], v188
	ds_read_b128 v[206:209], v188 offset:1024
	ds_read_b128 v[210:213], v188 offset:2048
	ds_read_b128 v[214:217], v188 offset:3072
	ds_read_b128 v[218:221], v188 offset:4096
	ds_read_b128 v[222:225], v188 offset:5120
	ds_read_b128 v[240:243], v188 offset:6144
	ds_read_b128 v[244:247], v188 offset:7168
	global_load_lds_dwordx4 v[236:237], off
	v_lshl_add_u64 v[236:237], s[42:43], 0, v[144:145]
	s_add_i32 m0, s51, 0xe000
	s_nop 0
	global_load_lds_dwordx4 v[236:237], off
	s_waitcnt vmcnt(8)
	s_waitcnt lgkmcnt(0)
	s_barrier
	s_setprio 1
	s_waitcnt lgkmcnt(0)
	v_mfma_f32_16x16x32_bf16 v[128:131], v[164:167], v[202:205], v[128:131]
	v_mfma_f32_16x16x32_bf16 v[124:127], v[172:175], v[202:205], v[124:127]
	v_mfma_f32_16x16x32_bf16 v[110:113], v[164:167], v[210:213], v[110:113]
	v_mfma_f32_16x16x32_bf16 v[106:109], v[172:175], v[210:213], v[106:109]
	v_mfma_f32_16x16x32_bf16 v[94:97], v[164:167], v[218:221], v[94:97]
	v_mfma_f32_16x16x32_bf16 v[90:93], v[172:175], v[218:221], v[90:93]
	v_mfma_f32_16x16x32_bf16 v[78:81], v[164:167], v[240:243], v[78:81]
	v_mfma_f32_16x16x32_bf16 v[74:77], v[172:175], v[240:243], v[74:77]
	v_mfma_f32_16x16x32_bf16 v[128:131], v[168:171], v[206:209], v[128:131]
	v_mfma_f32_16x16x32_bf16 v[124:127], v[176:179], v[206:209], v[124:127]
	v_mfma_f32_16x16x32_bf16 v[110:113], v[168:171], v[214:217], v[110:113]
	v_mfma_f32_16x16x32_bf16 v[106:109], v[176:179], v[214:217], v[106:109]
	v_mfma_f32_16x16x32_bf16 v[94:97], v[168:171], v[222:225], v[94:97]
	v_mfma_f32_16x16x32_bf16 v[90:93], v[176:179], v[222:225], v[90:93]
	v_mfma_f32_16x16x32_bf16 v[78:81], v[168:171], v[244:247], v[78:81]
	v_mfma_f32_16x16x32_bf16 v[74:77], v[176:179], v[244:247], v[74:77]
	s_setprio 0
	s_setprio 1
	v_mfma_f32_16x16x32_bf16 v[120:123], v[180:183], v[202:205], v[120:123]
	v_mfma_f32_16x16x32_bf16 v[116:119], v[194:197], v[202:205], v[116:119]
	v_mfma_f32_16x16x32_bf16 v[102:105], v[180:183], v[210:213], v[102:105]
	v_mfma_f32_16x16x32_bf16 v[98:101], v[194:197], v[210:213], v[98:101]
	v_mfma_f32_16x16x32_bf16 v[86:89], v[180:183], v[218:221], v[86:89]
	v_mfma_f32_16x16x32_bf16 v[82:85], v[194:197], v[218:221], v[82:85]
	v_mfma_f32_16x16x32_bf16 v[70:73], v[180:183], v[240:243], v[70:73]
	v_mfma_f32_16x16x32_bf16 v[66:69], v[194:197], v[240:243], v[66:69]
	v_mfma_f32_16x16x32_bf16 v[120:123], v[190:193], v[206:209], v[120:123]
	v_mfma_f32_16x16x32_bf16 v[116:119], v[198:201], v[206:209], v[116:119]
	v_mfma_f32_16x16x32_bf16 v[102:105], v[190:193], v[214:217], v[102:105]
	v_mfma_f32_16x16x32_bf16 v[98:101], v[198:201], v[214:217], v[98:101]
	v_mfma_f32_16x16x32_bf16 v[86:89], v[190:193], v[222:225], v[86:89]
	v_mfma_f32_16x16x32_bf16 v[82:85], v[198:201], v[222:225], v[82:85]
	v_mfma_f32_16x16x32_bf16 v[70:73], v[190:193], v[244:247], v[70:73]
	v_mfma_f32_16x16x32_bf16 v[66:69], v[198:201], v[244:247], v[66:69]
	s_setprio 0
	s_barrier
	s_add_i32 s59, s59, s50
	v_lshl_add_u64 v[236:237], s[44:45], 0, v[114:115]
	s_mov_b32 m0, s59
	ds_read_b128 v[202:205], v188 offset:16384
	ds_read_b128 v[206:209], v188 offset:17408
	ds_read_b128 v[210:213], v188 offset:18432
	ds_read_b128 v[214:217], v188 offset:19456
	ds_read_b128 v[218:221], v188 offset:20480
	ds_read_b128 v[222:225], v188 offset:21504
	ds_read_b128 v[240:243], v188 offset:22528
	ds_read_b128 v[244:247], v188 offset:23552
	global_load_lds_dwordx4 v[236:237], off
	s_add_i32 m0, s59, 0x2000
	s_add_u32 s62, s44, 0x20000
	v_lshl_add_u64 v[238:239], s[44:45], 0, v[136:137]
	s_addc_u32 s63, s45, 0
	s_add_i32 s59, s64, s50
	global_load_lds_dwordx4 v[238:239], off
	v_lshl_add_u64 v[248:249], s[62:63], 0, v[114:115]
	s_mov_b32 m0, s59
	v_lshl_add_u64 v[250:251], s[46:47], 0, v[134:135]
	global_load_lds_dwordx4 v[248:249], off
	v_lshl_add_u64 v[248:249], s[62:63], 0, v[136:137]
	s_add_i32 m0, s59, 0x2000
	s_nop 0
	global_load_lds_dwordx4 v[248:249], off
	v_lshl_add_u64 v[248:249], s[46:47], 0, v[132:133]
	s_mov_b32 m0, s51
	s_nop 0
	global_load_lds_dwordx4 v[248:249], off
	s_mov_b32 m0, s52
	s_nop 0
	global_load_lds_dwordx4 v[250:251], off
	s_waitcnt vmcnt(8)
	s_waitcnt lgkmcnt(0)
	s_barrier
	s_setprio 1
	s_waitcnt lgkmcnt(0)
	v_mfma_f32_16x16x32_bf16 v[62:65], v[164:167], v[202:205], v[62:65]
	v_mfma_f32_16x16x32_bf16 v[58:61], v[172:175], v[202:205], v[58:61]
	v_mfma_f32_16x16x32_bf16 v[46:49], v[164:167], v[210:213], v[46:49]
	v_mfma_f32_16x16x32_bf16 v[42:45], v[172:175], v[210:213], v[42:45]
	v_mfma_f32_16x16x32_bf16 v[30:33], v[164:167], v[218:221], v[30:33]
	v_mfma_f32_16x16x32_bf16 v[26:29], v[172:175], v[218:221], v[26:29]
	v_mfma_f32_16x16x32_bf16 v[14:17], v[164:167], v[240:243], v[14:17]
	v_mfma_f32_16x16x32_bf16 v[10:13], v[172:175], v[240:243], v[10:13]
	v_mfma_f32_16x16x32_bf16 v[62:65], v[168:171], v[206:209], v[62:65]
	v_mfma_f32_16x16x32_bf16 v[58:61], v[176:179], v[206:209], v[58:61]
	v_mfma_f32_16x16x32_bf16 v[46:49], v[168:171], v[214:217], v[46:49]
	v_mfma_f32_16x16x32_bf16 v[42:45], v[176:179], v[214:217], v[42:45]
	v_mfma_f32_16x16x32_bf16 v[30:33], v[168:171], v[222:225], v[30:33]
	v_mfma_f32_16x16x32_bf16 v[26:29], v[176:179], v[222:225], v[26:29]
	v_mfma_f32_16x16x32_bf16 v[14:17], v[168:171], v[244:247], v[14:17]
	v_mfma_f32_16x16x32_bf16 v[10:13], v[176:179], v[244:247], v[10:13]
	s_setprio 0
	s_setprio 1
	v_mfma_f32_16x16x32_bf16 v[54:57], v[180:183], v[202:205], v[54:57]
	v_mfma_f32_16x16x32_bf16 v[50:53], v[194:197], v[202:205], v[50:53]
	v_mfma_f32_16x16x32_bf16 v[38:41], v[180:183], v[210:213], v[38:41]
	v_mfma_f32_16x16x32_bf16 v[34:37], v[194:197], v[210:213], v[34:37]
	v_mfma_f32_16x16x32_bf16 v[22:25], v[180:183], v[218:221], v[22:25]
	v_mfma_f32_16x16x32_bf16 v[18:21], v[194:197], v[218:221], v[18:21]
	v_mfma_f32_16x16x32_bf16 v[6:9], v[180:183], v[240:243], v[6:9]
	v_mfma_f32_16x16x32_bf16 v[2:5], v[194:197], v[240:243], v[2:5]
	v_mfma_f32_16x16x32_bf16 v[54:57], v[190:193], v[206:209], v[54:57]
	v_mfma_f32_16x16x32_bf16 v[50:53], v[198:201], v[206:209], v[50:53]
	v_mfma_f32_16x16x32_bf16 v[38:41], v[190:193], v[214:217], v[38:41]
	v_mfma_f32_16x16x32_bf16 v[34:37], v[198:201], v[214:217], v[34:37]
	v_mfma_f32_16x16x32_bf16 v[22:25], v[190:193], v[222:225], v[22:25]
	v_mfma_f32_16x16x32_bf16 v[18:21], v[198:201], v[222:225], v[18:21]
	v_mfma_f32_16x16x32_bf16 v[6:9], v[190:193], v[244:247], v[6:9]
	v_mfma_f32_16x16x32_bf16 v[2:5], v[198:201], v[244:247], v[2:5]
	s_setprio 0
	s_barrier
	s_add_i32 s59, 0, 0x18000
	v_add_u32_e32 v146, s59, v149
	s_add_i32 s62, 0, 0x1c000
	ds_read_b128 v[164:167], v146
	ds_read_b128 v[168:171], v146 offset:1024
	ds_read_b128 v[172:175], v146 offset:2048
	ds_read_b128 v[176:179], v146 offset:3072
	v_add_u32_e32 v146, s62, v149
	ds_read_b128 v[180:183], v146
	ds_read_b128 v[190:193], v146 offset:1024
	ds_read_b128 v[194:197], v146 offset:2048
	ds_read_b128 v[198:201], v146 offset:3072
	s_add_u32 s46, s46, 0x80000
	s_addc_u32 s47, s47, 0
	s_mov_b32 m0, s53
	v_lshl_add_u64 v[230:231], s[46:47], 0, v[132:133]
	ds_read_b128 v[202:205], v188 offset:32768
	ds_read_b128 v[206:209], v188 offset:33792
	ds_read_b128 v[210:213], v188 offset:34816
	ds_read_b128 v[214:217], v188 offset:35840
	ds_read_b128 v[218:221], v188 offset:36864
	ds_read_b128 v[222:225], v188 offset:37888
	ds_read_b128 v[240:243], v188 offset:38912
	ds_read_b128 v[244:247], v188 offset:39936
	global_load_lds_dwordx4 v[230:231], off
	v_lshl_add_u64 v[230:231], s[46:47], 0, v[134:135]
	s_mov_b32 m0, s54
	s_nop 0
	global_load_lds_dwordx4 v[230:231], off
	s_waitcnt vmcnt(8)
	s_waitcnt lgkmcnt(0)
	s_barrier
	s_setprio 1
	s_waitcnt lgkmcnt(0)
	v_mfma_f32_16x16x32_bf16 v[128:131], v[164:167], v[202:205], v[128:131]
	v_mfma_f32_16x16x32_bf16 v[124:127], v[172:175], v[202:205], v[124:127]
	v_mfma_f32_16x16x32_bf16 v[110:113], v[164:167], v[210:213], v[110:113]
	v_mfma_f32_16x16x32_bf16 v[106:109], v[172:175], v[210:213], v[106:109]
	v_mfma_f32_16x16x32_bf16 v[94:97], v[164:167], v[218:221], v[94:97]
	v_mfma_f32_16x16x32_bf16 v[90:93], v[172:175], v[218:221], v[90:93]
	v_mfma_f32_16x16x32_bf16 v[78:81], v[164:167], v[240:243], v[78:81]
	v_mfma_f32_16x16x32_bf16 v[74:77], v[172:175], v[240:243], v[74:77]
	v_mfma_f32_16x16x32_bf16 v[128:131], v[168:171], v[206:209], v[128:131]
	v_mfma_f32_16x16x32_bf16 v[124:127], v[176:179], v[206:209], v[124:127]
	v_mfma_f32_16x16x32_bf16 v[110:113], v[168:171], v[214:217], v[110:113]
	v_mfma_f32_16x16x32_bf16 v[106:109], v[176:179], v[214:217], v[106:109]
	v_mfma_f32_16x16x32_bf16 v[94:97], v[168:171], v[222:225], v[94:97]
	v_mfma_f32_16x16x32_bf16 v[90:93], v[176:179], v[222:225], v[90:93]
	v_mfma_f32_16x16x32_bf16 v[78:81], v[168:171], v[244:247], v[78:81]
	v_mfma_f32_16x16x32_bf16 v[74:77], v[176:179], v[244:247], v[74:77]
	s_setprio 0
	s_setprio 1
	v_mfma_f32_16x16x32_bf16 v[120:123], v[180:183], v[202:205], v[120:123]
	v_mfma_f32_16x16x32_bf16 v[116:119], v[194:197], v[202:205], v[116:119]
	v_mfma_f32_16x16x32_bf16 v[102:105], v[180:183], v[210:213], v[102:105]
	v_mfma_f32_16x16x32_bf16 v[98:101], v[194:197], v[210:213], v[98:101]
	v_mfma_f32_16x16x32_bf16 v[86:89], v[180:183], v[218:221], v[86:89]
	v_mfma_f32_16x16x32_bf16 v[82:85], v[194:197], v[218:221], v[82:85]
	v_mfma_f32_16x16x32_bf16 v[70:73], v[180:183], v[240:243], v[70:73]
	v_mfma_f32_16x16x32_bf16 v[66:69], v[194:197], v[240:243], v[66:69]
	v_mfma_f32_16x16x32_bf16 v[120:123], v[190:193], v[206:209], v[120:123]
	v_mfma_f32_16x16x32_bf16 v[116:119], v[198:201], v[206:209], v[116:119]
	v_mfma_f32_16x16x32_bf16 v[102:105], v[190:193], v[214:217], v[102:105]
	v_mfma_f32_16x16x32_bf16 v[98:101], v[198:201], v[214:217], v[98:101]
	v_mfma_f32_16x16x32_bf16 v[86:89], v[190:193], v[222:225], v[86:89]
	v_mfma_f32_16x16x32_bf16 v[82:85], v[198:201], v[222:225], v[82:85]
	v_mfma_f32_16x16x32_bf16 v[70:73], v[190:193], v[244:247], v[70:73]
	v_mfma_f32_16x16x32_bf16 v[66:69], v[198:201], v[244:247], v[66:69]
	s_setprio 0
	s_barrier
	s_add_i32 s46, s59, s50
	v_lshl_add_u64 v[230:231], v[236:237], 0, s[28:29]
	s_mov_b32 m0, s46
	ds_read_b128 v[202:205], v188 offset:49152
	ds_read_b128 v[206:209], v188 offset:50176
	ds_read_b128 v[210:213], v188 offset:51200
	ds_read_b128 v[214:217], v188 offset:52224
	ds_read_b128 v[218:221], v188 offset:53248
	ds_read_b128 v[222:225], v188 offset:54272
	ds_read_b128 v[240:243], v188 offset:55296
	ds_read_b128 v[244:247], v188 offset:56320
	global_load_lds_dwordx4 v[230:231], off
	s_add_i32 m0, s46, 0x2000
	s_add_u32 s44, s44, 0x20080
	v_lshl_add_u64 v[230:231], v[238:239], 0, s[28:29]
	s_addc_u32 s45, s45, 0
	s_add_i32 s46, s62, s50
	global_load_lds_dwordx4 v[230:231], off
	v_lshl_add_u64 v[230:231], s[44:45], 0, v[114:115]
	s_mov_b32 m0, s46
	s_nop 0
	global_load_lds_dwordx4 v[230:231], off
	v_lshl_add_u64 v[230:231], s[44:45], 0, v[136:137]
	s_add_i32 m0, s46, 0x2000
	s_nop 0
	global_load_lds_dwordx4 v[230:231], off
	v_lshl_add_u64 v[230:231], v[248:249], 0, s[28:29]
	s_mov_b32 m0, s73
	s_nop 0
	global_load_lds_dwordx4 v[230:231], off
	v_lshl_add_u64 v[230:231], v[250:251], 0, s[28:29]
	s_mov_b32 m0, s74
	s_nop 0
	global_load_lds_dwordx4 v[230:231], off
	s_waitcnt vmcnt(8)
	s_waitcnt lgkmcnt(0)
	s_barrier
	s_setprio 1
	s_waitcnt lgkmcnt(0)
	v_mfma_f32_16x16x32_bf16 v[62:65], v[164:167], v[202:205], v[62:65]
	v_mfma_f32_16x16x32_bf16 v[58:61], v[172:175], v[202:205], v[58:61]
	v_mfma_f32_16x16x32_bf16 v[46:49], v[164:167], v[210:213], v[46:49]
	v_mfma_f32_16x16x32_bf16 v[42:45], v[172:175], v[210:213], v[42:45]
	v_mfma_f32_16x16x32_bf16 v[30:33], v[164:167], v[218:221], v[30:33]
	v_mfma_f32_16x16x32_bf16 v[26:29], v[172:175], v[218:221], v[26:29]
	v_mfma_f32_16x16x32_bf16 v[14:17], v[164:167], v[240:243], v[14:17]
	v_mfma_f32_16x16x32_bf16 v[10:13], v[172:175], v[240:243], v[10:13]
	v_mfma_f32_16x16x32_bf16 v[62:65], v[168:171], v[206:209], v[62:65]
	v_mfma_f32_16x16x32_bf16 v[58:61], v[176:179], v[206:209], v[58:61]
	v_mfma_f32_16x16x32_bf16 v[46:49], v[168:171], v[214:217], v[46:49]
	v_mfma_f32_16x16x32_bf16 v[42:45], v[176:179], v[214:217], v[42:45]
	v_mfma_f32_16x16x32_bf16 v[30:33], v[168:171], v[222:225], v[30:33]
	v_mfma_f32_16x16x32_bf16 v[26:29], v[176:179], v[222:225], v[26:29]
	v_mfma_f32_16x16x32_bf16 v[14:17], v[168:171], v[244:247], v[14:17]
	v_mfma_f32_16x16x32_bf16 v[10:13], v[176:179], v[244:247], v[10:13]
	s_setprio 0
	s_setprio 1
	v_mfma_f32_16x16x32_bf16 v[54:57], v[180:183], v[202:205], v[54:57]
	v_mfma_f32_16x16x32_bf16 v[50:53], v[194:197], v[202:205], v[50:53]
	v_mfma_f32_16x16x32_bf16 v[38:41], v[180:183], v[210:213], v[38:41]
	v_mfma_f32_16x16x32_bf16 v[34:37], v[194:197], v[210:213], v[34:37]
	v_mfma_f32_16x16x32_bf16 v[22:25], v[180:183], v[218:221], v[22:25]
	v_mfma_f32_16x16x32_bf16 v[18:21], v[194:197], v[218:221], v[18:21]
	v_mfma_f32_16x16x32_bf16 v[6:9], v[180:183], v[240:243], v[6:9]
	v_mfma_f32_16x16x32_bf16 v[2:5], v[194:197], v[240:243], v[2:5]
	v_mfma_f32_16x16x32_bf16 v[54:57], v[190:193], v[206:209], v[54:57]
	v_mfma_f32_16x16x32_bf16 v[50:53], v[198:201], v[206:209], v[50:53]
	v_mfma_f32_16x16x32_bf16 v[38:41], v[190:193], v[214:217], v[38:41]
	v_mfma_f32_16x16x32_bf16 v[34:37], v[198:201], v[214:217], v[34:37]
	v_mfma_f32_16x16x32_bf16 v[22:25], v[190:193], v[222:225], v[22:25]
	v_mfma_f32_16x16x32_bf16 v[18:21], v[198:201], v[222:225], v[18:21]
	v_mfma_f32_16x16x32_bf16 v[6:9], v[190:193], v[244:247], v[6:9]
	v_mfma_f32_16x16x32_bf16 v[2:5], v[198:201], v[244:247], v[2:5]
	s_setprio 0
	s_barrier
	s_add_i32 s57, s57, 2
	s_add_u32 s42, s42, 0x100
	s_addc_u32 s43, s43, 0
	s_add_u32 s25, s25, 0x100
	s_addc_u32 s27, s27, 0
	s_cmp_gt_u32 s57, 29
	s_cbranch_scc0 .LBB0_320
	s_and_b64 vcc, exec, s[12:13]
	s_cbranch_vccz .LBB0_323
	s_barrier

.LBB0_508:
	s_add_u32 s20, s16, 0x100
	s_addc_u32 s21, s17, 0
	s_add_i32 s59, 0, 0x10000
	s_cmp_eq_u32 s57, 4
	s_cselect_b32 s25, s13, s21
	s_cselect_b32 s24, s12, s20
	v_add_u32_e32 v160, s59, v150
	s_cselect_b32 s23, s11, s43
	s_cselect_b32 s22, s19, s42
	s_add_i32 s62, 0, 0x14000
	ds_read_b128 v[146:149], v160
	ds_read_b128 v[166:169], v160 offset:1024
	ds_read_b128 v[170:173], v160 offset:2048
	ds_read_b128 v[174:177], v160 offset:3072
	v_add_u32_e32 v160, s62, v150
	ds_read_b128 v[180:183], v160
	ds_read_b128 v[184:187], v160 offset:1024
	ds_read_b128 v[188:191], v160 offset:2048
	ds_read_b128 v[192:195], v160 offset:3072
	v_lshl_add_u64 v[224:225], s[16:17], 0, v[138:139]
	s_add_i32 m0, s44, 0xc000
	ds_read_b128 v[196:199], v164
	ds_read_b128 v[200:203], v164 offset:1024
	ds_read_b128 v[204:207], v164 offset:2048
	ds_read_b128 v[208:211], v164 offset:3072
	ds_read_b128 v[212:215], v164 offset:4096
	ds_read_b128 v[216:219], v164 offset:5120
	ds_read_b128 v[220:223], v164 offset:6144
	ds_read_b128 v[240:243], v164 offset:7168
	global_load_lds_dwordx4 v[224:225], off
	v_lshl_add_u64 v[224:225], s[16:17], 0, v[140:141]
	s_add_i32 m0, s44, 0xe000
	s_nop 0
	global_load_lds_dwordx4 v[224:225], off
	s_waitcnt vmcnt(8)
	s_waitcnt lgkmcnt(0)
	s_barrier
	s_setprio 1
	s_waitcnt lgkmcnt(0)
	v_mfma_f32_16x16x32_bf16 v[128:131], v[146:149], v[196:199], v[128:131]
	v_mfma_f32_16x16x32_bf16 v[124:127], v[170:173], v[196:199], v[124:127]
	v_mfma_f32_16x16x32_bf16 v[110:113], v[146:149], v[204:207], v[110:113]
	v_mfma_f32_16x16x32_bf16 v[106:109], v[170:173], v[204:207], v[106:109]
	v_mfma_f32_16x16x32_bf16 v[94:97], v[146:149], v[212:215], v[94:97]
	v_mfma_f32_16x16x32_bf16 v[90:93], v[170:173], v[212:215], v[90:93]
	v_mfma_f32_16x16x32_bf16 v[78:81], v[146:149], v[220:223], v[78:81]
	v_mfma_f32_16x16x32_bf16 v[74:77], v[170:173], v[220:223], v[74:77]
	v_mfma_f32_16x16x32_bf16 v[128:131], v[166:169], v[200:203], v[128:131]
	v_mfma_f32_16x16x32_bf16 v[124:127], v[174:177], v[200:203], v[124:127]
	v_mfma_f32_16x16x32_bf16 v[110:113], v[166:169], v[208:211], v[110:113]
	v_mfma_f32_16x16x32_bf16 v[106:109], v[174:177], v[208:211], v[106:109]
	v_mfma_f32_16x16x32_bf16 v[94:97], v[166:169], v[216:219], v[94:97]
	v_mfma_f32_16x16x32_bf16 v[90:93], v[174:177], v[216:219], v[90:93]
	v_mfma_f32_16x16x32_bf16 v[78:81], v[166:169], v[240:243], v[78:81]
	v_mfma_f32_16x16x32_bf16 v[74:77], v[174:177], v[240:243], v[74:77]
	s_setprio 0
	s_setprio 1
	v_mfma_f32_16x16x32_bf16 v[120:123], v[180:183], v[196:199], v[120:123]
	v_mfma_f32_16x16x32_bf16 v[116:119], v[188:191], v[196:199], v[116:119]
	v_mfma_f32_16x16x32_bf16 v[102:105], v[180:183], v[204:207], v[102:105]
	v_mfma_f32_16x16x32_bf16 v[98:101], v[188:191], v[204:207], v[98:101]
	v_mfma_f32_16x16x32_bf16 v[86:89], v[180:183], v[212:215], v[86:89]
	v_mfma_f32_16x16x32_bf16 v[82:85], v[188:191], v[212:215], v[82:85]
	v_mfma_f32_16x16x32_bf16 v[70:73], v[180:183], v[220:223], v[70:73]
	v_mfma_f32_16x16x32_bf16 v[66:69], v[188:191], v[220:223], v[66:69]
	v_mfma_f32_16x16x32_bf16 v[120:123], v[184:187], v[200:203], v[120:123]
	v_mfma_f32_16x16x32_bf16 v[116:119], v[192:195], v[200:203], v[116:119]
	v_mfma_f32_16x16x32_bf16 v[102:105], v[184:187], v[208:211], v[102:105]
	v_mfma_f32_16x16x32_bf16 v[98:101], v[192:195], v[208:211], v[98:101]
	v_mfma_f32_16x16x32_bf16 v[86:89], v[184:187], v[216:219], v[86:89]
	v_mfma_f32_16x16x32_bf16 v[82:85], v[192:195], v[216:219], v[82:85]
	v_mfma_f32_16x16x32_bf16 v[70:73], v[184:187], v[240:243], v[70:73]
	v_mfma_f32_16x16x32_bf16 v[66:69], v[192:195], v[240:243], v[66:69]
	s_setprio 0
	s_barrier
	s_add_i32 s16, s59, s34
	v_lshl_add_u64 v[224:225], s[22:23], 0, v[114:115]
	s_mov_b32 m0, s16
	ds_read_b128 v[196:199], v164 offset:16384
	ds_read_b128 v[200:203], v164 offset:17408
	ds_read_b128 v[204:207], v164 offset:18432
	ds_read_b128 v[208:211], v164 offset:19456
	ds_read_b128 v[212:215], v164 offset:20480
	ds_read_b128 v[216:219], v164 offset:21504
	ds_read_b128 v[220:223], v164 offset:22528
	ds_read_b128 v[240:243], v164 offset:23552
	global_load_lds_dwordx4 v[224:225], off
	s_add_i32 m0, s16, 0x2000
	s_add_u32 s16, s22, 0x8000
	v_lshl_add_u64 v[230:231], s[22:23], 0, v[136:137]
	s_addc_u32 s17, s23, 0
	s_add_i32 s59, s62, s34
	global_load_lds_dwordx4 v[230:231], off
	v_lshl_add_u64 v[236:237], s[16:17], 0, v[114:115]
	s_mov_b32 m0, s59
	v_lshl_add_u64 v[238:239], s[24:25], 0, v[134:135]
	global_load_lds_dwordx4 v[236:237], off
	v_lshl_add_u64 v[236:237], s[16:17], 0, v[136:137]
	s_add_i32 m0, s59, 0x2000
	s_nop 0
	global_load_lds_dwordx4 v[236:237], off
	v_lshl_add_u64 v[236:237], s[24:25], 0, v[132:133]
	s_mov_b32 m0, s44
	s_nop 0
	global_load_lds_dwordx4 v[236:237], off
	s_mov_b32 m0, s45
	s_nop 0
	global_load_lds_dwordx4 v[238:239], off
	s_waitcnt vmcnt(8)
	s_waitcnt lgkmcnt(0)
	s_barrier
	s_setprio 1
	s_waitcnt lgkmcnt(0)
	v_mfma_f32_16x16x32_bf16 v[62:65], v[146:149], v[196:199], v[62:65]
	v_mfma_f32_16x16x32_bf16 v[58:61], v[170:173], v[196:199], v[58:61]
	v_mfma_f32_16x16x32_bf16 v[46:49], v[146:149], v[204:207], v[46:49]
	v_mfma_f32_16x16x32_bf16 v[42:45], v[170:173], v[204:207], v[42:45]
	v_mfma_f32_16x16x32_bf16 v[30:33], v[146:149], v[212:215], v[30:33]
	v_mfma_f32_16x16x32_bf16 v[26:29], v[170:173], v[212:215], v[26:29]
	v_mfma_f32_16x16x32_bf16 v[14:17], v[146:149], v[220:223], v[14:17]
	v_mfma_f32_16x16x32_bf16 v[10:13], v[170:173], v[220:223], v[10:13]
	v_mfma_f32_16x16x32_bf16 v[62:65], v[166:169], v[200:203], v[62:65]
	v_mfma_f32_16x16x32_bf16 v[58:61], v[174:177], v[200:203], v[58:61]
	v_mfma_f32_16x16x32_bf16 v[46:49], v[166:169], v[208:211], v[46:49]
	v_mfma_f32_16x16x32_bf16 v[42:45], v[174:177], v[208:211], v[42:45]
	v_mfma_f32_16x16x32_bf16 v[30:33], v[166:169], v[216:219], v[30:33]
	v_mfma_f32_16x16x32_bf16 v[26:29], v[174:177], v[216:219], v[26:29]
	v_mfma_f32_16x16x32_bf16 v[14:17], v[166:169], v[240:243], v[14:17]
	v_mfma_f32_16x16x32_bf16 v[10:13], v[174:177], v[240:243], v[10:13]
	s_setprio 0
	s_setprio 1
	v_mfma_f32_16x16x32_bf16 v[54:57], v[180:183], v[196:199], v[54:57]
	v_mfma_f32_16x16x32_bf16 v[50:53], v[188:191], v[196:199], v[50:53]
	v_mfma_f32_16x16x32_bf16 v[38:41], v[180:183], v[204:207], v[38:41]
	v_mfma_f32_16x16x32_bf16 v[34:37], v[188:191], v[204:207], v[34:37]
	v_mfma_f32_16x16x32_bf16 v[22:25], v[180:183], v[212:215], v[22:25]
	v_mfma_f32_16x16x32_bf16 v[18:21], v[188:191], v[212:215], v[18:21]
	v_mfma_f32_16x16x32_bf16 v[6:9], v[180:183], v[220:223], v[6:9]
	v_mfma_f32_16x16x32_bf16 v[2:5], v[188:191], v[220:223], v[2:5]
	v_mfma_f32_16x16x32_bf16 v[54:57], v[184:187], v[200:203], v[54:57]
	v_mfma_f32_16x16x32_bf16 v[50:53], v[192:195], v[200:203], v[50:53]
	v_mfma_f32_16x16x32_bf16 v[38:41], v[184:187], v[208:211], v[38:41]
	v_mfma_f32_16x16x32_bf16 v[34:37], v[192:195], v[208:211], v[34:37]
	v_mfma_f32_16x16x32_bf16 v[22:25], v[184:187], v[216:219], v[22:25]
	v_mfma_f32_16x16x32_bf16 v[18:21], v[192:195], v[216:219], v[18:21]
	v_mfma_f32_16x16x32_bf16 v[6:9], v[184:187], v[240:243], v[6:9]
	v_mfma_f32_16x16x32_bf16 v[2:5], v[192:195], v[240:243], v[2:5]
	s_setprio 0
	s_barrier
	s_add_i32 s59, 0, 0x18000
	v_add_u32_e32 v160, s59, v150
	s_add_i32 s62, 0, 0x1c000
	ds_read_b128 v[146:149], v160
	ds_read_b128 v[166:169], v160 offset:1024
	ds_read_b128 v[170:173], v160 offset:2048
	ds_read_b128 v[174:177], v160 offset:3072
	v_add_u32_e32 v160, s62, v150
	ds_read_b128 v[180:183], v160
	ds_read_b128 v[184:187], v160 offset:1024
	ds_read_b128 v[188:191], v160 offset:2048
	ds_read_b128 v[192:195], v160 offset:3072
	s_add_u32 s16, s24, 0xc0000
	s_addc_u32 s17, s25, 0
	s_mov_b32 m0, s46
	v_lshl_add_u64 v[244:245], s[16:17], 0, v[132:133]
	ds_read_b128 v[196:199], v164 offset:32768
	ds_read_b128 v[200:203], v164 offset:33792
	ds_read_b128 v[204:207], v164 offset:34816
	ds_read_b128 v[208:211], v164 offset:35840
	ds_read_b128 v[212:215], v164 offset:36864
	ds_read_b128 v[216:219], v164 offset:37888
	ds_read_b128 v[220:223], v164 offset:38912
	ds_read_b128 v[240:243], v164 offset:39936
	global_load_lds_dwordx4 v[244:245], off
	v_lshl_add_u64 v[244:245], s[16:17], 0, v[134:135]
	s_mov_b32 m0, s47
	s_nop 0
	global_load_lds_dwordx4 v[244:245], off
	s_waitcnt vmcnt(8)
	s_waitcnt lgkmcnt(0)
	s_barrier
	s_setprio 1
	s_waitcnt lgkmcnt(0)
	v_mfma_f32_16x16x32_bf16 v[128:131], v[146:149], v[196:199], v[128:131]
	v_mfma_f32_16x16x32_bf16 v[124:127], v[170:173], v[196:199], v[124:127]
	v_mfma_f32_16x16x32_bf16 v[110:113], v[146:149], v[204:207], v[110:113]
	v_mfma_f32_16x16x32_bf16 v[106:109], v[170:173], v[204:207], v[106:109]
	v_mfma_f32_16x16x32_bf16 v[94:97], v[146:149], v[212:215], v[94:97]
	v_mfma_f32_16x16x32_bf16 v[90:93], v[170:173], v[212:215], v[90:93]
	v_mfma_f32_16x16x32_bf16 v[78:81], v[146:149], v[220:223], v[78:81]
	v_mfma_f32_16x16x32_bf16 v[74:77], v[170:173], v[220:223], v[74:77]
	v_mfma_f32_16x16x32_bf16 v[128:131], v[166:169], v[200:203], v[128:131]
	v_mfma_f32_16x16x32_bf16 v[124:127], v[174:177], v[200:203], v[124:127]
	v_mfma_f32_16x16x32_bf16 v[110:113], v[166:169], v[208:211], v[110:113]
	v_mfma_f32_16x16x32_bf16 v[106:109], v[174:177], v[208:211], v[106:109]
	v_mfma_f32_16x16x32_bf16 v[94:97], v[166:169], v[216:219], v[94:97]
	v_mfma_f32_16x16x32_bf16 v[90:93], v[174:177], v[216:219], v[90:93]
	v_mfma_f32_16x16x32_bf16 v[78:81], v[166:169], v[240:243], v[78:81]
	v_mfma_f32_16x16x32_bf16 v[74:77], v[174:177], v[240:243], v[74:77]
	s_setprio 0
	s_setprio 1
	v_mfma_f32_16x16x32_bf16 v[120:123], v[180:183], v[196:199], v[120:123]
	v_mfma_f32_16x16x32_bf16 v[116:119], v[188:191], v[196:199], v[116:119]
	v_mfma_f32_16x16x32_bf16 v[102:105], v[180:183], v[204:207], v[102:105]
	v_mfma_f32_16x16x32_bf16 v[98:101], v[188:191], v[204:207], v[98:101]
	v_mfma_f32_16x16x32_bf16 v[86:89], v[180:183], v[212:215], v[86:89]
	v_mfma_f32_16x16x32_bf16 v[82:85], v[188:191], v[212:215], v[82:85]
	v_mfma_f32_16x16x32_bf16 v[70:73], v[180:183], v[220:223], v[70:73]
	v_mfma_f32_16x16x32_bf16 v[66:69], v[188:191], v[220:223], v[66:69]
	v_mfma_f32_16x16x32_bf16 v[120:123], v[184:187], v[200:203], v[120:123]
	v_mfma_f32_16x16x32_bf16 v[116:119], v[192:195], v[200:203], v[116:119]
	v_mfma_f32_16x16x32_bf16 v[102:105], v[184:187], v[208:211], v[102:105]
	v_mfma_f32_16x16x32_bf16 v[98:101], v[192:195], v[208:211], v[98:101]
	v_mfma_f32_16x16x32_bf16 v[86:89], v[184:187], v[216:219], v[86:89]
	v_mfma_f32_16x16x32_bf16 v[82:85], v[192:195], v[216:219], v[82:85]
	v_mfma_f32_16x16x32_bf16 v[70:73], v[184:187], v[240:243], v[70:73]
	v_mfma_f32_16x16x32_bf16 v[66:69], v[192:195], v[240:243], v[66:69]
	s_setprio 0
	s_barrier
	s_add_i32 s16, s59, s34
	v_lshl_add_u64 v[224:225], v[224:225], 0, s[28:29]
	s_mov_b32 m0, s16
	ds_read_b128 v[196:199], v164 offset:49152
	ds_read_b128 v[200:203], v164 offset:50176
	ds_read_b128 v[204:207], v164 offset:51200
	ds_read_b128 v[208:211], v164 offset:52224
	ds_read_b128 v[212:215], v164 offset:53248
	ds_read_b128 v[216:219], v164 offset:54272
	ds_read_b128 v[220:223], v164 offset:55296
	ds_read_b128 v[240:243], v164 offset:56320
	global_load_lds_dwordx4 v[224:225], off
	s_add_i32 m0, s16, 0x2000
	s_add_u32 s16, s22, 0x8080
	v_lshl_add_u64 v[224:225], v[230:231], 0, s[28:29]
	s_addc_u32 s17, s23, 0
	s_add_i32 s22, s62, s34
	global_load_lds_dwordx4 v[224:225], off
	v_lshl_add_u64 v[224:225], s[16:17], 0, v[114:115]
	s_mov_b32 m0, s22
	s_nop 0
	global_load_lds_dwordx4 v[224:225], off
	v_lshl_add_u64 v[224:225], s[16:17], 0, v[136:137]
	s_add_i32 m0, s22, 0x2000
	s_nop 0
	global_load_lds_dwordx4 v[224:225], off
	v_lshl_add_u64 v[224:225], v[236:237], 0, s[28:29]
	s_mov_b32 m0, s50
	s_nop 0
	global_load_lds_dwordx4 v[224:225], off
	v_lshl_add_u64 v[224:225], v[238:239], 0, s[28:29]
	s_mov_b32 m0, s51
	s_nop 0
	global_load_lds_dwordx4 v[224:225], off
	s_waitcnt vmcnt(8)
	s_waitcnt lgkmcnt(0)
	s_barrier
	s_setprio 1
	s_waitcnt lgkmcnt(0)
	v_mfma_f32_16x16x32_bf16 v[62:65], v[146:149], v[196:199], v[62:65]
	v_mfma_f32_16x16x32_bf16 v[58:61], v[170:173], v[196:199], v[58:61]
	v_mfma_f32_16x16x32_bf16 v[46:49], v[146:149], v[204:207], v[46:49]
	v_mfma_f32_16x16x32_bf16 v[42:45], v[170:173], v[204:207], v[42:45]
	v_mfma_f32_16x16x32_bf16 v[30:33], v[146:149], v[212:215], v[30:33]
	v_mfma_f32_16x16x32_bf16 v[26:29], v[170:173], v[212:215], v[26:29]
	v_mfma_f32_16x16x32_bf16 v[14:17], v[146:149], v[220:223], v[14:17]
	v_mfma_f32_16x16x32_bf16 v[10:13], v[170:173], v[220:223], v[10:13]
	v_mfma_f32_16x16x32_bf16 v[62:65], v[166:169], v[200:203], v[62:65]
	v_mfma_f32_16x16x32_bf16 v[58:61], v[174:177], v[200:203], v[58:61]
	v_mfma_f32_16x16x32_bf16 v[46:49], v[166:169], v[208:211], v[46:49]
	v_mfma_f32_16x16x32_bf16 v[42:45], v[174:177], v[208:211], v[42:45]
	v_mfma_f32_16x16x32_bf16 v[30:33], v[166:169], v[216:219], v[30:33]
	v_mfma_f32_16x16x32_bf16 v[26:29], v[174:177], v[216:219], v[26:29]
	v_mfma_f32_16x16x32_bf16 v[14:17], v[166:169], v[240:243], v[14:17]
	v_mfma_f32_16x16x32_bf16 v[10:13], v[174:177], v[240:243], v[10:13]
	s_setprio 0
	s_setprio 1
	v_mfma_f32_16x16x32_bf16 v[54:57], v[180:183], v[196:199], v[54:57]
	v_mfma_f32_16x16x32_bf16 v[50:53], v[188:191], v[196:199], v[50:53]
	v_mfma_f32_16x16x32_bf16 v[38:41], v[180:183], v[204:207], v[38:41]
	v_mfma_f32_16x16x32_bf16 v[34:37], v[188:191], v[204:207], v[34:37]
	v_mfma_f32_16x16x32_bf16 v[22:25], v[180:183], v[212:215], v[22:25]
	v_mfma_f32_16x16x32_bf16 v[18:21], v[188:191], v[212:215], v[18:21]
	v_mfma_f32_16x16x32_bf16 v[6:9], v[180:183], v[220:223], v[6:9]
	v_mfma_f32_16x16x32_bf16 v[2:5], v[188:191], v[220:223], v[2:5]
	v_mfma_f32_16x16x32_bf16 v[54:57], v[184:187], v[200:203], v[54:57]
	v_mfma_f32_16x16x32_bf16 v[50:53], v[192:195], v[200:203], v[50:53]
	v_mfma_f32_16x16x32_bf16 v[38:41], v[184:187], v[208:211], v[38:41]
	v_mfma_f32_16x16x32_bf16 v[34:37], v[192:195], v[208:211], v[34:37]
	v_mfma_f32_16x16x32_bf16 v[22:25], v[184:187], v[216:219], v[22:25]
	v_mfma_f32_16x16x32_bf16 v[18:21], v[192:195], v[216:219], v[18:21]
	v_mfma_f32_16x16x32_bf16 v[6:9], v[184:187], v[240:243], v[6:9]
	v_mfma_f32_16x16x32_bf16 v[2:5], v[192:195], v[240:243], v[2:5]
	s_setprio 0
	s_barrier
	s_add_i32 s57, s57, 2
	s_add_u32 s42, s42, 0x100
	s_addc_u32 s43, s43, 0
	s_cmp_gt_u32 s57, 5
	s_mov_b64 s[16:17], s[20:21]
	s_cbranch_scc0 .LBB0_508
	s_and_b64 vcc, exec, s[8:9]
	s_cbranch_vccz .LBB0_511
	s_barrier
.LBB0_511:
	s_lshl_b32 s11, s56, 8
	s_mul_i32 s16, s56, 0xc0000
	s_mul_hi_i32 s11, s11, 0xc00
	s_add_u32 s19, s48, s16
	s_addc_u32 s11, s49, s11
	s_lshl_b32 s16, s18, 8
	s_ashr_i32 s17, s16, 31
	s_lshl_b64 s[16:17], s[16:17], 1
	s_add_u32 s16, s19, s16
	s_addc_u32 s17, s11, s17
	s_cmp_lg_u32 s18, -1
	v_lshl_add_u64 v[148:149], s[16:17], 0, v[142:143]
	v_lshl_add_u64 v[146:147], s[16:17], 0, v[144:145]
	s_cbranch_scc0 .LBB0_514
	v_cvt_pk_bf16_f32 v160, v128, v129
	v_cvt_pk_bf16_f32 v161, v130, v131
	v_cvt_pk_bf16_f32 v165, v124, v125
	v_cvt_pk_bf16_f32 v169, v126, v127
	v_cvt_pk_bf16_f32 v170, v120, v121
	v_mov_b32_e32 v175, v115
	v_cndmask_b32_e64 v174, v170, v160, s[38:39]
	v_cvt_pk_bf16_f32 v171, v122, v123
	v_cvt_pk_bf16_f32 v172, v116, v117
	v_cvt_pk_bf16_f32 v173, v118, v119
	v_mov_b32_e32 v176, v115
	v_cndmask_b32_e64 v166, v173, v169, s[38:39]
	v_cndmask_b32_e64 v167, v172, v165, s[38:39]
	v_cndmask_b32_e64 v168, v171, v161, s[38:39]
	v_mov_b32_dpp v175, v174 quad_perm:[1,0,3,2] row_mask:0xf bank_mask:0xf
	v_mov_b32_e32 v174, v115
	v_mov_b32_e32 v177, v115
	v_mov_b32_dpp v176, v167 quad_perm:[1,0,3,2] row_mask:0xf bank_mask:0xf
	v_mov_b32_dpp v174, v168 quad_perm:[1,0,3,2] row_mask:0xf bank_mask:0xf
	v_mov_b32_dpp v177, v166 quad_perm:[1,0,3,2] row_mask:0xf bank_mask:0xf
	v_cndmask_b32_e64 v166, v160, v175, s[38:39]
	v_cndmask_b32_e64 v167, v161, v174, s[38:39]
	v_cndmask_b32_e64 v168, v165, v176, s[38:39]
	v_cndmask_b32_e64 v169, v169, v177, s[38:39]
	global_store_dwordx4 v[148:149], v[166:169], off nt
	s_add_u32 s18, s16, 0xc000
	v_mov_b32_e32 v179, v115
	v_cndmask_b32_e64 v166, v175, v170, s[38:39]
	v_cndmask_b32_e64 v167, v174, v171, s[38:39]
	v_cndmask_b32_e64 v168, v176, v172, s[38:39]
	v_cndmask_b32_e64 v169, v177, v173, s[38:39]
	global_store_dwordx4 v[146:147], v[166:169], off nt
	v_cvt_pk_bf16_f32 v160, v110, v111
	v_cvt_pk_bf16_f32 v161, v112, v113
	v_cvt_pk_bf16_f32 v165, v106, v107
	v_mov_b32_e32 v176, v115
	s_nop 0
	v_cvt_pk_bf16_f32 v169, v108, v109
	v_cvt_pk_bf16_f32 v172, v102, v103
	v_cvt_pk_bf16_f32 v173, v104, v105
	v_cvt_pk_bf16_f32 v174, v98, v99
	v_cvt_pk_bf16_f32 v175, v100, v101
	v_mov_b32_e32 v177, v115
	v_cndmask_b32_e64 v166, v175, v169, s[38:39]
	v_cndmask_b32_e64 v167, v174, v165, s[38:39]
	v_cndmask_b32_e64 v168, v173, v161, s[38:39]
	v_cndmask_b32_e64 v170, v172, v160, s[38:39]
	v_mov_b32_e32 v180, v115
	s_addc_u32 s19, s17, 0
	v_mov_b32_dpp v176, v170 quad_perm:[1,0,3,2] row_mask:0xf bank_mask:0xf
	v_mov_b32_dpp v177, v168 quad_perm:[1,0,3,2] row_mask:0xf bank_mask:0xf
	v_mov_b32_dpp v179, v167 quad_perm:[1,0,3,2] row_mask:0xf bank_mask:0xf
	v_mov_b32_dpp v180, v166 quad_perm:[1,0,3,2] row_mask:0xf bank_mask:0xf
	v_cndmask_b32_e64 v166, v160, v176, s[38:39]
	v_cndmask_b32_e64 v167, v161, v177, s[38:39]
	v_cndmask_b32_e64 v168, v165, v179, s[38:39]
	v_cndmask_b32_e64 v169, v169, v180, s[38:39]
	v_lshl_add_u64 v[170:171], s[18:19], 0, v[142:143]
	global_store_dwordx4 v[170:171], v[166:169], off nt
	v_lshl_add_u64 v[170:171], s[18:19], 0, v[144:145]
	s_add_u32 s18, s16, 0x18000
	v_cndmask_b32_e64 v166, v176, v172, s[38:39]
	v_cndmask_b32_e64 v167, v177, v173, s[38:39]
	v_cndmask_b32_e64 v168, v179, v174, s[38:39]
	v_cndmask_b32_e64 v169, v180, v175, s[38:39]
	global_store_dwordx4 v[170:171], v[166:169], off nt
	v_cvt_pk_bf16_f32 v160, v94, v95
	v_cvt_pk_bf16_f32 v161, v96, v97
	v_cvt_pk_bf16_f32 v165, v90, v91
	v_mov_b32_e32 v176, v115
	s_nop 0
	v_cvt_pk_bf16_f32 v169, v92, v93
	v_cvt_pk_bf16_f32 v172, v86, v87
	v_cvt_pk_bf16_f32 v173, v88, v89
	v_cvt_pk_bf16_f32 v174, v82, v83
	v_cvt_pk_bf16_f32 v175, v84, v85
	v_mov_b32_e32 v177, v115
	v_cndmask_b32_e64 v166, v175, v169, s[38:39]
	v_cndmask_b32_e64 v167, v174, v165, s[38:39]
	v_cndmask_b32_e64 v168, v173, v161, s[38:39]
	v_cndmask_b32_e64 v170, v172, v160, s[38:39]
	v_mov_b32_e32 v179, v115
	v_mov_b32_e32 v180, v115
	s_addc_u32 s19, s17, 0
	v_mov_b32_dpp v176, v170 quad_perm:[1,0,3,2] row_mask:0xf bank_mask:0xf
	v_mov_b32_dpp v177, v168 quad_perm:[1,0,3,2] row_mask:0xf bank_mask:0xf
	v_mov_b32_dpp v179, v167 quad_perm:[1,0,3,2] row_mask:0xf bank_mask:0xf
	v_mov_b32_dpp v180, v166 quad_perm:[1,0,3,2] row_mask:0xf bank_mask:0xf
	v_cndmask_b32_e64 v166, v160, v176, s[38:39]
	v_cndmask_b32_e64 v167, v161, v177, s[38:39]
	v_cndmask_b32_e64 v168, v165, v179, s[38:39]
	v_cndmask_b32_e64 v169, v169, v180, s[38:39]
	v_lshl_add_u64 v[170:171], s[18:19], 0, v[142:143]
	global_store_dwordx4 v[170:171], v[166:169], off nt
	v_lshl_add_u64 v[170:171], s[18:19], 0, v[144:145]
	s_add_u32 s18, s16, 0x24000
	v_cndmask_b32_e64 v166, v176, v172, s[38:39]
	v_cndmask_b32_e64 v167, v177, v173, s[38:39]
	v_cndmask_b32_e64 v168, v179, v174, s[38:39]
	v_cndmask_b32_e64 v169, v180, v175, s[38:39]
	global_store_dwordx4 v[170:171], v[166:169], off nt
	v_cvt_pk_bf16_f32 v160, v78, v79
	v_cvt_pk_bf16_f32 v161, v80, v81
	v_cvt_pk_bf16_f32 v165, v74, v75
	v_mov_b32_e32 v176, v115
	s_nop 0
	v_cvt_pk_bf16_f32 v169, v76, v77
	v_cvt_pk_bf16_f32 v172, v70, v71
	v_cvt_pk_bf16_f32 v173, v72, v73
	v_cvt_pk_bf16_f32 v174, v66, v67
	v_cvt_pk_bf16_f32 v175, v68, v69
	v_mov_b32_e32 v177, v115
	v_cndmask_b32_e64 v166, v175, v169, s[38:39]
	v_cndmask_b32_e64 v167, v174, v165, s[38:39]
	v_cndmask_b32_e64 v168, v173, v161, s[38:39]
	v_cndmask_b32_e64 v170, v172, v160, s[38:39]
	v_mov_b32_e32 v179, v115
	v_mov_b32_e32 v180, v115
	s_addc_u32 s19, s17, 0
	v_mov_b32_dpp v176, v170 quad_perm:[1,0,3,2] row_mask:0xf bank_mask:0xf
	v_mov_b32_dpp v177, v168 quad_perm:[1,0,3,2] row_mask:0xf bank_mask:0xf
	v_mov_b32_dpp v179, v167 quad_perm:[1,0,3,2] row_mask:0xf bank_mask:0xf
	v_mov_b32_dpp v180, v166 quad_perm:[1,0,3,2] row_mask:0xf bank_mask:0xf
	v_cndmask_b32_e64 v166, v160, v176, s[38:39]
	v_cndmask_b32_e64 v167, v161, v177, s[38:39]
	v_cndmask_b32_e64 v168, v165, v179, s[38:39]
	v_cndmask_b32_e64 v169, v169, v180, s[38:39]
	v_lshl_add_u64 v[170:171], s[18:19], 0, v[142:143]
	global_store_dwordx4 v[170:171], v[166:169], off nt
	v_lshl_add_u64 v[170:171], s[18:19], 0, v[144:145]
	s_add_u32 s18, s16, 0x60000
	v_cndmask_b32_e64 v166, v176, v172, s[38:39]
	v_cndmask_b32_e64 v167, v177, v173, s[38:39]
	v_cndmask_b32_e64 v168, v179, v174, s[38:39]
	v_cndmask_b32_e64 v169, v180, v175, s[38:39]
	global_store_dwordx4 v[170:171], v[166:169], off nt
	v_cvt_pk_bf16_f32 v160, v62, v63
	v_cvt_pk_bf16_f32 v161, v64, v65
	v_cvt_pk_bf16_f32 v165, v58, v59
	v_mov_b32_e32 v176, v115
	s_nop 0
	v_cvt_pk_bf16_f32 v169, v60, v61
	v_cvt_pk_bf16_f32 v172, v54, v55
	v_cvt_pk_bf16_f32 v173, v56, v57
	v_cvt_pk_bf16_f32 v174, v50, v51
	v_cvt_pk_bf16_f32 v175, v52, v53
	v_mov_b32_e32 v177, v115
	v_cndmask_b32_e64 v166, v175, v169, s[38:39]
	v_cndmask_b32_e64 v167, v174, v165, s[38:39]
	v_cndmask_b32_e64 v168, v173, v161, s[38:39]
	v_cndmask_b32_e64 v170, v172, v160, s[38:39]
	v_mov_b32_e32 v179, v115
	v_mov_b32_e32 v180, v115
	s_addc_u32 s19, s17, 0
	v_mov_b32_dpp v176, v170 quad_perm:[1,0,3,2] row_mask:0xf bank_mask:0xf
	v_mov_b32_dpp v177, v168 quad_perm:[1,0,3,2] row_mask:0xf bank_mask:0xf
	v_mov_b32_dpp v179, v167 quad_perm:[1,0,3,2] row_mask:0xf bank_mask:0xf
	v_mov_b32_dpp v180, v166 quad_perm:[1,0,3,2] row_mask:0xf bank_mask:0xf
	v_cndmask_b32_e64 v166, v160, v176, s[38:39]
	v_cndmask_b32_e64 v167, v161, v177, s[38:39]
	v_cndmask_b32_e64 v168, v165, v179, s[38:39]
	v_cndmask_b32_e64 v169, v169, v180, s[38:39]
	v_lshl_add_u64 v[170:171], s[18:19], 0, v[142:143]
	global_store_dwordx4 v[170:171], v[166:169], off nt
	v_lshl_add_u64 v[170:171], s[18:19], 0, v[144:145]
	s_add_u32 s18, s16, 0x6c000
	v_cndmask_b32_e64 v166, v176, v172, s[38:39]
	v_cndmask_b32_e64 v167, v177, v173, s[38:39]
	v_cndmask_b32_e64 v168, v179, v174, s[38:39]
	v_cndmask_b32_e64 v169, v180, v175, s[38:39]
	global_store_dwordx4 v[170:171], v[166:169], off nt
	v_cvt_pk_bf16_f32 v160, v46, v47
	v_cvt_pk_bf16_f32 v161, v48, v49
	v_cvt_pk_bf16_f32 v165, v42, v43
	v_mov_b32_e32 v176, v115
	s_nop 0
	v_cvt_pk_bf16_f32 v169, v44, v45
	v_cvt_pk_bf16_f32 v172, v38, v39
	v_cvt_pk_bf16_f32 v173, v40, v41
	v_cvt_pk_bf16_f32 v174, v34, v35
	v_cvt_pk_bf16_f32 v175, v36, v37
	v_mov_b32_e32 v177, v115
	v_cndmask_b32_e64 v166, v175, v169, s[38:39]
	v_cndmask_b32_e64 v167, v174, v165, s[38:39]
	v_cndmask_b32_e64 v168, v173, v161, s[38:39]
	v_cndmask_b32_e64 v170, v172, v160, s[38:39]
	v_mov_b32_e32 v179, v115
	v_mov_b32_e32 v180, v115
	s_addc_u32 s19, s17, 0
	v_mov_b32_dpp v176, v170 quad_perm:[1,0,3,2] row_mask:0xf bank_mask:0xf
	v_mov_b32_dpp v177, v168 quad_perm:[1,0,3,2] row_mask:0xf bank_mask:0xf
	v_mov_b32_dpp v179, v167 quad_perm:[1,0,3,2] row_mask:0xf bank_mask:0xf
	v_mov_b32_dpp v180, v166 quad_perm:[1,0,3,2] row_mask:0xf bank_mask:0xf
	v_cndmask_b32_e64 v166, v160, v176, s[38:39]
	v_cndmask_b32_e64 v167, v161, v177, s[38:39]
	v_cndmask_b32_e64 v168, v165, v179, s[38:39]
	v_cndmask_b32_e64 v169, v169, v180, s[38:39]
	v_lshl_add_u64 v[170:171], s[18:19], 0, v[142:143]
	global_store_dwordx4 v[170:171], v[166:169], off nt
	v_lshl_add_u64 v[170:171], s[18:19], 0, v[144:145]
	s_add_u32 s18, s16, 0x78000
	v_cndmask_b32_e64 v166, v176, v172, s[38:39]
	v_cndmask_b32_e64 v167, v177, v173, s[38:39]
	v_cndmask_b32_e64 v168, v179, v174, s[38:39]
	v_cndmask_b32_e64 v169, v180, v175, s[38:39]
	global_store_dwordx4 v[170:171], v[166:169], off nt
	v_cvt_pk_bf16_f32 v160, v30, v31
	v_cvt_pk_bf16_f32 v161, v32, v33
	v_cvt_pk_bf16_f32 v165, v26, v27
	v_mov_b32_e32 v176, v115
	s_nop 0
	v_cvt_pk_bf16_f32 v169, v28, v29
	v_cvt_pk_bf16_f32 v172, v22, v23
	v_cvt_pk_bf16_f32 v173, v24, v25
	v_cvt_pk_bf16_f32 v174, v18, v19
	v_cvt_pk_bf16_f32 v175, v20, v21
	v_mov_b32_e32 v177, v115
	v_cndmask_b32_e64 v166, v175, v169, s[38:39]
	v_cndmask_b32_e64 v167, v174, v165, s[38:39]
	v_cndmask_b32_e64 v168, v173, v161, s[38:39]
	v_cndmask_b32_e64 v170, v172, v160, s[38:39]
	v_mov_b32_e32 v179, v115
	v_mov_b32_e32 v180, v115
	s_addc_u32 s19, s17, 0
	v_mov_b32_dpp v176, v170 quad_perm:[1,0,3,2] row_mask:0xf bank_mask:0xf
	v_mov_b32_dpp v177, v168 quad_perm:[1,0,3,2] row_mask:0xf bank_mask:0xf
	v_mov_b32_dpp v179, v167 quad_perm:[1,0,3,2] row_mask:0xf bank_mask:0xf
	v_mov_b32_dpp v180, v166 quad_perm:[1,0,3,2] row_mask:0xf bank_mask:0xf
	v_cndmask_b32_e64 v166, v160, v176, s[38:39]
	v_cndmask_b32_e64 v167, v161, v177, s[38:39]
	v_cndmask_b32_e64 v168, v165, v179, s[38:39]
	v_cndmask_b32_e64 v169, v169, v180, s[38:39]
	v_lshl_add_u64 v[170:171], s[18:19], 0, v[142:143]
	global_store_dwordx4 v[170:171], v[166:169], off nt
	v_lshl_add_u64 v[170:171], s[18:19], 0, v[144:145]
	s_add_u32 s18, s16, 0x84000
	v_cndmask_b32_e64 v166, v176, v172, s[38:39]
	v_cndmask_b32_e64 v167, v177, v173, s[38:39]
	v_cndmask_b32_e64 v168, v179, v174, s[38:39]
	v_cndmask_b32_e64 v169, v180, v175, s[38:39]
	global_store_dwordx4 v[170:171], v[166:169], off nt
	v_cvt_pk_bf16_f32 v160, v14, v15
	v_cvt_pk_bf16_f32 v161, v16, v17
	v_cvt_pk_bf16_f32 v165, v10, v11
	v_mov_b32_e32 v176, v115
	s_nop 0
	v_cvt_pk_bf16_f32 v169, v12, v13
	v_cvt_pk_bf16_f32 v172, v6, v7
	v_cvt_pk_bf16_f32 v173, v8, v9
	v_cvt_pk_bf16_f32 v174, v2, v3
	v_cvt_pk_bf16_f32 v175, v4, v5
	v_mov_b32_e32 v177, v115
	v_cndmask_b32_e64 v166, v175, v169, s[38:39]
	v_cndmask_b32_e64 v167, v174, v165, s[38:39]
	v_cndmask_b32_e64 v168, v173, v161, s[38:39]
	v_cndmask_b32_e64 v170, v172, v160, s[38:39]
	v_mov_b32_e32 v179, v115
	v_mov_b32_e32 v180, v115
	s_addc_u32 s19, s17, 0
	v_mov_b32_dpp v176, v170 quad_perm:[1,0,3,2] row_mask:0xf bank_mask:0xf
	v_mov_b32_dpp v177, v168 quad_perm:[1,0,3,2] row_mask:0xf bank_mask:0xf
	v_mov_b32_dpp v179, v167 quad_perm:[1,0,3,2] row_mask:0xf bank_mask:0xf
	v_mov_b32_dpp v180, v166 quad_perm:[1,0,3,2] row_mask:0xf bank_mask:0xf
	v_cndmask_b32_e64 v166, v160, v176, s[38:39]
	v_cndmask_b32_e64 v167, v161, v177, s[38:39]
	v_cndmask_b32_e64 v168, v165, v179, s[38:39]
	v_cndmask_b32_e64 v169, v169, v180, s[38:39]
	v_lshl_add_u64 v[170:171], s[18:19], 0, v[142:143]
	global_store_dwordx4 v[170:171], v[166:169], off nt
	v_lshl_add_u64 v[170:171], s[18:19], 0, v[144:145]
	s_nop 0
	v_cndmask_b32_e64 v166, v176, v172, s[38:39]
	v_cndmask_b32_e64 v167, v177, v173, s[38:39]
	v_cndmask_b32_e64 v168, v179, v174, s[38:39]
	v_cndmask_b32_e64 v169, v180, v175, s[38:39]
	global_store_dwordx4 v[170:171], v[166:169], off nt
	s_cbranch_execz .LBB0_515
	s_and_b64 vcc, exec, s[40:41]
	s_mov_b64 s[16:17], -1
	s_cbranch_vccnz .LBB0_502
	s_branch .LBB0_532

.LBB0_531:
	s_or_b64 exec, exec, s[18:19]
	s_waitcnt lgkmcnt(0)
	s_barrier
	s_waitcnt lgkmcnt(0)
	ds_read_b128 v[166:169], v151
	s_mov_b32 s11, 0x3b800000
	s_waitcnt lgkmcnt(0)
	v_mov_b32_e32 v170, v167
	v_mov_b32_e32 v171, v168
	v_mov_b32_e32 v167, v169
	v_pk_add_f32 v[166:167], v[170:171], v[166:167]
	s_nop 0
	v_add_f32_e32 v160, v166, v167
	v_fma_f32 v160, v160, s11, 0
	v_mul_f32_e32 v161, 0x4f800000, v160
	v_cmp_gt_f32_e32 vcc, s70, v160
	s_nop 1
	v_cndmask_b32_e32 v160, v160, v161, vcc
	v_sqrt_f32_e32 v161, v160
	s_nop 0
	v_add_u32_e32 v165, -1, v161
	v_fma_f32 v167, -v165, v161, v160
	v_add_u32_e32 v166, 1, v161
	v_cmp_ge_f32_e64 s[42:43], 0, v167
	s_nop 1
	v_cndmask_b32_e64 v165, v161, v165, s[42:43]
	v_fma_f32 v161, -v166, v161, v160
	v_cmp_lt_f32_e64 s[42:43], 0, v161
	s_nop 1
	v_cndmask_b32_e64 v161, v165, v166, s[42:43]
	v_mul_f32_e32 v165, 0x37800000, v161
	v_cndmask_b32_e32 v161, v161, v165, vcc
	v_cmp_class_f32_e32 vcc, v160, v226
	s_nop 1
	v_cndmask_b32_e32 v160, v161, v160, vcc
	v_div_scale_f32 v161, s[18:19], v160, v160, 1.0
	v_rcp_f32_e32 v165, v161
	s_nop 0
	v_fma_f32 v166, -v161, v165, 1.0
	v_fmac_f32_e32 v165, v166, v165
	v_div_scale_f32 v166, vcc, 1.0, v160, 1.0
	v_mul_f32_e32 v167, v166, v165
	v_fma_f32 v168, -v161, v167, v166
	v_fmac_f32_e32 v167, v168, v165
	v_fma_f32 v161, -v161, v167, v166
	v_div_fmas_f32 v161, v161, v165, v167
	v_div_fixup_f32 v166, v161, v160, 1.0
	v_pk_mul_f32 v[130:131], v[130:131], v[166:167] op_sel_hi:[1,0]
	v_pk_mul_f32 v[128:129], v[128:129], v[166:167] op_sel_hi:[1,0]
	v_pk_mul_f32 v[126:127], v[126:127], v[166:167] op_sel_hi:[1,0]
	v_pk_mul_f32 v[124:125], v[124:125], v[166:167] op_sel_hi:[1,0]
	v_pk_mul_f32 v[122:123], v[122:123], v[166:167] op_sel_hi:[1,0]
	v_pk_mul_f32 v[120:121], v[120:121], v[166:167] op_sel_hi:[1,0]
	v_pk_mul_f32 v[118:119], v[118:119], v[166:167] op_sel_hi:[1,0]
	v_pk_mul_f32 v[116:117], v[116:117], v[166:167] op_sel_hi:[1,0]
	v_cvt_pk_bf16_f32 v128, v128, v129
	v_cvt_pk_bf16_f32 v129, v130, v131
	v_cvt_pk_bf16_f32 v124, v124, v125
	v_cvt_pk_bf16_f32 v125, v126, v127
	v_cvt_pk_bf16_f32 v120, v120, v121
	v_cvt_pk_bf16_f32 v121, v122, v123
	s_nop 0
	v_cvt_pk_bf16_f32 v122, v116, v117
	v_cvt_pk_bf16_f32 v123, v118, v119
	v_mov_b32_e32 v126, v115
	v_cndmask_b32_e64 v116, v123, v125, s[38:39]
	v_cndmask_b32_e64 v117, v122, v124, s[38:39]
	v_cndmask_b32_e64 v118, v121, v129, s[38:39]
	v_cndmask_b32_e64 v119, v120, v128, s[38:39]
	v_mov_b32_e32 v127, v115
	v_mov_b32_e32 v130, v115
	v_mov_b32_e32 v131, v115
	v_mov_b32_dpp v126, v119 quad_perm:[1,0,3,2] row_mask:0xf bank_mask:0xf
	v_mov_b32_dpp v127, v118 quad_perm:[1,0,3,2] row_mask:0xf bank_mask:0xf
	v_mov_b32_dpp v130, v117 quad_perm:[1,0,3,2] row_mask:0xf bank_mask:0xf
	v_mov_b32_dpp v131, v116 quad_perm:[1,0,3,2] row_mask:0xf bank_mask:0xf
	v_cndmask_b32_e64 v116, v128, v126, s[38:39]
	v_cndmask_b32_e64 v117, v129, v127, s[38:39]
	v_cndmask_b32_e64 v118, v124, v130, s[38:39]
	v_cndmask_b32_e64 v119, v125, v131, s[38:39]
	global_store_dwordx4 v[148:149], v[116:119], off nt
	s_nop 1
	v_cndmask_b32_e64 v116, v126, v120, s[38:39]
	v_cndmask_b32_e64 v117, v127, v121, s[38:39]
	v_cndmask_b32_e64 v118, v130, v122, s[38:39]
	v_cndmask_b32_e64 v119, v131, v123, s[38:39]
	global_store_dwordx4 v[146:147], v[116:119], off nt
	ds_read_b128 v[116:119], v151 offset:256
	s_waitcnt lgkmcnt(0)
	v_mov_b32_e32 v120, v117
	v_mov_b32_e32 v121, v118
	v_mov_b32_e32 v117, v119
	v_pk_add_f32 v[116:117], v[120:121], v[116:117]
	s_nop 0
	v_add_f32_e32 v116, v116, v117
	v_fma_f32 v116, v116, s11, 0
	v_mul_f32_e32 v117, 0x4f800000, v116
	v_cmp_gt_f32_e32 vcc, s70, v116
	s_nop 1
	v_cndmask_b32_e32 v116, v116, v117, vcc
	v_sqrt_f32_e32 v117, v116
	s_nop 0
	v_add_u32_e32 v118, -1, v117
	v_fma_f32 v119, -v118, v117, v116
	v_cmp_ge_f32_e64 s[42:43], 0, v119
	v_add_u32_e32 v119, 1, v117
	s_nop 0
	v_cndmask_b32_e64 v118, v117, v118, s[42:43]
	v_fma_f32 v117, -v119, v117, v116
	v_cmp_lt_f32_e64 s[42:43], 0, v117
	s_nop 1
	v_cndmask_b32_e64 v117, v118, v119, s[42:43]
	v_mul_f32_e32 v118, 0x37800000, v117
	v_cndmask_b32_e32 v117, v117, v118, vcc
	v_cmp_class_f32_e32 vcc, v116, v226
	s_nop 1
	v_cndmask_b32_e32 v116, v117, v116, vcc
	v_div_scale_f32 v117, s[18:19], v116, v116, 1.0
	v_rcp_f32_e32 v118, v117
	s_add_u32 s18, s16, 0xc000
	s_addc_u32 s19, s17, 0
	v_fma_f32 v119, -v117, v118, 1.0
	v_fmac_f32_e32 v118, v119, v118
	v_div_scale_f32 v119, vcc, 1.0, v116, 1.0
	v_mul_f32_e32 v120, v119, v118
	v_fma_f32 v121, -v117, v120, v119
	v_fmac_f32_e32 v120, v121, v118
	v_fma_f32 v117, -v117, v120, v119
	v_div_fmas_f32 v117, v117, v118, v120
	v_div_fixup_f32 v116, v117, v116, 1.0
	v_pk_mul_f32 v[112:113], v[112:113], v[116:117] op_sel_hi:[1,0]
	v_pk_mul_f32 v[110:111], v[110:111], v[116:117] op_sel_hi:[1,0]
	v_pk_mul_f32 v[108:109], v[108:109], v[116:117] op_sel_hi:[1,0]
	v_pk_mul_f32 v[106:107], v[106:107], v[116:117] op_sel_hi:[1,0]
	v_pk_mul_f32 v[104:105], v[104:105], v[116:117] op_sel_hi:[1,0]
	v_pk_mul_f32 v[100:101], v[100:101], v[116:117] op_sel_hi:[1,0]
	v_pk_mul_f32 v[98:99], v[98:99], v[116:117] op_sel_hi:[1,0]
	v_cvt_pk_bf16_f32 v110, v110, v111
	v_cvt_pk_bf16_f32 v111, v112, v113
	v_cvt_pk_bf16_f32 v106, v106, v107
	v_cvt_pk_bf16_f32 v107, v108, v109
	v_pk_mul_f32 v[102:103], v[102:103], v[116:117] op_sel_hi:[1,0]
	v_mov_b32_e32 v112, v115
	v_cvt_pk_bf16_f32 v108, v102, v103
	v_cvt_pk_bf16_f32 v104, v104, v105
	v_cvt_pk_bf16_f32 v105, v98, v99
	v_cvt_pk_bf16_f32 v109, v100, v101
	v_mov_b32_e32 v113, v115
	v_cndmask_b32_e64 v98, v109, v107, s[38:39]
	v_cndmask_b32_e64 v99, v105, v106, s[38:39]
	v_cndmask_b32_e64 v100, v104, v111, s[38:39]
	v_cndmask_b32_e64 v101, v108, v110, s[38:39]
	v_mov_b32_e32 v116, v115
	v_mov_b32_e32 v117, v115
	v_mov_b32_dpp v112, v101 quad_perm:[1,0,3,2] row_mask:0xf bank_mask:0xf
	v_mov_b32_dpp v113, v100 quad_perm:[1,0,3,2] row_mask:0xf bank_mask:0xf
	v_mov_b32_dpp v116, v99 quad_perm:[1,0,3,2] row_mask:0xf bank_mask:0xf
	v_mov_b32_dpp v117, v98 quad_perm:[1,0,3,2] row_mask:0xf bank_mask:0xf
	v_cndmask_b32_e64 v98, v110, v112, s[38:39]
	v_cndmask_b32_e64 v99, v111, v113, s[38:39]
	v_cndmask_b32_e64 v100, v106, v116, s[38:39]
	v_cndmask_b32_e64 v101, v107, v117, s[38:39]
	v_lshl_add_u64 v[102:103], s[18:19], 0, v[142:143]
	global_store_dwordx4 v[102:103], v[98:101], off nt
	v_lshl_add_u64 v[102:103], s[18:19], 0, v[144:145]
	s_nop 0
	v_cndmask_b32_e64 v98, v112, v108, s[38:39]
	v_cndmask_b32_e64 v99, v113, v104, s[38:39]
	v_cndmask_b32_e64 v100, v116, v105, s[38:39]
	v_cndmask_b32_e64 v101, v117, v109, s[38:39]
	global_store_dwordx4 v[102:103], v[98:101], off nt
	ds_read_b128 v[98:101], v151 offset:512
	s_waitcnt lgkmcnt(0)
	v_mov_b32_e32 v102, v99
	v_mov_b32_e32 v103, v100
	v_mov_b32_e32 v99, v101
	v_pk_add_f32 v[98:99], v[102:103], v[98:99]
	s_nop 0
	v_add_f32_e32 v98, v98, v99
	v_fma_f32 v98, v98, s11, 0
	v_mul_f32_e32 v99, 0x4f800000, v98
	v_cmp_gt_f32_e32 vcc, s70, v98
	s_nop 1
	v_cndmask_b32_e32 v98, v98, v99, vcc
	v_sqrt_f32_e32 v99, v98
	s_nop 0
	v_add_u32_e32 v100, -1, v99
	v_fma_f32 v101, -v100, v99, v98
	v_cmp_ge_f32_e64 s[42:43], 0, v101
	v_add_u32_e32 v101, 1, v99
	s_nop 0
	v_cndmask_b32_e64 v100, v99, v100, s[42:43]
	v_fma_f32 v99, -v101, v99, v98
	v_cmp_lt_f32_e64 s[42:43], 0, v99
	s_nop 1
	v_cndmask_b32_e64 v99, v100, v101, s[42:43]
	v_mul_f32_e32 v100, 0x37800000, v99
	v_cndmask_b32_e32 v99, v99, v100, vcc
	v_cmp_class_f32_e32 vcc, v98, v226
	s_nop 1
	v_cndmask_b32_e32 v98, v99, v98, vcc
	v_div_scale_f32 v99, s[18:19], v98, v98, 1.0
	v_rcp_f32_e32 v100, v99
	s_add_u32 s18, s16, 0x18000
	s_addc_u32 s19, s17, 0
	v_fma_f32 v101, -v99, v100, 1.0
	v_fmac_f32_e32 v100, v101, v100
	v_div_scale_f32 v101, vcc, 1.0, v98, 1.0
	v_mul_f32_e32 v102, v101, v100
	v_fma_f32 v103, -v99, v102, v101
	v_fmac_f32_e32 v102, v103, v100
	v_fma_f32 v99, -v99, v102, v101
	v_div_fmas_f32 v99, v99, v100, v102
	v_div_fixup_f32 v98, v99, v98, 1.0
	v_pk_mul_f32 v[96:97], v[96:97], v[98:99] op_sel_hi:[1,0]
	v_pk_mul_f32 v[94:95], v[94:95], v[98:99] op_sel_hi:[1,0]
	v_pk_mul_f32 v[92:93], v[92:93], v[98:99] op_sel_hi:[1,0]
	v_pk_mul_f32 v[90:91], v[90:91], v[98:99] op_sel_hi:[1,0]
	v_pk_mul_f32 v[88:89], v[88:89], v[98:99] op_sel_hi:[1,0]
	v_pk_mul_f32 v[84:85], v[84:85], v[98:99] op_sel_hi:[1,0]
	v_pk_mul_f32 v[82:83], v[82:83], v[98:99] op_sel_hi:[1,0]
	v_cvt_pk_bf16_f32 v94, v94, v95
	v_cvt_pk_bf16_f32 v95, v96, v97
	v_cvt_pk_bf16_f32 v90, v90, v91
	v_cvt_pk_bf16_f32 v91, v92, v93
	v_pk_mul_f32 v[86:87], v[86:87], v[98:99] op_sel_hi:[1,0]
	v_mov_b32_e32 v96, v115
	v_cvt_pk_bf16_f32 v92, v86, v87
	v_cvt_pk_bf16_f32 v88, v88, v89
	v_cvt_pk_bf16_f32 v89, v82, v83
	v_cvt_pk_bf16_f32 v93, v84, v85
	v_mov_b32_e32 v97, v115
	v_cndmask_b32_e64 v82, v93, v91, s[38:39]
	v_cndmask_b32_e64 v83, v89, v90, s[38:39]
	v_cndmask_b32_e64 v84, v88, v95, s[38:39]
	v_cndmask_b32_e64 v85, v92, v94, s[38:39]
	v_mov_b32_e32 v98, v115
	v_mov_b32_e32 v99, v115
	v_mov_b32_dpp v96, v85 quad_perm:[1,0,3,2] row_mask:0xf bank_mask:0xf
	v_mov_b32_dpp v97, v84 quad_perm:[1,0,3,2] row_mask:0xf bank_mask:0xf
	v_mov_b32_dpp v98, v83 quad_perm:[1,0,3,2] row_mask:0xf bank_mask:0xf
	v_mov_b32_dpp v99, v82 quad_perm:[1,0,3,2] row_mask:0xf bank_mask:0xf
	v_cndmask_b32_e64 v82, v94, v96, s[38:39]
	v_cndmask_b32_e64 v83, v95, v97, s[38:39]
	v_cndmask_b32_e64 v84, v90, v98, s[38:39]
	v_cndmask_b32_e64 v85, v91, v99, s[38:39]
	v_lshl_add_u64 v[86:87], s[18:19], 0, v[142:143]
	global_store_dwordx4 v[86:87], v[82:85], off nt
	v_lshl_add_u64 v[86:87], s[18:19], 0, v[144:145]
	s_nop 0
	v_cndmask_b32_e64 v82, v96, v92, s[38:39]
	v_cndmask_b32_e64 v83, v97, v88, s[38:39]
	v_cndmask_b32_e64 v84, v98, v89, s[38:39]
	v_cndmask_b32_e64 v85, v99, v93, s[38:39]
	global_store_dwordx4 v[86:87], v[82:85], off nt
	ds_read_b128 v[82:85], v151 offset:768
	s_waitcnt lgkmcnt(0)
	v_mov_b32_e32 v86, v83
	v_mov_b32_e32 v87, v84
	v_mov_b32_e32 v83, v85
	v_pk_add_f32 v[82:83], v[86:87], v[82:83]
	s_nop 0
	v_add_f32_e32 v82, v82, v83
	v_fma_f32 v82, v82, s11, 0
	v_mul_f32_e32 v83, 0x4f800000, v82
	v_cmp_gt_f32_e32 vcc, s70, v82
	s_nop 1
	v_cndmask_b32_e32 v82, v82, v83, vcc
	v_sqrt_f32_e32 v83, v82
	s_nop 0
	v_add_u32_e32 v84, -1, v83
	v_fma_f32 v85, -v84, v83, v82
	v_cmp_ge_f32_e64 s[42:43], 0, v85
	v_add_u32_e32 v85, 1, v83
	s_nop 0
	v_cndmask_b32_e64 v84, v83, v84, s[42:43]
	v_fma_f32 v83, -v85, v83, v82
	v_cmp_lt_f32_e64 s[42:43], 0, v83
	s_nop 1
	v_cndmask_b32_e64 v83, v84, v85, s[42:43]
	v_mul_f32_e32 v84, 0x37800000, v83
	v_cndmask_b32_e32 v83, v83, v84, vcc
	v_cmp_class_f32_e32 vcc, v82, v226
	s_nop 1
	v_cndmask_b32_e32 v82, v83, v82, vcc
	v_div_scale_f32 v83, s[18:19], v82, v82, 1.0
	v_rcp_f32_e32 v84, v83
	s_add_u32 s18, s16, 0x24000
	s_addc_u32 s19, s17, 0
	v_fma_f32 v85, -v83, v84, 1.0
	v_fmac_f32_e32 v84, v85, v84
	v_div_scale_f32 v85, vcc, 1.0, v82, 1.0
	v_mul_f32_e32 v86, v85, v84
	v_fma_f32 v87, -v83, v86, v85
	v_fmac_f32_e32 v86, v87, v84
	v_fma_f32 v83, -v83, v86, v85
	v_div_fmas_f32 v83, v83, v84, v86
	v_div_fixup_f32 v82, v83, v82, 1.0
	v_pk_mul_f32 v[80:81], v[80:81], v[82:83] op_sel_hi:[1,0]
	v_pk_mul_f32 v[78:79], v[78:79], v[82:83] op_sel_hi:[1,0]
	v_pk_mul_f32 v[76:77], v[76:77], v[82:83] op_sel_hi:[1,0]
	v_pk_mul_f32 v[74:75], v[74:75], v[82:83] op_sel_hi:[1,0]
	v_pk_mul_f32 v[72:73], v[72:73], v[82:83] op_sel_hi:[1,0]
	v_pk_mul_f32 v[68:69], v[68:69], v[82:83] op_sel_hi:[1,0]
	v_pk_mul_f32 v[66:67], v[66:67], v[82:83] op_sel_hi:[1,0]
	v_cvt_pk_bf16_f32 v78, v78, v79
	v_cvt_pk_bf16_f32 v79, v80, v81
	v_cvt_pk_bf16_f32 v74, v74, v75
	v_cvt_pk_bf16_f32 v75, v76, v77
	v_pk_mul_f32 v[70:71], v[70:71], v[82:83] op_sel_hi:[1,0]
	v_mov_b32_e32 v80, v115
	v_cvt_pk_bf16_f32 v76, v70, v71
	v_cvt_pk_bf16_f32 v72, v72, v73
	v_cvt_pk_bf16_f32 v73, v66, v67
	v_cvt_pk_bf16_f32 v77, v68, v69
	v_mov_b32_e32 v81, v115
	v_cndmask_b32_e64 v66, v77, v75, s[38:39]
	v_cndmask_b32_e64 v67, v73, v74, s[38:39]
	v_cndmask_b32_e64 v68, v72, v79, s[38:39]
	v_cndmask_b32_e64 v69, v76, v78, s[38:39]
	v_mov_b32_e32 v82, v115
	v_mov_b32_e32 v83, v115
	v_mov_b32_dpp v80, v69 quad_perm:[1,0,3,2] row_mask:0xf bank_mask:0xf
	v_mov_b32_dpp v81, v68 quad_perm:[1,0,3,2] row_mask:0xf bank_mask:0xf
	v_mov_b32_dpp v82, v67 quad_perm:[1,0,3,2] row_mask:0xf bank_mask:0xf
	v_mov_b32_dpp v83, v66 quad_perm:[1,0,3,2] row_mask:0xf bank_mask:0xf
	v_cndmask_b32_e64 v66, v78, v80, s[38:39]
	v_cndmask_b32_e64 v67, v79, v81, s[38:39]
	v_cndmask_b32_e64 v68, v74, v82, s[38:39]
	v_cndmask_b32_e64 v69, v75, v83, s[38:39]
	v_lshl_add_u64 v[70:71], s[18:19], 0, v[142:143]
	global_store_dwordx4 v[70:71], v[66:69], off nt
	v_lshl_add_u64 v[70:71], s[18:19], 0, v[144:145]
	s_nop 0
	v_cndmask_b32_e64 v66, v80, v76, s[38:39]
	v_cndmask_b32_e64 v67, v81, v72, s[38:39]
	v_cndmask_b32_e64 v68, v82, v73, s[38:39]
	v_cndmask_b32_e64 v69, v83, v77, s[38:39]
	global_store_dwordx4 v[70:71], v[66:69], off nt
	ds_read_b128 v[66:69], v151 offset:2048
	s_waitcnt lgkmcnt(0)
	v_mov_b32_e32 v70, v67
	v_mov_b32_e32 v71, v68
	v_mov_b32_e32 v67, v69
	v_pk_add_f32 v[66:67], v[70:71], v[66:67]
	s_nop 0
	v_add_f32_e32 v66, v66, v67
	v_fma_f32 v66, v66, s11, 0
	v_mul_f32_e32 v67, 0x4f800000, v66
	v_cmp_gt_f32_e32 vcc, s70, v66
	s_nop 1
	v_cndmask_b32_e32 v66, v66, v67, vcc
	v_sqrt_f32_e32 v67, v66
	s_nop 0
	v_add_u32_e32 v68, -1, v67
	v_fma_f32 v69, -v68, v67, v66
	v_cmp_ge_f32_e64 s[42:43], 0, v69
	v_add_u32_e32 v69, 1, v67
	s_nop 0
	v_cndmask_b32_e64 v68, v67, v68, s[42:43]
	v_fma_f32 v67, -v69, v67, v66
	v_cmp_lt_f32_e64 s[42:43], 0, v67
	s_nop 1
	v_cndmask_b32_e64 v67, v68, v69, s[42:43]
	v_mul_f32_e32 v68, 0x37800000, v67
	v_cndmask_b32_e32 v67, v67, v68, vcc
	v_cmp_class_f32_e32 vcc, v66, v226
	s_nop 1
	v_cndmask_b32_e32 v66, v67, v66, vcc
	v_div_scale_f32 v67, s[18:19], v66, v66, 1.0
	v_rcp_f32_e32 v68, v67
	s_add_u32 s18, s16, 0x60000
	s_addc_u32 s19, s17, 0
	v_fma_f32 v69, -v67, v68, 1.0
	v_fmac_f32_e32 v68, v69, v68
	v_div_scale_f32 v69, vcc, 1.0, v66, 1.0
	v_mul_f32_e32 v70, v69, v68
	v_fma_f32 v71, -v67, v70, v69
	v_fmac_f32_e32 v70, v71, v68
	v_fma_f32 v67, -v67, v70, v69
	v_div_fmas_f32 v67, v67, v68, v70
	v_div_fixup_f32 v66, v67, v66, 1.0
	v_pk_mul_f32 v[64:65], v[64:65], v[66:67] op_sel_hi:[1,0]
	v_pk_mul_f32 v[62:63], v[62:63], v[66:67] op_sel_hi:[1,0]
	v_pk_mul_f32 v[60:61], v[60:61], v[66:67] op_sel_hi:[1,0]
	v_pk_mul_f32 v[58:59], v[58:59], v[66:67] op_sel_hi:[1,0]
	v_pk_mul_f32 v[56:57], v[56:57], v[66:67] op_sel_hi:[1,0]
	v_pk_mul_f32 v[52:53], v[52:53], v[66:67] op_sel_hi:[1,0]
	v_pk_mul_f32 v[50:51], v[50:51], v[66:67] op_sel_hi:[1,0]
	v_cvt_pk_bf16_f32 v62, v62, v63
	v_cvt_pk_bf16_f32 v63, v64, v65
	v_cvt_pk_bf16_f32 v58, v58, v59
	v_cvt_pk_bf16_f32 v59, v60, v61
	v_pk_mul_f32 v[54:55], v[54:55], v[66:67] op_sel_hi:[1,0]
	v_mov_b32_e32 v64, v115
	v_cvt_pk_bf16_f32 v60, v54, v55
	v_cvt_pk_bf16_f32 v56, v56, v57
	v_cvt_pk_bf16_f32 v57, v50, v51
	v_cvt_pk_bf16_f32 v61, v52, v53
	v_mov_b32_e32 v65, v115
	v_cndmask_b32_e64 v50, v61, v59, s[38:39]
	v_cndmask_b32_e64 v51, v57, v58, s[38:39]
	v_cndmask_b32_e64 v52, v56, v63, s[38:39]
	v_cndmask_b32_e64 v53, v60, v62, s[38:39]
	v_mov_b32_e32 v66, v115
	v_mov_b32_e32 v67, v115
	v_mov_b32_dpp v64, v53 quad_perm:[1,0,3,2] row_mask:0xf bank_mask:0xf
	v_mov_b32_dpp v65, v52 quad_perm:[1,0,3,2] row_mask:0xf bank_mask:0xf
	v_mov_b32_dpp v66, v51 quad_perm:[1,0,3,2] row_mask:0xf bank_mask:0xf
	v_mov_b32_dpp v67, v50 quad_perm:[1,0,3,2] row_mask:0xf bank_mask:0xf
	v_cndmask_b32_e64 v50, v62, v64, s[38:39]
	v_cndmask_b32_e64 v51, v63, v65, s[38:39]
	v_cndmask_b32_e64 v52, v58, v66, s[38:39]
	v_cndmask_b32_e64 v53, v59, v67, s[38:39]
	v_lshl_add_u64 v[54:55], s[18:19], 0, v[142:143]
	global_store_dwordx4 v[54:55], v[50:53], off nt
	v_lshl_add_u64 v[54:55], s[18:19], 0, v[144:145]
	s_nop 0
	v_cndmask_b32_e64 v50, v64, v60, s[38:39]
	v_cndmask_b32_e64 v51, v65, v56, s[38:39]
	v_cndmask_b32_e64 v52, v66, v57, s[38:39]
	v_cndmask_b32_e64 v53, v67, v61, s[38:39]
	global_store_dwordx4 v[54:55], v[50:53], off nt
	ds_read_b128 v[50:53], v151 offset:2304
	s_waitcnt lgkmcnt(0)
	v_mov_b32_e32 v54, v51
	v_mov_b32_e32 v55, v52
	v_mov_b32_e32 v51, v53
	v_pk_add_f32 v[50:51], v[54:55], v[50:51]
	s_nop 0
	v_add_f32_e32 v50, v50, v51
	v_fma_f32 v50, v50, s11, 0
	v_mul_f32_e32 v51, 0x4f800000, v50
	v_cmp_gt_f32_e32 vcc, s70, v50
	s_nop 1
	v_cndmask_b32_e32 v50, v50, v51, vcc
	v_sqrt_f32_e32 v51, v50
	s_nop 0
	v_add_u32_e32 v52, -1, v51
	v_fma_f32 v53, -v52, v51, v50
	v_cmp_ge_f32_e64 s[42:43], 0, v53
	v_add_u32_e32 v53, 1, v51
	s_nop 0
	v_cndmask_b32_e64 v52, v51, v52, s[42:43]
	v_fma_f32 v51, -v53, v51, v50
	v_cmp_lt_f32_e64 s[42:43], 0, v51
	s_nop 1
	v_cndmask_b32_e64 v51, v52, v53, s[42:43]
	v_mul_f32_e32 v52, 0x37800000, v51
	v_cndmask_b32_e32 v51, v51, v52, vcc
	v_cmp_class_f32_e32 vcc, v50, v226
	s_nop 1
	v_cndmask_b32_e32 v50, v51, v50, vcc
	v_div_scale_f32 v51, s[18:19], v50, v50, 1.0
	v_rcp_f32_e32 v52, v51
	s_add_u32 s18, s16, 0x6c000
	s_addc_u32 s19, s17, 0
	v_fma_f32 v53, -v51, v52, 1.0
	v_fmac_f32_e32 v52, v53, v52
	v_div_scale_f32 v53, vcc, 1.0, v50, 1.0
	v_mul_f32_e32 v54, v53, v52
	v_fma_f32 v55, -v51, v54, v53
	v_fmac_f32_e32 v54, v55, v52
	v_fma_f32 v51, -v51, v54, v53
	v_div_fmas_f32 v51, v51, v52, v54
	v_div_fixup_f32 v50, v51, v50, 1.0
	v_pk_mul_f32 v[48:49], v[48:49], v[50:51] op_sel_hi:[1,0]
	v_pk_mul_f32 v[46:47], v[46:47], v[50:51] op_sel_hi:[1,0]
	v_pk_mul_f32 v[44:45], v[44:45], v[50:51] op_sel_hi:[1,0]
	v_pk_mul_f32 v[42:43], v[42:43], v[50:51] op_sel_hi:[1,0]
	v_pk_mul_f32 v[40:41], v[40:41], v[50:51] op_sel_hi:[1,0]
	v_pk_mul_f32 v[36:37], v[36:37], v[50:51] op_sel_hi:[1,0]
	v_pk_mul_f32 v[34:35], v[34:35], v[50:51] op_sel_hi:[1,0]
	v_cvt_pk_bf16_f32 v46, v46, v47
	v_cvt_pk_bf16_f32 v47, v48, v49
	v_cvt_pk_bf16_f32 v42, v42, v43
	v_cvt_pk_bf16_f32 v43, v44, v45
	v_pk_mul_f32 v[38:39], v[38:39], v[50:51] op_sel_hi:[1,0]
	v_mov_b32_e32 v48, v115
	v_cvt_pk_bf16_f32 v44, v38, v39
	v_cvt_pk_bf16_f32 v40, v40, v41
	v_cvt_pk_bf16_f32 v41, v34, v35
	v_cvt_pk_bf16_f32 v45, v36, v37
	v_mov_b32_e32 v49, v115
	v_cndmask_b32_e64 v34, v45, v43, s[38:39]
	v_cndmask_b32_e64 v35, v41, v42, s[38:39]
	v_cndmask_b32_e64 v36, v40, v47, s[38:39]
	v_cndmask_b32_e64 v37, v44, v46, s[38:39]
	v_mov_b32_e32 v50, v115
	v_mov_b32_e32 v51, v115
	v_mov_b32_dpp v48, v37 quad_perm:[1,0,3,2] row_mask:0xf bank_mask:0xf
	v_mov_b32_dpp v49, v36 quad_perm:[1,0,3,2] row_mask:0xf bank_mask:0xf
	v_mov_b32_dpp v50, v35 quad_perm:[1,0,3,2] row_mask:0xf bank_mask:0xf
	v_mov_b32_dpp v51, v34 quad_perm:[1,0,3,2] row_mask:0xf bank_mask:0xf
	v_cndmask_b32_e64 v34, v46, v48, s[38:39]
	v_cndmask_b32_e64 v35, v47, v49, s[38:39]
	v_cndmask_b32_e64 v36, v42, v50, s[38:39]
	v_cndmask_b32_e64 v37, v43, v51, s[38:39]
	v_lshl_add_u64 v[38:39], s[18:19], 0, v[142:143]
	global_store_dwordx4 v[38:39], v[34:37], off nt
	v_lshl_add_u64 v[38:39], s[18:19], 0, v[144:145]
	s_nop 0
	v_cndmask_b32_e64 v34, v48, v44, s[38:39]
	v_cndmask_b32_e64 v35, v49, v40, s[38:39]
	v_cndmask_b32_e64 v36, v50, v41, s[38:39]
	v_cndmask_b32_e64 v37, v51, v45, s[38:39]
	global_store_dwordx4 v[38:39], v[34:37], off nt
	ds_read_b128 v[34:37], v151 offset:2560
	s_waitcnt lgkmcnt(0)
	v_mov_b32_e32 v38, v35
	v_mov_b32_e32 v39, v36
	v_mov_b32_e32 v35, v37
	v_pk_add_f32 v[34:35], v[38:39], v[34:35]
	s_nop 0
	v_add_f32_e32 v34, v34, v35
	v_fma_f32 v34, v34, s11, 0
	v_mul_f32_e32 v35, 0x4f800000, v34
	v_cmp_gt_f32_e32 vcc, s70, v34
	s_nop 1
	v_cndmask_b32_e32 v34, v34, v35, vcc
	v_sqrt_f32_e32 v35, v34
	s_nop 0
	v_add_u32_e32 v36, -1, v35
	v_fma_f32 v37, -v36, v35, v34
	v_cmp_ge_f32_e64 s[42:43], 0, v37
	v_add_u32_e32 v37, 1, v35
	s_nop 0
	v_cndmask_b32_e64 v36, v35, v36, s[42:43]
	v_fma_f32 v35, -v37, v35, v34
	v_cmp_lt_f32_e64 s[42:43], 0, v35
	s_nop 1
	v_cndmask_b32_e64 v35, v36, v37, s[42:43]
	v_mul_f32_e32 v36, 0x37800000, v35
	v_cndmask_b32_e32 v35, v35, v36, vcc
	v_cmp_class_f32_e32 vcc, v34, v226
	s_nop 1
	v_cndmask_b32_e32 v34, v35, v34, vcc
	v_div_scale_f32 v35, s[18:19], v34, v34, 1.0
	v_rcp_f32_e32 v36, v35
	s_add_u32 s18, s16, 0x78000
	s_addc_u32 s19, s17, 0
	s_add_u32 s16, s16, 0x84000
	v_fma_f32 v37, -v35, v36, 1.0
	v_fmac_f32_e32 v36, v37, v36
	v_div_scale_f32 v37, vcc, 1.0, v34, 1.0
	v_mul_f32_e32 v38, v37, v36
	v_fma_f32 v39, -v35, v38, v37
	v_fmac_f32_e32 v38, v39, v36
	v_fma_f32 v35, -v35, v38, v37
	v_div_fmas_f32 v35, v35, v36, v38
	v_div_fixup_f32 v34, v35, v34, 1.0
	v_pk_mul_f32 v[32:33], v[32:33], v[34:35] op_sel_hi:[1,0]
	v_pk_mul_f32 v[30:31], v[30:31], v[34:35] op_sel_hi:[1,0]
	v_pk_mul_f32 v[28:29], v[28:29], v[34:35] op_sel_hi:[1,0]
	v_pk_mul_f32 v[26:27], v[26:27], v[34:35] op_sel_hi:[1,0]
	v_pk_mul_f32 v[24:25], v[24:25], v[34:35] op_sel_hi:[1,0]
	v_pk_mul_f32 v[20:21], v[20:21], v[34:35] op_sel_hi:[1,0]
	v_pk_mul_f32 v[18:19], v[18:19], v[34:35] op_sel_hi:[1,0]
	v_cvt_pk_bf16_f32 v30, v30, v31
	v_cvt_pk_bf16_f32 v31, v32, v33
	v_cvt_pk_bf16_f32 v26, v26, v27
	v_cvt_pk_bf16_f32 v27, v28, v29
	v_pk_mul_f32 v[22:23], v[22:23], v[34:35] op_sel_hi:[1,0]
	v_mov_b32_e32 v32, v115
	v_cvt_pk_bf16_f32 v28, v22, v23
	v_cvt_pk_bf16_f32 v24, v24, v25
	v_cvt_pk_bf16_f32 v25, v18, v19
	v_cvt_pk_bf16_f32 v29, v20, v21
	v_mov_b32_e32 v33, v115
	v_cndmask_b32_e64 v18, v29, v27, s[38:39]
	v_cndmask_b32_e64 v19, v25, v26, s[38:39]
	v_cndmask_b32_e64 v20, v24, v31, s[38:39]
	v_cndmask_b32_e64 v21, v28, v30, s[38:39]
	v_mov_b32_e32 v34, v115
	v_mov_b32_e32 v35, v115
	v_mov_b32_dpp v32, v21 quad_perm:[1,0,3,2] row_mask:0xf bank_mask:0xf
	v_mov_b32_dpp v33, v20 quad_perm:[1,0,3,2] row_mask:0xf bank_mask:0xf
	v_mov_b32_dpp v34, v19 quad_perm:[1,0,3,2] row_mask:0xf bank_mask:0xf
	v_mov_b32_dpp v35, v18 quad_perm:[1,0,3,2] row_mask:0xf bank_mask:0xf
	v_cndmask_b32_e64 v18, v30, v32, s[38:39]
	v_cndmask_b32_e64 v19, v31, v33, s[38:39]
	v_cndmask_b32_e64 v20, v26, v34, s[38:39]
	v_cndmask_b32_e64 v21, v27, v35, s[38:39]
	v_lshl_add_u64 v[22:23], s[18:19], 0, v[142:143]
	global_store_dwordx4 v[22:23], v[18:21], off nt
	v_lshl_add_u64 v[22:23], s[18:19], 0, v[144:145]
	s_addc_u32 s17, s17, 0
	v_cndmask_b32_e64 v18, v32, v28, s[38:39]
	v_cndmask_b32_e64 v19, v33, v24, s[38:39]
	v_cndmask_b32_e64 v20, v34, v25, s[38:39]
	v_cndmask_b32_e64 v21, v35, v29, s[38:39]
	global_store_dwordx4 v[22:23], v[18:21], off nt
	ds_read_b128 v[18:21], v151 offset:2816
	s_waitcnt lgkmcnt(0)
	v_mov_b32_e32 v22, v19
	v_mov_b32_e32 v23, v20
	v_mov_b32_e32 v19, v21
	v_pk_add_f32 v[18:19], v[22:23], v[18:19]
	s_nop 0
	v_add_f32_e32 v18, v18, v19
	v_fma_f32 v18, v18, s11, 0
	v_mul_f32_e32 v19, 0x4f800000, v18
	v_cmp_gt_f32_e32 vcc, s70, v18
	s_nop 1
	v_cndmask_b32_e32 v18, v18, v19, vcc
	v_sqrt_f32_e32 v19, v18
	s_nop 0
	v_add_u32_e32 v20, -1, v19
	v_fma_f32 v21, -v20, v19, v18
	v_cmp_ge_f32_e64 s[42:43], 0, v21
	v_add_u32_e32 v21, 1, v19
	s_nop 0
	v_cndmask_b32_e64 v20, v19, v20, s[42:43]
	v_fma_f32 v19, -v21, v19, v18
	v_cmp_lt_f32_e64 s[42:43], 0, v19
	s_nop 1
	v_cndmask_b32_e64 v19, v20, v21, s[42:43]
	v_mul_f32_e32 v20, 0x37800000, v19
	v_cndmask_b32_e32 v19, v19, v20, vcc
	v_cmp_class_f32_e32 vcc, v18, v226
	s_nop 1
	v_cndmask_b32_e32 v18, v19, v18, vcc
	v_div_scale_f32 v19, s[18:19], v18, v18, 1.0
	v_rcp_f32_e32 v20, v19
	s_nop 0
	v_fma_f32 v21, -v19, v20, 1.0
	v_fmac_f32_e32 v20, v21, v20
	v_div_scale_f32 v21, vcc, 1.0, v18, 1.0
	v_mul_f32_e32 v22, v21, v20
	v_fma_f32 v23, -v19, v22, v21
	v_fmac_f32_e32 v22, v23, v20
	v_fma_f32 v19, -v19, v22, v21
	v_div_fmas_f32 v19, v19, v20, v22
	v_div_fixup_f32 v18, v19, v18, 1.0
	v_pk_mul_f32 v[16:17], v[16:17], v[18:19] op_sel_hi:[1,0]
	v_pk_mul_f32 v[14:15], v[14:15], v[18:19] op_sel_hi:[1,0]
	v_pk_mul_f32 v[12:13], v[12:13], v[18:19] op_sel_hi:[1,0]
	v_pk_mul_f32 v[10:11], v[10:11], v[18:19] op_sel_hi:[1,0]
	v_pk_mul_f32 v[8:9], v[8:9], v[18:19] op_sel_hi:[1,0]
	v_pk_mul_f32 v[4:5], v[4:5], v[18:19] op_sel_hi:[1,0]
	v_pk_mul_f32 v[2:3], v[2:3], v[18:19] op_sel_hi:[1,0]
	v_cvt_pk_bf16_f32 v14, v14, v15
	v_cvt_pk_bf16_f32 v15, v16, v17
	v_cvt_pk_bf16_f32 v10, v10, v11
	v_cvt_pk_bf16_f32 v11, v12, v13
	v_pk_mul_f32 v[6:7], v[6:7], v[18:19] op_sel_hi:[1,0]
	v_mov_b32_e32 v16, v115
	v_cvt_pk_bf16_f32 v12, v6, v7
	v_cvt_pk_bf16_f32 v8, v8, v9
	v_cvt_pk_bf16_f32 v9, v2, v3
	v_cvt_pk_bf16_f32 v13, v4, v5
	v_mov_b32_e32 v17, v115
	v_cndmask_b32_e64 v2, v13, v11, s[38:39]
	v_cndmask_b32_e64 v3, v9, v10, s[38:39]
	v_cndmask_b32_e64 v4, v8, v15, s[38:39]
	v_cndmask_b32_e64 v5, v12, v14, s[38:39]
	v_mov_b32_e32 v18, v115
	v_mov_b32_e32 v19, v115
	v_mov_b32_dpp v16, v5 quad_perm:[1,0,3,2] row_mask:0xf bank_mask:0xf
	v_mov_b32_dpp v17, v4 quad_perm:[1,0,3,2] row_mask:0xf bank_mask:0xf
	v_mov_b32_dpp v18, v3 quad_perm:[1,0,3,2] row_mask:0xf bank_mask:0xf
	v_mov_b32_dpp v19, v2 quad_perm:[1,0,3,2] row_mask:0xf bank_mask:0xf
	v_cndmask_b32_e64 v2, v14, v16, s[38:39]
	v_cndmask_b32_e64 v3, v15, v17, s[38:39]
	v_cndmask_b32_e64 v4, v10, v18, s[38:39]
	v_cndmask_b32_e64 v5, v11, v19, s[38:39]
	v_lshl_add_u64 v[6:7], s[16:17], 0, v[142:143]
	global_store_dwordx4 v[6:7], v[2:5], off nt
	v_lshl_add_u64 v[6:7], s[16:17], 0, v[144:145]
	s_nop 0
	v_cndmask_b32_e64 v2, v16, v12, s[38:39]
	v_cndmask_b32_e64 v3, v17, v8, s[38:39]
	v_cndmask_b32_e64 v4, v18, v9, s[38:39]
	v_cndmask_b32_e64 v5, v19, v13, s[38:39]
	global_store_dwordx4 v[6:7], v[2:5], off nt
	s_and_b64 vcc, exec, s[40:41]
	s_mov_b64 s[16:17], -1
	s_cbranch_vccnz .LBB0_502

.LBB0_548:
	s_add_u32 s49, s22, s48
	s_addc_u32 s54, s23, 0
	s_add_u32 s52, s49, 0x100
	s_addc_u32 s53, s54, 0
	s_and_b64 s[50:51], s[42:43], exec
	s_cselect_b32 s51, s45, s53
	s_cselect_b32 s50, s44, s52
	s_add_u32 s48, s20, s48
	s_addc_u32 s52, s21, 0
	s_add_u32 s48, s48, 0x100
	s_addc_u32 s52, s52, 0
	s_add_i32 s62, 0, 0x10000
	s_and_b64 s[42:43], s[42:43], exec
	s_cselect_b32 s53, s19, s52
	s_cselect_b32 s52, s25, s48
	s_add_i32 s43, 0, 0x14000
	s_add_u32 s64, s49, 0xc0080
	s_addc_u32 s65, s54, 0
	s_add_i32 s69, s62, s76
	s_add_i32 m0, s79, 0xc000
	s_add_i32 s68, s79, 0xe000
	s_add_i32 s88, s69, 0x2000
	v_add_u32_e32 v114, s62, v180
	s_add_u32 s54, s52, 0x4000
	s_waitcnt lgkmcnt(0)
	ds_read_b128 v[132:135], v114
	ds_read_b128 v[136:139], v114 offset:1024
	ds_read_b128 v[166:169], v114 offset:2048
	ds_read_b128 v[170:173], v114 offset:3072
	v_add_u32_e32 v114, s43, v180
	s_addc_u32 s55, s53, 0
	s_add_i32 s89, s43, s76
	ds_read_b128 v[174:177], v114
	ds_read_b128 v[192:195], v114 offset:1024
	ds_read_b128 v[196:199], v114 offset:2048
	ds_read_b128 v[200:203], v114 offset:3072
	s_add_i32 s91, s89, 0x2000
	s_add_i32 s92, 0, 0x18000
	s_add_i32 s93, 0, 0x1c000
	s_add_u32 s48, s50, 0xc0000
	s_addc_u32 s49, s51, 0
	s_add_i32 s59, s92, s76
	s_add_i32 s57, s59, 0x2000
	s_add_u32 s42, s52, 0x4080
	s_addc_u32 s43, s53, 0
	s_add_i32 s63, s93, s76
	s_add_i32 s62, s63, 0x2000
	v_lshl_add_u64 v[224:225], s[64:65], 0, v[140:141]
	ds_read_b128 v[204:207], v190
	ds_read_b128 v[208:211], v190 offset:1024
	ds_read_b128 v[212:215], v190 offset:2048
	ds_read_b128 v[216:219], v190 offset:3072
	ds_read_b128 v[220:223], v190 offset:4096
	ds_read_b128 v[240:243], v190 offset:5120
	ds_read_b128 v[244:247], v190 offset:6144
	ds_read_b128 v[248:251], v190 offset:7168
	global_load_lds_dwordx4 v[224:225], off
	v_lshl_add_u64 v[224:225], s[64:65], 0, v[144:145]
	s_mov_b32 m0, s68
	s_nop 0
	global_load_lds_dwordx4 v[224:225], off
	s_waitcnt vmcnt(8)
	s_waitcnt lgkmcnt(0)
	s_barrier
	s_setprio 1
	s_waitcnt lgkmcnt(0)
	v_mfma_f32_16x16x32_bf16 v[128:131], v[132:135], v[204:207], v[128:131]
	v_mfma_f32_16x16x32_bf16 v[124:127], v[166:169], v[204:207], v[124:127]
	v_mfma_f32_16x16x32_bf16 v[110:113], v[132:135], v[212:215], v[110:113]
	v_mfma_f32_16x16x32_bf16 v[106:109], v[166:169], v[212:215], v[106:109]
	v_mfma_f32_16x16x32_bf16 v[94:97], v[132:135], v[220:223], v[94:97]
	v_mfma_f32_16x16x32_bf16 v[90:93], v[166:169], v[220:223], v[90:93]
	v_mfma_f32_16x16x32_bf16 v[78:81], v[132:135], v[244:247], v[78:81]
	v_mfma_f32_16x16x32_bf16 v[74:77], v[166:169], v[244:247], v[74:77]
	v_mfma_f32_16x16x32_bf16 v[128:131], v[136:139], v[208:211], v[128:131]
	v_mfma_f32_16x16x32_bf16 v[124:127], v[170:173], v[208:211], v[124:127]
	v_mfma_f32_16x16x32_bf16 v[110:113], v[136:139], v[216:219], v[110:113]
	v_mfma_f32_16x16x32_bf16 v[106:109], v[170:173], v[216:219], v[106:109]
	v_mfma_f32_16x16x32_bf16 v[94:97], v[136:139], v[240:243], v[94:97]
	v_mfma_f32_16x16x32_bf16 v[90:93], v[170:173], v[240:243], v[90:93]
	v_mfma_f32_16x16x32_bf16 v[78:81], v[136:139], v[248:251], v[78:81]
	v_mfma_f32_16x16x32_bf16 v[74:77], v[170:173], v[248:251], v[74:77]
	s_setprio 0
	s_setprio 1
	v_mfma_f32_16x16x32_bf16 v[120:123], v[174:177], v[204:207], v[120:123]
	v_mfma_f32_16x16x32_bf16 v[116:119], v[196:199], v[204:207], v[116:119]
	v_mfma_f32_16x16x32_bf16 v[102:105], v[174:177], v[212:215], v[102:105]
	v_mfma_f32_16x16x32_bf16 v[98:101], v[196:199], v[212:215], v[98:101]
	v_mfma_f32_16x16x32_bf16 v[86:89], v[174:177], v[220:223], v[86:89]
	v_mfma_f32_16x16x32_bf16 v[82:85], v[196:199], v[220:223], v[82:85]
	v_mfma_f32_16x16x32_bf16 v[70:73], v[174:177], v[244:247], v[70:73]
	v_mfma_f32_16x16x32_bf16 v[66:69], v[196:199], v[244:247], v[66:69]
	v_mfma_f32_16x16x32_bf16 v[120:123], v[192:195], v[208:211], v[120:123]
	v_mfma_f32_16x16x32_bf16 v[116:119], v[200:203], v[208:211], v[116:119]
	v_mfma_f32_16x16x32_bf16 v[102:105], v[192:195], v[216:219], v[102:105]
	v_mfma_f32_16x16x32_bf16 v[98:101], v[200:203], v[216:219], v[98:101]
	v_mfma_f32_16x16x32_bf16 v[86:89], v[192:195], v[240:243], v[86:89]
	v_mfma_f32_16x16x32_bf16 v[82:85], v[200:203], v[240:243], v[82:85]
	v_mfma_f32_16x16x32_bf16 v[70:73], v[192:195], v[248:251], v[70:73]
	v_mfma_f32_16x16x32_bf16 v[66:69], v[200:203], v[248:251], v[66:69]
	s_setprio 0
	s_barrier
	s_mov_b32 m0, s69
	v_lshl_add_u64 v[224:225], s[52:53], 0, v[142:143]
	ds_read_b128 v[204:207], v190 offset:16384
	ds_read_b128 v[208:211], v190 offset:17408
	ds_read_b128 v[212:215], v190 offset:18432
	ds_read_b128 v[216:219], v190 offset:19456
	ds_read_b128 v[220:223], v190 offset:20480
	ds_read_b128 v[240:243], v190 offset:21504
	ds_read_b128 v[244:247], v190 offset:22528
	ds_read_b128 v[248:251], v190 offset:23552
	global_load_lds_dwordx4 v[224:225], off
	v_lshl_add_u64 v[230:231], s[52:53], 0, v[146:147]
	s_mov_b32 m0, s88
	v_lshl_add_u64 v[236:237], s[54:55], 0, v[142:143]
	global_load_lds_dwordx4 v[230:231], off
	s_mov_b32 m0, s89
	v_lshl_add_u64 v[238:239], s[50:51], 0, v[144:145]
	global_load_lds_dwordx4 v[236:237], off
	v_lshl_add_u64 v[236:237], s[54:55], 0, v[146:147]
	s_mov_b32 m0, s91
	s_nop 0
	global_load_lds_dwordx4 v[236:237], off
	v_lshl_add_u64 v[236:237], s[50:51], 0, v[140:141]
	s_mov_b32 m0, s79
	s_nop 0
	global_load_lds_dwordx4 v[236:237], off
	s_mov_b32 m0, s80
	s_nop 0
	global_load_lds_dwordx4 v[238:239], off
	s_waitcnt vmcnt(8)
	s_waitcnt lgkmcnt(0)
	s_barrier
	s_setprio 1
	s_waitcnt lgkmcnt(0)
	v_mfma_f32_16x16x32_bf16 v[62:65], v[132:135], v[204:207], v[62:65]
	v_mfma_f32_16x16x32_bf16 v[58:61], v[166:169], v[204:207], v[58:61]
	v_mfma_f32_16x16x32_bf16 v[46:49], v[132:135], v[212:215], v[46:49]
	v_mfma_f32_16x16x32_bf16 v[42:45], v[166:169], v[212:215], v[42:45]
	v_mfma_f32_16x16x32_bf16 v[30:33], v[132:135], v[220:223], v[30:33]
	v_mfma_f32_16x16x32_bf16 v[26:29], v[166:169], v[220:223], v[26:29]
	v_mfma_f32_16x16x32_bf16 v[14:17], v[132:135], v[244:247], v[14:17]
	v_mfma_f32_16x16x32_bf16 v[10:13], v[166:169], v[244:247], v[10:13]
	v_mfma_f32_16x16x32_bf16 v[62:65], v[136:139], v[208:211], v[62:65]
	v_mfma_f32_16x16x32_bf16 v[58:61], v[170:173], v[208:211], v[58:61]
	v_mfma_f32_16x16x32_bf16 v[46:49], v[136:139], v[216:219], v[46:49]
	v_mfma_f32_16x16x32_bf16 v[42:45], v[170:173], v[216:219], v[42:45]
	v_mfma_f32_16x16x32_bf16 v[30:33], v[136:139], v[240:243], v[30:33]
	v_mfma_f32_16x16x32_bf16 v[26:29], v[170:173], v[240:243], v[26:29]
	v_mfma_f32_16x16x32_bf16 v[14:17], v[136:139], v[248:251], v[14:17]
	v_mfma_f32_16x16x32_bf16 v[10:13], v[170:173], v[248:251], v[10:13]
	s_setprio 0
	s_setprio 1
	v_mfma_f32_16x16x32_bf16 v[54:57], v[174:177], v[204:207], v[54:57]
	v_mfma_f32_16x16x32_bf16 v[50:53], v[196:199], v[204:207], v[50:53]
	v_mfma_f32_16x16x32_bf16 v[38:41], v[174:177], v[212:215], v[38:41]
	v_mfma_f32_16x16x32_bf16 v[34:37], v[196:199], v[212:215], v[34:37]
	v_mfma_f32_16x16x32_bf16 v[22:25], v[174:177], v[220:223], v[22:25]
	v_mfma_f32_16x16x32_bf16 v[18:21], v[196:199], v[220:223], v[18:21]
	v_mfma_f32_16x16x32_bf16 v[6:9], v[174:177], v[244:247], v[6:9]
	v_mfma_f32_16x16x32_bf16 v[2:5], v[196:199], v[244:247], v[2:5]
	v_mfma_f32_16x16x32_bf16 v[54:57], v[192:195], v[208:211], v[54:57]
	v_mfma_f32_16x16x32_bf16 v[50:53], v[200:203], v[208:211], v[50:53]
	v_mfma_f32_16x16x32_bf16 v[38:41], v[192:195], v[216:219], v[38:41]
	v_mfma_f32_16x16x32_bf16 v[34:37], v[200:203], v[216:219], v[34:37]
	v_mfma_f32_16x16x32_bf16 v[22:25], v[192:195], v[240:243], v[22:25]
	v_mfma_f32_16x16x32_bf16 v[18:21], v[200:203], v[240:243], v[18:21]
	v_mfma_f32_16x16x32_bf16 v[6:9], v[192:195], v[248:251], v[6:9]
	v_mfma_f32_16x16x32_bf16 v[2:5], v[200:203], v[248:251], v[2:5]
	s_setprio 0
	s_barrier
	v_add_u32_e32 v114, s92, v180
	ds_read_b128 v[132:135], v114
	ds_read_b128 v[136:139], v114 offset:1024
	ds_read_b128 v[166:169], v114 offset:2048
	ds_read_b128 v[170:173], v114 offset:3072
	v_add_u32_e32 v114, s93, v180
	ds_read_b128 v[174:177], v114
	ds_read_b128 v[192:195], v114 offset:1024
	ds_read_b128 v[196:199], v114 offset:2048
	ds_read_b128 v[200:203], v114 offset:3072
	s_mov_b32 m0, s81
	v_lshl_add_u64 v[232:233], s[48:49], 0, v[140:141]
	ds_read_b128 v[204:207], v190 offset:32768
	ds_read_b128 v[208:211], v190 offset:33792
	ds_read_b128 v[212:215], v190 offset:34816
	ds_read_b128 v[216:219], v190 offset:35840
	ds_read_b128 v[220:223], v190 offset:36864
	ds_read_b128 v[240:243], v190 offset:37888
	ds_read_b128 v[244:247], v190 offset:38912
	ds_read_b128 v[248:251], v190 offset:39936
	global_load_lds_dwordx4 v[232:233], off
	v_lshl_add_u64 v[232:233], s[48:49], 0, v[144:145]
	s_mov_b32 m0, s82
	s_nop 0
	global_load_lds_dwordx4 v[232:233], off
	s_waitcnt vmcnt(8)
	s_waitcnt lgkmcnt(0)
	s_barrier
	s_setprio 1
	s_waitcnt lgkmcnt(0)
	v_mfma_f32_16x16x32_bf16 v[128:131], v[132:135], v[204:207], v[128:131]
	v_mfma_f32_16x16x32_bf16 v[124:127], v[166:169], v[204:207], v[124:127]
	v_mfma_f32_16x16x32_bf16 v[110:113], v[132:135], v[212:215], v[110:113]
	v_mfma_f32_16x16x32_bf16 v[106:109], v[166:169], v[212:215], v[106:109]
	v_mfma_f32_16x16x32_bf16 v[94:97], v[132:135], v[220:223], v[94:97]
	v_mfma_f32_16x16x32_bf16 v[90:93], v[166:169], v[220:223], v[90:93]
	v_mfma_f32_16x16x32_bf16 v[78:81], v[132:135], v[244:247], v[78:81]
	v_mfma_f32_16x16x32_bf16 v[74:77], v[166:169], v[244:247], v[74:77]
	v_mfma_f32_16x16x32_bf16 v[128:131], v[136:139], v[208:211], v[128:131]
	v_mfma_f32_16x16x32_bf16 v[124:127], v[170:173], v[208:211], v[124:127]
	v_mfma_f32_16x16x32_bf16 v[110:113], v[136:139], v[216:219], v[110:113]
	v_mfma_f32_16x16x32_bf16 v[106:109], v[170:173], v[216:219], v[106:109]
	v_mfma_f32_16x16x32_bf16 v[94:97], v[136:139], v[240:243], v[94:97]
	v_mfma_f32_16x16x32_bf16 v[90:93], v[170:173], v[240:243], v[90:93]
	v_mfma_f32_16x16x32_bf16 v[78:81], v[136:139], v[248:251], v[78:81]
	v_mfma_f32_16x16x32_bf16 v[74:77], v[170:173], v[248:251], v[74:77]
	s_setprio 0
	s_setprio 1
	v_mfma_f32_16x16x32_bf16 v[120:123], v[174:177], v[204:207], v[120:123]
	v_mfma_f32_16x16x32_bf16 v[116:119], v[196:199], v[204:207], v[116:119]
	v_mfma_f32_16x16x32_bf16 v[102:105], v[174:177], v[212:215], v[102:105]
	v_mfma_f32_16x16x32_bf16 v[98:101], v[196:199], v[212:215], v[98:101]
	v_mfma_f32_16x16x32_bf16 v[86:89], v[174:177], v[220:223], v[86:89]
	v_mfma_f32_16x16x32_bf16 v[82:85], v[196:199], v[220:223], v[82:85]
	v_mfma_f32_16x16x32_bf16 v[70:73], v[174:177], v[244:247], v[70:73]
	v_mfma_f32_16x16x32_bf16 v[66:69], v[196:199], v[244:247], v[66:69]
	v_mfma_f32_16x16x32_bf16 v[120:123], v[192:195], v[208:211], v[120:123]
	v_mfma_f32_16x16x32_bf16 v[116:119], v[200:203], v[208:211], v[116:119]
	v_mfma_f32_16x16x32_bf16 v[102:105], v[192:195], v[216:219], v[102:105]
	v_mfma_f32_16x16x32_bf16 v[98:101], v[200:203], v[216:219], v[98:101]
	v_mfma_f32_16x16x32_bf16 v[86:89], v[192:195], v[240:243], v[86:89]
	v_mfma_f32_16x16x32_bf16 v[82:85], v[200:203], v[240:243], v[82:85]
	v_mfma_f32_16x16x32_bf16 v[70:73], v[192:195], v[248:251], v[70:73]
	v_mfma_f32_16x16x32_bf16 v[66:69], v[200:203], v[248:251], v[66:69]
	s_setprio 0
	s_barrier
	s_mov_b32 m0, s59
	v_lshl_add_u64 v[224:225], v[224:225], 0, s[28:29]
	ds_read_b128 v[204:207], v190 offset:49152
	ds_read_b128 v[208:211], v190 offset:50176
	ds_read_b128 v[212:215], v190 offset:51200
	ds_read_b128 v[216:219], v190 offset:52224
	ds_read_b128 v[220:223], v190 offset:53248
	ds_read_b128 v[240:243], v190 offset:54272
	ds_read_b128 v[244:247], v190 offset:55296
	ds_read_b128 v[248:251], v190 offset:56320
	global_load_lds_dwordx4 v[224:225], off
	v_lshl_add_u64 v[224:225], v[230:231], 0, s[28:29]
	s_mov_b32 m0, s57
	s_nop 0
	global_load_lds_dwordx4 v[224:225], off
	v_lshl_add_u64 v[224:225], s[42:43], 0, v[142:143]
	s_mov_b32 m0, s63
	s_nop 0
	global_load_lds_dwordx4 v[224:225], off
	v_lshl_add_u64 v[224:225], s[42:43], 0, v[146:147]
	s_mov_b32 m0, s62
	s_nop 0
	global_load_lds_dwordx4 v[224:225], off
	v_lshl_add_u64 v[224:225], v[236:237], 0, s[28:29]
	s_mov_b32 m0, s83
	s_nop 0
	global_load_lds_dwordx4 v[224:225], off
	v_lshl_add_u64 v[224:225], v[238:239], 0, s[28:29]
	s_mov_b32 m0, s84
	s_nop 0
	global_load_lds_dwordx4 v[224:225], off
	s_waitcnt vmcnt(8)
	s_waitcnt lgkmcnt(0)
	s_barrier
	s_setprio 1
	s_waitcnt lgkmcnt(0)
	v_mfma_f32_16x16x32_bf16 v[62:65], v[132:135], v[204:207], v[62:65]
	v_mfma_f32_16x16x32_bf16 v[58:61], v[166:169], v[204:207], v[58:61]
	v_mfma_f32_16x16x32_bf16 v[46:49], v[132:135], v[212:215], v[46:49]
	v_mfma_f32_16x16x32_bf16 v[42:45], v[166:169], v[212:215], v[42:45]
	v_mfma_f32_16x16x32_bf16 v[30:33], v[132:135], v[220:223], v[30:33]
	v_mfma_f32_16x16x32_bf16 v[26:29], v[166:169], v[220:223], v[26:29]
	v_mfma_f32_16x16x32_bf16 v[14:17], v[132:135], v[244:247], v[14:17]
	v_mfma_f32_16x16x32_bf16 v[10:13], v[166:169], v[244:247], v[10:13]
	v_mfma_f32_16x16x32_bf16 v[62:65], v[136:139], v[208:211], v[62:65]
	v_mfma_f32_16x16x32_bf16 v[58:61], v[170:173], v[208:211], v[58:61]
	v_mfma_f32_16x16x32_bf16 v[46:49], v[136:139], v[216:219], v[46:49]
	v_mfma_f32_16x16x32_bf16 v[42:45], v[170:173], v[216:219], v[42:45]
	v_mfma_f32_16x16x32_bf16 v[30:33], v[136:139], v[240:243], v[30:33]
	v_mfma_f32_16x16x32_bf16 v[26:29], v[170:173], v[240:243], v[26:29]
	v_mfma_f32_16x16x32_bf16 v[14:17], v[136:139], v[248:251], v[14:17]
	v_mfma_f32_16x16x32_bf16 v[10:13], v[170:173], v[248:251], v[10:13]
	s_setprio 0
	s_setprio 1
	v_mfma_f32_16x16x32_bf16 v[54:57], v[174:177], v[204:207], v[54:57]
	v_mfma_f32_16x16x32_bf16 v[50:53], v[196:199], v[204:207], v[50:53]
	v_mfma_f32_16x16x32_bf16 v[38:41], v[174:177], v[212:215], v[38:41]
	v_mfma_f32_16x16x32_bf16 v[34:37], v[196:199], v[212:215], v[34:37]
	v_mfma_f32_16x16x32_bf16 v[22:25], v[174:177], v[220:223], v[22:25]
	v_mfma_f32_16x16x32_bf16 v[18:21], v[196:199], v[220:223], v[18:21]
	v_mfma_f32_16x16x32_bf16 v[6:9], v[174:177], v[244:247], v[6:9]
	v_mfma_f32_16x16x32_bf16 v[2:5], v[196:199], v[244:247], v[2:5]
	v_mfma_f32_16x16x32_bf16 v[54:57], v[192:195], v[208:211], v[54:57]
	v_mfma_f32_16x16x32_bf16 v[50:53], v[200:203], v[208:211], v[50:53]
	v_mfma_f32_16x16x32_bf16 v[38:41], v[192:195], v[216:219], v[38:41]
	v_mfma_f32_16x16x32_bf16 v[34:37], v[200:203], v[216:219], v[34:37]
	v_mfma_f32_16x16x32_bf16 v[22:25], v[192:195], v[240:243], v[22:25]
	v_mfma_f32_16x16x32_bf16 v[18:21], v[200:203], v[240:243], v[18:21]
	v_mfma_f32_16x16x32_bf16 v[6:9], v[192:195], v[248:251], v[6:9]
	v_mfma_f32_16x16x32_bf16 v[2:5], v[200:203], v[248:251], v[2:5]
	s_setprio 0
	s_barrier
	s_movk_i32 s48, 0x100
	s_andn2_b64 vcc, exec, s[26:27]
	s_mov_b64 s[42:43], -1
	s_mov_b64 s[26:27], 0
	s_cbranch_vccz .LBB0_548
	s_and_b64 vcc, exec, s[12:13]
	s_cbranch_vccz .LBB0_551
	s_barrier

.LBB0_570:
	s_waitcnt lgkmcnt(0)
	s_barrier
	s_andn2_b64 vcc, exec, s[16:17]
	s_mov_b64 s[24:25], -1
	s_cbranch_vccnz .LBB0_574
	v_cvt_pk_bf16_f32 v132, v128, v129
	v_cvt_pk_bf16_f32 v133, v130, v131
	v_cvt_pk_bf16_f32 v136, v124, v125
	v_cvt_pk_bf16_f32 v137, v126, v127
	v_cvt_pk_bf16_f32 v160, v120, v121
	v_cvt_pk_bf16_f32 v161, v122, v123
	v_mov_b32_e32 v168, v115
	v_cndmask_b32_e64 v138, v161, v133, s[38:39]
	v_cndmask_b32_e64 v139, v160, v132, s[38:39]
	v_mov_b32_e32 v169, v115
	v_cvt_pk_bf16_f32 v166, v116, v117
	v_cvt_pk_bf16_f32 v167, v118, v119
	v_mov_b32_e32 v170, v115
	s_waitcnt lgkmcnt(0)
	v_cndmask_b32_e64 v134, v167, v137, s[38:39]
	v_cndmask_b32_e64 v135, v166, v136, s[38:39]
	v_mov_b32_dpp v168, v139 quad_perm:[1,0,3,2] row_mask:0xf bank_mask:0xf
	v_mov_b32_dpp v169, v138 quad_perm:[1,0,3,2] row_mask:0xf bank_mask:0xf
	v_mov_b32_e32 v171, v115
	v_mov_b32_dpp v170, v135 quad_perm:[1,0,3,2] row_mask:0xf bank_mask:0xf
	v_cndmask_b32_e64 v135, v133, v169, s[38:39]
	v_mov_b32_dpp v171, v134 quad_perm:[1,0,3,2] row_mask:0xf bank_mask:0xf
	v_cndmask_b32_e64 v134, v132, v168, s[38:39]
	v_lshlrev_b64 v[132:133], 1, v[148:149]
	v_cndmask_b32_e64 v136, v136, v170, s[38:39]
	v_cndmask_b32_e64 v137, v137, v171, s[38:39]
	v_lshl_add_u64 v[138:139], s[20:21], 0, v[132:133]
	global_store_dwordx4 v[138:139], v[134:137], off nt
	v_cndmask_b32_e64 v138, v170, v166, s[38:39]
	v_cndmask_b32_e64 v139, v171, v167, s[38:39]
	v_lshlrev_b64 v[134:135], 1, v[150:151]
	v_cndmask_b32_e64 v136, v168, v160, s[38:39]
	v_cndmask_b32_e64 v137, v169, v161, s[38:39]
	v_lshl_add_u64 v[166:167], s[20:21], 0, v[134:135]
	global_store_dwordx4 v[166:167], v[136:139], off nt
	v_mov_b32_e32 v172, v115
	s_add_u32 s24, s20, 0x14000
	v_cvt_pk_bf16_f32 v136, v110, v111
	v_cvt_pk_bf16_f32 v137, v112, v113
	v_cvt_pk_bf16_f32 v138, v106, v107
	v_cvt_pk_bf16_f32 v139, v108, v109
	v_cvt_pk_bf16_f32 v160, v102, v103
	v_cvt_pk_bf16_f32 v161, v104, v105
	v_cvt_pk_bf16_f32 v168, v98, v99
	v_cvt_pk_bf16_f32 v169, v100, v101
	v_mov_b32_e32 v173, v115
	v_cndmask_b32_e64 v171, v160, v136, s[38:39]
	v_cndmask_b32_e64 v170, v161, v137, s[38:39]
	v_cndmask_b32_e64 v166, v169, v139, s[38:39]
	v_mov_b32_dpp v172, v171 quad_perm:[1,0,3,2] row_mask:0xf bank_mask:0xf
	v_mov_b32_e32 v171, v115
	v_cndmask_b32_e64 v167, v168, v138, s[38:39]
	s_addc_u32 s25, s21, 0
	v_mov_b32_dpp v171, v170 quad_perm:[1,0,3,2] row_mask:0xf bank_mask:0xf
	v_mov_b32_e32 v170, v115
	v_mov_b32_dpp v173, v166 quad_perm:[1,0,3,2] row_mask:0xf bank_mask:0xf
	v_cndmask_b32_e64 v136, v136, v172, s[38:39]
	v_mov_b32_dpp v170, v167 quad_perm:[1,0,3,2] row_mask:0xf bank_mask:0xf
	v_cndmask_b32_e64 v137, v137, v171, s[38:39]
	v_cndmask_b32_e64 v138, v138, v170, s[38:39]
	v_cndmask_b32_e64 v139, v139, v173, s[38:39]
	v_lshl_add_u64 v[166:167], s[24:25], 0, v[132:133]
	global_store_dwordx4 v[166:167], v[136:139], off nt
	v_lshl_add_u64 v[166:167], s[24:25], 0, v[134:135]
	s_add_u32 s24, s20, 0x28000
	v_cndmask_b32_e64 v136, v172, v160, s[38:39]
	v_cndmask_b32_e64 v137, v171, v161, s[38:39]
	v_cndmask_b32_e64 v138, v170, v168, s[38:39]
	v_cndmask_b32_e64 v139, v173, v169, s[38:39]
	global_store_dwordx4 v[166:167], v[136:139], off nt
	v_mov_b32_e32 v172, v115
	v_mov_b32_e32 v173, v115
	v_cvt_pk_bf16_f32 v136, v94, v95
	v_cvt_pk_bf16_f32 v137, v96, v97
	v_cvt_pk_bf16_f32 v138, v90, v91
	v_cvt_pk_bf16_f32 v139, v92, v93
	v_cvt_pk_bf16_f32 v160, v86, v87
	v_cvt_pk_bf16_f32 v161, v88, v89
	v_cvt_pk_bf16_f32 v168, v82, v83
	v_cvt_pk_bf16_f32 v169, v84, v85
	s_addc_u32 s25, s21, 0
	v_cndmask_b32_e64 v171, v160, v136, s[38:39]
	v_cndmask_b32_e64 v170, v161, v137, s[38:39]
	v_cndmask_b32_e64 v166, v169, v139, s[38:39]
	v_mov_b32_dpp v172, v171 quad_perm:[1,0,3,2] row_mask:0xf bank_mask:0xf
	v_mov_b32_e32 v171, v115
	v_cndmask_b32_e64 v167, v168, v138, s[38:39]
	v_mov_b32_dpp v173, v166 quad_perm:[1,0,3,2] row_mask:0xf bank_mask:0xf
	v_mov_b32_dpp v171, v170 quad_perm:[1,0,3,2] row_mask:0xf bank_mask:0xf
	v_mov_b32_e32 v170, v115
	v_cndmask_b32_e64 v136, v136, v172, s[38:39]
	v_cndmask_b32_e64 v137, v137, v171, s[38:39]
	v_mov_b32_dpp v170, v167 quad_perm:[1,0,3,2] row_mask:0xf bank_mask:0xf
	v_cndmask_b32_e64 v138, v138, v170, s[38:39]
	v_cndmask_b32_e64 v139, v139, v173, s[38:39]
	v_lshl_add_u64 v[166:167], s[24:25], 0, v[132:133]
	global_store_dwordx4 v[166:167], v[136:139], off nt
	v_lshl_add_u64 v[166:167], s[24:25], 0, v[134:135]
	s_add_u32 s24, s20, 0x3c000
	v_cndmask_b32_e64 v136, v172, v160, s[38:39]
	v_cndmask_b32_e64 v137, v171, v161, s[38:39]
	v_cndmask_b32_e64 v138, v170, v168, s[38:39]
	v_cndmask_b32_e64 v139, v173, v169, s[38:39]
	global_store_dwordx4 v[166:167], v[136:139], off nt
	v_mov_b32_e32 v172, v115
	v_mov_b32_e32 v173, v115
	v_cvt_pk_bf16_f32 v136, v78, v79
	v_cvt_pk_bf16_f32 v137, v80, v81
	v_cvt_pk_bf16_f32 v138, v74, v75
	v_cvt_pk_bf16_f32 v139, v76, v77
	v_cvt_pk_bf16_f32 v160, v70, v71
	v_cvt_pk_bf16_f32 v161, v72, v73
	v_cvt_pk_bf16_f32 v168, v66, v67
	v_cvt_pk_bf16_f32 v169, v68, v69
	s_addc_u32 s25, s21, 0
	v_cndmask_b32_e64 v171, v160, v136, s[38:39]
	v_cndmask_b32_e64 v170, v161, v137, s[38:39]
	v_cndmask_b32_e64 v166, v169, v139, s[38:39]
	v_mov_b32_dpp v172, v171 quad_perm:[1,0,3,2] row_mask:0xf bank_mask:0xf
	v_mov_b32_e32 v171, v115
	v_cndmask_b32_e64 v167, v168, v138, s[38:39]
	v_mov_b32_dpp v173, v166 quad_perm:[1,0,3,2] row_mask:0xf bank_mask:0xf
	v_mov_b32_dpp v171, v170 quad_perm:[1,0,3,2] row_mask:0xf bank_mask:0xf
	v_mov_b32_e32 v170, v115
	v_cndmask_b32_e64 v136, v136, v172, s[38:39]
	v_cndmask_b32_e64 v137, v137, v171, s[38:39]
	v_mov_b32_dpp v170, v167 quad_perm:[1,0,3,2] row_mask:0xf bank_mask:0xf
	v_cndmask_b32_e64 v138, v138, v170, s[38:39]
	v_cndmask_b32_e64 v139, v139, v173, s[38:39]
	v_lshl_add_u64 v[166:167], s[24:25], 0, v[132:133]
	global_store_dwordx4 v[166:167], v[136:139], off nt
	v_lshl_add_u64 v[166:167], s[24:25], 0, v[134:135]
	s_add_u32 s24, s20, 0xa0000
	v_cndmask_b32_e64 v136, v172, v160, s[38:39]
	v_cndmask_b32_e64 v137, v171, v161, s[38:39]
	v_cndmask_b32_e64 v138, v170, v168, s[38:39]
	v_cndmask_b32_e64 v139, v173, v169, s[38:39]
	global_store_dwordx4 v[166:167], v[136:139], off nt
	v_mov_b32_e32 v172, v115
	v_mov_b32_e32 v173, v115
	v_cvt_pk_bf16_f32 v136, v62, v63
	v_cvt_pk_bf16_f32 v137, v64, v65
	v_cvt_pk_bf16_f32 v138, v58, v59
	v_cvt_pk_bf16_f32 v139, v60, v61
	v_cvt_pk_bf16_f32 v160, v54, v55
	v_cvt_pk_bf16_f32 v161, v56, v57
	v_cvt_pk_bf16_f32 v168, v50, v51
	v_cvt_pk_bf16_f32 v169, v52, v53
	s_addc_u32 s25, s21, 0
	v_cndmask_b32_e64 v171, v160, v136, s[38:39]
	v_cndmask_b32_e64 v170, v161, v137, s[38:39]
	v_cndmask_b32_e64 v166, v169, v139, s[38:39]
	v_mov_b32_dpp v172, v171 quad_perm:[1,0,3,2] row_mask:0xf bank_mask:0xf
	v_mov_b32_e32 v171, v115
	v_cndmask_b32_e64 v167, v168, v138, s[38:39]
	v_mov_b32_dpp v173, v166 quad_perm:[1,0,3,2] row_mask:0xf bank_mask:0xf
	v_mov_b32_dpp v171, v170 quad_perm:[1,0,3,2] row_mask:0xf bank_mask:0xf
	v_mov_b32_e32 v170, v115
	v_cndmask_b32_e64 v136, v136, v172, s[38:39]
	v_cndmask_b32_e64 v137, v137, v171, s[38:39]
	v_mov_b32_dpp v170, v167 quad_perm:[1,0,3,2] row_mask:0xf bank_mask:0xf
	v_cndmask_b32_e64 v138, v138, v170, s[38:39]
	v_cndmask_b32_e64 v139, v139, v173, s[38:39]
	v_lshl_add_u64 v[166:167], s[24:25], 0, v[132:133]
	global_store_dwordx4 v[166:167], v[136:139], off nt
	v_lshl_add_u64 v[166:167], s[24:25], 0, v[134:135]
	s_add_u32 s24, s20, 0xb4000
	v_cndmask_b32_e64 v136, v172, v160, s[38:39]
	v_cndmask_b32_e64 v137, v171, v161, s[38:39]
	v_cndmask_b32_e64 v138, v170, v168, s[38:39]
	v_cndmask_b32_e64 v139, v173, v169, s[38:39]
	global_store_dwordx4 v[166:167], v[136:139], off nt
	v_mov_b32_e32 v172, v115
	v_mov_b32_e32 v173, v115
	v_cvt_pk_bf16_f32 v136, v46, v47
	v_cvt_pk_bf16_f32 v137, v48, v49
	v_cvt_pk_bf16_f32 v138, v42, v43
	v_cvt_pk_bf16_f32 v139, v44, v45
	v_cvt_pk_bf16_f32 v160, v38, v39
	v_cvt_pk_bf16_f32 v161, v40, v41
	v_cvt_pk_bf16_f32 v168, v34, v35
	v_cvt_pk_bf16_f32 v169, v36, v37
	s_addc_u32 s25, s21, 0
	v_cndmask_b32_e64 v171, v160, v136, s[38:39]
	v_cndmask_b32_e64 v170, v161, v137, s[38:39]
	v_cndmask_b32_e64 v166, v169, v139, s[38:39]
	v_mov_b32_dpp v172, v171 quad_perm:[1,0,3,2] row_mask:0xf bank_mask:0xf
	v_mov_b32_e32 v171, v115
	v_cndmask_b32_e64 v167, v168, v138, s[38:39]
	v_mov_b32_dpp v173, v166 quad_perm:[1,0,3,2] row_mask:0xf bank_mask:0xf
	v_mov_b32_dpp v171, v170 quad_perm:[1,0,3,2] row_mask:0xf bank_mask:0xf
	v_mov_b32_e32 v170, v115
	v_cndmask_b32_e64 v136, v136, v172, s[38:39]
	v_cndmask_b32_e64 v137, v137, v171, s[38:39]
	v_mov_b32_dpp v170, v167 quad_perm:[1,0,3,2] row_mask:0xf bank_mask:0xf
	v_cndmask_b32_e64 v138, v138, v170, s[38:39]
	v_cndmask_b32_e64 v139, v139, v173, s[38:39]
	v_lshl_add_u64 v[166:167], s[24:25], 0, v[132:133]
	global_store_dwordx4 v[166:167], v[136:139], off nt
	v_lshl_add_u64 v[166:167], s[24:25], 0, v[134:135]
	s_add_u32 s24, s20, 0xc8000
	v_cndmask_b32_e64 v136, v172, v160, s[38:39]
	v_cndmask_b32_e64 v137, v171, v161, s[38:39]
	v_cndmask_b32_e64 v138, v170, v168, s[38:39]
	v_cndmask_b32_e64 v139, v173, v169, s[38:39]
	global_store_dwordx4 v[166:167], v[136:139], off nt
	v_mov_b32_e32 v172, v115
	v_mov_b32_e32 v173, v115
	v_cvt_pk_bf16_f32 v136, v30, v31
	v_cvt_pk_bf16_f32 v137, v32, v33
	v_cvt_pk_bf16_f32 v138, v26, v27
	v_cvt_pk_bf16_f32 v139, v28, v29
	v_cvt_pk_bf16_f32 v160, v22, v23
	v_cvt_pk_bf16_f32 v161, v24, v25
	v_cvt_pk_bf16_f32 v168, v18, v19
	v_cvt_pk_bf16_f32 v169, v20, v21
	s_addc_u32 s25, s21, 0
	v_cndmask_b32_e64 v171, v160, v136, s[38:39]
	v_cndmask_b32_e64 v170, v161, v137, s[38:39]
	v_cndmask_b32_e64 v166, v169, v139, s[38:39]
	v_mov_b32_dpp v172, v171 quad_perm:[1,0,3,2] row_mask:0xf bank_mask:0xf
	v_mov_b32_e32 v171, v115
	v_cndmask_b32_e64 v167, v168, v138, s[38:39]
	v_mov_b32_dpp v173, v166 quad_perm:[1,0,3,2] row_mask:0xf bank_mask:0xf
	v_mov_b32_dpp v171, v170 quad_perm:[1,0,3,2] row_mask:0xf bank_mask:0xf
	v_mov_b32_e32 v170, v115
	v_cndmask_b32_e64 v136, v136, v172, s[38:39]
	v_cndmask_b32_e64 v137, v137, v171, s[38:39]
	v_mov_b32_dpp v170, v167 quad_perm:[1,0,3,2] row_mask:0xf bank_mask:0xf
	v_cndmask_b32_e64 v138, v138, v170, s[38:39]
	v_cndmask_b32_e64 v139, v139, v173, s[38:39]
	v_lshl_add_u64 v[166:167], s[24:25], 0, v[132:133]
	global_store_dwordx4 v[166:167], v[136:139], off nt
	v_lshl_add_u64 v[166:167], s[24:25], 0, v[134:135]
	s_add_u32 s24, s20, 0xdc000
	v_cndmask_b32_e64 v136, v172, v160, s[38:39]
	v_cndmask_b32_e64 v137, v171, v161, s[38:39]
	v_cndmask_b32_e64 v138, v170, v168, s[38:39]
	v_cndmask_b32_e64 v139, v173, v169, s[38:39]
	global_store_dwordx4 v[166:167], v[136:139], off nt
	v_mov_b32_e32 v172, v115
	s_addc_u32 s25, s21, 0
	v_cvt_pk_bf16_f32 v136, v14, v15
	v_cvt_pk_bf16_f32 v137, v16, v17
	v_cvt_pk_bf16_f32 v138, v10, v11
	v_cvt_pk_bf16_f32 v139, v12, v13
	v_cvt_pk_bf16_f32 v160, v6, v7
	v_cvt_pk_bf16_f32 v161, v8, v9
	v_cvt_pk_bf16_f32 v166, v2, v3
	v_cvt_pk_bf16_f32 v167, v4, v5
	v_lshl_add_u64 v[132:133], s[24:25], 0, v[132:133]
	v_cndmask_b32_e64 v171, v160, v136, s[38:39]
	v_cndmask_b32_e64 v170, v161, v137, s[38:39]
	v_cndmask_b32_e64 v169, v166, v138, s[38:39]
	v_mov_b32_dpp v172, v171 quad_perm:[1,0,3,2] row_mask:0xf bank_mask:0xf
	v_mov_b32_e32 v171, v115
	v_cndmask_b32_e64 v168, v167, v139, s[38:39]
	v_cndmask_b32_e64 v136, v136, v172, s[38:39]
	v_mov_b32_dpp v171, v170 quad_perm:[1,0,3,2] row_mask:0xf bank_mask:0xf
	v_mov_b32_e32 v170, v115
	v_cndmask_b32_e64 v137, v137, v171, s[38:39]
	s_nop 0
	v_mov_b32_dpp v170, v169 quad_perm:[1,0,3,2] row_mask:0xf bank_mask:0xf
	v_mov_b32_e32 v169, v115
	v_cndmask_b32_e64 v138, v138, v170, s[38:39]
	s_nop 0
	v_mov_b32_dpp v169, v168 quad_perm:[1,0,3,2] row_mask:0xf bank_mask:0xf
	v_cndmask_b32_e64 v139, v139, v169, s[38:39]
	global_store_dwordx4 v[132:133], v[136:139], off nt
	v_lshl_add_u64 v[132:133], s[24:25], 0, v[134:135]
	s_nop 0
	v_cndmask_b32_e64 v136, v172, v160, s[38:39]
	v_cndmask_b32_e64 v137, v171, v161, s[38:39]
	v_cndmask_b32_e64 v138, v170, v166, s[38:39]
	v_cndmask_b32_e64 v139, v169, v167, s[38:39]
	global_store_dwordx4 v[132:133], v[136:139], off nt
	global_load_dwordx4 v[132:135], v[152:153], off offset:512
	global_load_dwordx4 v[136:139], v[152:153], off offset:528
	global_load_dwordx4 v[174:177], v[152:153], off offset:640
	global_load_dwordx4 v[170:173], v[152:153], off offset:656
	s_add_i32 s3, s19, s95
	v_lshl_add_u32 v192, v114, 3, s94
	s_waitcnt vmcnt(0)
	v_mov_b32_e32 v167, v138
	v_mov_b32_e32 v169, v136
	v_mov_b32_e32 v168, v170
	v_mov_b32_e32 v170, v176
	v_add_u32_e32 v176, s3, v114
	v_mov_b32_e32 v166, v172
	v_mov_b32_e32 v138, v173
	v_mov_b32_e32 v136, v171
	v_mov_b32_e32 v171, v134
	v_mov_b32_e32 v134, v177
	v_mov_b32_e32 v172, v174
	v_mov_b32_e32 v173, v132
	v_mov_b32_e32 v132, v175
	v_lshl_add_u64 v[174:175], s[22:23], 1, v[164:165]
	v_lshlrev_b32_e32 v193, 8, v176
	s_mov_b32 s3, 0
.LBB0_572:
	v_add_u32_e32 v114, s3, v192
	ds_read_b64 v[194:195], v114
	v_ashrrev_i32_e32 v177, 31, v176
	v_mad_i64_i32 v[198:199], s[22:23], v176, s2, v[158:159]
	s_addk_i32 s3, 0x80
	s_waitcnt lgkmcnt(0)
	v_add_f32_e32 v114, v194, v195
	v_lshl_add_u64 v[194:195], v[176:177], 2, s[10:11]
	global_load_dword v160, v[194:195], off
	s_cmpk_lg_i32 s3, 0x200
	s_waitcnt vmcnt(0)
	v_add_f32_e32 v114, v160, v114
	v_fmamk_f32 v114, v114, 0x3baaaaab, v1
	v_cmp_gt_f32_e32 vcc, s70, v114
	v_mul_f32_e32 v160, 0x4f800000, v114
	s_nop 0
	v_cndmask_b32_e32 v114, v114, v160, vcc
	v_sqrt_f32_e32 v160, v114
	s_nop 0
	v_add_u32_e32 v161, -1, v160
	v_fma_f32 v177, -v161, v160, v114
	v_cmp_ge_f32_e64 s[42:43], 0, v177
	v_add_u32_e32 v177, 1, v160
	s_nop 0
	v_cndmask_b32_e64 v161, v160, v161, s[42:43]
	v_fma_f32 v160, -v177, v160, v114
	v_cmp_lt_f32_e64 s[42:43], 0, v160
	s_nop 1
	v_cndmask_b32_e64 v160, v161, v177, s[42:43]
	v_mul_f32_e32 v161, 0x37800000, v160
	v_cndmask_b32_e32 v160, v160, v161, vcc
	v_cmp_class_f32_e32 vcc, v114, v226
	s_nop 1
	v_cndmask_b32_e32 v114, v160, v114, vcc
	v_div_scale_f32 v160, s[22:23], v114, v114, 1.0
	v_rcp_f32_e32 v161, v160
	s_movk_i32 s22, 0x1400
	v_fma_f32 v177, -v160, v161, 1.0
	v_fmac_f32_e32 v161, v177, v161
	v_div_scale_f32 v177, vcc, 1.0, v114, 1.0
	v_mul_f32_e32 v194, v177, v161
	v_fma_f32 v195, -v160, v194, v177
	v_fmac_f32_e32 v194, v195, v161
	v_fma_f32 v160, -v160, v194, v177
	v_div_fmas_f32 v160, v160, v161, v194
	v_div_fixup_f32 v218, v160, v114, 1.0
	global_load_dwordx4 v[194:197], v[198:199], off
	s_nop 0
	global_load_dwordx4 v[198:201], v[198:199], off offset:64
	v_and_b32_e32 v114, 0x7ff00, v193
	v_lshl_add_u64 v[214:215], v[154:155], 0, v[114:115]
	global_load_dwordx4 v[202:205], v[214:215], off offset:16
	global_load_dwordx4 v[206:209], v[214:215], off
	global_load_dwordx4 v[210:213], v[214:215], off offset:144
	s_nop 0
	global_load_dwordx4 v[214:217], v[214:215], off offset:128
	v_add_u32_e32 v193, 0x1000, v193
	s_waitcnt vmcnt(5)
	v_lshlrev_b32_e32 v221, 16, v194
	s_waitcnt vmcnt(4)
	v_lshlrev_b32_e32 v220, 16, v198
	v_pk_mul_f32 v[220:221], v[218:219], v[220:221] op_sel_hi:[0,1]
	v_pk_mul_f32 v[220:221], v[172:173], v[220:221]
	s_waitcnt vmcnt(0)
	v_mov_b32_e32 v222, v214
	v_mov_b32_e32 v223, v206
	v_pk_mul_f32 v[222:223], v[222:223], v[220:221]
	s_nop 0
	v_sub_f32_e32 v114, v223, v222
	v_mov_b32_e32 v222, v206
	v_mov_b32_e32 v223, v214
	v_pk_mul_f32 v[220:221], v[222:223], v[220:221]
	v_mov_b32_e32 v206, v215
	v_add_f32_e32 v160, v220, v221
	v_and_b32_e32 v221, 0xffff0000, v194
	v_and_b32_e32 v220, 0xffff0000, v198
	v_pk_mul_f32 v[220:221], v[218:219], v[220:221] op_sel_hi:[0,1]
	v_pk_mul_f32 v[220:221], v[132:133], v[220:221]
	v_mov_b32_e32 v214, v207
	v_pk_mul_f32 v[222:223], v[206:207], v[220:221]
	v_pk_mul_f32 v[206:207], v[214:215], v[220:221]
	v_mov_b32_e32 v214, v216
	v_add_f32_e32 v177, v206, v207
	v_lshlrev_b32_e32 v207, 16, v195
	v_lshlrev_b32_e32 v206, 16, v199
	v_pk_mul_f32 v[206:207], v[218:219], v[206:207] op_sel_hi:[0,1]
	v_pk_mul_f32 v[206:207], v[170:171], v[206:207]
	v_mov_b32_e32 v215, v208
	v_pk_mul_f32 v[214:215], v[214:215], v[206:207]
	v_and_b32_e32 v195, 0xffff0000, v195
	v_sub_f32_e32 v219, v215, v214
	v_and_b32_e32 v194, 0xffff0000, v199
	v_pk_mul_f32 v[194:195], v[218:219], v[194:195] op_sel_hi:[0,1]
	v_mov_b32_e32 v214, v208
	v_mov_b32_e32 v215, v216
	v_pk_mul_f32 v[194:195], v[134:135], v[194:195]
	v_mov_b32_e32 v208, v217
	v_mov_b32_e32 v216, v209
	v_pk_mul_f32 v[198:199], v[208:209], v[194:195]
	v_pk_mul_f32 v[194:195], v[216:217], v[194:195]
	v_pk_mul_f32 v[206:207], v[214:215], v[206:207]
	v_add_f32_e32 v208, v194, v195
	v_lshlrev_b32_e32 v195, 16, v196
	v_lshlrev_b32_e32 v194, 16, v200
	v_pk_mul_f32 v[194:195], v[218:219], v[194:195] op_sel_hi:[0,1]
	v_add_f32_e32 v206, v206, v207
	v_sub_f32_e32 v207, v199, v198
	v_pk_mul_f32 v[194:195], v[168:169], v[194:195]
	v_mov_b32_e32 v198, v210
	v_mov_b32_e32 v199, v202
	v_pk_mul_f32 v[198:199], v[198:199], v[194:195]
	v_sub_f32_e32 v161, v223, v222
	v_sub_f32_e32 v209, v199, v198
	v_mov_b32_e32 v198, v202
	v_mov_b32_e32 v199, v210
	v_pk_mul_f32 v[194:195], v[198:199], v[194:195]
	v_mov_b32_e32 v202, v211
	v_add_f32_e32 v214, v194, v195
	v_and_b32_e32 v195, 0xffff0000, v196
	v_and_b32_e32 v194, 0xffff0000, v200
	v_pk_mul_f32 v[194:195], v[218:219], v[194:195] op_sel_hi:[0,1]
	v_pk_mul_f32 v[194:195], v[136:137], v[194:195]
	v_mov_b32_e32 v210, v203
	v_pk_mul_f32 v[198:199], v[202:203], v[194:195]
	v_pk_mul_f32 v[194:195], v[210:211], v[194:195]
	v_sub_f32_e32 v200, v199, v198
	v_add_f32_e32 v202, v194, v195
	v_lshlrev_b32_e32 v195, 16, v197
	v_lshlrev_b32_e32 v194, 16, v201
	v_pk_mul_f32 v[194:195], v[218:219], v[194:195] op_sel_hi:[0,1]
	v_pk_mul_f32 v[194:195], v[166:167], v[194:195]
	v_mov_b32_e32 v198, v212
	v_mov_b32_e32 v199, v204
	v_pk_mul_f32 v[198:199], v[198:199], v[194:195]
	s_nop 0
	v_sub_f32_e32 v203, v199, v198
	v_mov_b32_e32 v198, v204
	v_mov_b32_e32 v199, v212
	v_pk_mul_f32 v[194:195], v[198:199], v[194:195]
	v_mov_b32_e32 v204, v213
	v_add_f32_e32 v210, v194, v195
	v_and_b32_e32 v195, 0xffff0000, v197
	v_and_b32_e32 v194, 0xffff0000, v201
	v_pk_mul_f32 v[194:195], v[218:219], v[194:195] op_sel_hi:[0,1]
	v_pk_mul_f32 v[194:195], v[138:139], v[194:195]
	v_mov_b32_e32 v212, v205
	v_pk_mul_f32 v[196:197], v[204:205], v[194:195]
	v_pk_mul_f32 v[194:195], v[212:213], v[194:195]
	v_sub_f32_e32 v197, v197, v196
	v_add_f32_e32 v201, v194, v195
	v_cvt_pk_bf16_f32 v194, v114, v161
	v_cvt_pk_bf16_f32 v195, v219, v207
	v_cvt_pk_bf16_f32 v196, v209, v200
	v_cvt_pk_bf16_f32 v197, v203, v197
	v_cvt_pk_bf16_f32 v198, v160, v177
	v_cvt_pk_bf16_f32 v199, v206, v208
	v_cvt_pk_bf16_f32 v200, v214, v202
	v_mad_i64_i32 v[202:203], s[22:23], v176, s22, v[174:175]
	v_add_u32_e32 v176, 16, v176
	v_cvt_pk_bf16_f32 v201, v210, v201
	global_store_dwordx4 v[202:203], v[194:197], off offset:256 nt
	global_store_dwordx4 v[202:203], v[198:201], off offset:320 nt
	s_cbranch_scc1 .LBB0_572
	s_mov_b64 s[24:25], 0
.LBB0_574:
	s_and_b64 vcc, exec, s[24:25]
	s_cbranch_vccz .LBB0_576
	v_lshl_add_u32 v114, v191, 3, s73
	ds_read_b64 v[132:133], v114
	v_mov_b32_e32 v172, v115
	v_mov_b32_e32 v173, v115
	v_mov_b32_e32 v174, v115
	v_mov_b32_e32 v176, v115
	s_waitcnt lgkmcnt(0)
	v_add_f32_e32 v114, v132, v133
	v_add_u32_e32 v132, s19, v191
	v_ashrrev_i32_e32 v133, 31, v132
	v_lshl_add_u64 v[132:133], v[132:133], 2, s[10:11]
	global_load_dword v132, v[132:133], off
	s_waitcnt vmcnt(0)
	v_add_f32_e32 v114, v132, v114
	v_fmamk_f32 v114, v114, 0x3baaaaab, v1
	v_cmp_gt_f32_e32 vcc, s70, v114
	v_mul_f32_e32 v132, 0x4f800000, v114
	s_nop 0
	v_cndmask_b32_e32 v114, v114, v132, vcc
	v_sqrt_f32_e32 v132, v114
	s_nop 0
	v_add_u32_e32 v133, -1, v132
	v_fma_f32 v134, -v133, v132, v114
	v_cmp_ge_f32_e64 s[42:43], 0, v134
	v_add_u32_e32 v134, 1, v132
	s_nop 0
	v_cndmask_b32_e64 v133, v132, v133, s[42:43]
	v_fma_f32 v132, -v134, v132, v114
	v_cmp_lt_f32_e64 s[42:43], 0, v132
	s_nop 1
	v_cndmask_b32_e64 v132, v133, v134, s[42:43]
	v_mul_f32_e32 v133, 0x37800000, v132
	v_cndmask_b32_e32 v132, v132, v133, vcc
	v_cmp_class_f32_e32 vcc, v114, v226
	s_nop 1
	v_cndmask_b32_e32 v114, v132, v114, vcc
	v_div_scale_f32 v132, s[22:23], v114, v114, 1.0
	v_rcp_f32_e32 v133, v132
	s_nop 0
	v_fma_f32 v134, -v132, v133, 1.0
	v_fmac_f32_e32 v133, v134, v133
	v_div_scale_f32 v134, vcc, 1.0, v114, 1.0
	v_mul_f32_e32 v135, v134, v133
	v_fma_f32 v136, -v132, v135, v134
	v_fmac_f32_e32 v135, v136, v133
	v_fma_f32 v132, -v132, v135, v134
	v_div_fmas_f32 v132, v132, v133, v135
	v_div_fixup_f32 v114, v132, v114, 1.0
	global_load_dwordx4 v[132:135], v[156:157], off offset:16
	global_load_dwordx4 v[136:139], v[156:157], off
	v_pk_mul_f32 v[166:167], v[128:129], v[114:115] op_sel_hi:[1,0]
	v_pk_mul_f32 v[168:169], v[130:131], v[114:115] op_sel_hi:[1,0]
	s_waitcnt vmcnt(0)
	v_pk_mul_f32 v[136:137], v[136:137], v[166:167]
	v_pk_mul_f32 v[138:139], v[138:139], v[168:169]
	v_pk_mul_f32 v[166:167], v[124:125], v[114:115] op_sel_hi:[1,0]
	v_pk_mul_f32 v[168:169], v[126:127], v[114:115] op_sel_hi:[1,0]
	v_pk_mul_f32 v[132:133], v[132:133], v[166:167]
	v_pk_mul_f32 v[134:135], v[134:135], v[168:169]
	v_cvt_pk_bf16_f32 v160, v136, v137
	v_cvt_pk_bf16_f32 v161, v138, v139
	v_cvt_pk_bf16_f32 v170, v132, v133
	v_pk_mul_f32 v[166:167], v[120:121], v[114:115] op_sel_hi:[1,0]
	v_cvt_pk_bf16_f32 v171, v134, v135
	global_load_dwordx4 v[132:135], v[156:157], off offset:144
	global_load_dwordx4 v[136:139], v[156:157], off offset:128
	v_pk_mul_f32 v[168:169], v[122:123], v[114:115] op_sel_hi:[1,0]
	s_waitcnt vmcnt(0)
	v_pk_mul_f32 v[136:137], v[136:137], v[166:167]
	v_pk_mul_f32 v[138:139], v[138:139], v[168:169]
	v_pk_mul_f32 v[166:167], v[116:117], v[114:115] op_sel_hi:[1,0]
	v_pk_mul_f32 v[168:169], v[118:119], v[114:115] op_sel_hi:[1,0]
	v_pk_mul_f32 v[132:133], v[132:133], v[166:167]
	v_pk_mul_f32 v[134:135], v[134:135], v[168:169]
	v_cvt_pk_bf16_f32 v114, v136, v137
	v_cvt_pk_bf16_f32 v166, v138, v139
	v_cvt_pk_bf16_f32 v167, v132, v133
	v_mov_b32_e32 v169, v115
	v_cvt_pk_bf16_f32 v168, v134, v135
	v_cndmask_b32_e64 v133, v167, v170, s[38:39]
	v_cndmask_b32_e64 v132, v168, v171, s[38:39]
	v_cndmask_b32_e64 v134, v166, v161, s[38:39]
	v_cndmask_b32_e64 v135, v114, v160, s[38:39]
	v_mov_b32_dpp v173, v133 quad_perm:[1,0,3,2] row_mask:0xf bank_mask:0xf
	v_mov_b32_dpp v172, v134 quad_perm:[1,0,3,2] row_mask:0xf bank_mask:0xf
	v_mov_b32_dpp v169, v135 quad_perm:[1,0,3,2] row_mask:0xf bank_mask:0xf
	v_mov_b32_dpp v174, v132 quad_perm:[1,0,3,2] row_mask:0xf bank_mask:0xf
	v_lshlrev_b64 v[136:137], 1, v[148:149]
	v_cndmask_b32_e64 v132, v160, v169, s[38:39]
	v_cndmask_b32_e64 v133, v161, v172, s[38:39]
	v_cndmask_b32_e64 v134, v170, v173, s[38:39]
	v_cndmask_b32_e64 v135, v171, v174, s[38:39]
	v_lshl_add_u64 v[138:139], s[20:21], 0, v[136:137]
	global_store_dwordx4 v[138:139], v[132:135], off nt
	v_lshlrev_b64 v[138:139], 1, v[150:151]
	s_nop 0
	v_cndmask_b32_e64 v132, v169, v114, s[38:39]
	v_cndmask_b32_e64 v133, v172, v166, s[38:39]
	v_cndmask_b32_e64 v134, v173, v167, s[38:39]
	v_cndmask_b32_e64 v135, v174, v168, s[38:39]
	v_lshl_add_u64 v[166:167], s[20:21], 0, v[138:139]
	global_store_dwordx4 v[166:167], v[132:135], off nt
	v_add_u32_e32 v114, 16, v191
	s_nop 0
	v_lshl_add_u32 v132, v114, 3, s73
	ds_read_b64 v[132:133], v132
	s_waitcnt lgkmcnt(0)
	v_add_f32_e32 v134, v132, v133
	v_add_u32_e32 v132, s19, v114
	v_ashrrev_i32_e32 v133, 31, v132
	v_lshl_add_u64 v[132:133], v[132:133], 2, s[10:11]
	global_load_dword v114, v[132:133], off
	s_waitcnt vmcnt(0)
	v_add_f32_e32 v114, v114, v134
	v_fmamk_f32 v114, v114, 0x3baaaaab, v1
	v_cmp_gt_f32_e32 vcc, s70, v114
	v_mul_f32_e32 v132, 0x4f800000, v114
	s_nop 0
	v_cndmask_b32_e32 v114, v114, v132, vcc
	v_sqrt_f32_e32 v132, v114
	s_nop 0
	v_add_u32_e32 v133, -1, v132
	v_fma_f32 v134, -v133, v132, v114
	v_cmp_ge_f32_e64 s[42:43], 0, v134
	v_add_u32_e32 v134, 1, v132
	s_nop 0
	v_cndmask_b32_e64 v133, v132, v133, s[42:43]
	v_fma_f32 v132, -v134, v132, v114
	v_cmp_lt_f32_e64 s[42:43], 0, v132
	s_nop 1
	v_cndmask_b32_e64 v132, v133, v134, s[42:43]
	v_mul_f32_e32 v133, 0x37800000, v132
	v_cndmask_b32_e32 v132, v132, v133, vcc
	v_cmp_class_f32_e32 vcc, v114, v226
	s_nop 1
	v_cndmask_b32_e32 v114, v132, v114, vcc
	v_div_scale_f32 v132, s[22:23], v114, v114, 1.0
	v_rcp_f32_e32 v133, v132
	s_add_u32 s22, s20, 0x14000
	s_addc_u32 s23, s21, 0
	v_fma_f32 v134, -v132, v133, 1.0
	v_fmac_f32_e32 v133, v134, v133
	v_div_scale_f32 v134, vcc, 1.0, v114, 1.0
	v_mul_f32_e32 v135, v134, v133
	v_fma_f32 v160, -v132, v135, v134
	v_fmac_f32_e32 v135, v160, v133
	v_fma_f32 v132, -v132, v135, v134
	v_div_fmas_f32 v132, v132, v133, v135
	v_div_fixup_f32 v114, v132, v114, 1.0
	global_load_dwordx4 v[132:135], v[156:157], off offset:16
	global_load_dwordx4 v[166:169], v[156:157], off
	v_pk_mul_f32 v[170:171], v[110:111], v[114:115] op_sel_hi:[1,0]
	v_pk_mul_f32 v[172:173], v[112:113], v[114:115] op_sel_hi:[1,0]
	s_waitcnt vmcnt(0)
	v_pk_mul_f32 v[166:167], v[166:167], v[170:171]
	v_pk_mul_f32 v[168:169], v[168:169], v[172:173]
	v_pk_mul_f32 v[170:171], v[106:107], v[114:115] op_sel_hi:[1,0]
	v_pk_mul_f32 v[172:173], v[108:109], v[114:115] op_sel_hi:[1,0]
	v_pk_mul_f32 v[132:133], v[132:133], v[170:171]
	v_pk_mul_f32 v[134:135], v[134:135], v[172:173]
	v_cvt_pk_bf16_f32 v160, v166, v167
	v_cvt_pk_bf16_f32 v161, v168, v169
	v_cvt_pk_bf16_f32 v174, v132, v133
	v_pk_mul_f32 v[170:171], v[102:103], v[114:115] op_sel_hi:[1,0]
	v_cvt_pk_bf16_f32 v175, v134, v135
	global_load_dwordx4 v[132:135], v[156:157], off offset:144
	global_load_dwordx4 v[166:169], v[156:157], off offset:128
	v_pk_mul_f32 v[172:173], v[104:105], v[114:115] op_sel_hi:[1,0]
	s_waitcnt vmcnt(0)
	v_pk_mul_f32 v[166:167], v[166:167], v[170:171]
	v_pk_mul_f32 v[168:169], v[168:169], v[172:173]
	v_pk_mul_f32 v[170:171], v[98:99], v[114:115] op_sel_hi:[1,0]
	v_pk_mul_f32 v[172:173], v[100:101], v[114:115] op_sel_hi:[1,0]
	v_pk_mul_f32 v[132:133], v[132:133], v[170:171]
	v_pk_mul_f32 v[134:135], v[134:135], v[172:173]
	v_cvt_pk_bf16_f32 v114, v166, v167
	v_cvt_pk_bf16_f32 v168, v168, v169
	v_cvt_pk_bf16_f32 v169, v132, v133
	v_mov_b32_e32 v171, v115
	v_cvt_pk_bf16_f32 v170, v134, v135
	v_cndmask_b32_e64 v133, v169, v174, s[38:39]
	v_cndmask_b32_e64 v132, v170, v175, s[38:39]
	v_cndmask_b32_e64 v134, v168, v161, s[38:39]
	v_cndmask_b32_e64 v135, v114, v160, s[38:39]
	v_mov_b32_e32 v172, v115
	v_mov_b32_e32 v173, v115
	v_mov_b32_dpp v171, v135 quad_perm:[1,0,3,2] row_mask:0xf bank_mask:0xf
	v_mov_b32_dpp v172, v134 quad_perm:[1,0,3,2] row_mask:0xf bank_mask:0xf
	v_mov_b32_dpp v173, v133 quad_perm:[1,0,3,2] row_mask:0xf bank_mask:0xf
	v_mov_b32_dpp v176, v132 quad_perm:[1,0,3,2] row_mask:0xf bank_mask:0xf
	v_cndmask_b32_e64 v132, v160, v171, s[38:39]
	v_cndmask_b32_e64 v133, v161, v172, s[38:39]
	v_cndmask_b32_e64 v134, v174, v173, s[38:39]
	v_cndmask_b32_e64 v135, v175, v176, s[38:39]
	v_lshl_add_u64 v[166:167], s[22:23], 0, v[136:137]
	global_store_dwordx4 v[166:167], v[132:135], off nt
	v_lshl_add_u64 v[166:167], s[22:23], 0, v[138:139]
	s_nop 0
	v_cndmask_b32_e64 v132, v171, v114, s[38:39]
	v_cndmask_b32_e64 v133, v172, v168, s[38:39]
	v_cndmask_b32_e64 v134, v173, v169, s[38:39]
	v_cndmask_b32_e64 v135, v176, v170, s[38:39]
	global_store_dwordx4 v[166:167], v[132:135], off nt
	v_add_u32_e32 v114, 32, v191
	v_mov_b32_e32 v176, v115
	v_lshl_add_u32 v132, v114, 3, s73
	ds_read_b64 v[132:133], v132
	s_waitcnt lgkmcnt(0)
	v_add_f32_e32 v134, v132, v133
	v_add_u32_e32 v132, s19, v114
	v_ashrrev_i32_e32 v133, 31, v132
	v_lshl_add_u64 v[132:133], v[132:133], 2, s[10:11]
	global_load_dword v114, v[132:133], off
	s_waitcnt vmcnt(0)
	v_add_f32_e32 v114, v114, v134
	v_fmamk_f32 v114, v114, 0x3baaaaab, v1
	v_cmp_gt_f32_e32 vcc, s70, v114
	v_mul_f32_e32 v132, 0x4f800000, v114
	s_nop 0
	v_cndmask_b32_e32 v114, v114, v132, vcc
	v_sqrt_f32_e32 v132, v114
	s_nop 0
	v_add_u32_e32 v133, -1, v132
	v_fma_f32 v134, -v133, v132, v114
	v_cmp_ge_f32_e64 s[42:43], 0, v134
	v_add_u32_e32 v134, 1, v132
	s_nop 0
	v_cndmask_b32_e64 v133, v132, v133, s[42:43]
	v_fma_f32 v132, -v134, v132, v114
	v_cmp_lt_f32_e64 s[42:43], 0, v132
	s_nop 1
	v_cndmask_b32_e64 v132, v133, v134, s[42:43]
	v_mul_f32_e32 v133, 0x37800000, v132
	v_cndmask_b32_e32 v132, v132, v133, vcc
	v_cmp_class_f32_e32 vcc, v114, v226
	s_nop 1
	v_cndmask_b32_e32 v114, v132, v114, vcc
	v_div_scale_f32 v132, s[22:23], v114, v114, 1.0
	v_rcp_f32_e32 v133, v132
	s_add_u32 s22, s20, 0x28000
	s_addc_u32 s23, s21, 0
	v_fma_f32 v134, -v132, v133, 1.0
	v_fmac_f32_e32 v133, v134, v133
	v_div_scale_f32 v134, vcc, 1.0, v114, 1.0
	v_mul_f32_e32 v135, v134, v133
	v_fma_f32 v160, -v132, v135, v134
	v_fmac_f32_e32 v135, v160, v133
	v_fma_f32 v132, -v132, v135, v134
	v_div_fmas_f32 v132, v132, v133, v135
	v_div_fixup_f32 v114, v132, v114, 1.0
	global_load_dwordx4 v[132:135], v[156:157], off offset:16
	global_load_dwordx4 v[166:169], v[156:157], off
	v_pk_mul_f32 v[170:171], v[94:95], v[114:115] op_sel_hi:[1,0]
	v_pk_mul_f32 v[172:173], v[96:97], v[114:115] op_sel_hi:[1,0]
	s_waitcnt vmcnt(0)
	v_pk_mul_f32 v[166:167], v[166:167], v[170:171]
	v_pk_mul_f32 v[168:169], v[168:169], v[172:173]
	v_pk_mul_f32 v[170:171], v[90:91], v[114:115] op_sel_hi:[1,0]
	v_pk_mul_f32 v[172:173], v[92:93], v[114:115] op_sel_hi:[1,0]
	v_pk_mul_f32 v[132:133], v[132:133], v[170:171]
	v_pk_mul_f32 v[134:135], v[134:135], v[172:173]
	v_cvt_pk_bf16_f32 v160, v166, v167
	v_cvt_pk_bf16_f32 v161, v168, v169
	v_cvt_pk_bf16_f32 v174, v132, v133
	v_pk_mul_f32 v[170:171], v[86:87], v[114:115] op_sel_hi:[1,0]
	v_cvt_pk_bf16_f32 v175, v134, v135
	global_load_dwordx4 v[132:135], v[156:157], off offset:144
	global_load_dwordx4 v[166:169], v[156:157], off offset:128
	v_pk_mul_f32 v[172:173], v[88:89], v[114:115] op_sel_hi:[1,0]
	s_waitcnt vmcnt(0)
	v_pk_mul_f32 v[166:167], v[166:167], v[170:171]
	v_pk_mul_f32 v[168:169], v[168:169], v[172:173]
	v_pk_mul_f32 v[170:171], v[82:83], v[114:115] op_sel_hi:[1,0]
	v_pk_mul_f32 v[172:173], v[84:85], v[114:115] op_sel_hi:[1,0]
	v_pk_mul_f32 v[132:133], v[132:133], v[170:171]
	v_pk_mul_f32 v[134:135], v[134:135], v[172:173]
	v_cvt_pk_bf16_f32 v114, v166, v167
	v_cvt_pk_bf16_f32 v168, v168, v169
	v_cvt_pk_bf16_f32 v169, v132, v133
	v_mov_b32_e32 v171, v115
	v_cvt_pk_bf16_f32 v170, v134, v135
	v_cndmask_b32_e64 v133, v169, v174, s[38:39]
	v_cndmask_b32_e64 v132, v170, v175, s[38:39]
	v_cndmask_b32_e64 v134, v168, v161, s[38:39]
	v_cndmask_b32_e64 v135, v114, v160, s[38:39]
	v_mov_b32_e32 v172, v115
	v_mov_b32_e32 v173, v115
	v_mov_b32_dpp v171, v135 quad_perm:[1,0,3,2] row_mask:0xf bank_mask:0xf
	v_mov_b32_dpp v172, v134 quad_perm:[1,0,3,2] row_mask:0xf bank_mask:0xf
	v_mov_b32_dpp v173, v133 quad_perm:[1,0,3,2] row_mask:0xf bank_mask:0xf
	v_mov_b32_dpp v176, v132 quad_perm:[1,0,3,2] row_mask:0xf bank_mask:0xf
	v_cndmask_b32_e64 v132, v160, v171, s[38:39]
	v_cndmask_b32_e64 v133, v161, v172, s[38:39]
	v_cndmask_b32_e64 v134, v174, v173, s[38:39]
	v_cndmask_b32_e64 v135, v175, v176, s[38:39]
	v_lshl_add_u64 v[166:167], s[22:23], 0, v[136:137]
	global_store_dwordx4 v[166:167], v[132:135], off nt
	v_lshl_add_u64 v[166:167], s[22:23], 0, v[138:139]
	s_nop 0
	v_cndmask_b32_e64 v132, v171, v114, s[38:39]
	v_cndmask_b32_e64 v133, v172, v168, s[38:39]
	v_cndmask_b32_e64 v134, v173, v169, s[38:39]
	v_cndmask_b32_e64 v135, v176, v170, s[38:39]
	global_store_dwordx4 v[166:167], v[132:135], off nt
	v_add_u32_e32 v114, 48, v191
	v_mov_b32_e32 v176, v115
	v_lshl_add_u32 v132, v114, 3, s73
	ds_read_b64 v[132:133], v132
	s_waitcnt lgkmcnt(0)
	v_add_f32_e32 v134, v132, v133
	v_add_u32_e32 v132, s19, v114
	v_ashrrev_i32_e32 v133, 31, v132
	v_lshl_add_u64 v[132:133], v[132:133], 2, s[10:11]
	global_load_dword v114, v[132:133], off
	s_waitcnt vmcnt(0)
	v_add_f32_e32 v114, v114, v134
	v_fmamk_f32 v114, v114, 0x3baaaaab, v1
	v_cmp_gt_f32_e32 vcc, s70, v114
	v_mul_f32_e32 v132, 0x4f800000, v114
	s_nop 0
	v_cndmask_b32_e32 v114, v114, v132, vcc
	v_sqrt_f32_e32 v132, v114
	s_nop 0
	v_add_u32_e32 v133, -1, v132
	v_fma_f32 v134, -v133, v132, v114
	v_cmp_ge_f32_e64 s[42:43], 0, v134
	v_add_u32_e32 v134, 1, v132
	s_nop 0
	v_cndmask_b32_e64 v133, v132, v133, s[42:43]
	v_fma_f32 v132, -v134, v132, v114
	v_cmp_lt_f32_e64 s[42:43], 0, v132
	s_nop 1
	v_cndmask_b32_e64 v132, v133, v134, s[42:43]
	v_mul_f32_e32 v133, 0x37800000, v132
	v_cndmask_b32_e32 v132, v132, v133, vcc
	v_cmp_class_f32_e32 vcc, v114, v226
	s_nop 1
	v_cndmask_b32_e32 v114, v132, v114, vcc
	v_div_scale_f32 v132, s[22:23], v114, v114, 1.0
	v_rcp_f32_e32 v133, v132
	s_add_u32 s22, s20, 0x3c000
	s_addc_u32 s23, s21, 0
	v_fma_f32 v134, -v132, v133, 1.0
	v_fmac_f32_e32 v133, v134, v133
	v_div_scale_f32 v134, vcc, 1.0, v114, 1.0
	v_mul_f32_e32 v135, v134, v133
	v_fma_f32 v160, -v132, v135, v134
	v_fmac_f32_e32 v135, v160, v133
	v_fma_f32 v132, -v132, v135, v134
	v_div_fmas_f32 v132, v132, v133, v135
	v_div_fixup_f32 v114, v132, v114, 1.0
	global_load_dwordx4 v[132:135], v[156:157], off offset:16
	global_load_dwordx4 v[166:169], v[156:157], off
	v_pk_mul_f32 v[170:171], v[78:79], v[114:115] op_sel_hi:[1,0]
	v_pk_mul_f32 v[172:173], v[80:81], v[114:115] op_sel_hi:[1,0]
	s_waitcnt vmcnt(0)
	v_pk_mul_f32 v[166:167], v[166:167], v[170:171]
	v_pk_mul_f32 v[168:169], v[168:169], v[172:173]
	v_pk_mul_f32 v[170:171], v[74:75], v[114:115] op_sel_hi:[1,0]
	v_pk_mul_f32 v[172:173], v[76:77], v[114:115] op_sel_hi:[1,0]
	v_pk_mul_f32 v[132:133], v[132:133], v[170:171]
	v_pk_mul_f32 v[134:135], v[134:135], v[172:173]
	v_cvt_pk_bf16_f32 v160, v166, v167
	v_cvt_pk_bf16_f32 v161, v168, v169
	v_cvt_pk_bf16_f32 v174, v132, v133
	v_pk_mul_f32 v[170:171], v[70:71], v[114:115] op_sel_hi:[1,0]
	v_cvt_pk_bf16_f32 v175, v134, v135
	global_load_dwordx4 v[132:135], v[156:157], off offset:144
	global_load_dwordx4 v[166:169], v[156:157], off offset:128
	v_pk_mul_f32 v[172:173], v[72:73], v[114:115] op_sel_hi:[1,0]
	s_waitcnt vmcnt(0)
	v_pk_mul_f32 v[166:167], v[166:167], v[170:171]
	v_pk_mul_f32 v[168:169], v[168:169], v[172:173]
	v_pk_mul_f32 v[170:171], v[66:67], v[114:115] op_sel_hi:[1,0]
	v_pk_mul_f32 v[172:173], v[68:69], v[114:115] op_sel_hi:[1,0]
	v_pk_mul_f32 v[132:133], v[132:133], v[170:171]
	v_pk_mul_f32 v[134:135], v[134:135], v[172:173]
	v_cvt_pk_bf16_f32 v114, v166, v167
	v_cvt_pk_bf16_f32 v168, v168, v169
	v_cvt_pk_bf16_f32 v169, v132, v133
	v_mov_b32_e32 v171, v115
	v_cvt_pk_bf16_f32 v170, v134, v135
	v_cndmask_b32_e64 v133, v169, v174, s[38:39]
	v_cndmask_b32_e64 v132, v170, v175, s[38:39]
	v_cndmask_b32_e64 v134, v168, v161, s[38:39]
	v_cndmask_b32_e64 v135, v114, v160, s[38:39]
	v_mov_b32_e32 v172, v115
	v_mov_b32_e32 v173, v115
	v_mov_b32_dpp v171, v135 quad_perm:[1,0,3,2] row_mask:0xf bank_mask:0xf
	v_mov_b32_dpp v172, v134 quad_perm:[1,0,3,2] row_mask:0xf bank_mask:0xf
	v_mov_b32_dpp v173, v133 quad_perm:[1,0,3,2] row_mask:0xf bank_mask:0xf
	v_mov_b32_dpp v176, v132 quad_perm:[1,0,3,2] row_mask:0xf bank_mask:0xf
	v_cndmask_b32_e64 v132, v160, v171, s[38:39]
	v_cndmask_b32_e64 v133, v161, v172, s[38:39]
	v_cndmask_b32_e64 v134, v174, v173, s[38:39]
	v_cndmask_b32_e64 v135, v175, v176, s[38:39]
	v_lshl_add_u64 v[166:167], s[22:23], 0, v[136:137]
	global_store_dwordx4 v[166:167], v[132:135], off nt
	v_lshl_add_u64 v[166:167], s[22:23], 0, v[138:139]
	s_nop 0
	v_cndmask_b32_e64 v132, v171, v114, s[38:39]
	v_cndmask_b32_e64 v133, v172, v168, s[38:39]
	v_cndmask_b32_e64 v134, v173, v169, s[38:39]
	v_cndmask_b32_e64 v135, v176, v170, s[38:39]
	global_store_dwordx4 v[166:167], v[132:135], off nt
	v_add_u32_e32 v114, 0x80, v191
	v_mov_b32_e32 v176, v115
	v_lshl_add_u32 v132, v114, 3, s73
	ds_read_b64 v[132:133], v132
	s_waitcnt lgkmcnt(0)
	v_add_f32_e32 v134, v132, v133
	v_add_u32_e32 v132, s19, v114
	v_ashrrev_i32_e32 v133, 31, v132
	v_lshl_add_u64 v[132:133], v[132:133], 2, s[10:11]
	global_load_dword v114, v[132:133], off
	s_waitcnt vmcnt(0)
	v_add_f32_e32 v114, v114, v134
	v_fmamk_f32 v114, v114, 0x3baaaaab, v1
	v_cmp_gt_f32_e32 vcc, s70, v114
	v_mul_f32_e32 v132, 0x4f800000, v114
	s_nop 0
	v_cndmask_b32_e32 v114, v114, v132, vcc
	v_sqrt_f32_e32 v132, v114
	s_nop 0
	v_add_u32_e32 v133, -1, v132
	v_fma_f32 v134, -v133, v132, v114
	v_cmp_ge_f32_e64 s[42:43], 0, v134
	v_add_u32_e32 v134, 1, v132
	s_nop 0
	v_cndmask_b32_e64 v133, v132, v133, s[42:43]
	v_fma_f32 v132, -v134, v132, v114
	v_cmp_lt_f32_e64 s[42:43], 0, v132
	s_nop 1
	v_cndmask_b32_e64 v132, v133, v134, s[42:43]
	v_mul_f32_e32 v133, 0x37800000, v132
	v_cndmask_b32_e32 v132, v132, v133, vcc
	v_cmp_class_f32_e32 vcc, v114, v226
	s_nop 1
	v_cndmask_b32_e32 v114, v132, v114, vcc
	v_div_scale_f32 v132, s[22:23], v114, v114, 1.0
	v_rcp_f32_e32 v133, v132
	s_add_u32 s22, s20, 0xa0000
	s_addc_u32 s23, s21, 0
	v_fma_f32 v134, -v132, v133, 1.0
	v_fmac_f32_e32 v133, v134, v133
	v_div_scale_f32 v134, vcc, 1.0, v114, 1.0
	v_mul_f32_e32 v135, v134, v133
	v_fma_f32 v160, -v132, v135, v134
	v_fmac_f32_e32 v135, v160, v133
	v_fma_f32 v132, -v132, v135, v134
	v_div_fmas_f32 v132, v132, v133, v135
	v_div_fixup_f32 v114, v132, v114, 1.0
	global_load_dwordx4 v[132:135], v[156:157], off offset:16
	global_load_dwordx4 v[166:169], v[156:157], off
	v_pk_mul_f32 v[170:171], v[62:63], v[114:115] op_sel_hi:[1,0]
	v_pk_mul_f32 v[172:173], v[64:65], v[114:115] op_sel_hi:[1,0]
	s_waitcnt vmcnt(0)
	v_pk_mul_f32 v[166:167], v[166:167], v[170:171]
	v_pk_mul_f32 v[168:169], v[168:169], v[172:173]
	v_pk_mul_f32 v[170:171], v[58:59], v[114:115] op_sel_hi:[1,0]
	v_pk_mul_f32 v[172:173], v[60:61], v[114:115] op_sel_hi:[1,0]
	v_pk_mul_f32 v[132:133], v[132:133], v[170:171]
	v_pk_mul_f32 v[134:135], v[134:135], v[172:173]
	v_cvt_pk_bf16_f32 v160, v166, v167
	v_cvt_pk_bf16_f32 v161, v168, v169
	v_cvt_pk_bf16_f32 v174, v132, v133
	v_pk_mul_f32 v[170:171], v[54:55], v[114:115] op_sel_hi:[1,0]
	v_cvt_pk_bf16_f32 v175, v134, v135
	global_load_dwordx4 v[132:135], v[156:157], off offset:144
	global_load_dwordx4 v[166:169], v[156:157], off offset:128
	v_pk_mul_f32 v[172:173], v[56:57], v[114:115] op_sel_hi:[1,0]
	s_waitcnt vmcnt(0)
	v_pk_mul_f32 v[166:167], v[166:167], v[170:171]
	v_pk_mul_f32 v[168:169], v[168:169], v[172:173]
	v_pk_mul_f32 v[170:171], v[50:51], v[114:115] op_sel_hi:[1,0]
	v_pk_mul_f32 v[172:173], v[52:53], v[114:115] op_sel_hi:[1,0]
	v_pk_mul_f32 v[132:133], v[132:133], v[170:171]
	v_pk_mul_f32 v[134:135], v[134:135], v[172:173]
	v_cvt_pk_bf16_f32 v114, v166, v167
	v_cvt_pk_bf16_f32 v168, v168, v169
	v_cvt_pk_bf16_f32 v169, v132, v133
	v_mov_b32_e32 v171, v115
	v_cvt_pk_bf16_f32 v170, v134, v135
	v_cndmask_b32_e64 v133, v169, v174, s[38:39]
	v_cndmask_b32_e64 v132, v170, v175, s[38:39]
	v_cndmask_b32_e64 v134, v168, v161, s[38:39]
	v_cndmask_b32_e64 v135, v114, v160, s[38:39]
	v_mov_b32_e32 v172, v115
	v_mov_b32_e32 v173, v115
	v_mov_b32_dpp v171, v135 quad_perm:[1,0,3,2] row_mask:0xf bank_mask:0xf
	v_mov_b32_dpp v172, v134 quad_perm:[1,0,3,2] row_mask:0xf bank_mask:0xf
	v_mov_b32_dpp v173, v133 quad_perm:[1,0,3,2] row_mask:0xf bank_mask:0xf
	v_mov_b32_dpp v176, v132 quad_perm:[1,0,3,2] row_mask:0xf bank_mask:0xf
	v_cndmask_b32_e64 v132, v160, v171, s[38:39]
	v_cndmask_b32_e64 v133, v161, v172, s[38:39]
	v_cndmask_b32_e64 v134, v174, v173, s[38:39]
	v_cndmask_b32_e64 v135, v175, v176, s[38:39]
	v_lshl_add_u64 v[166:167], s[22:23], 0, v[136:137]
	global_store_dwordx4 v[166:167], v[132:135], off nt
	v_lshl_add_u64 v[166:167], s[22:23], 0, v[138:139]
	s_nop 0
	v_cndmask_b32_e64 v132, v171, v114, s[38:39]
	v_cndmask_b32_e64 v133, v172, v168, s[38:39]
	v_cndmask_b32_e64 v134, v173, v169, s[38:39]
	v_cndmask_b32_e64 v135, v176, v170, s[38:39]
	global_store_dwordx4 v[166:167], v[132:135], off nt
	v_add_u32_e32 v114, 0x90, v191
	v_mov_b32_e32 v176, v115
	v_lshl_add_u32 v132, v114, 3, s73
	ds_read_b64 v[132:133], v132
	s_waitcnt lgkmcnt(0)
	v_add_f32_e32 v134, v132, v133
	v_add_u32_e32 v132, s19, v114
	v_ashrrev_i32_e32 v133, 31, v132
	v_lshl_add_u64 v[132:133], v[132:133], 2, s[10:11]
	global_load_dword v114, v[132:133], off
	s_waitcnt vmcnt(0)
	v_add_f32_e32 v114, v114, v134
	v_fmamk_f32 v114, v114, 0x3baaaaab, v1
	v_cmp_gt_f32_e32 vcc, s70, v114
	v_mul_f32_e32 v132, 0x4f800000, v114
	s_nop 0
	v_cndmask_b32_e32 v114, v114, v132, vcc
	v_sqrt_f32_e32 v132, v114
	s_nop 0
	v_add_u32_e32 v133, -1, v132
	v_fma_f32 v134, -v133, v132, v114
	v_cmp_ge_f32_e64 s[42:43], 0, v134
	v_add_u32_e32 v134, 1, v132
	s_nop 0
	v_cndmask_b32_e64 v133, v132, v133, s[42:43]
	v_fma_f32 v132, -v134, v132, v114
	v_cmp_lt_f32_e64 s[42:43], 0, v132
	s_nop 1
	v_cndmask_b32_e64 v132, v133, v134, s[42:43]
	v_mul_f32_e32 v133, 0x37800000, v132
	v_cndmask_b32_e32 v132, v132, v133, vcc
	v_cmp_class_f32_e32 vcc, v114, v226
	s_nop 1
	v_cndmask_b32_e32 v114, v132, v114, vcc
	v_div_scale_f32 v132, s[22:23], v114, v114, 1.0
	v_rcp_f32_e32 v133, v132
	s_add_u32 s22, s20, 0xb4000
	s_addc_u32 s23, s21, 0
	v_fma_f32 v134, -v132, v133, 1.0
	v_fmac_f32_e32 v133, v134, v133
	v_div_scale_f32 v134, vcc, 1.0, v114, 1.0
	v_mul_f32_e32 v135, v134, v133
	v_fma_f32 v160, -v132, v135, v134
	v_fmac_f32_e32 v135, v160, v133
	v_fma_f32 v132, -v132, v135, v134
	v_div_fmas_f32 v132, v132, v133, v135
	v_div_fixup_f32 v114, v132, v114, 1.0
	global_load_dwordx4 v[132:135], v[156:157], off offset:16
	global_load_dwordx4 v[166:169], v[156:157], off
	v_pk_mul_f32 v[170:171], v[46:47], v[114:115] op_sel_hi:[1,0]
	v_pk_mul_f32 v[172:173], v[48:49], v[114:115] op_sel_hi:[1,0]
	s_waitcnt vmcnt(0)
	v_pk_mul_f32 v[166:167], v[166:167], v[170:171]
	v_pk_mul_f32 v[168:169], v[168:169], v[172:173]
	v_pk_mul_f32 v[170:171], v[42:43], v[114:115] op_sel_hi:[1,0]
	v_pk_mul_f32 v[172:173], v[44:45], v[114:115] op_sel_hi:[1,0]
	v_pk_mul_f32 v[132:133], v[132:133], v[170:171]
	v_pk_mul_f32 v[134:135], v[134:135], v[172:173]
	v_cvt_pk_bf16_f32 v160, v166, v167
	v_cvt_pk_bf16_f32 v161, v168, v169
	v_cvt_pk_bf16_f32 v174, v132, v133
	v_pk_mul_f32 v[170:171], v[38:39], v[114:115] op_sel_hi:[1,0]
	v_cvt_pk_bf16_f32 v175, v134, v135
	global_load_dwordx4 v[132:135], v[156:157], off offset:144
	global_load_dwordx4 v[166:169], v[156:157], off offset:128
	v_pk_mul_f32 v[172:173], v[40:41], v[114:115] op_sel_hi:[1,0]
	s_waitcnt vmcnt(0)
	v_pk_mul_f32 v[166:167], v[166:167], v[170:171]
	v_pk_mul_f32 v[168:169], v[168:169], v[172:173]
	v_pk_mul_f32 v[170:171], v[34:35], v[114:115] op_sel_hi:[1,0]
	v_pk_mul_f32 v[172:173], v[36:37], v[114:115] op_sel_hi:[1,0]
	v_pk_mul_f32 v[132:133], v[132:133], v[170:171]
	v_pk_mul_f32 v[134:135], v[134:135], v[172:173]
	v_cvt_pk_bf16_f32 v114, v166, v167
	v_cvt_pk_bf16_f32 v168, v168, v169
	v_cvt_pk_bf16_f32 v169, v132, v133
	v_mov_b32_e32 v171, v115
	v_cvt_pk_bf16_f32 v170, v134, v135
	v_cndmask_b32_e64 v133, v169, v174, s[38:39]
	v_cndmask_b32_e64 v132, v170, v175, s[38:39]
	v_cndmask_b32_e64 v134, v168, v161, s[38:39]
	v_cndmask_b32_e64 v135, v114, v160, s[38:39]
	v_mov_b32_e32 v172, v115
	v_mov_b32_e32 v173, v115
	v_mov_b32_dpp v171, v135 quad_perm:[1,0,3,2] row_mask:0xf bank_mask:0xf
	v_mov_b32_dpp v172, v134 quad_perm:[1,0,3,2] row_mask:0xf bank_mask:0xf
	v_mov_b32_dpp v173, v133 quad_perm:[1,0,3,2] row_mask:0xf bank_mask:0xf
	v_mov_b32_dpp v176, v132 quad_perm:[1,0,3,2] row_mask:0xf bank_mask:0xf
	v_cndmask_b32_e64 v132, v160, v171, s[38:39]
	v_cndmask_b32_e64 v133, v161, v172, s[38:39]
	v_cndmask_b32_e64 v134, v174, v173, s[38:39]
	v_cndmask_b32_e64 v135, v175, v176, s[38:39]
	v_lshl_add_u64 v[166:167], s[22:23], 0, v[136:137]
	global_store_dwordx4 v[166:167], v[132:135], off nt
	v_lshl_add_u64 v[166:167], s[22:23], 0, v[138:139]
	s_nop 0
	v_cndmask_b32_e64 v132, v171, v114, s[38:39]
	v_cndmask_b32_e64 v133, v172, v168, s[38:39]
	v_cndmask_b32_e64 v134, v173, v169, s[38:39]
	v_cndmask_b32_e64 v135, v176, v170, s[38:39]
	global_store_dwordx4 v[166:167], v[132:135], off nt
	v_add_u32_e32 v114, 0xa0, v191
	v_mov_b32_e32 v176, v115
	v_lshl_add_u32 v132, v114, 3, s73
	ds_read_b64 v[132:133], v132
	s_waitcnt lgkmcnt(0)
	v_add_f32_e32 v134, v132, v133
	v_add_u32_e32 v132, s19, v114
	v_ashrrev_i32_e32 v133, 31, v132
	v_lshl_add_u64 v[132:133], v[132:133], 2, s[10:11]
	global_load_dword v114, v[132:133], off
	s_waitcnt vmcnt(0)
	v_add_f32_e32 v114, v114, v134
	v_fmamk_f32 v114, v114, 0x3baaaaab, v1
	v_cmp_gt_f32_e32 vcc, s70, v114
	v_mul_f32_e32 v132, 0x4f800000, v114
	s_nop 0
	v_cndmask_b32_e32 v114, v114, v132, vcc
	v_sqrt_f32_e32 v132, v114
	s_nop 0
	v_add_u32_e32 v133, -1, v132
	v_fma_f32 v134, -v133, v132, v114
	v_cmp_ge_f32_e64 s[42:43], 0, v134
	v_add_u32_e32 v134, 1, v132
	s_nop 0
	v_cndmask_b32_e64 v133, v132, v133, s[42:43]
	v_fma_f32 v132, -v134, v132, v114
	v_cmp_lt_f32_e64 s[42:43], 0, v132
	s_nop 1
	v_cndmask_b32_e64 v132, v133, v134, s[42:43]
	v_mul_f32_e32 v133, 0x37800000, v132
	v_cndmask_b32_e32 v132, v132, v133, vcc
	v_cmp_class_f32_e32 vcc, v114, v226
	s_nop 1
	v_cndmask_b32_e32 v114, v132, v114, vcc
	v_div_scale_f32 v132, s[22:23], v114, v114, 1.0
	v_rcp_f32_e32 v133, v132
	s_add_u32 s22, s20, 0xc8000
	s_addc_u32 s23, s21, 0
	v_fma_f32 v134, -v132, v133, 1.0
	v_fmac_f32_e32 v133, v134, v133
	v_div_scale_f32 v134, vcc, 1.0, v114, 1.0
	v_mul_f32_e32 v135, v134, v133
	v_fma_f32 v160, -v132, v135, v134
	v_fmac_f32_e32 v135, v160, v133
	v_fma_f32 v132, -v132, v135, v134
	v_div_fmas_f32 v132, v132, v133, v135
	v_div_fixup_f32 v114, v132, v114, 1.0
	global_load_dwordx4 v[132:135], v[156:157], off offset:16
	global_load_dwordx4 v[166:169], v[156:157], off
	v_pk_mul_f32 v[170:171], v[30:31], v[114:115] op_sel_hi:[1,0]
	v_pk_mul_f32 v[172:173], v[32:33], v[114:115] op_sel_hi:[1,0]
	s_waitcnt vmcnt(0)
	v_pk_mul_f32 v[166:167], v[166:167], v[170:171]
	v_pk_mul_f32 v[168:169], v[168:169], v[172:173]
	v_pk_mul_f32 v[170:171], v[26:27], v[114:115] op_sel_hi:[1,0]
	v_pk_mul_f32 v[172:173], v[28:29], v[114:115] op_sel_hi:[1,0]
	v_pk_mul_f32 v[132:133], v[132:133], v[170:171]
	v_pk_mul_f32 v[134:135], v[134:135], v[172:173]
	v_cvt_pk_bf16_f32 v160, v166, v167
	v_cvt_pk_bf16_f32 v161, v168, v169
	v_cvt_pk_bf16_f32 v174, v132, v133
	v_pk_mul_f32 v[170:171], v[22:23], v[114:115] op_sel_hi:[1,0]
	v_cvt_pk_bf16_f32 v175, v134, v135
	global_load_dwordx4 v[132:135], v[156:157], off offset:144
	global_load_dwordx4 v[166:169], v[156:157], off offset:128
	v_pk_mul_f32 v[172:173], v[24:25], v[114:115] op_sel_hi:[1,0]
	s_waitcnt vmcnt(0)
	v_pk_mul_f32 v[166:167], v[166:167], v[170:171]
	v_pk_mul_f32 v[168:169], v[168:169], v[172:173]
	v_pk_mul_f32 v[170:171], v[18:19], v[114:115] op_sel_hi:[1,0]
	v_pk_mul_f32 v[172:173], v[20:21], v[114:115] op_sel_hi:[1,0]
	v_pk_mul_f32 v[132:133], v[132:133], v[170:171]
	v_pk_mul_f32 v[134:135], v[134:135], v[172:173]
	v_cvt_pk_bf16_f32 v114, v166, v167
	v_cvt_pk_bf16_f32 v168, v168, v169
	v_cvt_pk_bf16_f32 v169, v132, v133
	v_mov_b32_e32 v171, v115
	v_cvt_pk_bf16_f32 v170, v134, v135
	v_cndmask_b32_e64 v133, v169, v174, s[38:39]
	v_cndmask_b32_e64 v132, v170, v175, s[38:39]
	v_cndmask_b32_e64 v134, v168, v161, s[38:39]
	v_cndmask_b32_e64 v135, v114, v160, s[38:39]
	v_mov_b32_e32 v172, v115
	v_mov_b32_e32 v173, v115
	v_mov_b32_dpp v171, v135 quad_perm:[1,0,3,2] row_mask:0xf bank_mask:0xf
	v_mov_b32_dpp v172, v134 quad_perm:[1,0,3,2] row_mask:0xf bank_mask:0xf
	v_mov_b32_dpp v173, v133 quad_perm:[1,0,3,2] row_mask:0xf bank_mask:0xf
	v_mov_b32_dpp v176, v132 quad_perm:[1,0,3,2] row_mask:0xf bank_mask:0xf
	v_cndmask_b32_e64 v132, v160, v171, s[38:39]
	v_cndmask_b32_e64 v133, v161, v172, s[38:39]
	v_cndmask_b32_e64 v134, v174, v173, s[38:39]
	v_cndmask_b32_e64 v135, v175, v176, s[38:39]
	v_lshl_add_u64 v[166:167], s[22:23], 0, v[136:137]
	global_store_dwordx4 v[166:167], v[132:135], off nt
	v_lshl_add_u64 v[166:167], s[22:23], 0, v[138:139]
	s_nop 0
	v_cndmask_b32_e64 v132, v171, v114, s[38:39]
	v_cndmask_b32_e64 v133, v172, v168, s[38:39]
	v_cndmask_b32_e64 v134, v173, v169, s[38:39]
	v_cndmask_b32_e64 v135, v176, v170, s[38:39]
	global_store_dwordx4 v[166:167], v[132:135], off nt
	v_add_u32_e32 v114, 0xb0, v191
	s_nop 0
	v_lshl_add_u32 v132, v114, 3, s73
	ds_read_b64 v[132:133], v132
	s_waitcnt lgkmcnt(0)
	v_add_f32_e32 v134, v132, v133
	v_add_u32_e32 v132, s19, v114
	v_ashrrev_i32_e32 v133, 31, v132
	v_lshl_add_u64 v[132:133], v[132:133], 2, s[10:11]
	global_load_dword v114, v[132:133], off
	s_waitcnt vmcnt(0)
	v_add_f32_e32 v114, v114, v134
	v_fmamk_f32 v114, v114, 0x3baaaaab, v1
	v_cmp_gt_f32_e32 vcc, s70, v114
	v_mul_f32_e32 v132, 0x4f800000, v114
	s_nop 0
	v_cndmask_b32_e32 v114, v114, v132, vcc
	v_sqrt_f32_e32 v132, v114
	s_nop 0
	v_add_u32_e32 v133, -1, v132
	v_fma_f32 v134, -v133, v132, v114
	v_cmp_ge_f32_e64 s[42:43], 0, v134
	v_add_u32_e32 v134, 1, v132
	s_nop 0
	v_cndmask_b32_e64 v133, v132, v133, s[42:43]
	v_fma_f32 v132, -v134, v132, v114
	v_cmp_lt_f32_e64 s[42:43], 0, v132
	s_nop 1
	v_cndmask_b32_e64 v132, v133, v134, s[42:43]
	v_mul_f32_e32 v133, 0x37800000, v132
	v_cndmask_b32_e32 v132, v132, v133, vcc
	v_cmp_class_f32_e32 vcc, v114, v226
	s_nop 1
	v_cndmask_b32_e32 v114, v132, v114, vcc
	v_div_scale_f32 v132, s[22:23], v114, v114, 1.0
	v_rcp_f32_e32 v133, v132
	s_add_u32 s22, s20, 0xdc000
	s_addc_u32 s23, s21, 0
	v_lshl_add_u64 v[136:137], s[22:23], 0, v[136:137]
	v_fma_f32 v134, -v132, v133, 1.0
	v_fmac_f32_e32 v133, v134, v133
	v_div_scale_f32 v134, vcc, 1.0, v114, 1.0
	v_mul_f32_e32 v135, v134, v133
	v_fma_f32 v160, -v132, v135, v134
	v_fmac_f32_e32 v135, v160, v133
	v_fma_f32 v132, -v132, v135, v134
	v_div_fmas_f32 v132, v132, v133, v135
	v_div_fixup_f32 v114, v132, v114, 1.0
	global_load_dwordx4 v[132:135], v[156:157], off offset:16
	global_load_dwordx4 v[166:169], v[156:157], off
	v_pk_mul_f32 v[170:171], v[14:15], v[114:115] op_sel_hi:[1,0]
	v_pk_mul_f32 v[172:173], v[16:17], v[114:115] op_sel_hi:[1,0]
	s_waitcnt vmcnt(0)
	v_pk_mul_f32 v[166:167], v[166:167], v[170:171]
	v_pk_mul_f32 v[168:169], v[168:169], v[172:173]
	v_pk_mul_f32 v[170:171], v[10:11], v[114:115] op_sel_hi:[1,0]
	v_pk_mul_f32 v[172:173], v[12:13], v[114:115] op_sel_hi:[1,0]
	v_pk_mul_f32 v[132:133], v[132:133], v[170:171]
	v_pk_mul_f32 v[134:135], v[134:135], v[172:173]
	v_cvt_pk_bf16_f32 v160, v166, v167
	v_cvt_pk_bf16_f32 v161, v168, v169
	v_cvt_pk_bf16_f32 v174, v132, v133
	v_pk_mul_f32 v[170:171], v[6:7], v[114:115] op_sel_hi:[1,0]
	v_cvt_pk_bf16_f32 v175, v134, v135
	global_load_dwordx4 v[132:135], v[156:157], off offset:144
	global_load_dwordx4 v[166:169], v[156:157], off offset:128
	v_pk_mul_f32 v[172:173], v[8:9], v[114:115] op_sel_hi:[1,0]
	s_waitcnt vmcnt(0)
	v_pk_mul_f32 v[166:167], v[166:167], v[170:171]
	v_pk_mul_f32 v[168:169], v[168:169], v[172:173]
	v_pk_mul_f32 v[170:171], v[2:3], v[114:115] op_sel_hi:[1,0]
	v_pk_mul_f32 v[172:173], v[4:5], v[114:115] op_sel_hi:[1,0]
	v_pk_mul_f32 v[132:133], v[132:133], v[170:171]
	v_pk_mul_f32 v[134:135], v[134:135], v[172:173]
	v_cvt_pk_bf16_f32 v114, v166, v167
	v_cvt_pk_bf16_f32 v166, v168, v169
	v_cvt_pk_bf16_f32 v167, v132, v133
	v_mov_b32_e32 v169, v115
	v_cvt_pk_bf16_f32 v168, v134, v135
	v_cndmask_b32_e64 v133, v167, v174, s[38:39]
	v_cndmask_b32_e64 v132, v168, v175, s[38:39]
	v_cndmask_b32_e64 v134, v166, v161, s[38:39]
	v_cndmask_b32_e64 v135, v114, v160, s[38:39]
	v_mov_b32_e32 v170, v115
	v_mov_b32_e32 v171, v115
	v_mov_b32_e32 v172, v115
	v_mov_b32_dpp v169, v135 quad_perm:[1,0,3,2] row_mask:0xf bank_mask:0xf
	v_mov_b32_dpp v170, v134 quad_perm:[1,0,3,2] row_mask:0xf bank_mask:0xf
	v_mov_b32_dpp v171, v133 quad_perm:[1,0,3,2] row_mask:0xf bank_mask:0xf
	v_mov_b32_dpp v172, v132 quad_perm:[1,0,3,2] row_mask:0xf bank_mask:0xf
	v_cndmask_b32_e64 v132, v160, v169, s[38:39]
	v_cndmask_b32_e64 v133, v161, v170, s[38:39]
	v_cndmask_b32_e64 v134, v174, v171, s[38:39]
	v_cndmask_b32_e64 v135, v175, v172, s[38:39]
	global_store_dwordx4 v[136:137], v[132:135], off nt
	v_lshl_add_u64 v[136:137], s[22:23], 0, v[138:139]
	s_nop 0
	v_cndmask_b32_e64 v132, v169, v114, s[38:39]
	v_cndmask_b32_e64 v133, v170, v166, s[38:39]
	v_cndmask_b32_e64 v134, v171, v167, s[38:39]
	v_cndmask_b32_e64 v135, v172, v168, s[38:39]
	global_store_dwordx4 v[136:137], v[132:135], off nt

.LBB0_595:
	s_or_b64 exec, exec, s[22:23]
	s_waitcnt lgkmcnt(0)
	s_barrier
	s_waitcnt lgkmcnt(0)
	ds_read_b128 v[132:135], v181
	s_waitcnt lgkmcnt(0)
	v_mov_b32_e32 v136, v133
	v_mov_b32_e32 v137, v134
	v_mov_b32_e32 v133, v135
	v_pk_add_f32 v[132:133], v[136:137], v[132:133]
	s_nop 0
	v_add_f32_e32 v114, v132, v133
	v_fmamk_f32 v114, v114, 0x3b800000, v1
	v_mul_f32_e32 v132, 0x4f800000, v114
	v_cmp_gt_f32_e32 vcc, s70, v114
	s_nop 1
	v_cndmask_b32_e32 v114, v114, v132, vcc
	v_sqrt_f32_e32 v132, v114
	s_nop 0
	v_add_u32_e32 v133, -1, v132
	v_fma_f32 v135, -v133, v132, v114
	v_add_u32_e32 v134, 1, v132
	v_cmp_ge_f32_e64 s[42:43], 0, v135
	s_nop 1
	v_cndmask_b32_e64 v133, v132, v133, s[42:43]
	v_fma_f32 v132, -v134, v132, v114
	v_cmp_lt_f32_e64 s[42:43], 0, v132
	s_nop 1
	v_cndmask_b32_e64 v132, v133, v134, s[42:43]
	v_mul_f32_e32 v133, 0x37800000, v132
	v_cndmask_b32_e32 v132, v132, v133, vcc
	v_cmp_class_f32_e32 vcc, v114, v226
	s_nop 1
	v_cndmask_b32_e32 v114, v132, v114, vcc
	v_div_scale_f32 v132, s[22:23], v114, v114, 1.0
	v_rcp_f32_e32 v133, v132
	s_nop 0
	v_fma_f32 v134, -v132, v133, 1.0
	v_fmac_f32_e32 v133, v134, v133
	v_div_scale_f32 v134, vcc, 1.0, v114, 1.0
	v_mul_f32_e32 v135, v134, v133
	v_fma_f32 v136, -v132, v135, v134
	v_fmac_f32_e32 v135, v136, v133
	v_fma_f32 v132, -v132, v135, v134
	v_div_fmas_f32 v132, v132, v133, v135
	v_div_fixup_f32 v114, v132, v114, 1.0
	v_pk_mul_f32 v[130:131], v[130:131], v[114:115] op_sel_hi:[1,0]
	v_pk_mul_f32 v[128:129], v[128:129], v[114:115] op_sel_hi:[1,0]
	v_pk_mul_f32 v[126:127], v[126:127], v[114:115] op_sel_hi:[1,0]
	v_pk_mul_f32 v[124:125], v[124:125], v[114:115] op_sel_hi:[1,0]
	v_pk_mul_f32 v[118:119], v[118:119], v[114:115] op_sel_hi:[1,0]
	v_pk_mul_f32 v[116:117], v[116:117], v[114:115] op_sel_hi:[1,0]
	v_cvt_pk_bf16_f32 v128, v128, v129
	v_cvt_pk_bf16_f32 v129, v130, v131
	v_cvt_pk_bf16_f32 v124, v124, v125
	v_cvt_pk_bf16_f32 v125, v126, v127
	v_pk_mul_f32 v[122:123], v[122:123], v[114:115] op_sel_hi:[1,0]
	v_pk_mul_f32 v[120:121], v[120:121], v[114:115] op_sel_hi:[1,0]
	v_mov_b32_e32 v131, v115
	v_cvt_pk_bf16_f32 v114, v120, v121
	v_cvt_pk_bf16_f32 v126, v122, v123
	v_cvt_pk_bf16_f32 v127, v116, v117
	v_cvt_pk_bf16_f32 v130, v118, v119
	v_mov_b32_e32 v132, v115
	v_cndmask_b32_e64 v116, v130, v125, s[38:39]
	v_cndmask_b32_e64 v117, v127, v124, s[38:39]
	v_cndmask_b32_e64 v118, v126, v129, s[38:39]
	v_cndmask_b32_e64 v119, v114, v128, s[38:39]
	v_mov_b32_e32 v133, v115
	v_mov_b32_e32 v134, v115
	v_mov_b32_dpp v131, v119 quad_perm:[1,0,3,2] row_mask:0xf bank_mask:0xf
	v_mov_b32_dpp v132, v118 quad_perm:[1,0,3,2] row_mask:0xf bank_mask:0xf
	v_mov_b32_dpp v133, v117 quad_perm:[1,0,3,2] row_mask:0xf bank_mask:0xf
	v_mov_b32_dpp v134, v116 quad_perm:[1,0,3,2] row_mask:0xf bank_mask:0xf
	v_lshlrev_b64 v[116:117], 1, v[148:149]
	v_cndmask_b32_e64 v118, v128, v131, s[38:39]
	v_cndmask_b32_e64 v119, v129, v132, s[38:39]
	v_cndmask_b32_e64 v120, v124, v133, s[38:39]
	v_cndmask_b32_e64 v121, v125, v134, s[38:39]
	v_lshl_add_u64 v[122:123], s[20:21], 0, v[116:117]
	global_store_dwordx4 v[122:123], v[118:121], off nt
	v_cndmask_b32_e64 v122, v133, v127, s[38:39]
	v_cndmask_b32_e64 v123, v134, v130, s[38:39]
	v_lshlrev_b64 v[118:119], 1, v[150:151]
	v_cndmask_b32_e64 v120, v131, v114, s[38:39]
	v_cndmask_b32_e64 v121, v132, v126, s[38:39]
	v_lshl_add_u64 v[124:125], s[20:21], 0, v[118:119]
	global_store_dwordx4 v[124:125], v[120:123], off nt
	ds_read_b128 v[120:123], v181 offset:256
	s_waitcnt lgkmcnt(0)
	v_mov_b32_e32 v124, v121
	v_mov_b32_e32 v125, v122
	v_mov_b32_e32 v121, v123
	v_pk_add_f32 v[120:121], v[124:125], v[120:121]
	s_nop 0
	v_add_f32_e32 v114, v120, v121
	v_fmamk_f32 v114, v114, 0x3b800000, v1
	v_mul_f32_e32 v120, 0x4f800000, v114
	v_cmp_gt_f32_e32 vcc, s70, v114
	s_nop 1
	v_cndmask_b32_e32 v114, v114, v120, vcc
	v_sqrt_f32_e32 v120, v114
	s_nop 0
	v_add_u32_e32 v121, -1, v120
	v_fma_f32 v122, -v121, v120, v114
	v_cmp_ge_f32_e64 s[42:43], 0, v122
	v_add_u32_e32 v122, 1, v120
	s_nop 0
	v_cndmask_b32_e64 v121, v120, v121, s[42:43]
	v_fma_f32 v120, -v122, v120, v114
	v_cmp_lt_f32_e64 s[42:43], 0, v120
	s_nop 1
	v_cndmask_b32_e64 v120, v121, v122, s[42:43]
	v_mul_f32_e32 v121, 0x37800000, v120
	v_cndmask_b32_e32 v120, v120, v121, vcc
	v_cmp_class_f32_e32 vcc, v114, v226
	s_nop 1
	v_cndmask_b32_e32 v114, v120, v114, vcc
	v_div_scale_f32 v120, s[22:23], v114, v114, 1.0
	v_rcp_f32_e32 v121, v120
	s_add_u32 s22, s20, 0x14000
	s_addc_u32 s23, s21, 0
	v_fma_f32 v122, -v120, v121, 1.0
	v_fmac_f32_e32 v121, v122, v121
	v_div_scale_f32 v122, vcc, 1.0, v114, 1.0
	v_mul_f32_e32 v123, v122, v121
	v_fma_f32 v124, -v120, v123, v122
	v_fmac_f32_e32 v123, v124, v121
	v_fma_f32 v120, -v120, v123, v122
	v_div_fmas_f32 v120, v120, v121, v123
	v_div_fixup_f32 v114, v120, v114, 1.0
	v_pk_mul_f32 v[112:113], v[112:113], v[114:115] op_sel_hi:[1,0]
	v_pk_mul_f32 v[110:111], v[110:111], v[114:115] op_sel_hi:[1,0]
	v_pk_mul_f32 v[108:109], v[108:109], v[114:115] op_sel_hi:[1,0]
	v_pk_mul_f32 v[106:107], v[106:107], v[114:115] op_sel_hi:[1,0]
	v_pk_mul_f32 v[104:105], v[104:105], v[114:115] op_sel_hi:[1,0]
	v_pk_mul_f32 v[100:101], v[100:101], v[114:115] op_sel_hi:[1,0]
	v_pk_mul_f32 v[98:99], v[98:99], v[114:115] op_sel_hi:[1,0]
	v_cvt_pk_bf16_f32 v110, v110, v111
	v_cvt_pk_bf16_f32 v111, v112, v113
	v_cvt_pk_bf16_f32 v106, v106, v107
	v_cvt_pk_bf16_f32 v107, v108, v109
	v_pk_mul_f32 v[102:103], v[102:103], v[114:115] op_sel_hi:[1,0]
	v_mov_b32_e32 v112, v115
	v_cvt_pk_bf16_f32 v108, v102, v103
	v_cvt_pk_bf16_f32 v104, v104, v105
	v_cvt_pk_bf16_f32 v105, v98, v99
	v_cvt_pk_bf16_f32 v109, v100, v101
	v_mov_b32_e32 v113, v115
	v_cndmask_b32_e64 v98, v109, v107, s[38:39]
	v_cndmask_b32_e64 v99, v105, v106, s[38:39]
	v_cndmask_b32_e64 v100, v104, v111, s[38:39]
	v_cndmask_b32_e64 v101, v108, v110, s[38:39]
	v_mov_b32_e32 v114, v115
	v_mov_b32_e32 v120, v115
	v_mov_b32_dpp v112, v101 quad_perm:[1,0,3,2] row_mask:0xf bank_mask:0xf
	v_mov_b32_dpp v113, v100 quad_perm:[1,0,3,2] row_mask:0xf bank_mask:0xf
	v_mov_b32_dpp v114, v99 quad_perm:[1,0,3,2] row_mask:0xf bank_mask:0xf
	v_mov_b32_dpp v120, v98 quad_perm:[1,0,3,2] row_mask:0xf bank_mask:0xf
	v_cndmask_b32_e64 v98, v110, v112, s[38:39]
	v_cndmask_b32_e64 v99, v111, v113, s[38:39]
	v_cndmask_b32_e64 v100, v106, v114, s[38:39]
	v_cndmask_b32_e64 v101, v107, v120, s[38:39]
	v_lshl_add_u64 v[102:103], s[22:23], 0, v[116:117]
	global_store_dwordx4 v[102:103], v[98:101], off nt
	v_lshl_add_u64 v[102:103], s[22:23], 0, v[118:119]
	s_nop 0
	v_cndmask_b32_e64 v98, v112, v108, s[38:39]
	v_cndmask_b32_e64 v99, v113, v104, s[38:39]
	v_cndmask_b32_e64 v100, v114, v105, s[38:39]
	v_cndmask_b32_e64 v101, v120, v109, s[38:39]
	global_store_dwordx4 v[102:103], v[98:101], off nt
	ds_read_b128 v[98:101], v181 offset:512
	s_waitcnt lgkmcnt(0)
	v_mov_b32_e32 v102, v99
	v_mov_b32_e32 v103, v100
	v_mov_b32_e32 v99, v101
	v_pk_add_f32 v[98:99], v[102:103], v[98:99]
	s_nop 0
	v_add_f32_e32 v98, v98, v99
	v_fmamk_f32 v98, v98, 0x3b800000, v1
	v_mul_f32_e32 v99, 0x4f800000, v98
	v_cmp_gt_f32_e32 vcc, s70, v98
	s_nop 1
	v_cndmask_b32_e32 v98, v98, v99, vcc
	v_sqrt_f32_e32 v99, v98
	s_nop 0
	v_add_u32_e32 v100, -1, v99
	v_fma_f32 v101, -v100, v99, v98
	v_cmp_ge_f32_e64 s[42:43], 0, v101
	v_add_u32_e32 v101, 1, v99
	s_nop 0
	v_cndmask_b32_e64 v100, v99, v100, s[42:43]
	v_fma_f32 v99, -v101, v99, v98
	v_cmp_lt_f32_e64 s[42:43], 0, v99
	s_nop 1
	v_cndmask_b32_e64 v99, v100, v101, s[42:43]
	v_mul_f32_e32 v100, 0x37800000, v99
	v_cndmask_b32_e32 v99, v99, v100, vcc
	v_cmp_class_f32_e32 vcc, v98, v226
	s_nop 1
	v_cndmask_b32_e32 v98, v99, v98, vcc
	v_div_scale_f32 v99, s[22:23], v98, v98, 1.0
	v_rcp_f32_e32 v100, v99
	s_add_u32 s22, s20, 0x28000
	s_addc_u32 s23, s21, 0
	v_fma_f32 v101, -v99, v100, 1.0
	v_fmac_f32_e32 v100, v101, v100
	v_div_scale_f32 v101, vcc, 1.0, v98, 1.0
	v_mul_f32_e32 v102, v101, v100
	v_fma_f32 v103, -v99, v102, v101
	v_fmac_f32_e32 v102, v103, v100
	v_fma_f32 v99, -v99, v102, v101
	v_div_fmas_f32 v99, v99, v100, v102
	v_div_fixup_f32 v98, v99, v98, 1.0
	v_pk_mul_f32 v[96:97], v[96:97], v[98:99] op_sel_hi:[1,0]
	v_pk_mul_f32 v[94:95], v[94:95], v[98:99] op_sel_hi:[1,0]
	v_pk_mul_f32 v[92:93], v[92:93], v[98:99] op_sel_hi:[1,0]
	v_pk_mul_f32 v[90:91], v[90:91], v[98:99] op_sel_hi:[1,0]
	v_pk_mul_f32 v[88:89], v[88:89], v[98:99] op_sel_hi:[1,0]
	v_pk_mul_f32 v[84:85], v[84:85], v[98:99] op_sel_hi:[1,0]
	v_pk_mul_f32 v[82:83], v[82:83], v[98:99] op_sel_hi:[1,0]
	v_cvt_pk_bf16_f32 v94, v94, v95
	v_cvt_pk_bf16_f32 v95, v96, v97
	v_cvt_pk_bf16_f32 v90, v90, v91
	v_cvt_pk_bf16_f32 v91, v92, v93
	v_pk_mul_f32 v[86:87], v[86:87], v[98:99] op_sel_hi:[1,0]
	v_mov_b32_e32 v96, v115
	v_cvt_pk_bf16_f32 v92, v86, v87
	v_cvt_pk_bf16_f32 v88, v88, v89
	v_cvt_pk_bf16_f32 v89, v82, v83
	v_cvt_pk_bf16_f32 v93, v84, v85
	v_mov_b32_e32 v97, v115
	v_cndmask_b32_e64 v82, v93, v91, s[38:39]
	v_cndmask_b32_e64 v83, v89, v90, s[38:39]
	v_cndmask_b32_e64 v84, v88, v95, s[38:39]
	v_cndmask_b32_e64 v85, v92, v94, s[38:39]
	v_mov_b32_e32 v98, v115
	v_mov_b32_e32 v99, v115
	v_mov_b32_dpp v96, v85 quad_perm:[1,0,3,2] row_mask:0xf bank_mask:0xf
	v_mov_b32_dpp v97, v84 quad_perm:[1,0,3,2] row_mask:0xf bank_mask:0xf
	v_mov_b32_dpp v98, v83 quad_perm:[1,0,3,2] row_mask:0xf bank_mask:0xf
	v_mov_b32_dpp v99, v82 quad_perm:[1,0,3,2] row_mask:0xf bank_mask:0xf
	v_cndmask_b32_e64 v82, v94, v96, s[38:39]
	v_cndmask_b32_e64 v83, v95, v97, s[38:39]
	v_cndmask_b32_e64 v84, v90, v98, s[38:39]
	v_cndmask_b32_e64 v85, v91, v99, s[38:39]
	v_lshl_add_u64 v[86:87], s[22:23], 0, v[116:117]
	global_store_dwordx4 v[86:87], v[82:85], off nt
	v_lshl_add_u64 v[86:87], s[22:23], 0, v[118:119]
	s_nop 0
	v_cndmask_b32_e64 v82, v96, v92, s[38:39]
	v_cndmask_b32_e64 v83, v97, v88, s[38:39]
	v_cndmask_b32_e64 v84, v98, v89, s[38:39]
	v_cndmask_b32_e64 v85, v99, v93, s[38:39]
	global_store_dwordx4 v[86:87], v[82:85], off nt
	ds_read_b128 v[82:85], v181 offset:768
	s_waitcnt lgkmcnt(0)
	v_mov_b32_e32 v86, v83
	v_mov_b32_e32 v87, v84
	v_mov_b32_e32 v83, v85
	v_pk_add_f32 v[82:83], v[86:87], v[82:83]
	s_nop 0
	v_add_f32_e32 v82, v82, v83
	v_fmamk_f32 v82, v82, 0x3b800000, v1
	v_mul_f32_e32 v83, 0x4f800000, v82
	v_cmp_gt_f32_e32 vcc, s70, v82
	s_nop 1
	v_cndmask_b32_e32 v82, v82, v83, vcc
	v_sqrt_f32_e32 v83, v82
	s_nop 0
	v_add_u32_e32 v84, -1, v83
	v_fma_f32 v85, -v84, v83, v82
	v_cmp_ge_f32_e64 s[42:43], 0, v85
	v_add_u32_e32 v85, 1, v83
	s_nop 0
	v_cndmask_b32_e64 v84, v83, v84, s[42:43]
	v_fma_f32 v83, -v85, v83, v82
	v_cmp_lt_f32_e64 s[42:43], 0, v83
	s_nop 1
	v_cndmask_b32_e64 v83, v84, v85, s[42:43]
	v_mul_f32_e32 v84, 0x37800000, v83
	v_cndmask_b32_e32 v83, v83, v84, vcc
	v_cmp_class_f32_e32 vcc, v82, v226
	s_nop 1
	v_cndmask_b32_e32 v82, v83, v82, vcc
	v_div_scale_f32 v83, s[22:23], v82, v82, 1.0
	v_rcp_f32_e32 v84, v83
	s_add_u32 s22, s20, 0x3c000
	s_addc_u32 s23, s21, 0
	v_fma_f32 v85, -v83, v84, 1.0
	v_fmac_f32_e32 v84, v85, v84
	v_div_scale_f32 v85, vcc, 1.0, v82, 1.0
	v_mul_f32_e32 v86, v85, v84
	v_fma_f32 v87, -v83, v86, v85
	v_fmac_f32_e32 v86, v87, v84
	v_fma_f32 v83, -v83, v86, v85
	v_div_fmas_f32 v83, v83, v84, v86
	v_div_fixup_f32 v82, v83, v82, 1.0
	v_pk_mul_f32 v[80:81], v[80:81], v[82:83] op_sel_hi:[1,0]
	v_pk_mul_f32 v[78:79], v[78:79], v[82:83] op_sel_hi:[1,0]
	v_pk_mul_f32 v[76:77], v[76:77], v[82:83] op_sel_hi:[1,0]
	v_pk_mul_f32 v[74:75], v[74:75], v[82:83] op_sel_hi:[1,0]
	v_pk_mul_f32 v[72:73], v[72:73], v[82:83] op_sel_hi:[1,0]
	v_pk_mul_f32 v[68:69], v[68:69], v[82:83] op_sel_hi:[1,0]
	v_pk_mul_f32 v[66:67], v[66:67], v[82:83] op_sel_hi:[1,0]
	v_cvt_pk_bf16_f32 v78, v78, v79
	v_cvt_pk_bf16_f32 v79, v80, v81
	v_cvt_pk_bf16_f32 v74, v74, v75
	v_cvt_pk_bf16_f32 v75, v76, v77
	v_pk_mul_f32 v[70:71], v[70:71], v[82:83] op_sel_hi:[1,0]
	v_mov_b32_e32 v80, v115
	v_cvt_pk_bf16_f32 v76, v70, v71
	v_cvt_pk_bf16_f32 v72, v72, v73
	v_cvt_pk_bf16_f32 v73, v66, v67
	v_cvt_pk_bf16_f32 v77, v68, v69
	v_mov_b32_e32 v81, v115
	v_cndmask_b32_e64 v66, v77, v75, s[38:39]
	v_cndmask_b32_e64 v67, v73, v74, s[38:39]
	v_cndmask_b32_e64 v68, v72, v79, s[38:39]
	v_cndmask_b32_e64 v69, v76, v78, s[38:39]
	v_mov_b32_e32 v82, v115
	v_mov_b32_e32 v83, v115
	v_mov_b32_dpp v80, v69 quad_perm:[1,0,3,2] row_mask:0xf bank_mask:0xf
	v_mov_b32_dpp v81, v68 quad_perm:[1,0,3,2] row_mask:0xf bank_mask:0xf
	v_mov_b32_dpp v82, v67 quad_perm:[1,0,3,2] row_mask:0xf bank_mask:0xf
	v_mov_b32_dpp v83, v66 quad_perm:[1,0,3,2] row_mask:0xf bank_mask:0xf
	v_cndmask_b32_e64 v66, v78, v80, s[38:39]
	v_cndmask_b32_e64 v67, v79, v81, s[38:39]
	v_cndmask_b32_e64 v68, v74, v82, s[38:39]
	v_cndmask_b32_e64 v69, v75, v83, s[38:39]
	v_lshl_add_u64 v[70:71], s[22:23], 0, v[116:117]
	global_store_dwordx4 v[70:71], v[66:69], off nt
	v_lshl_add_u64 v[70:71], s[22:23], 0, v[118:119]
	s_nop 0
	v_cndmask_b32_e64 v66, v80, v76, s[38:39]
	v_cndmask_b32_e64 v67, v81, v72, s[38:39]
	v_cndmask_b32_e64 v68, v82, v73, s[38:39]
	v_cndmask_b32_e64 v69, v83, v77, s[38:39]
	global_store_dwordx4 v[70:71], v[66:69], off nt
	ds_read_b128 v[66:69], v181 offset:2048
	s_waitcnt lgkmcnt(0)
	v_mov_b32_e32 v70, v67
	v_mov_b32_e32 v71, v68
	v_mov_b32_e32 v67, v69
	v_pk_add_f32 v[66:67], v[70:71], v[66:67]
	s_nop 0
	v_add_f32_e32 v66, v66, v67
	v_fmamk_f32 v66, v66, 0x3b800000, v1
	v_mul_f32_e32 v67, 0x4f800000, v66
	v_cmp_gt_f32_e32 vcc, s70, v66
	s_nop 1
	v_cndmask_b32_e32 v66, v66, v67, vcc
	v_sqrt_f32_e32 v67, v66
	s_nop 0
	v_add_u32_e32 v68, -1, v67
	v_fma_f32 v69, -v68, v67, v66
	v_cmp_ge_f32_e64 s[42:43], 0, v69
	v_add_u32_e32 v69, 1, v67
	s_nop 0
	v_cndmask_b32_e64 v68, v67, v68, s[42:43]
	v_fma_f32 v67, -v69, v67, v66
	v_cmp_lt_f32_e64 s[42:43], 0, v67
	s_nop 1
	v_cndmask_b32_e64 v67, v68, v69, s[42:43]
	v_mul_f32_e32 v68, 0x37800000, v67
	v_cndmask_b32_e32 v67, v67, v68, vcc
	v_cmp_class_f32_e32 vcc, v66, v226
	s_nop 1
	v_cndmask_b32_e32 v66, v67, v66, vcc
	v_div_scale_f32 v67, s[22:23], v66, v66, 1.0
	v_rcp_f32_e32 v68, v67
	s_add_u32 s22, s20, 0xa0000
	s_addc_u32 s23, s21, 0
	v_fma_f32 v69, -v67, v68, 1.0
	v_fmac_f32_e32 v68, v69, v68
	v_div_scale_f32 v69, vcc, 1.0, v66, 1.0
	v_mul_f32_e32 v70, v69, v68
	v_fma_f32 v71, -v67, v70, v69
	v_fmac_f32_e32 v70, v71, v68
	v_fma_f32 v67, -v67, v70, v69
	v_div_fmas_f32 v67, v67, v68, v70
	v_div_fixup_f32 v66, v67, v66, 1.0
	v_pk_mul_f32 v[64:65], v[64:65], v[66:67] op_sel_hi:[1,0]
	v_pk_mul_f32 v[62:63], v[62:63], v[66:67] op_sel_hi:[1,0]
	v_pk_mul_f32 v[60:61], v[60:61], v[66:67] op_sel_hi:[1,0]
	v_pk_mul_f32 v[58:59], v[58:59], v[66:67] op_sel_hi:[1,0]
	v_pk_mul_f32 v[56:57], v[56:57], v[66:67] op_sel_hi:[1,0]
	v_pk_mul_f32 v[52:53], v[52:53], v[66:67] op_sel_hi:[1,0]
	v_pk_mul_f32 v[50:51], v[50:51], v[66:67] op_sel_hi:[1,0]
	v_cvt_pk_bf16_f32 v62, v62, v63
	v_cvt_pk_bf16_f32 v63, v64, v65
	v_cvt_pk_bf16_f32 v58, v58, v59
	v_cvt_pk_bf16_f32 v59, v60, v61
	v_pk_mul_f32 v[54:55], v[54:55], v[66:67] op_sel_hi:[1,0]
	v_mov_b32_e32 v64, v115
	v_cvt_pk_bf16_f32 v60, v54, v55
	v_cvt_pk_bf16_f32 v56, v56, v57
	v_cvt_pk_bf16_f32 v57, v50, v51
	v_cvt_pk_bf16_f32 v61, v52, v53
	v_mov_b32_e32 v65, v115
	v_cndmask_b32_e64 v50, v61, v59, s[38:39]
	v_cndmask_b32_e64 v51, v57, v58, s[38:39]
	v_cndmask_b32_e64 v52, v56, v63, s[38:39]
	v_cndmask_b32_e64 v53, v60, v62, s[38:39]
	v_mov_b32_e32 v66, v115
	v_mov_b32_e32 v67, v115
	v_mov_b32_dpp v64, v53 quad_perm:[1,0,3,2] row_mask:0xf bank_mask:0xf
	v_mov_b32_dpp v65, v52 quad_perm:[1,0,3,2] row_mask:0xf bank_mask:0xf
	v_mov_b32_dpp v66, v51 quad_perm:[1,0,3,2] row_mask:0xf bank_mask:0xf
	v_mov_b32_dpp v67, v50 quad_perm:[1,0,3,2] row_mask:0xf bank_mask:0xf
	v_cndmask_b32_e64 v50, v62, v64, s[38:39]
	v_cndmask_b32_e64 v51, v63, v65, s[38:39]
	v_cndmask_b32_e64 v52, v58, v66, s[38:39]
	v_cndmask_b32_e64 v53, v59, v67, s[38:39]
	v_lshl_add_u64 v[54:55], s[22:23], 0, v[116:117]
	global_store_dwordx4 v[54:55], v[50:53], off nt
	v_lshl_add_u64 v[54:55], s[22:23], 0, v[118:119]
	s_nop 0
	v_cndmask_b32_e64 v50, v64, v60, s[38:39]
	v_cndmask_b32_e64 v51, v65, v56, s[38:39]
	v_cndmask_b32_e64 v52, v66, v57, s[38:39]
	v_cndmask_b32_e64 v53, v67, v61, s[38:39]
	global_store_dwordx4 v[54:55], v[50:53], off nt
	ds_read_b128 v[50:53], v181 offset:2304
	s_waitcnt lgkmcnt(0)
	v_mov_b32_e32 v54, v51
	v_mov_b32_e32 v55, v52
	v_mov_b32_e32 v51, v53
	v_pk_add_f32 v[50:51], v[54:55], v[50:51]
	s_nop 0
	v_add_f32_e32 v50, v50, v51
	v_fmamk_f32 v50, v50, 0x3b800000, v1
	v_mul_f32_e32 v51, 0x4f800000, v50
	v_cmp_gt_f32_e32 vcc, s70, v50
	s_nop 1
	v_cndmask_b32_e32 v50, v50, v51, vcc
	v_sqrt_f32_e32 v51, v50
	s_nop 0
	v_add_u32_e32 v52, -1, v51
	v_fma_f32 v53, -v52, v51, v50
	v_cmp_ge_f32_e64 s[42:43], 0, v53
	v_add_u32_e32 v53, 1, v51
	s_nop 0
	v_cndmask_b32_e64 v52, v51, v52, s[42:43]
	v_fma_f32 v51, -v53, v51, v50
	v_cmp_lt_f32_e64 s[42:43], 0, v51
	s_nop 1
	v_cndmask_b32_e64 v51, v52, v53, s[42:43]
	v_mul_f32_e32 v52, 0x37800000, v51
	v_cndmask_b32_e32 v51, v51, v52, vcc
	v_cmp_class_f32_e32 vcc, v50, v226
	s_nop 1
	v_cndmask_b32_e32 v50, v51, v50, vcc
	v_div_scale_f32 v51, s[22:23], v50, v50, 1.0
	v_rcp_f32_e32 v52, v51
	s_add_u32 s22, s20, 0xb4000
	s_addc_u32 s23, s21, 0
	v_fma_f32 v53, -v51, v52, 1.0
	v_fmac_f32_e32 v52, v53, v52
	v_div_scale_f32 v53, vcc, 1.0, v50, 1.0
	v_mul_f32_e32 v54, v53, v52
	v_fma_f32 v55, -v51, v54, v53
	v_fmac_f32_e32 v54, v55, v52
	v_fma_f32 v51, -v51, v54, v53
	v_div_fmas_f32 v51, v51, v52, v54
	v_div_fixup_f32 v50, v51, v50, 1.0
	v_pk_mul_f32 v[48:49], v[48:49], v[50:51] op_sel_hi:[1,0]
	v_pk_mul_f32 v[46:47], v[46:47], v[50:51] op_sel_hi:[1,0]
	v_pk_mul_f32 v[44:45], v[44:45], v[50:51] op_sel_hi:[1,0]
	v_pk_mul_f32 v[42:43], v[42:43], v[50:51] op_sel_hi:[1,0]
	v_pk_mul_f32 v[40:41], v[40:41], v[50:51] op_sel_hi:[1,0]
	v_pk_mul_f32 v[36:37], v[36:37], v[50:51] op_sel_hi:[1,0]
	v_pk_mul_f32 v[34:35], v[34:35], v[50:51] op_sel_hi:[1,0]
	v_cvt_pk_bf16_f32 v46, v46, v47
	v_cvt_pk_bf16_f32 v47, v48, v49
	v_cvt_pk_bf16_f32 v42, v42, v43
	v_cvt_pk_bf16_f32 v43, v44, v45
	v_pk_mul_f32 v[38:39], v[38:39], v[50:51] op_sel_hi:[1,0]
	v_mov_b32_e32 v48, v115
	v_cvt_pk_bf16_f32 v44, v38, v39
	v_cvt_pk_bf16_f32 v40, v40, v41
	v_cvt_pk_bf16_f32 v41, v34, v35
	v_cvt_pk_bf16_f32 v45, v36, v37
	v_mov_b32_e32 v49, v115
	v_cndmask_b32_e64 v34, v45, v43, s[38:39]
	v_cndmask_b32_e64 v35, v41, v42, s[38:39]
	v_cndmask_b32_e64 v36, v40, v47, s[38:39]
	v_cndmask_b32_e64 v37, v44, v46, s[38:39]
	v_mov_b32_e32 v50, v115
	v_mov_b32_e32 v51, v115
	v_mov_b32_dpp v48, v37 quad_perm:[1,0,3,2] row_mask:0xf bank_mask:0xf
	v_mov_b32_dpp v49, v36 quad_perm:[1,0,3,2] row_mask:0xf bank_mask:0xf
	v_mov_b32_dpp v50, v35 quad_perm:[1,0,3,2] row_mask:0xf bank_mask:0xf
	v_mov_b32_dpp v51, v34 quad_perm:[1,0,3,2] row_mask:0xf bank_mask:0xf
	v_cndmask_b32_e64 v34, v46, v48, s[38:39]
	v_cndmask_b32_e64 v35, v47, v49, s[38:39]
	v_cndmask_b32_e64 v36, v42, v50, s[38:39]
	v_cndmask_b32_e64 v37, v43, v51, s[38:39]
	v_lshl_add_u64 v[38:39], s[22:23], 0, v[116:117]
	global_store_dwordx4 v[38:39], v[34:37], off nt
	v_lshl_add_u64 v[38:39], s[22:23], 0, v[118:119]
	s_nop 0
	v_cndmask_b32_e64 v34, v48, v44, s[38:39]
	v_cndmask_b32_e64 v35, v49, v40, s[38:39]
	v_cndmask_b32_e64 v36, v50, v41, s[38:39]
	v_cndmask_b32_e64 v37, v51, v45, s[38:39]
	global_store_dwordx4 v[38:39], v[34:37], off nt
	ds_read_b128 v[34:37], v181 offset:2560
	s_waitcnt lgkmcnt(0)
	v_mov_b32_e32 v38, v35
	v_mov_b32_e32 v39, v36
	v_mov_b32_e32 v35, v37
	v_pk_add_f32 v[34:35], v[38:39], v[34:35]
	s_nop 0
	v_add_f32_e32 v34, v34, v35
	v_fmamk_f32 v34, v34, 0x3b800000, v1
	v_mul_f32_e32 v35, 0x4f800000, v34
	v_cmp_gt_f32_e32 vcc, s70, v34
	s_nop 1
	v_cndmask_b32_e32 v34, v34, v35, vcc
	v_sqrt_f32_e32 v35, v34
	s_nop 0
	v_add_u32_e32 v36, -1, v35
	v_fma_f32 v37, -v36, v35, v34
	v_cmp_ge_f32_e64 s[42:43], 0, v37
	v_add_u32_e32 v37, 1, v35
	s_nop 0
	v_cndmask_b32_e64 v36, v35, v36, s[42:43]
	v_fma_f32 v35, -v37, v35, v34
	v_cmp_lt_f32_e64 s[42:43], 0, v35
	s_nop 1
	v_cndmask_b32_e64 v35, v36, v37, s[42:43]
	v_mul_f32_e32 v36, 0x37800000, v35
	v_cndmask_b32_e32 v35, v35, v36, vcc
	v_cmp_class_f32_e32 vcc, v34, v226
	s_nop 1
	v_cndmask_b32_e32 v34, v35, v34, vcc
	v_div_scale_f32 v35, s[22:23], v34, v34, 1.0
	v_rcp_f32_e32 v36, v35
	s_add_u32 s22, s20, 0xc8000
	s_addc_u32 s23, s21, 0
	s_add_u32 s20, s20, 0xdc000
	v_fma_f32 v37, -v35, v36, 1.0
	v_fmac_f32_e32 v36, v37, v36
	v_div_scale_f32 v37, vcc, 1.0, v34, 1.0
	v_mul_f32_e32 v38, v37, v36
	v_fma_f32 v39, -v35, v38, v37
	v_fmac_f32_e32 v38, v39, v36
	v_fma_f32 v35, -v35, v38, v37
	v_div_fmas_f32 v35, v35, v36, v38
	v_div_fixup_f32 v34, v35, v34, 1.0
	v_pk_mul_f32 v[32:33], v[32:33], v[34:35] op_sel_hi:[1,0]
	v_pk_mul_f32 v[30:31], v[30:31], v[34:35] op_sel_hi:[1,0]
	v_pk_mul_f32 v[28:29], v[28:29], v[34:35] op_sel_hi:[1,0]
	v_pk_mul_f32 v[26:27], v[26:27], v[34:35] op_sel_hi:[1,0]
	v_pk_mul_f32 v[24:25], v[24:25], v[34:35] op_sel_hi:[1,0]
	v_pk_mul_f32 v[20:21], v[20:21], v[34:35] op_sel_hi:[1,0]
	v_pk_mul_f32 v[18:19], v[18:19], v[34:35] op_sel_hi:[1,0]
	v_cvt_pk_bf16_f32 v30, v30, v31
	v_cvt_pk_bf16_f32 v31, v32, v33
	v_cvt_pk_bf16_f32 v26, v26, v27
	v_cvt_pk_bf16_f32 v27, v28, v29
	v_pk_mul_f32 v[22:23], v[22:23], v[34:35] op_sel_hi:[1,0]
	v_mov_b32_e32 v32, v115
	v_cvt_pk_bf16_f32 v28, v22, v23
	v_cvt_pk_bf16_f32 v24, v24, v25
	v_cvt_pk_bf16_f32 v25, v18, v19
	v_cvt_pk_bf16_f32 v29, v20, v21
	v_mov_b32_e32 v33, v115
	v_cndmask_b32_e64 v18, v29, v27, s[38:39]
	v_cndmask_b32_e64 v19, v25, v26, s[38:39]
	v_cndmask_b32_e64 v20, v24, v31, s[38:39]
	v_cndmask_b32_e64 v21, v28, v30, s[38:39]
	v_mov_b32_e32 v34, v115
	v_mov_b32_e32 v35, v115
	v_mov_b32_dpp v32, v21 quad_perm:[1,0,3,2] row_mask:0xf bank_mask:0xf
	v_mov_b32_dpp v33, v20 quad_perm:[1,0,3,2] row_mask:0xf bank_mask:0xf
	v_mov_b32_dpp v34, v19 quad_perm:[1,0,3,2] row_mask:0xf bank_mask:0xf
	v_mov_b32_dpp v35, v18 quad_perm:[1,0,3,2] row_mask:0xf bank_mask:0xf
	v_cndmask_b32_e64 v18, v30, v32, s[38:39]
	v_cndmask_b32_e64 v19, v31, v33, s[38:39]
	v_cndmask_b32_e64 v20, v26, v34, s[38:39]
	v_cndmask_b32_e64 v21, v27, v35, s[38:39]
	v_lshl_add_u64 v[22:23], s[22:23], 0, v[116:117]
	global_store_dwordx4 v[22:23], v[18:21], off nt
	v_lshl_add_u64 v[22:23], s[22:23], 0, v[118:119]
	s_addc_u32 s21, s21, 0
	v_cndmask_b32_e64 v18, v32, v28, s[38:39]
	v_cndmask_b32_e64 v19, v33, v24, s[38:39]
	v_cndmask_b32_e64 v20, v34, v25, s[38:39]
	v_cndmask_b32_e64 v21, v35, v29, s[38:39]
	global_store_dwordx4 v[22:23], v[18:21], off nt
	ds_read_b128 v[18:21], v181 offset:2816
	s_waitcnt lgkmcnt(0)
	v_mov_b32_e32 v22, v19
	v_mov_b32_e32 v23, v20
	v_mov_b32_e32 v19, v21
	v_pk_add_f32 v[18:19], v[22:23], v[18:19]
	s_nop 0
	v_add_f32_e32 v18, v18, v19
	v_fmamk_f32 v18, v18, 0x3b800000, v1
	v_mul_f32_e32 v19, 0x4f800000, v18
	v_cmp_gt_f32_e32 vcc, s70, v18
	s_nop 1
	v_cndmask_b32_e32 v18, v18, v19, vcc
	v_sqrt_f32_e32 v19, v18
	s_nop 0
	v_add_u32_e32 v20, -1, v19
	v_fma_f32 v21, -v20, v19, v18
	v_cmp_ge_f32_e64 s[42:43], 0, v21
	v_add_u32_e32 v21, 1, v19
	s_nop 0
	v_cndmask_b32_e64 v20, v19, v20, s[42:43]
	v_fma_f32 v19, -v21, v19, v18
	v_cmp_lt_f32_e64 s[42:43], 0, v19
	s_nop 1
	v_cndmask_b32_e64 v19, v20, v21, s[42:43]
	v_mul_f32_e32 v20, 0x37800000, v19
	v_cndmask_b32_e32 v19, v19, v20, vcc
	v_cmp_class_f32_e32 vcc, v18, v226
	s_nop 1
	v_cndmask_b32_e32 v18, v19, v18, vcc
	v_div_scale_f32 v19, s[22:23], v18, v18, 1.0
	v_rcp_f32_e32 v20, v19
	s_nop 0
	v_fma_f32 v21, -v19, v20, 1.0
	v_fmac_f32_e32 v20, v21, v20
	v_div_scale_f32 v21, vcc, 1.0, v18, 1.0
	v_mul_f32_e32 v22, v21, v20
	v_fma_f32 v23, -v19, v22, v21
	v_fmac_f32_e32 v22, v23, v20
	v_fma_f32 v19, -v19, v22, v21
	v_div_fmas_f32 v19, v19, v20, v22
	v_div_fixup_f32 v18, v19, v18, 1.0
	v_pk_mul_f32 v[16:17], v[16:17], v[18:19] op_sel_hi:[1,0]
	v_pk_mul_f32 v[14:15], v[14:15], v[18:19] op_sel_hi:[1,0]
	v_pk_mul_f32 v[12:13], v[12:13], v[18:19] op_sel_hi:[1,0]
	v_pk_mul_f32 v[10:11], v[10:11], v[18:19] op_sel_hi:[1,0]
	v_pk_mul_f32 v[8:9], v[8:9], v[18:19] op_sel_hi:[1,0]
	v_pk_mul_f32 v[4:5], v[4:5], v[18:19] op_sel_hi:[1,0]
	v_pk_mul_f32 v[2:3], v[2:3], v[18:19] op_sel_hi:[1,0]
	v_cvt_pk_bf16_f32 v14, v14, v15
	v_cvt_pk_bf16_f32 v15, v16, v17
	v_cvt_pk_bf16_f32 v10, v10, v11
	v_cvt_pk_bf16_f32 v11, v12, v13
	v_pk_mul_f32 v[6:7], v[6:7], v[18:19] op_sel_hi:[1,0]
	v_mov_b32_e32 v16, v115
	v_cvt_pk_bf16_f32 v12, v6, v7
	v_cvt_pk_bf16_f32 v8, v8, v9
	v_cvt_pk_bf16_f32 v9, v2, v3
	v_cvt_pk_bf16_f32 v13, v4, v5
	v_mov_b32_e32 v17, v115
	v_cndmask_b32_e64 v2, v13, v11, s[38:39]
	v_cndmask_b32_e64 v3, v9, v10, s[38:39]
	v_cndmask_b32_e64 v4, v8, v15, s[38:39]
	v_cndmask_b32_e64 v5, v12, v14, s[38:39]
	v_mov_b32_e32 v18, v115
	v_mov_b32_e32 v19, v115
	v_mov_b32_dpp v16, v5 quad_perm:[1,0,3,2] row_mask:0xf bank_mask:0xf
	v_mov_b32_dpp v17, v4 quad_perm:[1,0,3,2] row_mask:0xf bank_mask:0xf
	v_mov_b32_dpp v18, v3 quad_perm:[1,0,3,2] row_mask:0xf bank_mask:0xf
	v_mov_b32_dpp v19, v2 quad_perm:[1,0,3,2] row_mask:0xf bank_mask:0xf
	v_cndmask_b32_e64 v2, v14, v16, s[38:39]
	v_cndmask_b32_e64 v3, v15, v17, s[38:39]
	v_cndmask_b32_e64 v4, v10, v18, s[38:39]
	v_cndmask_b32_e64 v5, v11, v19, s[38:39]
	v_lshl_add_u64 v[6:7], s[20:21], 0, v[116:117]
	global_store_dwordx4 v[6:7], v[2:5], off nt
	v_lshl_add_u64 v[6:7], s[20:21], 0, v[118:119]
	s_nop 0
	v_cndmask_b32_e64 v2, v16, v12, s[38:39]
	v_cndmask_b32_e64 v3, v17, v8, s[38:39]
	v_cndmask_b32_e64 v4, v18, v9, s[38:39]
	v_cndmask_b32_e64 v5, v19, v13, s[38:39]
	global_store_dwordx4 v[6:7], v[2:5], off nt
	s_and_b64 vcc, exec, s[40:41]
	s_mov_b64 s[20:21], -1
	s_cbranch_vccnz .LBB0_542

.LBB0_940:
	s_add_u32 s24, s22, 0xfff80080
	s_addc_u32 s25, s23, -1
	s_add_i32 s59, 0, 0x10000
	s_cmp_eq_u32 s57, 28
	s_cselect_b32 s27, s3, s25
	s_cselect_b32 s26, s4, s24
	v_add_u32_e32 v160, s59, v165
	s_cselect_b32 s25, s11, s21
	s_cselect_b32 s24, s13, s19
	s_add_i32 s64, 0, 0x14000
	ds_read_b128 v[132:135], v160
	ds_read_b128 v[136:139], v160 offset:1024
	ds_read_b128 v[156:159], v160 offset:2048
	ds_read_b128 v[168:171], v160 offset:3072
	v_add_u32_e32 v160, s64, v165
	ds_read_b128 v[172:175], v160
	ds_read_b128 v[176:179], v160 offset:1024
	ds_read_b128 v[180:183], v160 offset:2048
	ds_read_b128 v[184:187], v160 offset:3072
	v_lshl_add_u64 v[220:221], s[22:23], 0, v[152:153]
	s_add_i32 m0, s47, 0xc000
	ds_read_b128 v[188:191], v166
	ds_read_b128 v[192:195], v166 offset:1024
	ds_read_b128 v[196:199], v166 offset:2048
	ds_read_b128 v[200:203], v166 offset:3072
	ds_read_b128 v[204:207], v166 offset:4096
	ds_read_b128 v[208:211], v166 offset:5120
	ds_read_b128 v[212:215], v166 offset:6144
	ds_read_b128 v[216:219], v166 offset:7168
	global_load_lds_dwordx4 v[220:221], off
	v_lshl_add_u64 v[220:221], s[22:23], 0, v[154:155]
	s_add_i32 m0, s47, 0xe000
	s_nop 0
	global_load_lds_dwordx4 v[220:221], off
	s_waitcnt vmcnt(8)
	s_waitcnt lgkmcnt(0)
	s_barrier
	s_setprio 1
	s_waitcnt lgkmcnt(0)
	v_mfma_f32_16x16x32_bf16 v[128:131], v[132:135], v[188:191], v[128:131]
	v_mfma_f32_16x16x32_bf16 v[124:127], v[156:159], v[188:191], v[124:127]
	v_mfma_f32_16x16x32_bf16 v[110:113], v[132:135], v[196:199], v[110:113]
	v_mfma_f32_16x16x32_bf16 v[106:109], v[156:159], v[196:199], v[106:109]
	v_mfma_f32_16x16x32_bf16 v[102:105], v[132:135], v[204:207], v[102:105]
	v_mfma_f32_16x16x32_bf16 v[98:101], v[156:159], v[204:207], v[98:101]
	v_mfma_f32_16x16x32_bf16 v[78:81], v[132:135], v[212:215], v[78:81]
	v_mfma_f32_16x16x32_bf16 v[74:77], v[156:159], v[212:215], v[74:77]
	v_mfma_f32_16x16x32_bf16 v[128:131], v[136:139], v[192:195], v[128:131]
	v_mfma_f32_16x16x32_bf16 v[124:127], v[168:171], v[192:195], v[124:127]
	v_mfma_f32_16x16x32_bf16 v[110:113], v[136:139], v[200:203], v[110:113]
	v_mfma_f32_16x16x32_bf16 v[106:109], v[168:171], v[200:203], v[106:109]
	v_mfma_f32_16x16x32_bf16 v[102:105], v[136:139], v[208:211], v[102:105]
	v_mfma_f32_16x16x32_bf16 v[98:101], v[168:171], v[208:211], v[98:101]
	v_mfma_f32_16x16x32_bf16 v[78:81], v[136:139], v[216:219], v[78:81]
	v_mfma_f32_16x16x32_bf16 v[74:77], v[168:171], v[216:219], v[74:77]
	s_setprio 0
	s_setprio 1
	v_mfma_f32_16x16x32_bf16 v[120:123], v[172:175], v[188:191], v[120:123]
	v_mfma_f32_16x16x32_bf16 v[116:119], v[180:183], v[188:191], v[116:119]
	v_mfma_f32_16x16x32_bf16 v[86:89], v[172:175], v[196:199], v[86:89]
	v_mfma_f32_16x16x32_bf16 v[82:85], v[180:183], v[196:199], v[82:85]
	v_mfma_f32_16x16x32_bf16 v[94:97], v[172:175], v[204:207], v[94:97]
	v_mfma_f32_16x16x32_bf16 v[90:93], v[180:183], v[204:207], v[90:93]
	v_mfma_f32_16x16x32_bf16 v[70:73], v[172:175], v[212:215], v[70:73]
	v_mfma_f32_16x16x32_bf16 v[66:69], v[180:183], v[212:215], v[66:69]
	v_mfma_f32_16x16x32_bf16 v[120:123], v[176:179], v[192:195], v[120:123]
	v_mfma_f32_16x16x32_bf16 v[116:119], v[184:187], v[192:195], v[116:119]
	v_mfma_f32_16x16x32_bf16 v[86:89], v[176:179], v[200:203], v[86:89]
	v_mfma_f32_16x16x32_bf16 v[82:85], v[184:187], v[200:203], v[82:85]
	v_mfma_f32_16x16x32_bf16 v[94:97], v[176:179], v[208:211], v[94:97]
	v_mfma_f32_16x16x32_bf16 v[90:93], v[184:187], v[208:211], v[90:93]
	v_mfma_f32_16x16x32_bf16 v[70:73], v[176:179], v[216:219], v[70:73]
	v_mfma_f32_16x16x32_bf16 v[66:69], v[184:187], v[216:219], v[66:69]
	s_setprio 0
	s_barrier
	s_add_i32 s59, s59, s46
	v_lshl_add_u64 v[220:221], s[24:25], 0, v[114:115]
	s_mov_b32 m0, s59
	ds_read_b128 v[188:191], v166 offset:16384
	ds_read_b128 v[192:195], v166 offset:17408
	ds_read_b128 v[196:199], v166 offset:18432
	ds_read_b128 v[200:203], v166 offset:19456
	ds_read_b128 v[204:207], v166 offset:20480
	ds_read_b128 v[208:211], v166 offset:21504
	ds_read_b128 v[212:215], v166 offset:22528
	ds_read_b128 v[216:219], v166 offset:23552
	global_load_lds_dwordx4 v[220:221], off
	s_add_i32 m0, s59, 0x2000
	s_add_u32 s62, s24, 0x20000
	v_lshl_add_u64 v[222:223], s[24:25], 0, v[144:145]
	s_addc_u32 s63, s25, 0
	s_add_i32 s59, s64, s46
	global_load_lds_dwordx4 v[222:223], off
	v_lshl_add_u64 v[224:225], s[62:63], 0, v[114:115]
	s_mov_b32 m0, s59
	v_lshl_add_u64 v[230:231], s[26:27], 0, v[142:143]
	global_load_lds_dwordx4 v[224:225], off
	v_lshl_add_u64 v[224:225], s[62:63], 0, v[144:145]
	s_add_i32 m0, s59, 0x2000
	s_nop 0
	global_load_lds_dwordx4 v[224:225], off
	v_lshl_add_u64 v[224:225], s[26:27], 0, v[140:141]
	s_mov_b32 m0, s47
	s_nop 0
	global_load_lds_dwordx4 v[224:225], off
	s_mov_b32 m0, s48
	s_nop 0
	global_load_lds_dwordx4 v[230:231], off
	s_waitcnt vmcnt(8)
	s_waitcnt lgkmcnt(0)
	s_barrier
	s_setprio 1
	s_waitcnt lgkmcnt(0)
	v_mfma_f32_16x16x32_bf16 v[62:65], v[132:135], v[188:191], v[62:65]
	v_mfma_f32_16x16x32_bf16 v[58:61], v[156:159], v[188:191], v[58:61]
	v_mfma_f32_16x16x32_bf16 v[46:49], v[132:135], v[196:199], v[46:49]
	v_mfma_f32_16x16x32_bf16 v[42:45], v[156:159], v[196:199], v[42:45]
	v_mfma_f32_16x16x32_bf16 v[30:33], v[132:135], v[204:207], v[30:33]
	v_mfma_f32_16x16x32_bf16 v[26:29], v[156:159], v[204:207], v[26:29]
	v_mfma_f32_16x16x32_bf16 v[14:17], v[132:135], v[212:215], v[14:17]
	v_mfma_f32_16x16x32_bf16 v[10:13], v[156:159], v[212:215], v[10:13]
	v_mfma_f32_16x16x32_bf16 v[62:65], v[136:139], v[192:195], v[62:65]
	v_mfma_f32_16x16x32_bf16 v[58:61], v[168:171], v[192:195], v[58:61]
	v_mfma_f32_16x16x32_bf16 v[46:49], v[136:139], v[200:203], v[46:49]
	v_mfma_f32_16x16x32_bf16 v[42:45], v[168:171], v[200:203], v[42:45]
	v_mfma_f32_16x16x32_bf16 v[30:33], v[136:139], v[208:211], v[30:33]
	v_mfma_f32_16x16x32_bf16 v[26:29], v[168:171], v[208:211], v[26:29]
	v_mfma_f32_16x16x32_bf16 v[14:17], v[136:139], v[216:219], v[14:17]
	v_mfma_f32_16x16x32_bf16 v[10:13], v[168:171], v[216:219], v[10:13]
	s_setprio 0
	s_setprio 1
	v_mfma_f32_16x16x32_bf16 v[54:57], v[172:175], v[188:191], v[54:57]
	v_mfma_f32_16x16x32_bf16 v[50:53], v[180:183], v[188:191], v[50:53]
	v_mfma_f32_16x16x32_bf16 v[38:41], v[172:175], v[196:199], v[38:41]
	v_mfma_f32_16x16x32_bf16 v[34:37], v[180:183], v[196:199], v[34:37]
	v_mfma_f32_16x16x32_bf16 v[22:25], v[172:175], v[204:207], v[22:25]
	v_mfma_f32_16x16x32_bf16 v[18:21], v[180:183], v[204:207], v[18:21]
	v_mfma_f32_16x16x32_bf16 v[6:9], v[172:175], v[212:215], v[6:9]
	v_mfma_f32_16x16x32_bf16 v[2:5], v[180:183], v[212:215], v[2:5]
	v_mfma_f32_16x16x32_bf16 v[54:57], v[176:179], v[192:195], v[54:57]
	v_mfma_f32_16x16x32_bf16 v[50:53], v[184:187], v[192:195], v[50:53]
	v_mfma_f32_16x16x32_bf16 v[38:41], v[176:179], v[200:203], v[38:41]
	v_mfma_f32_16x16x32_bf16 v[34:37], v[184:187], v[200:203], v[34:37]
	v_mfma_f32_16x16x32_bf16 v[22:25], v[176:179], v[208:211], v[22:25]
	v_mfma_f32_16x16x32_bf16 v[18:21], v[184:187], v[208:211], v[18:21]
	v_mfma_f32_16x16x32_bf16 v[6:9], v[176:179], v[216:219], v[6:9]
	v_mfma_f32_16x16x32_bf16 v[2:5], v[184:187], v[216:219], v[2:5]
	s_setprio 0
	s_barrier
	s_add_i32 s59, 0, 0x18000
	v_add_u32_e32 v160, s59, v165
	s_add_i32 s62, 0, 0x1c000
	ds_read_b128 v[132:135], v160
	ds_read_b128 v[136:139], v160 offset:1024
	ds_read_b128 v[156:159], v160 offset:2048
	ds_read_b128 v[168:171], v160 offset:3072
	v_add_u32_e32 v160, s62, v165
	ds_read_b128 v[172:175], v160
	ds_read_b128 v[176:179], v160 offset:1024
	ds_read_b128 v[180:183], v160 offset:2048
	ds_read_b128 v[184:187], v160 offset:3072
	s_add_u32 s26, s26, 0x80000
	s_addc_u32 s27, s27, 0
	s_mov_b32 m0, s49
	v_lshl_add_u64 v[232:233], s[26:27], 0, v[140:141]
	ds_read_b128 v[188:191], v166 offset:32768
	ds_read_b128 v[192:195], v166 offset:33792
	ds_read_b128 v[196:199], v166 offset:34816
	ds_read_b128 v[200:203], v166 offset:35840
	ds_read_b128 v[204:207], v166 offset:36864
	ds_read_b128 v[208:211], v166 offset:37888
	ds_read_b128 v[212:215], v166 offset:38912
	ds_read_b128 v[216:219], v166 offset:39936
	global_load_lds_dwordx4 v[232:233], off
	v_lshl_add_u64 v[232:233], s[26:27], 0, v[142:143]
	s_mov_b32 m0, s50
	s_nop 0
	global_load_lds_dwordx4 v[232:233], off
	s_waitcnt vmcnt(8)
	s_waitcnt lgkmcnt(0)
	s_barrier
	s_setprio 1
	s_waitcnt lgkmcnt(0)
	v_mfma_f32_16x16x32_bf16 v[128:131], v[132:135], v[188:191], v[128:131]
	v_mfma_f32_16x16x32_bf16 v[124:127], v[156:159], v[188:191], v[124:127]
	v_mfma_f32_16x16x32_bf16 v[110:113], v[132:135], v[196:199], v[110:113]
	v_mfma_f32_16x16x32_bf16 v[106:109], v[156:159], v[196:199], v[106:109]
	v_mfma_f32_16x16x32_bf16 v[102:105], v[132:135], v[204:207], v[102:105]
	v_mfma_f32_16x16x32_bf16 v[98:101], v[156:159], v[204:207], v[98:101]
	v_mfma_f32_16x16x32_bf16 v[78:81], v[132:135], v[212:215], v[78:81]
	v_mfma_f32_16x16x32_bf16 v[74:77], v[156:159], v[212:215], v[74:77]
	v_mfma_f32_16x16x32_bf16 v[128:131], v[136:139], v[192:195], v[128:131]
	v_mfma_f32_16x16x32_bf16 v[124:127], v[168:171], v[192:195], v[124:127]
	v_mfma_f32_16x16x32_bf16 v[110:113], v[136:139], v[200:203], v[110:113]
	v_mfma_f32_16x16x32_bf16 v[106:109], v[168:171], v[200:203], v[106:109]
	v_mfma_f32_16x16x32_bf16 v[102:105], v[136:139], v[208:211], v[102:105]
	v_mfma_f32_16x16x32_bf16 v[98:101], v[168:171], v[208:211], v[98:101]
	v_mfma_f32_16x16x32_bf16 v[78:81], v[136:139], v[216:219], v[78:81]
	v_mfma_f32_16x16x32_bf16 v[74:77], v[168:171], v[216:219], v[74:77]
	s_setprio 0
	s_setprio 1
	v_mfma_f32_16x16x32_bf16 v[120:123], v[172:175], v[188:191], v[120:123]
	v_mfma_f32_16x16x32_bf16 v[116:119], v[180:183], v[188:191], v[116:119]
	v_mfma_f32_16x16x32_bf16 v[86:89], v[172:175], v[196:199], v[86:89]
	v_mfma_f32_16x16x32_bf16 v[82:85], v[180:183], v[196:199], v[82:85]
	v_mfma_f32_16x16x32_bf16 v[94:97], v[172:175], v[204:207], v[94:97]
	v_mfma_f32_16x16x32_bf16 v[90:93], v[180:183], v[204:207], v[90:93]
	v_mfma_f32_16x16x32_bf16 v[70:73], v[172:175], v[212:215], v[70:73]
	v_mfma_f32_16x16x32_bf16 v[66:69], v[180:183], v[212:215], v[66:69]
	v_mfma_f32_16x16x32_bf16 v[120:123], v[176:179], v[192:195], v[120:123]
	v_mfma_f32_16x16x32_bf16 v[116:119], v[184:187], v[192:195], v[116:119]
	v_mfma_f32_16x16x32_bf16 v[86:89], v[176:179], v[200:203], v[86:89]
	v_mfma_f32_16x16x32_bf16 v[82:85], v[184:187], v[200:203], v[82:85]
	v_mfma_f32_16x16x32_bf16 v[94:97], v[176:179], v[208:211], v[94:97]
	v_mfma_f32_16x16x32_bf16 v[90:93], v[184:187], v[208:211], v[90:93]
	v_mfma_f32_16x16x32_bf16 v[70:73], v[176:179], v[216:219], v[70:73]
	v_mfma_f32_16x16x32_bf16 v[66:69], v[184:187], v[216:219], v[66:69]
	s_setprio 0
	s_barrier
	s_add_i32 s26, s59, s46
	v_lshl_add_u64 v[220:221], v[220:221], 0, s[28:29]
	s_mov_b32 m0, s26
	ds_read_b128 v[188:191], v166 offset:49152
	ds_read_b128 v[192:195], v166 offset:50176
	ds_read_b128 v[196:199], v166 offset:51200
	ds_read_b128 v[200:203], v166 offset:52224
	ds_read_b128 v[204:207], v166 offset:53248
	ds_read_b128 v[208:211], v166 offset:54272
	ds_read_b128 v[212:215], v166 offset:55296
	ds_read_b128 v[216:219], v166 offset:56320
	global_load_lds_dwordx4 v[220:221], off
	s_add_i32 m0, s26, 0x2000
	s_add_u32 s24, s24, 0x20080
	v_lshl_add_u64 v[220:221], v[222:223], 0, s[28:29]
	s_addc_u32 s25, s25, 0
	s_add_i32 s26, s62, s46
	global_load_lds_dwordx4 v[220:221], off
	v_lshl_add_u64 v[220:221], s[24:25], 0, v[114:115]
	s_mov_b32 m0, s26
	s_nop 0
	global_load_lds_dwordx4 v[220:221], off
	v_lshl_add_u64 v[220:221], s[24:25], 0, v[144:145]
	s_add_i32 m0, s26, 0x2000
	s_nop 0
	global_load_lds_dwordx4 v[220:221], off
	v_lshl_add_u64 v[220:221], v[224:225], 0, s[28:29]
	s_mov_b32 m0, s54
	s_nop 0
	global_load_lds_dwordx4 v[220:221], off
	v_lshl_add_u64 v[220:221], v[230:231], 0, s[28:29]
	s_mov_b32 m0, s55
	s_nop 0
	global_load_lds_dwordx4 v[220:221], off
	s_waitcnt vmcnt(8)
	s_waitcnt lgkmcnt(0)
	s_barrier
	s_setprio 1
	s_waitcnt lgkmcnt(0)
	v_mfma_f32_16x16x32_bf16 v[62:65], v[132:135], v[188:191], v[62:65]
	v_mfma_f32_16x16x32_bf16 v[58:61], v[156:159], v[188:191], v[58:61]
	v_mfma_f32_16x16x32_bf16 v[46:49], v[132:135], v[196:199], v[46:49]
	v_mfma_f32_16x16x32_bf16 v[42:45], v[156:159], v[196:199], v[42:45]
	v_mfma_f32_16x16x32_bf16 v[30:33], v[132:135], v[204:207], v[30:33]
	v_mfma_f32_16x16x32_bf16 v[26:29], v[156:159], v[204:207], v[26:29]
	v_mfma_f32_16x16x32_bf16 v[14:17], v[132:135], v[212:215], v[14:17]
	v_mfma_f32_16x16x32_bf16 v[10:13], v[156:159], v[212:215], v[10:13]
	v_mfma_f32_16x16x32_bf16 v[62:65], v[136:139], v[192:195], v[62:65]
	v_mfma_f32_16x16x32_bf16 v[58:61], v[168:171], v[192:195], v[58:61]
	v_mfma_f32_16x16x32_bf16 v[46:49], v[136:139], v[200:203], v[46:49]
	v_mfma_f32_16x16x32_bf16 v[42:45], v[168:171], v[200:203], v[42:45]
	v_mfma_f32_16x16x32_bf16 v[30:33], v[136:139], v[208:211], v[30:33]
	v_mfma_f32_16x16x32_bf16 v[26:29], v[168:171], v[208:211], v[26:29]
	v_mfma_f32_16x16x32_bf16 v[14:17], v[136:139], v[216:219], v[14:17]
	v_mfma_f32_16x16x32_bf16 v[10:13], v[168:171], v[216:219], v[10:13]
	s_setprio 0
	s_setprio 1
	v_mfma_f32_16x16x32_bf16 v[54:57], v[172:175], v[188:191], v[54:57]
	v_mfma_f32_16x16x32_bf16 v[50:53], v[180:183], v[188:191], v[50:53]
	v_mfma_f32_16x16x32_bf16 v[38:41], v[172:175], v[196:199], v[38:41]
	v_mfma_f32_16x16x32_bf16 v[34:37], v[180:183], v[196:199], v[34:37]
	v_mfma_f32_16x16x32_bf16 v[22:25], v[172:175], v[204:207], v[22:25]
	v_mfma_f32_16x16x32_bf16 v[18:21], v[180:183], v[204:207], v[18:21]
	v_mfma_f32_16x16x32_bf16 v[6:9], v[172:175], v[212:215], v[6:9]
	v_mfma_f32_16x16x32_bf16 v[2:5], v[180:183], v[212:215], v[2:5]
	v_mfma_f32_16x16x32_bf16 v[54:57], v[176:179], v[192:195], v[54:57]
	v_mfma_f32_16x16x32_bf16 v[50:53], v[184:187], v[192:195], v[50:53]
	v_mfma_f32_16x16x32_bf16 v[38:41], v[176:179], v[200:203], v[38:41]
	v_mfma_f32_16x16x32_bf16 v[34:37], v[184:187], v[200:203], v[34:37]
	v_mfma_f32_16x16x32_bf16 v[22:25], v[176:179], v[208:211], v[22:25]
	v_mfma_f32_16x16x32_bf16 v[18:21], v[184:187], v[208:211], v[18:21]
	v_mfma_f32_16x16x32_bf16 v[6:9], v[176:179], v[216:219], v[6:9]
	v_mfma_f32_16x16x32_bf16 v[2:5], v[184:187], v[216:219], v[2:5]
	s_setprio 0
	s_barrier
	s_add_i32 s57, s57, 2
	s_add_u32 s19, s19, 0x100
	s_addc_u32 s21, s21, 0
	s_add_u32 s22, s22, 0x100
	s_addc_u32 s23, s23, 0
	s_cmp_gt_u32 s57, 29
	s_cbranch_scc0 .LBB0_940
	s_and_b64 vcc, exec, s[8:9]
	s_cbranch_vccz .LBB0_943
	s_barrier
.LBB0_943:
	s_lshl_b32 s20, s20, 8
	s_ashr_i32 s21, s20, 31
	s_lshl_b32 s3, s18, 8
	s_lshl_b64 s[22:23], s[20:21], 11
	s_ashr_i32 s4, s3, 31
	s_add_u32 s22, s22, s3
	s_addc_u32 s23, s23, s4
	s_lshl_b64 s[22:23], s[22:23], 1
	v_lshl_add_u64 v[158:159], v[150:151], 0, s[22:23]
	global_load_dwordx4 v[168:171], v[158:159], off
	global_load_dwordx4 v[172:175], v[158:159], off offset:64
	s_mov_b32 s3, 0x10000
	v_add_co_u32_e32 v132, vcc, s3, v158
	v_mov_b32_e32 v157, v115
	s_nop 0
	v_addc_co_u32_e32 v133, vcc, 0, v159, vcc
	global_load_dwordx4 v[136:139], v[132:133], off
	s_nop 0
	global_load_dwordx4 v[132:135], v[132:133], off offset:64
	v_mov_b32_e32 v160, v115
	v_mov_b32_e32 v161, v115
	v_add_u32_e32 v156, s20, v164
	s_add_u32 s20, s51, s22
	s_addc_u32 s21, s52, s23
	s_lshl_b32 s18, s18, 2
	s_ashr_i32 s19, s18, 31
	s_waitcnt vmcnt(0)
	v_lshlrev_b32_e32 v167, 16, v168
	v_and_b32_e32 v168, 0xffff0000, v168
	v_lshlrev_b32_e32 v176, 16, v169
	v_and_b32_e32 v169, 0xffff0000, v169
	v_lshlrev_b32_e32 v177, 16, v170
	v_and_b32_e32 v170, 0xffff0000, v170
	v_lshlrev_b32_e32 v178, 16, v171
	v_and_b32_e32 v171, 0xffff0000, v171
	v_lshlrev_b32_e32 v181, 16, v174
	v_and_b32_e32 v174, 0xffff0000, v174
	v_lshlrev_b32_e32 v182, 16, v175
	v_and_b32_e32 v175, 0xffff0000, v175
	v_add_f32_e32 v129, v129, v168
	v_add_f32_e32 v131, v131, v169
	v_add_f32_e32 v125, v125, v170
	v_add_f32_e32 v127, v127, v171
	v_lshlrev_b32_e32 v179, 16, v172
	v_and_b32_e32 v172, 0xffff0000, v172
	v_lshlrev_b32_e32 v180, 16, v173
	v_and_b32_e32 v173, 0xffff0000, v173
	v_add_f32_e32 v128, v128, v167
	v_add_f32_e32 v130, v130, v176
	v_add_f32_e32 v124, v124, v177
	v_add_f32_e32 v126, v126, v178
	v_add_f32_e32 v117, v117, v174
	v_add_f32_e32 v119, v119, v175
	v_cvt_pk_bf16_f32 v167, v128, v129
	v_cvt_pk_bf16_f32 v168, v130, v131
	v_cvt_pk_bf16_f32 v169, v124, v125
	v_cvt_pk_bf16_f32 v170, v126, v127
	v_mul_f32_e32 v129, v129, v129
	v_mul_f32_e32 v131, v131, v131
	v_mul_f32_e32 v125, v125, v125
	v_mul_f32_e32 v127, v127, v127
	v_add_f32_e32 v120, v120, v179
	v_add_f32_e32 v121, v121, v172
	v_add_f32_e32 v122, v122, v180
	v_add_f32_e32 v123, v123, v173
	v_add_f32_e32 v116, v116, v181
	v_add_f32_e32 v118, v118, v182
	v_cvt_pk_bf16_f32 v171, v120, v121
	v_cvt_pk_bf16_f32 v172, v122, v123
	v_cvt_pk_bf16_f32 v173, v116, v117
	v_cvt_pk_bf16_f32 v174, v118, v119
	v_mul_f32_e32 v117, v117, v117
	v_mul_f32_e32 v119, v119, v119
	v_fmac_f32_e32 v129, v128, v128
	v_fmac_f32_e32 v131, v130, v130
	v_fmac_f32_e32 v125, v124, v124
	v_fmac_f32_e32 v127, v126, v126
	v_fmac_f32_e32 v117, v116, v116
	v_fmac_f32_e32 v119, v118, v118
	v_add_f32_e32 v124, v129, v131
	v_add_f32_e32 v125, v125, v127
	v_mul_f32_e32 v121, v121, v121
	v_mul_f32_e32 v123, v123, v123
	v_cndmask_b32_e64 v116, v174, v170, s[36:37]
	v_add_f32_e32 v117, v117, v119
	v_add_f32_e32 v119, v124, v125
	v_mov_b32_e32 v124, v115
	v_and_b32_e32 v125, 64, v234
	v_fmac_f32_e32 v121, v120, v120
	v_fmac_f32_e32 v123, v122, v122
	v_mov_b32_dpp v124, v116 quad_perm:[1,0,3,2] row_mask:0xf bank_mask:0xf
	v_xor_b32_e32 v116, 16, v234
	v_add_u32_e32 v125, 64, v125
	v_add_f32_e32 v121, v121, v123
	v_cmp_lt_i32_e32 vcc, v116, v125
	v_add_f32_e32 v117, v121, v117
	v_add_f32_e32 v117, v119, v117
	v_cndmask_b32_e32 v116, v234, v116, vcc
	v_lshlrev_b32_e32 v116, 2, v116
	ds_bpermute_b32 v126, v116, v117
	v_cndmask_b32_e64 v118, v173, v169, s[36:37]
	v_cndmask_b32_e64 v120, v172, v168, s[36:37]
	v_cndmask_b32_e64 v122, v171, v167, s[36:37]
	v_mov_b32_dpp v161, v118 quad_perm:[1,0,3,2] row_mask:0xf bank_mask:0xf
	v_mov_b32_dpp v160, v120 quad_perm:[1,0,3,2] row_mask:0xf bank_mask:0xf
	v_mov_b32_dpp v157, v122 quad_perm:[1,0,3,2] row_mask:0xf bank_mask:0xf
	v_cndmask_b32_e64 v118, v167, v157, s[36:37]
	v_cndmask_b32_e64 v119, v168, v160, s[36:37]
	v_cndmask_b32_e64 v120, v169, v161, s[36:37]
	v_cndmask_b32_e64 v121, v170, v124, s[36:37]
	v_lshl_add_u64 v[122:123], v[146:147], 1, s[20:21]
	global_store_dwordx4 v[122:123], v[118:121], off nt
	v_cndmask_b32_e64 v122, v161, v173, s[36:37]
	v_cndmask_b32_e64 v123, v124, v174, s[36:37]
	s_waitcnt lgkmcnt(0)
	v_add_f32_e32 v118, v117, v126
	v_xor_b32_e32 v117, 32, v234
	v_cmp_lt_i32_e32 vcc, v117, v125
	v_cndmask_b32_e64 v120, v157, v171, s[36:37]
	v_cndmask_b32_e64 v121, v160, v172, s[36:37]
	v_cndmask_b32_e32 v117, v234, v117, vcc
	v_lshlrev_b32_e32 v117, 2, v117
	ds_bpermute_b32 v119, v117, v118
	v_lshl_add_u64 v[124:125], v[148:149], 1, s[20:21]
	v_ashrrev_i32_e32 v157, 31, v156
	global_store_dwordx4 v[124:125], v[120:123], off nt
	s_and_saveexec_b64 s[22:23], s[38:39]
	s_cbranch_execz .LBB0_945
	v_lshlrev_b64 v[120:121], 7, v[156:157]
	v_lshl_add_u64 v[120:121], s[6:7], 0, v[120:121]
	v_lshl_add_u64 v[120:121], s[18:19], 2, v[120:121]
	s_lshl_b32 s4, s53, 2
	v_lshl_add_u64 v[120:121], v[120:121], 0, s[4:5]
	s_waitcnt lgkmcnt(0)
	v_add_f32_e32 v118, v118, v119
	global_store_dword v[120:121], v118, off nt
.LBB0_945:
	s_or_b64 exec, exec, s[22:23]
	v_lshlrev_b32_e32 v118, 16, v136
	v_add_f32_e32 v110, v110, v118
	v_and_b32_e32 v118, 0xffff0000, v136
	v_add_f32_e32 v111, v111, v118
	v_lshlrev_b32_e32 v118, 16, v137
	v_add_f32_e32 v112, v112, v118
	v_and_b32_e32 v118, 0xffff0000, v137
	v_add_f32_e32 v113, v113, v118
	v_lshlrev_b32_e32 v118, 16, v138
	v_add_f32_e32 v106, v106, v118
	v_and_b32_e32 v118, 0xffff0000, v138
	v_add_f32_e32 v107, v107, v118
	v_lshlrev_b32_e32 v118, 16, v139
	v_add_f32_e32 v108, v108, v118
	v_and_b32_e32 v118, 0xffff0000, v139
	v_add_f32_e32 v109, v109, v118
	v_cvt_pk_bf16_f32 v118, v110, v111
	s_waitcnt lgkmcnt(0)
	v_cvt_pk_bf16_f32 v119, v112, v113
	v_cvt_pk_bf16_f32 v120, v106, v107
	v_mul_f32_e32 v107, v107, v107
	v_fmac_f32_e32 v107, v106, v106
	v_mul_f32_e32 v106, v109, v109
	v_fmac_f32_e32 v106, v108, v108
	v_add_f32_e32 v106, v107, v106
	v_lshlrev_b32_e32 v107, 16, v132
	v_add_f32_e32 v86, v86, v107
	v_and_b32_e32 v107, 0xffff0000, v132
	v_add_f32_e32 v87, v87, v107
	v_lshlrev_b32_e32 v107, 16, v133
	v_add_f32_e32 v88, v88, v107
	v_and_b32_e32 v107, 0xffff0000, v133
	v_add_f32_e32 v89, v89, v107
	v_lshlrev_b32_e32 v107, 16, v134
	v_add_f32_e32 v82, v82, v107
	v_and_b32_e32 v107, 0xffff0000, v134
	v_add_f32_e32 v83, v83, v107
	v_lshlrev_b32_e32 v107, 16, v135
	v_add_f32_e32 v84, v84, v107
	v_and_b32_e32 v107, 0xffff0000, v135
	v_cvt_pk_bf16_f32 v121, v108, v109
	v_mul_f32_e32 v111, v111, v111
	v_add_f32_e32 v85, v85, v107
	v_cvt_pk_bf16_f32 v107, v86, v87
	v_cvt_pk_bf16_f32 v108, v88, v89
	v_cvt_pk_bf16_f32 v109, v82, v83
	v_mul_f32_e32 v87, v87, v87
	v_mul_f32_e32 v83, v83, v83
	v_fmac_f32_e32 v111, v110, v110
	v_mul_f32_e32 v110, v113, v113
	v_fmac_f32_e32 v87, v86, v86
	v_mul_f32_e32 v86, v89, v89
	v_fmac_f32_e32 v83, v82, v82
	v_mul_f32_e32 v82, v85, v85
	v_fmac_f32_e32 v110, v112, v112
	v_fmac_f32_e32 v86, v88, v88
	v_fmac_f32_e32 v82, v84, v84
	v_add_f32_e32 v110, v111, v110
	v_add_f32_e32 v86, v87, v86
	v_add_f32_e32 v82, v83, v82
	v_add_f32_e32 v106, v110, v106
	v_add_f32_e32 v82, v86, v82
	v_add_f32_e32 v88, v106, v82
	ds_bpermute_b32 v113, v116, v88
	v_cvt_pk_bf16_f32 v110, v84, v85
	s_add_u32 s22, s20, 0x10000
	v_cndmask_b32_e64 v82, v110, v121, s[36:37]
	v_cndmask_b32_e64 v83, v109, v120, s[36:37]
	v_cndmask_b32_e64 v84, v108, v119, s[36:37]
	v_cndmask_b32_e64 v85, v107, v118, s[36:37]
	v_mov_b32_e32 v89, v115
	v_mov_b32_e32 v106, v115
	v_mov_b32_e32 v111, v115
	v_mov_b32_e32 v112, v115
	s_addc_u32 s23, s21, 0
	v_mov_b32_dpp v89, v85 quad_perm:[1,0,3,2] row_mask:0xf bank_mask:0xf
	v_mov_b32_dpp v106, v84 quad_perm:[1,0,3,2] row_mask:0xf bank_mask:0xf
	v_mov_b32_dpp v111, v83 quad_perm:[1,0,3,2] row_mask:0xf bank_mask:0xf
	v_mov_b32_dpp v112, v82 quad_perm:[1,0,3,2] row_mask:0xf bank_mask:0xf
	v_cndmask_b32_e64 v82, v118, v89, s[36:37]
	v_cndmask_b32_e64 v83, v119, v106, s[36:37]
	v_cndmask_b32_e64 v84, v120, v111, s[36:37]
	v_cndmask_b32_e64 v85, v121, v112, s[36:37]
	v_lshl_add_u64 v[86:87], v[146:147], 1, s[22:23]
	global_store_dwordx4 v[86:87], v[82:85], off nt
	v_cndmask_b32_e64 v86, v111, v109, s[36:37]
	v_cndmask_b32_e64 v87, v112, v110, s[36:37]
	s_waitcnt lgkmcnt(0)
	v_add_f32_e32 v82, v88, v113
	ds_bpermute_b32 v83, v117, v82
	v_cndmask_b32_e64 v84, v89, v107, s[36:37]
	v_cndmask_b32_e64 v85, v106, v108, s[36:37]
	v_lshl_add_u64 v[88:89], v[148:149], 1, s[22:23]
	global_store_dwordx4 v[88:89], v[84:87], off nt
	s_and_saveexec_b64 s[22:23], s[38:39]
	s_cbranch_execz .LBB0_947
	s_waitcnt lgkmcnt(0)
	v_add_f32_e32 v84, v82, v83
	v_or_b32_e32 v82, 16, v156
	v_ashrrev_i32_e32 v83, 31, v82
	v_lshlrev_b64 v[82:83], 7, v[82:83]
	v_lshl_add_u64 v[82:83], s[6:7], 0, v[82:83]
	v_lshl_add_u64 v[82:83], s[18:19], 2, v[82:83]
	s_lshl_b32 s4, s53, 2
	v_lshl_add_u64 v[82:83], v[82:83], 0, s[4:5]
	global_store_dword v[82:83], v84, off nt
.LBB0_947:
	s_or_b64 exec, exec, s[22:23]
	v_add_co_u32_e32 v82, vcc, 0x20000, v158
	s_add_u32 s22, s20, 0x20000
	s_waitcnt lgkmcnt(0)
	v_addc_co_u32_e32 v83, vcc, 0, v159, vcc
	global_load_dwordx4 v[106:109], v[82:83], off
	global_load_dwordx4 v[110:113], v[82:83], off offset:64
	v_add_co_u32_e32 v82, vcc, 0x30000, v158
	s_addc_u32 s23, s21, 0
	s_nop 0
	v_addc_co_u32_e32 v83, vcc, 0, v159, vcc
	global_load_dwordx4 v[86:89], v[82:83], off
	s_nop 0
	global_load_dwordx4 v[82:85], v[82:83], off offset:64
	s_waitcnt vmcnt(3)
	v_lshlrev_b32_e32 v118, 16, v106
	v_and_b32_e32 v106, 0xffff0000, v106
	v_add_f32_e32 v103, v103, v106
	v_lshlrev_b32_e32 v106, 16, v107
	v_add_f32_e32 v104, v104, v106
	v_and_b32_e32 v106, 0xffff0000, v107
	v_add_f32_e32 v105, v105, v106
	v_lshlrev_b32_e32 v106, 16, v108
	v_add_f32_e32 v106, v98, v106
	v_and_b32_e32 v98, 0xffff0000, v108
	v_add_f32_e32 v107, v99, v98
	v_lshlrev_b32_e32 v98, 16, v109
	v_add_f32_e32 v108, v100, v98
	v_and_b32_e32 v98, 0xffff0000, v109
	v_add_f32_e32 v102, v102, v118
	v_add_f32_e32 v109, v101, v98
	v_cvt_pk_bf16_f32 v98, v102, v103
	v_mul_f32_e32 v103, v103, v103
	v_fmac_f32_e32 v103, v102, v102
	v_mul_f32_e32 v102, v105, v105
	v_fmac_f32_e32 v102, v104, v104
	v_cvt_pk_bf16_f32 v99, v104, v105
	v_add_f32_e32 v102, v103, v102
	v_mul_f32_e32 v103, v107, v107
	v_mul_f32_e32 v104, v109, v109
	v_fmac_f32_e32 v103, v106, v106
	v_fmac_f32_e32 v104, v108, v108
	v_add_f32_e32 v103, v103, v104
	v_add_f32_e32 v102, v102, v103
	s_waitcnt vmcnt(2)
	v_lshlrev_b32_e32 v103, 16, v110
	v_add_f32_e32 v103, v94, v103
	v_and_b32_e32 v94, 0xffff0000, v110
	v_add_f32_e32 v95, v95, v94
	v_lshlrev_b32_e32 v94, 16, v111
	v_add_f32_e32 v96, v96, v94
	v_and_b32_e32 v94, 0xffff0000, v111
	v_add_f32_e32 v97, v97, v94
	v_lshlrev_b32_e32 v94, 16, v112
	v_add_f32_e32 v90, v90, v94
	v_and_b32_e32 v94, 0xffff0000, v112
	v_add_f32_e32 v104, v91, v94
	v_lshlrev_b32_e32 v91, 16, v113
	v_add_f32_e32 v105, v92, v91
	v_and_b32_e32 v91, 0xffff0000, v113
	v_cvt_pk_bf16_f32 v100, v106, v107
	v_cvt_pk_bf16_f32 v101, v108, v109
	v_add_f32_e32 v106, v93, v91
	v_cvt_pk_bf16_f32 v91, v103, v95
	v_cvt_pk_bf16_f32 v92, v96, v97
	v_mul_f32_e32 v97, v97, v97
	v_fmac_f32_e32 v97, v96, v96
	v_mul_f32_e32 v96, v104, v104
	v_cvt_pk_bf16_f32 v93, v90, v104
	v_mul_f32_e32 v95, v95, v95
	v_fmac_f32_e32 v96, v90, v90
	v_mul_f32_e32 v90, v106, v106
	v_fmac_f32_e32 v95, v103, v103
	v_fmac_f32_e32 v90, v105, v105
	v_add_f32_e32 v95, v95, v97
	v_add_f32_e32 v90, v96, v90
	v_add_f32_e32 v90, v95, v90
	v_add_f32_e32 v90, v102, v90
	v_cndmask_b32_e64 v102, v91, v98, s[36:37]
	v_mov_b32_e32 v103, v115
	v_cvt_pk_bf16_f32 v94, v105, v106
	v_cndmask_b32_e64 v96, v93, v100, s[36:37]
	v_cndmask_b32_e64 v95, v94, v101, s[36:37]
	v_cndmask_b32_e64 v97, v92, v99, s[36:37]
	v_mov_b32_dpp v103, v102 quad_perm:[1,0,3,2] row_mask:0xf bank_mask:0xf
	v_mov_b32_e32 v102, v115
	v_mov_b32_e32 v104, v115
	v_mov_b32_e32 v105, v115
	v_mov_b32_dpp v102, v97 quad_perm:[1,0,3,2] row_mask:0xf bank_mask:0xf
	v_mov_b32_dpp v104, v96 quad_perm:[1,0,3,2] row_mask:0xf bank_mask:0xf
	v_mov_b32_dpp v105, v95 quad_perm:[1,0,3,2] row_mask:0xf bank_mask:0xf
	v_cndmask_b32_e64 v96, v98, v103, s[36:37]
	v_cndmask_b32_e64 v97, v99, v102, s[36:37]
	v_cndmask_b32_e64 v98, v100, v104, s[36:37]
	v_cndmask_b32_e64 v99, v101, v105, s[36:37]
	v_lshl_add_u64 v[100:101], v[146:147], 1, s[22:23]
	global_store_dwordx4 v[100:101], v[96:99], off nt
	s_nop 1
	v_cndmask_b32_e64 v96, v103, v91, s[36:37]
	ds_bpermute_b32 v91, v116, v90
	v_cndmask_b32_e64 v97, v102, v92, s[36:37]
	v_cndmask_b32_e64 v98, v104, v93, s[36:37]
	v_cndmask_b32_e64 v99, v105, v94, s[36:37]
	v_lshl_add_u64 v[92:93], v[148:149], 1, s[22:23]
	s_waitcnt lgkmcnt(0)
	v_add_f32_e32 v90, v90, v91
	ds_bpermute_b32 v91, v117, v90
	global_store_dwordx4 v[92:93], v[96:99], off nt
	s_and_saveexec_b64 s[22:23], s[38:39]
	s_cbranch_execz .LBB0_949
	s_waitcnt lgkmcnt(0)
	v_add_f32_e32 v92, v90, v91
	v_or_b32_e32 v90, 32, v156
	v_ashrrev_i32_e32 v91, 31, v90
	v_lshlrev_b64 v[90:91], 7, v[90:91]
	v_lshl_add_u64 v[90:91], s[6:7], 0, v[90:91]
	v_lshl_add_u64 v[90:91], s[18:19], 2, v[90:91]
	s_lshl_b32 s4, s53, 2
	v_lshl_add_u64 v[90:91], v[90:91], 0, s[4:5]
	global_store_dword v[90:91], v92, off nt
.LBB0_949:
	s_or_b64 exec, exec, s[22:23]
	s_waitcnt vmcnt(3)
	v_lshlrev_b32_e32 v90, 16, v86
	v_and_b32_e32 v86, 0xffff0000, v86
	v_add_f32_e32 v79, v79, v86
	v_lshlrev_b32_e32 v86, 16, v87
	v_add_f32_e32 v80, v80, v86
	v_and_b32_e32 v86, 0xffff0000, v87
	v_add_f32_e32 v81, v81, v86
	v_lshlrev_b32_e32 v86, 16, v88
	v_add_f32_e32 v74, v74, v86
	v_and_b32_e32 v86, 0xffff0000, v88
	v_add_f32_e32 v75, v75, v86
	v_lshlrev_b32_e32 v86, 16, v89
	v_add_f32_e32 v76, v76, v86
	v_and_b32_e32 v86, 0xffff0000, v89
	v_add_f32_e32 v78, v78, v90
	v_add_f32_e32 v77, v77, v86
	v_cvt_pk_bf16_f32 v86, v78, v79
	v_cvt_pk_bf16_f32 v87, v80, v81
	v_cvt_pk_bf16_f32 v88, v74, v75
	v_mul_f32_e32 v75, v75, v75
	v_fmac_f32_e32 v75, v74, v74
	v_mul_f32_e32 v74, v77, v77
	v_fmac_f32_e32 v74, v76, v76
	v_add_f32_e32 v74, v75, v74
	s_waitcnt vmcnt(2)
	v_lshlrev_b32_e32 v75, 16, v82
	v_add_f32_e32 v70, v70, v75
	v_and_b32_e32 v75, 0xffff0000, v82
	v_add_f32_e32 v71, v71, v75
	v_lshlrev_b32_e32 v75, 16, v83
	v_add_f32_e32 v72, v72, v75
	v_and_b32_e32 v75, 0xffff0000, v83
	v_add_f32_e32 v73, v73, v75
	v_lshlrev_b32_e32 v75, 16, v84
	v_add_f32_e32 v66, v66, v75
	v_and_b32_e32 v75, 0xffff0000, v84
	v_add_f32_e32 v67, v67, v75
	v_lshlrev_b32_e32 v75, 16, v85
	v_add_f32_e32 v68, v68, v75
	v_and_b32_e32 v75, 0xffff0000, v85
	v_cvt_pk_bf16_f32 v89, v76, v77
	v_mul_f32_e32 v79, v79, v79
	v_add_f32_e32 v69, v69, v75
	v_cvt_pk_bf16_f32 v75, v70, v71
	v_cvt_pk_bf16_f32 v76, v72, v73
	v_cvt_pk_bf16_f32 v77, v66, v67
	v_mul_f32_e32 v71, v71, v71
	v_mul_f32_e32 v67, v67, v67
	v_fmac_f32_e32 v79, v78, v78
	v_mul_f32_e32 v78, v81, v81
	v_fmac_f32_e32 v71, v70, v70
	v_mul_f32_e32 v70, v73, v73
	v_fmac_f32_e32 v67, v66, v66
	v_mul_f32_e32 v66, v69, v69
	v_fmac_f32_e32 v78, v80, v80
	v_fmac_f32_e32 v70, v72, v72
	v_fmac_f32_e32 v66, v68, v68
	v_add_f32_e32 v78, v79, v78
	v_add_f32_e32 v70, v71, v70
	v_add_f32_e32 v66, v67, v66
	v_add_f32_e32 v74, v78, v74
	v_add_f32_e32 v66, v70, v66
	v_add_f32_e32 v72, v74, v66
	ds_bpermute_b32 v81, v116, v72
	v_cvt_pk_bf16_f32 v78, v68, v69
	s_add_u32 s22, s20, 0x30000
	v_cndmask_b32_e64 v66, v78, v89, s[36:37]
	v_cndmask_b32_e64 v67, v77, v88, s[36:37]
	v_cndmask_b32_e64 v68, v76, v87, s[36:37]
	v_cndmask_b32_e64 v69, v75, v86, s[36:37]
	v_mov_b32_e32 v73, v115
	v_mov_b32_e32 v74, v115
	v_mov_b32_e32 v79, v115
	v_mov_b32_e32 v80, v115
	s_addc_u32 s23, s21, 0
	v_mov_b32_dpp v73, v69 quad_perm:[1,0,3,2] row_mask:0xf bank_mask:0xf
	v_mov_b32_dpp v74, v68 quad_perm:[1,0,3,2] row_mask:0xf bank_mask:0xf
	v_mov_b32_dpp v79, v67 quad_perm:[1,0,3,2] row_mask:0xf bank_mask:0xf
	v_mov_b32_dpp v80, v66 quad_perm:[1,0,3,2] row_mask:0xf bank_mask:0xf
	v_cndmask_b32_e64 v66, v86, v73, s[36:37]
	v_cndmask_b32_e64 v67, v87, v74, s[36:37]
	v_cndmask_b32_e64 v68, v88, v79, s[36:37]
	v_cndmask_b32_e64 v69, v89, v80, s[36:37]
	v_lshl_add_u64 v[70:71], v[146:147], 1, s[22:23]
	global_store_dwordx4 v[70:71], v[66:69], off nt
	v_cndmask_b32_e64 v70, v79, v77, s[36:37]
	v_cndmask_b32_e64 v71, v80, v78, s[36:37]
	s_waitcnt lgkmcnt(0)
	v_add_f32_e32 v66, v72, v81
	ds_bpermute_b32 v67, v117, v66
	v_cndmask_b32_e64 v68, v73, v75, s[36:37]
	v_cndmask_b32_e64 v69, v74, v76, s[36:37]
	v_lshl_add_u64 v[72:73], v[148:149], 1, s[22:23]
	global_store_dwordx4 v[72:73], v[68:71], off nt
	s_and_saveexec_b64 s[22:23], s[38:39]
	s_cbranch_execz .LBB0_951
	s_waitcnt lgkmcnt(0)
	v_add_f32_e32 v68, v66, v67
	v_or_b32_e32 v66, 48, v156
	v_ashrrev_i32_e32 v67, 31, v66
	v_lshlrev_b64 v[66:67], 7, v[66:67]
	v_lshl_add_u64 v[66:67], s[6:7], 0, v[66:67]
	v_lshl_add_u64 v[66:67], s[18:19], 2, v[66:67]
	s_lshl_b32 s4, s53, 2
	v_lshl_add_u64 v[66:67], v[66:67], 0, s[4:5]
	global_store_dword v[66:67], v68, off nt
.LBB0_951:
	s_or_b64 exec, exec, s[22:23]
	v_add_co_u32_e32 v66, vcc, 0x80000, v158
	s_add_u32 s22, s20, 0x80000
	s_waitcnt lgkmcnt(0)
	v_addc_co_u32_e32 v67, vcc, 0, v159, vcc
	global_load_dwordx4 v[74:77], v[66:67], off
	global_load_dwordx4 v[78:81], v[66:67], off offset:64
	v_add_co_u32_e32 v66, vcc, 0x90000, v158
	s_addc_u32 s23, s21, 0
	s_nop 0
	v_addc_co_u32_e32 v67, vcc, 0, v159, vcc
	global_load_dwordx4 v[70:73], v[66:67], off
	s_nop 0
	global_load_dwordx4 v[66:69], v[66:67], off offset:64
	s_waitcnt vmcnt(3)
	v_lshlrev_b32_e32 v82, 16, v74
	v_and_b32_e32 v74, 0xffff0000, v74
	v_add_f32_e32 v63, v63, v74
	v_lshlrev_b32_e32 v74, 16, v75
	v_add_f32_e32 v64, v64, v74
	v_and_b32_e32 v74, 0xffff0000, v75
	v_add_f32_e32 v65, v65, v74
	v_lshlrev_b32_e32 v74, 16, v76
	v_add_f32_e32 v74, v58, v74
	v_and_b32_e32 v58, 0xffff0000, v76
	v_add_f32_e32 v75, v59, v58
	v_lshlrev_b32_e32 v58, 16, v77
	v_add_f32_e32 v76, v60, v58
	v_and_b32_e32 v58, 0xffff0000, v77
	v_add_f32_e32 v62, v62, v82
	v_add_f32_e32 v77, v61, v58
	v_cvt_pk_bf16_f32 v58, v62, v63
	v_mul_f32_e32 v63, v63, v63
	v_fmac_f32_e32 v63, v62, v62
	v_mul_f32_e32 v62, v65, v65
	v_fmac_f32_e32 v62, v64, v64
	v_cvt_pk_bf16_f32 v59, v64, v65
	v_add_f32_e32 v62, v63, v62
	v_mul_f32_e32 v63, v75, v75
	v_mul_f32_e32 v64, v77, v77
	v_fmac_f32_e32 v63, v74, v74
	v_fmac_f32_e32 v64, v76, v76
	v_add_f32_e32 v63, v63, v64
	v_add_f32_e32 v62, v62, v63
	s_waitcnt vmcnt(2)
	v_lshlrev_b32_e32 v63, 16, v78
	v_add_f32_e32 v63, v54, v63
	v_and_b32_e32 v54, 0xffff0000, v78
	v_add_f32_e32 v55, v55, v54
	v_lshlrev_b32_e32 v54, 16, v79
	v_add_f32_e32 v56, v56, v54
	v_and_b32_e32 v54, 0xffff0000, v79
	v_add_f32_e32 v57, v57, v54
	v_lshlrev_b32_e32 v54, 16, v80
	v_add_f32_e32 v50, v50, v54
	v_and_b32_e32 v54, 0xffff0000, v80
	v_add_f32_e32 v64, v51, v54
	v_lshlrev_b32_e32 v51, 16, v81
	v_add_f32_e32 v65, v52, v51
	v_and_b32_e32 v51, 0xffff0000, v81
	v_cvt_pk_bf16_f32 v60, v74, v75
	v_cvt_pk_bf16_f32 v61, v76, v77
	v_add_f32_e32 v74, v53, v51
	v_cvt_pk_bf16_f32 v51, v63, v55
	v_cvt_pk_bf16_f32 v52, v56, v57
	v_mul_f32_e32 v57, v57, v57
	v_fmac_f32_e32 v57, v56, v56
	v_mul_f32_e32 v56, v64, v64
	v_cvt_pk_bf16_f32 v53, v50, v64
	v_mul_f32_e32 v55, v55, v55
	v_fmac_f32_e32 v56, v50, v50
	v_mul_f32_e32 v50, v74, v74
	v_fmac_f32_e32 v55, v63, v63
	v_fmac_f32_e32 v50, v65, v65
	v_add_f32_e32 v55, v55, v57
	v_add_f32_e32 v50, v56, v50
	v_add_f32_e32 v50, v55, v50
	v_add_f32_e32 v50, v62, v50
	v_cndmask_b32_e64 v62, v51, v58, s[36:37]
	v_mov_b32_e32 v63, v115
	v_cvt_pk_bf16_f32 v54, v65, v74
	v_cndmask_b32_e64 v56, v53, v60, s[36:37]
	v_cndmask_b32_e64 v55, v54, v61, s[36:37]
	v_cndmask_b32_e64 v57, v52, v59, s[36:37]
	v_mov_b32_dpp v63, v62 quad_perm:[1,0,3,2] row_mask:0xf bank_mask:0xf
	v_mov_b32_e32 v62, v115
	v_mov_b32_e32 v64, v115
	v_mov_b32_e32 v65, v115
	v_mov_b32_dpp v62, v57 quad_perm:[1,0,3,2] row_mask:0xf bank_mask:0xf
	v_mov_b32_dpp v64, v56 quad_perm:[1,0,3,2] row_mask:0xf bank_mask:0xf
	v_mov_b32_dpp v65, v55 quad_perm:[1,0,3,2] row_mask:0xf bank_mask:0xf
	v_cndmask_b32_e64 v56, v58, v63, s[36:37]
	v_cndmask_b32_e64 v57, v59, v62, s[36:37]
	v_cndmask_b32_e64 v58, v60, v64, s[36:37]
	v_cndmask_b32_e64 v59, v61, v65, s[36:37]
	v_lshl_add_u64 v[60:61], v[146:147], 1, s[22:23]
	global_store_dwordx4 v[60:61], v[56:59], off nt
	s_nop 1
	v_cndmask_b32_e64 v56, v63, v51, s[36:37]
	ds_bpermute_b32 v51, v116, v50
	v_cndmask_b32_e64 v57, v62, v52, s[36:37]
	v_cndmask_b32_e64 v58, v64, v53, s[36:37]
	v_cndmask_b32_e64 v59, v65, v54, s[36:37]
	v_lshl_add_u64 v[52:53], v[148:149], 1, s[22:23]
	s_waitcnt lgkmcnt(0)
	v_add_f32_e32 v50, v50, v51
	ds_bpermute_b32 v51, v117, v50
	global_store_dwordx4 v[52:53], v[56:59], off nt
	s_and_saveexec_b64 s[22:23], s[38:39]
	s_cbranch_execz .LBB0_953
	s_waitcnt lgkmcnt(0)
	v_add_f32_e32 v52, v50, v51
	v_lshlrev_b64 v[50:51], 7, v[156:157]
	v_lshl_add_u64 v[50:51], s[6:7], 0, v[50:51]
	v_lshl_add_u64 v[50:51], s[18:19], 2, v[50:51]
	s_lshl_b32 s4, s53, 2
	v_lshl_add_u64 v[50:51], v[50:51], 0, s[4:5]
	v_add_co_u32_e32 v50, vcc, 0x4000, v50
	s_nop 1
	v_addc_co_u32_e32 v51, vcc, 0, v51, vcc
	global_store_dword v[50:51], v52, off nt
.LBB0_953:
	s_or_b64 exec, exec, s[22:23]
	s_waitcnt vmcnt(3)
	v_lshlrev_b32_e32 v50, 16, v70
	v_add_f32_e32 v46, v46, v50
	v_and_b32_e32 v50, 0xffff0000, v70
	v_add_f32_e32 v47, v47, v50
	v_lshlrev_b32_e32 v50, 16, v71
	v_add_f32_e32 v48, v48, v50
	v_and_b32_e32 v50, 0xffff0000, v71
	v_add_f32_e32 v49, v49, v50
	v_lshlrev_b32_e32 v50, 16, v72
	v_add_f32_e32 v42, v42, v50
	v_and_b32_e32 v50, 0xffff0000, v72
	v_add_f32_e32 v43, v43, v50
	v_lshlrev_b32_e32 v50, 16, v73
	v_add_f32_e32 v44, v44, v50
	v_and_b32_e32 v50, 0xffff0000, v73
	v_add_f32_e32 v45, v45, v50
	v_cvt_pk_bf16_f32 v50, v46, v47
	s_waitcnt lgkmcnt(0)
	v_cvt_pk_bf16_f32 v51, v48, v49
	v_cvt_pk_bf16_f32 v52, v42, v43
	v_mul_f32_e32 v43, v43, v43
	v_fmac_f32_e32 v43, v42, v42
	v_mul_f32_e32 v42, v45, v45
	v_fmac_f32_e32 v42, v44, v44
	v_add_f32_e32 v42, v43, v42
	s_waitcnt vmcnt(2)
	v_lshlrev_b32_e32 v43, 16, v66
	v_add_f32_e32 v38, v38, v43
	v_and_b32_e32 v43, 0xffff0000, v66
	v_add_f32_e32 v39, v39, v43
	v_lshlrev_b32_e32 v43, 16, v67
	v_add_f32_e32 v40, v40, v43
	v_and_b32_e32 v43, 0xffff0000, v67
	v_add_f32_e32 v41, v41, v43
	v_lshlrev_b32_e32 v43, 16, v68
	v_add_f32_e32 v34, v34, v43
	v_and_b32_e32 v43, 0xffff0000, v68
	v_add_f32_e32 v35, v35, v43
	v_lshlrev_b32_e32 v43, 16, v69
	v_add_f32_e32 v36, v36, v43
	v_and_b32_e32 v43, 0xffff0000, v69
	v_cvt_pk_bf16_f32 v53, v44, v45
	v_mul_f32_e32 v47, v47, v47
	v_add_f32_e32 v37, v37, v43
	v_cvt_pk_bf16_f32 v43, v38, v39
	v_cvt_pk_bf16_f32 v44, v40, v41
	v_cvt_pk_bf16_f32 v45, v34, v35
	v_mul_f32_e32 v39, v39, v39
	v_mul_f32_e32 v35, v35, v35
	v_fmac_f32_e32 v47, v46, v46
	v_mul_f32_e32 v46, v49, v49
	v_fmac_f32_e32 v39, v38, v38
	v_mul_f32_e32 v38, v41, v41
	v_fmac_f32_e32 v35, v34, v34
	v_mul_f32_e32 v34, v37, v37
	v_fmac_f32_e32 v46, v48, v48
	v_fmac_f32_e32 v38, v40, v40
	v_fmac_f32_e32 v34, v36, v36
	v_add_f32_e32 v46, v47, v46
	v_add_f32_e32 v38, v39, v38
	v_add_f32_e32 v34, v35, v34
	v_add_f32_e32 v42, v46, v42
	v_add_f32_e32 v34, v38, v34
	v_add_f32_e32 v40, v42, v34
	ds_bpermute_b32 v49, v116, v40
	v_cvt_pk_bf16_f32 v46, v36, v37
	s_add_u32 s22, s20, 0x90000
	v_cndmask_b32_e64 v34, v46, v53, s[36:37]
	v_cndmask_b32_e64 v35, v45, v52, s[36:37]
	v_cndmask_b32_e64 v36, v44, v51, s[36:37]
	v_cndmask_b32_e64 v37, v43, v50, s[36:37]
	v_mov_b32_e32 v41, v115
	v_mov_b32_e32 v42, v115
	v_mov_b32_e32 v47, v115
	v_mov_b32_e32 v48, v115
	s_addc_u32 s23, s21, 0
	v_mov_b32_dpp v41, v37 quad_perm:[1,0,3,2] row_mask:0xf bank_mask:0xf
	v_mov_b32_dpp v42, v36 quad_perm:[1,0,3,2] row_mask:0xf bank_mask:0xf
	v_mov_b32_dpp v47, v35 quad_perm:[1,0,3,2] row_mask:0xf bank_mask:0xf
	v_mov_b32_dpp v48, v34 quad_perm:[1,0,3,2] row_mask:0xf bank_mask:0xf
	v_cndmask_b32_e64 v34, v50, v41, s[36:37]
	v_cndmask_b32_e64 v35, v51, v42, s[36:37]
	v_cndmask_b32_e64 v36, v52, v47, s[36:37]
	v_cndmask_b32_e64 v37, v53, v48, s[36:37]
	v_lshl_add_u64 v[38:39], v[146:147], 1, s[22:23]
	global_store_dwordx4 v[38:39], v[34:37], off nt
	v_cndmask_b32_e64 v38, v47, v45, s[36:37]
	v_cndmask_b32_e64 v39, v48, v46, s[36:37]
	s_waitcnt lgkmcnt(0)
	v_add_f32_e32 v34, v40, v49
	ds_bpermute_b32 v35, v117, v34
	v_cndmask_b32_e64 v36, v41, v43, s[36:37]
	v_cndmask_b32_e64 v37, v42, v44, s[36:37]
	v_lshl_add_u64 v[40:41], v[148:149], 1, s[22:23]
	global_store_dwordx4 v[40:41], v[36:39], off nt
	s_and_saveexec_b64 s[22:23], s[38:39]
	s_cbranch_execz .LBB0_955
	s_waitcnt lgkmcnt(0)
	v_add_f32_e32 v36, v34, v35
	v_lshlrev_b64 v[34:35], 7, v[156:157]
	v_lshl_add_u64 v[34:35], s[6:7], 0, v[34:35]
	v_lshl_add_u64 v[34:35], s[18:19], 2, v[34:35]
	s_lshl_b32 s4, s53, 2
	v_lshl_add_u64 v[34:35], v[34:35], 0, s[4:5]
	v_add_co_u32_e32 v34, vcc, 0x4000, v34
	s_nop 1
	v_addc_co_u32_e32 v35, vcc, 0, v35, vcc
	global_store_dword v[34:35], v36, off offset:2048 nt
.LBB0_955:
	s_or_b64 exec, exec, s[22:23]
	v_add_co_u32_e32 v34, vcc, 0xa0000, v158
	s_add_u32 s22, s20, 0xa0000
	s_waitcnt lgkmcnt(0)
	v_addc_co_u32_e32 v35, vcc, 0, v159, vcc
	global_load_dwordx4 v[42:45], v[34:35], off
	global_load_dwordx4 v[46:49], v[34:35], off offset:64
	v_add_co_u32_e32 v34, vcc, 0xb0000, v158
	s_addc_u32 s23, s21, 0
	s_nop 0
	v_addc_co_u32_e32 v35, vcc, 0, v159, vcc
	global_load_dwordx4 v[38:41], v[34:35], off
	s_nop 0
	global_load_dwordx4 v[34:37], v[34:35], off offset:64
	s_waitcnt vmcnt(3)
	v_lshlrev_b32_e32 v50, 16, v42
	v_and_b32_e32 v42, 0xffff0000, v42
	v_add_f32_e32 v31, v31, v42
	v_lshlrev_b32_e32 v42, 16, v43
	v_add_f32_e32 v32, v32, v42
	v_and_b32_e32 v42, 0xffff0000, v43
	v_add_f32_e32 v33, v33, v42
	v_lshlrev_b32_e32 v42, 16, v44
	v_add_f32_e32 v42, v26, v42
	v_and_b32_e32 v26, 0xffff0000, v44
	v_add_f32_e32 v43, v27, v26
	v_lshlrev_b32_e32 v26, 16, v45
	v_add_f32_e32 v44, v28, v26
	v_and_b32_e32 v26, 0xffff0000, v45
	v_add_f32_e32 v30, v30, v50
	v_add_f32_e32 v45, v29, v26
	v_cvt_pk_bf16_f32 v26, v30, v31
	v_mul_f32_e32 v31, v31, v31
	v_fmac_f32_e32 v31, v30, v30
	v_mul_f32_e32 v30, v33, v33
	v_fmac_f32_e32 v30, v32, v32
	v_cvt_pk_bf16_f32 v27, v32, v33
	v_add_f32_e32 v30, v31, v30
	v_mul_f32_e32 v31, v43, v43
	v_mul_f32_e32 v32, v45, v45
	v_fmac_f32_e32 v31, v42, v42
	v_fmac_f32_e32 v32, v44, v44
	v_add_f32_e32 v31, v31, v32
	v_add_f32_e32 v30, v30, v31
	s_waitcnt vmcnt(2)
	v_lshlrev_b32_e32 v31, 16, v46
	v_add_f32_e32 v31, v22, v31
	v_and_b32_e32 v22, 0xffff0000, v46
	v_add_f32_e32 v23, v23, v22
	v_lshlrev_b32_e32 v22, 16, v47
	v_add_f32_e32 v24, v24, v22
	v_and_b32_e32 v22, 0xffff0000, v47
	v_add_f32_e32 v25, v25, v22
	v_lshlrev_b32_e32 v22, 16, v48
	v_add_f32_e32 v18, v18, v22
	v_and_b32_e32 v22, 0xffff0000, v48
	v_add_f32_e32 v32, v19, v22
	v_lshlrev_b32_e32 v19, 16, v49
	v_add_f32_e32 v33, v20, v19
	v_and_b32_e32 v19, 0xffff0000, v49
	v_cvt_pk_bf16_f32 v28, v42, v43
	v_cvt_pk_bf16_f32 v29, v44, v45
	v_add_f32_e32 v42, v21, v19
	v_cvt_pk_bf16_f32 v19, v31, v23
	v_cvt_pk_bf16_f32 v20, v24, v25
	v_mul_f32_e32 v25, v25, v25
	v_fmac_f32_e32 v25, v24, v24
	v_mul_f32_e32 v24, v32, v32
	v_cvt_pk_bf16_f32 v21, v18, v32
	v_mul_f32_e32 v23, v23, v23
	v_fmac_f32_e32 v24, v18, v18
	v_mul_f32_e32 v18, v42, v42
	v_fmac_f32_e32 v23, v31, v31
	v_fmac_f32_e32 v18, v33, v33
	v_add_f32_e32 v23, v23, v25
	v_add_f32_e32 v18, v24, v18
	v_add_f32_e32 v18, v23, v18
	v_add_f32_e32 v18, v30, v18
	v_cndmask_b32_e64 v30, v19, v26, s[36:37]
	v_mov_b32_e32 v31, v115
	v_cvt_pk_bf16_f32 v22, v33, v42
	v_cndmask_b32_e64 v24, v21, v28, s[36:37]
	v_cndmask_b32_e64 v23, v22, v29, s[36:37]
	v_cndmask_b32_e64 v25, v20, v27, s[36:37]
	v_mov_b32_dpp v31, v30 quad_perm:[1,0,3,2] row_mask:0xf bank_mask:0xf
	v_mov_b32_e32 v30, v115
	v_mov_b32_e32 v32, v115
	v_mov_b32_e32 v33, v115
	v_mov_b32_dpp v30, v25 quad_perm:[1,0,3,2] row_mask:0xf bank_mask:0xf
	v_mov_b32_dpp v32, v24 quad_perm:[1,0,3,2] row_mask:0xf bank_mask:0xf
	v_mov_b32_dpp v33, v23 quad_perm:[1,0,3,2] row_mask:0xf bank_mask:0xf
	v_cndmask_b32_e64 v24, v26, v31, s[36:37]
	v_cndmask_b32_e64 v25, v27, v30, s[36:37]
	v_cndmask_b32_e64 v26, v28, v32, s[36:37]
	v_cndmask_b32_e64 v27, v29, v33, s[36:37]
	v_lshl_add_u64 v[28:29], v[146:147], 1, s[22:23]
	global_store_dwordx4 v[28:29], v[24:27], off nt
	s_nop 1
	v_cndmask_b32_e64 v24, v31, v19, s[36:37]
	ds_bpermute_b32 v19, v116, v18
	v_cndmask_b32_e64 v25, v30, v20, s[36:37]
	v_cndmask_b32_e64 v26, v32, v21, s[36:37]
	v_cndmask_b32_e64 v27, v33, v22, s[36:37]
	v_lshl_add_u64 v[20:21], v[148:149], 1, s[22:23]
	s_waitcnt lgkmcnt(0)
	v_add_f32_e32 v18, v18, v19
	ds_bpermute_b32 v19, v117, v18
	global_store_dwordx4 v[20:21], v[24:27], off nt
	s_and_saveexec_b64 s[22:23], s[38:39]
	s_cbranch_execz .LBB0_957
	s_waitcnt lgkmcnt(0)
	v_add_f32_e32 v20, v18, v19
	v_lshlrev_b64 v[18:19], 7, v[156:157]
	v_lshl_add_u64 v[18:19], s[6:7], 0, v[18:19]
	v_lshl_add_u64 v[18:19], s[18:19], 2, v[18:19]
	s_lshl_b32 s4, s53, 2
	v_lshl_add_u64 v[18:19], v[18:19], 0, s[4:5]
	v_add_co_u32_e32 v18, vcc, 0x5000, v18
	s_nop 1
	v_addc_co_u32_e32 v19, vcc, 0, v19, vcc
	global_store_dword v[18:19], v20, off nt
.LBB0_957:
	s_or_b64 exec, exec, s[22:23]
	s_waitcnt vmcnt(3)
	v_lshlrev_b32_e32 v18, 16, v38
	v_add_f32_e32 v14, v14, v18
	v_and_b32_e32 v18, 0xffff0000, v38
	v_add_f32_e32 v15, v15, v18
	v_lshlrev_b32_e32 v18, 16, v39
	v_add_f32_e32 v16, v16, v18
	v_and_b32_e32 v18, 0xffff0000, v39
	v_add_f32_e32 v17, v17, v18
	v_lshlrev_b32_e32 v18, 16, v40
	v_add_f32_e32 v10, v10, v18
	v_and_b32_e32 v18, 0xffff0000, v40
	v_add_f32_e32 v11, v11, v18
	v_lshlrev_b32_e32 v18, 16, v41
	v_add_f32_e32 v12, v12, v18
	v_and_b32_e32 v18, 0xffff0000, v41
	v_add_f32_e32 v13, v13, v18
	v_cvt_pk_bf16_f32 v18, v14, v15
	s_waitcnt lgkmcnt(0)
	v_cvt_pk_bf16_f32 v19, v16, v17
	v_cvt_pk_bf16_f32 v20, v10, v11
	v_mul_f32_e32 v11, v11, v11
	v_fmac_f32_e32 v11, v10, v10
	v_mul_f32_e32 v10, v13, v13
	v_fmac_f32_e32 v10, v12, v12
	v_add_f32_e32 v10, v11, v10
	s_waitcnt vmcnt(2)
	v_lshlrev_b32_e32 v11, 16, v34
	v_add_f32_e32 v6, v6, v11
	v_and_b32_e32 v11, 0xffff0000, v34
	v_add_f32_e32 v7, v7, v11
	v_lshlrev_b32_e32 v11, 16, v35
	v_add_f32_e32 v8, v8, v11
	v_and_b32_e32 v11, 0xffff0000, v35
	v_add_f32_e32 v9, v9, v11
	v_lshlrev_b32_e32 v11, 16, v36
	v_add_f32_e32 v2, v2, v11
	v_and_b32_e32 v11, 0xffff0000, v36
	v_add_f32_e32 v3, v3, v11
	v_lshlrev_b32_e32 v11, 16, v37
	v_add_f32_e32 v4, v4, v11
	v_and_b32_e32 v11, 0xffff0000, v37
	v_cvt_pk_bf16_f32 v21, v12, v13
	v_mul_f32_e32 v15, v15, v15
	v_add_f32_e32 v5, v5, v11
	v_cvt_pk_bf16_f32 v11, v6, v7
	v_cvt_pk_bf16_f32 v12, v8, v9
	v_cvt_pk_bf16_f32 v13, v2, v3
	v_mul_f32_e32 v7, v7, v7
	v_mul_f32_e32 v3, v3, v3
	v_fmac_f32_e32 v15, v14, v14
	v_mul_f32_e32 v14, v17, v17
	v_fmac_f32_e32 v7, v6, v6
	v_mul_f32_e32 v6, v9, v9
	v_fmac_f32_e32 v3, v2, v2
	v_mul_f32_e32 v2, v5, v5
	v_fmac_f32_e32 v14, v16, v16
	v_fmac_f32_e32 v6, v8, v8
	v_fmac_f32_e32 v2, v4, v4
	v_add_f32_e32 v14, v15, v14
	v_add_f32_e32 v6, v7, v6
	v_add_f32_e32 v2, v3, v2
	v_add_f32_e32 v10, v14, v10
	v_add_f32_e32 v2, v6, v2
	v_add_f32_e32 v8, v10, v2
	ds_bpermute_b32 v17, v116, v8
	v_cvt_pk_bf16_f32 v14, v4, v5
	s_add_u32 s20, s20, 0xb0000
	v_cndmask_b32_e64 v2, v14, v21, s[36:37]
	v_cndmask_b32_e64 v3, v13, v20, s[36:37]
	v_cndmask_b32_e64 v4, v12, v19, s[36:37]
	v_cndmask_b32_e64 v5, v11, v18, s[36:37]
	v_mov_b32_e32 v9, v115
	v_mov_b32_e32 v10, v115
	v_mov_b32_e32 v15, v115
	v_mov_b32_e32 v16, v115
	s_addc_u32 s21, s21, 0
	v_mov_b32_dpp v9, v5 quad_perm:[1,0,3,2] row_mask:0xf bank_mask:0xf
	v_mov_b32_dpp v10, v4 quad_perm:[1,0,3,2] row_mask:0xf bank_mask:0xf
	v_mov_b32_dpp v15, v3 quad_perm:[1,0,3,2] row_mask:0xf bank_mask:0xf
	v_mov_b32_dpp v16, v2 quad_perm:[1,0,3,2] row_mask:0xf bank_mask:0xf
	v_cndmask_b32_e64 v2, v18, v9, s[36:37]
	v_cndmask_b32_e64 v3, v19, v10, s[36:37]
	v_cndmask_b32_e64 v4, v20, v15, s[36:37]
	v_cndmask_b32_e64 v5, v21, v16, s[36:37]
	v_lshl_add_u64 v[6:7], v[146:147], 1, s[20:21]
	global_store_dwordx4 v[6:7], v[2:5], off nt
	v_cndmask_b32_e64 v6, v15, v13, s[36:37]
	v_cndmask_b32_e64 v7, v16, v14, s[36:37]
	s_waitcnt lgkmcnt(0)
	v_add_f32_e32 v2, v8, v17
	ds_bpermute_b32 v3, v117, v2
	v_cndmask_b32_e64 v4, v9, v11, s[36:37]
	v_cndmask_b32_e64 v5, v10, v12, s[36:37]
	v_lshl_add_u64 v[8:9], v[148:149], 1, s[20:21]
	global_store_dwordx4 v[8:9], v[4:7], off nt
	s_and_saveexec_b64 s[20:21], s[38:39]
	s_cbranch_execz .LBB0_959
	s_waitcnt lgkmcnt(0)
	v_add_f32_e32 v4, v2, v3
	v_lshlrev_b64 v[2:3], 7, v[156:157]
	v_lshl_add_u64 v[2:3], s[6:7], 0, v[2:3]
	v_lshl_add_u64 v[2:3], s[18:19], 2, v[2:3]
	s_lshl_b32 s4, s53, 2
	v_lshl_add_u64 v[2:3], v[2:3], 0, s[4:5]
	v_add_co_u32_e32 v2, vcc, 0x5000, v2
	s_nop 1
	v_addc_co_u32_e32 v3, vcc, 0, v3, vcc
	global_store_dword v[2:3], v4, off offset:2048 nt

.LBB0_1106:
	s_add_u32 s68, s54, 0xfffc0080
	s_addc_u32 s69, s55, -1
	s_add_i32 s90, 0, 0x10000
	s_cmp_eq_u32 vcc_hi, 12
	s_cselect_b32 s81, s25, s69
	s_cselect_b32 s80, s82, s68
	v_add_u32_e32 v114, s90, v208
	s_cselect_b32 s79, s23, vcc_lo
	s_cselect_b32 s78, s83, s95
	s_add_i32 s0, 0, 0x14000
	ds_read_b128 v[106:109], v114
	ds_read_b128 v[136:139], v114 offset:1024
	ds_read_b128 v[140:143], v114 offset:2048
	ds_read_b128 v[144:147], v114 offset:3072
	v_add_u32_e32 v114, s0, v208
	ds_read_b128 v[148:151], v114
	ds_read_b128 v[170:173], v114 offset:1024
	ds_read_b128 v[174:177], v114 offset:2048
	ds_read_b128 v[178:181], v114 offset:3072
	v_lshl_add_u64 v[152:153], s[54:55], 0, v[166:167]
	s_add_i32 m0, s75, 0xc000
	ds_read_b128 v[182:185], v219
	ds_read_b128 v[186:189], v219 offset:1024
	ds_read_b128 v[190:193], v219 offset:2048
	ds_read_b128 v[194:197], v219 offset:3072
	ds_read_b128 v[198:201], v219 offset:4096
	ds_read_b128 v[202:205], v219 offset:5120
	ds_read_b128 v[220:223], v219 offset:6144
	ds_read_b128 v[240:243], v219 offset:7168
	global_load_lds_dwordx4 v[152:153], off
	v_lshl_add_u64 v[152:153], s[54:55], 0, v[168:169]
	s_add_i32 m0, s75, 0xe000
	s_nop 0
	global_load_lds_dwordx4 v[152:153], off
	s_waitcnt vmcnt(8)
	s_waitcnt lgkmcnt(0)
	s_barrier
	s_setprio 1
	s_waitcnt lgkmcnt(0)
	v_mfma_i32_16x16x64_i8 v[132:135], v[106:109], v[182:185], v[132:135]
	v_mfma_i32_16x16x64_i8 v[128:131], v[140:143], v[182:185], v[128:131]
	v_mfma_i32_16x16x64_i8 v[124:127], v[106:109], v[190:193], v[124:127]
	v_mfma_i32_16x16x64_i8 v[86:89], v[140:143], v[190:193], v[86:89]
	v_mfma_i32_16x16x64_i8 v[120:123], v[106:109], v[198:201], v[120:123]
	v_mfma_i32_16x16x64_i8 v[82:85], v[140:143], v[198:201], v[82:85]
	v_mfma_i32_16x16x64_i8 v[102:105], v[106:109], v[220:223], v[102:105]
	v_mfma_i32_16x16x64_i8 v[90:93], v[140:143], v[220:223], v[90:93]
	v_mfma_i32_16x16x64_i8 v[132:135], v[136:139], v[186:189], v[132:135]
	v_mfma_i32_16x16x64_i8 v[128:131], v[144:147], v[186:189], v[128:131]
	v_mfma_i32_16x16x64_i8 v[124:127], v[136:139], v[194:197], v[124:127]
	v_mfma_i32_16x16x64_i8 v[86:89], v[144:147], v[194:197], v[86:89]
	v_mfma_i32_16x16x64_i8 v[120:123], v[136:139], v[202:205], v[120:123]
	v_mfma_i32_16x16x64_i8 v[82:85], v[144:147], v[202:205], v[82:85]
	v_mfma_i32_16x16x64_i8 v[102:105], v[136:139], v[240:243], v[102:105]
	v_mfma_i32_16x16x64_i8 v[90:93], v[144:147], v[240:243], v[90:93]
	s_setprio 0
	s_setprio 1
	v_mfma_i32_16x16x64_i8 v[116:119], v[148:151], v[182:185], v[116:119]
	v_mfma_i32_16x16x64_i8 v[78:81], v[174:177], v[182:185], v[78:81]
	v_mfma_i32_16x16x64_i8 v[98:101], v[148:151], v[190:193], v[98:101]
	v_mfma_i32_16x16x64_i8 v[66:69], v[174:177], v[190:193], v[66:69]
	v_mfma_i32_16x16x64_i8 v[94:97], v[148:151], v[198:201], v[94:97]
	v_mfma_i32_16x16x64_i8 v[58:61], v[174:177], v[198:201], v[58:61]
	v_mfma_i32_16x16x64_i8 v[110:113], v[148:151], v[220:223], v[110:113]
	v_mfma_i32_16x16x64_i8 v[74:77], v[174:177], v[220:223], v[74:77]
	v_mfma_i32_16x16x64_i8 v[116:119], v[170:173], v[186:189], v[116:119]
	v_mfma_i32_16x16x64_i8 v[78:81], v[178:181], v[186:189], v[78:81]
	v_mfma_i32_16x16x64_i8 v[98:101], v[170:173], v[194:197], v[98:101]
	v_mfma_i32_16x16x64_i8 v[66:69], v[178:181], v[194:197], v[66:69]
	v_mfma_i32_16x16x64_i8 v[94:97], v[170:173], v[202:205], v[94:97]
	v_mfma_i32_16x16x64_i8 v[58:61], v[178:181], v[202:205], v[58:61]
	v_mfma_i32_16x16x64_i8 v[110:113], v[170:173], v[240:243], v[110:113]
	v_mfma_i32_16x16x64_i8 v[74:77], v[178:181], v[240:243], v[74:77]
	s_setprio 0
	s_barrier
	s_add_i32 s1, s90, s87
	v_lshl_add_u64 v[152:153], s[78:79], 0, v[156:157]
	s_mov_b32 m0, s1
	ds_read_b128 v[182:185], v219 offset:16384
	ds_read_b128 v[186:189], v219 offset:17408
	ds_read_b128 v[190:193], v219 offset:18432
	ds_read_b128 v[194:197], v219 offset:19456
	ds_read_b128 v[198:201], v219 offset:20480
	ds_read_b128 v[202:205], v219 offset:21504
	ds_read_b128 v[220:223], v219 offset:22528
	ds_read_b128 v[240:243], v219 offset:23552
	global_load_lds_dwordx4 v[152:153], off
	s_add_i32 m0, s1, 0x2000
	s_add_u32 s68, s78, 0x10000
	v_lshl_add_u64 v[224:225], s[78:79], 0, v[164:165]
	s_addc_u32 s69, s79, 0
	s_add_i32 s0, s0, s87
	global_load_lds_dwordx4 v[224:225], off
	v_lshl_add_u64 v[230:231], s[68:69], 0, v[156:157]
	s_mov_b32 m0, s0
	v_lshl_add_u64 v[232:233], s[80:81], 0, v[158:159]
	global_load_lds_dwordx4 v[230:231], off
	v_lshl_add_u64 v[230:231], s[68:69], 0, v[164:165]
	s_add_i32 m0, s0, 0x2000
	s_nop 0
	global_load_lds_dwordx4 v[230:231], off
	v_lshl_add_u64 v[230:231], s[80:81], 0, v[154:155]
	s_mov_b32 m0, s75
	s_nop 0
	global_load_lds_dwordx4 v[230:231], off
	s_mov_b32 m0, s77
	s_nop 0
	global_load_lds_dwordx4 v[232:233], off
	s_waitcnt vmcnt(8)
	s_waitcnt lgkmcnt(0)
	s_barrier
	s_setprio 1
	s_waitcnt lgkmcnt(0)
	v_mfma_i32_16x16x64_i8 v[70:73], v[106:109], v[182:185], v[70:73]
	v_mfma_i32_16x16x64_i8 v[62:65], v[140:143], v[182:185], v[62:65]
	v_mfma_i32_16x16x64_i8 v[54:57], v[106:109], v[190:193], v[54:57]
	v_mfma_i32_16x16x64_i8 v[22:25], v[140:143], v[190:193], v[22:25]
	v_mfma_i32_16x16x64_i8 v[50:53], v[106:109], v[198:201], v[50:53]
	v_mfma_i32_16x16x64_i8 v[18:21], v[140:143], v[198:201], v[18:21]
	v_mfma_i32_16x16x64_i8 v[42:45], v[106:109], v[220:223], v[42:45]
	v_mfma_i32_16x16x64_i8 v[34:37], v[140:143], v[220:223], v[34:37]
	v_mfma_i32_16x16x64_i8 v[70:73], v[136:139], v[186:189], v[70:73]
	v_mfma_i32_16x16x64_i8 v[62:65], v[144:147], v[186:189], v[62:65]
	v_mfma_i32_16x16x64_i8 v[54:57], v[136:139], v[194:197], v[54:57]
	v_mfma_i32_16x16x64_i8 v[22:25], v[144:147], v[194:197], v[22:25]
	v_mfma_i32_16x16x64_i8 v[50:53], v[136:139], v[202:205], v[50:53]
	v_mfma_i32_16x16x64_i8 v[18:21], v[144:147], v[202:205], v[18:21]
	v_mfma_i32_16x16x64_i8 v[42:45], v[136:139], v[240:243], v[42:45]
	v_mfma_i32_16x16x64_i8 v[34:37], v[144:147], v[240:243], v[34:37]
	s_setprio 0
	s_setprio 1
	v_mfma_i32_16x16x64_i8 v[46:49], v[148:151], v[182:185], v[46:49]
	v_mfma_i32_16x16x64_i8 v[14:17], v[174:177], v[182:185], v[14:17]
	v_mfma_i32_16x16x64_i8 v[30:33], v[148:151], v[190:193], v[30:33]
	v_mfma_i32_16x16x64_i8 v[10:13], v[174:177], v[190:193], v[10:13]
	v_mfma_i32_16x16x64_i8 v[26:29], v[148:151], v[198:201], v[26:29]
	v_mfma_i32_16x16x64_i8 v[6:9], v[174:177], v[198:201], v[6:9]
	v_mfma_i32_16x16x64_i8 v[38:41], v[148:151], v[220:223], v[38:41]
	v_mfma_i32_16x16x64_i8 v[2:5], v[174:177], v[220:223], v[2:5]
	v_mfma_i32_16x16x64_i8 v[46:49], v[170:173], v[186:189], v[46:49]
	v_mfma_i32_16x16x64_i8 v[14:17], v[178:181], v[186:189], v[14:17]
	v_mfma_i32_16x16x64_i8 v[30:33], v[170:173], v[194:197], v[30:33]
	v_mfma_i32_16x16x64_i8 v[10:13], v[178:181], v[194:197], v[10:13]
	v_mfma_i32_16x16x64_i8 v[26:29], v[170:173], v[202:205], v[26:29]
	v_mfma_i32_16x16x64_i8 v[6:9], v[178:181], v[202:205], v[6:9]
	v_mfma_i32_16x16x64_i8 v[38:41], v[170:173], v[240:243], v[38:41]
	v_mfma_i32_16x16x64_i8 v[2:5], v[178:181], v[240:243], v[2:5]
	s_setprio 0
	s_barrier
	s_add_i32 s0, 0, 0x18000
	v_add_u32_e32 v114, s0, v208
	s_add_i32 s1, 0, 0x1c000
	ds_read_b128 v[106:109], v114
	ds_read_b128 v[136:139], v114 offset:1024
	ds_read_b128 v[140:143], v114 offset:2048
	ds_read_b128 v[144:147], v114 offset:3072
	v_add_u32_e32 v114, s1, v208
	ds_read_b128 v[148:151], v114
	ds_read_b128 v[170:173], v114 offset:1024
	ds_read_b128 v[174:177], v114 offset:2048
	ds_read_b128 v[178:181], v114 offset:3072
	s_add_u32 s68, s80, 0x40000
	s_addc_u32 s69, s81, 0
	s_mov_b32 m0, s59
	v_lshl_add_u64 v[236:237], s[68:69], 0, v[154:155]
	ds_read_b128 v[182:185], v219 offset:32768
	ds_read_b128 v[186:189], v219 offset:33792
	ds_read_b128 v[190:193], v219 offset:34816
	ds_read_b128 v[194:197], v219 offset:35840
	ds_read_b128 v[198:201], v219 offset:36864
	ds_read_b128 v[202:205], v219 offset:37888
	ds_read_b128 v[220:223], v219 offset:38912
	ds_read_b128 v[240:243], v219 offset:39936
	global_load_lds_dwordx4 v[236:237], off
	v_lshl_add_u64 v[236:237], s[68:69], 0, v[158:159]
	s_mov_b32 m0, s63
	s_nop 0
	global_load_lds_dwordx4 v[236:237], off
	s_waitcnt vmcnt(8)
	s_waitcnt lgkmcnt(0)
	s_barrier
	s_setprio 1
	s_waitcnt lgkmcnt(0)
	v_mfma_i32_16x16x64_i8 v[132:135], v[106:109], v[182:185], v[132:135]
	v_mfma_i32_16x16x64_i8 v[128:131], v[140:143], v[182:185], v[128:131]
	v_mfma_i32_16x16x64_i8 v[124:127], v[106:109], v[190:193], v[124:127]
	v_mfma_i32_16x16x64_i8 v[86:89], v[140:143], v[190:193], v[86:89]
	v_mfma_i32_16x16x64_i8 v[120:123], v[106:109], v[198:201], v[120:123]
	v_mfma_i32_16x16x64_i8 v[82:85], v[140:143], v[198:201], v[82:85]
	v_mfma_i32_16x16x64_i8 v[102:105], v[106:109], v[220:223], v[102:105]
	v_mfma_i32_16x16x64_i8 v[90:93], v[140:143], v[220:223], v[90:93]
	v_mfma_i32_16x16x64_i8 v[132:135], v[136:139], v[186:189], v[132:135]
	v_mfma_i32_16x16x64_i8 v[128:131], v[144:147], v[186:189], v[128:131]
	v_mfma_i32_16x16x64_i8 v[124:127], v[136:139], v[194:197], v[124:127]
	v_mfma_i32_16x16x64_i8 v[86:89], v[144:147], v[194:197], v[86:89]
	v_mfma_i32_16x16x64_i8 v[120:123], v[136:139], v[202:205], v[120:123]
	v_mfma_i32_16x16x64_i8 v[82:85], v[144:147], v[202:205], v[82:85]
	v_mfma_i32_16x16x64_i8 v[102:105], v[136:139], v[240:243], v[102:105]
	v_mfma_i32_16x16x64_i8 v[90:93], v[144:147], v[240:243], v[90:93]
	s_setprio 0
	s_setprio 1
	v_mfma_i32_16x16x64_i8 v[116:119], v[148:151], v[182:185], v[116:119]
	v_mfma_i32_16x16x64_i8 v[78:81], v[174:177], v[182:185], v[78:81]
	v_mfma_i32_16x16x64_i8 v[98:101], v[148:151], v[190:193], v[98:101]
	v_mfma_i32_16x16x64_i8 v[66:69], v[174:177], v[190:193], v[66:69]
	v_mfma_i32_16x16x64_i8 v[94:97], v[148:151], v[198:201], v[94:97]
	v_mfma_i32_16x16x64_i8 v[58:61], v[174:177], v[198:201], v[58:61]
	v_mfma_i32_16x16x64_i8 v[110:113], v[148:151], v[220:223], v[110:113]
	v_mfma_i32_16x16x64_i8 v[74:77], v[174:177], v[220:223], v[74:77]
	v_mfma_i32_16x16x64_i8 v[116:119], v[170:173], v[186:189], v[116:119]
	v_mfma_i32_16x16x64_i8 v[78:81], v[178:181], v[186:189], v[78:81]
	v_mfma_i32_16x16x64_i8 v[98:101], v[170:173], v[194:197], v[98:101]
	v_mfma_i32_16x16x64_i8 v[66:69], v[178:181], v[194:197], v[66:69]
	v_mfma_i32_16x16x64_i8 v[94:97], v[170:173], v[202:205], v[94:97]
	v_mfma_i32_16x16x64_i8 v[58:61], v[178:181], v[202:205], v[58:61]
	v_mfma_i32_16x16x64_i8 v[110:113], v[170:173], v[240:243], v[110:113]
	v_mfma_i32_16x16x64_i8 v[74:77], v[178:181], v[240:243], v[74:77]
	s_setprio 0
	s_barrier
	s_add_i32 s0, s0, s87
	v_lshl_add_u64 v[152:153], v[152:153], 0, s[28:29]
	s_mov_b32 m0, s0
	ds_read_b128 v[182:185], v219 offset:49152
	ds_read_b128 v[186:189], v219 offset:50176
	ds_read_b128 v[190:193], v219 offset:51200
	ds_read_b128 v[194:197], v219 offset:52224
	ds_read_b128 v[198:201], v219 offset:53248
	ds_read_b128 v[202:205], v219 offset:54272
	ds_read_b128 v[220:223], v219 offset:55296
	ds_read_b128 v[240:243], v219 offset:56320
	global_load_lds_dwordx4 v[152:153], off
	s_add_i32 m0, s0, 0x2000
	s_add_u32 s68, s78, 0x10080
	v_lshl_add_u64 v[152:153], v[224:225], 0, s[28:29]
	s_addc_u32 s69, s79, 0
	s_add_i32 s0, s1, s87
	global_load_lds_dwordx4 v[152:153], off
	v_lshl_add_u64 v[152:153], s[68:69], 0, v[156:157]
	s_mov_b32 m0, s0
	s_nop 0
	global_load_lds_dwordx4 v[152:153], off
	v_lshl_add_u64 v[152:153], s[68:69], 0, v[164:165]
	s_add_i32 m0, s0, 0x2000
	s_nop 0
	global_load_lds_dwordx4 v[152:153], off
	v_lshl_add_u64 v[152:153], v[230:231], 0, s[28:29]
	s_mov_b32 m0, s4
	s_nop 0
	global_load_lds_dwordx4 v[152:153], off
	v_lshl_add_u64 v[152:153], v[232:233], 0, s[28:29]
	s_mov_b32 m0, s65
	s_nop 0
	global_load_lds_dwordx4 v[152:153], off
	s_waitcnt vmcnt(8)
	s_waitcnt lgkmcnt(0)
	s_barrier
	s_setprio 1
	s_waitcnt lgkmcnt(0)
	v_mfma_i32_16x16x64_i8 v[70:73], v[106:109], v[182:185], v[70:73]
	v_mfma_i32_16x16x64_i8 v[62:65], v[140:143], v[182:185], v[62:65]
	v_mfma_i32_16x16x64_i8 v[54:57], v[106:109], v[190:193], v[54:57]
	v_mfma_i32_16x16x64_i8 v[22:25], v[140:143], v[190:193], v[22:25]
	v_mfma_i32_16x16x64_i8 v[50:53], v[106:109], v[198:201], v[50:53]
	v_mfma_i32_16x16x64_i8 v[18:21], v[140:143], v[198:201], v[18:21]
	v_mfma_i32_16x16x64_i8 v[42:45], v[106:109], v[220:223], v[42:45]
	v_mfma_i32_16x16x64_i8 v[34:37], v[140:143], v[220:223], v[34:37]
	v_mfma_i32_16x16x64_i8 v[70:73], v[136:139], v[186:189], v[70:73]
	v_mfma_i32_16x16x64_i8 v[62:65], v[144:147], v[186:189], v[62:65]
	v_mfma_i32_16x16x64_i8 v[54:57], v[136:139], v[194:197], v[54:57]
	v_mfma_i32_16x16x64_i8 v[22:25], v[144:147], v[194:197], v[22:25]
	v_mfma_i32_16x16x64_i8 v[50:53], v[136:139], v[202:205], v[50:53]
	v_mfma_i32_16x16x64_i8 v[18:21], v[144:147], v[202:205], v[18:21]
	v_mfma_i32_16x16x64_i8 v[42:45], v[136:139], v[240:243], v[42:45]
	v_mfma_i32_16x16x64_i8 v[34:37], v[144:147], v[240:243], v[34:37]
	s_setprio 0
	s_setprio 1
	v_mfma_i32_16x16x64_i8 v[46:49], v[148:151], v[182:185], v[46:49]
	v_mfma_i32_16x16x64_i8 v[14:17], v[174:177], v[182:185], v[14:17]
	v_mfma_i32_16x16x64_i8 v[30:33], v[148:151], v[190:193], v[30:33]
	v_mfma_i32_16x16x64_i8 v[10:13], v[174:177], v[190:193], v[10:13]
	v_mfma_i32_16x16x64_i8 v[26:29], v[148:151], v[198:201], v[26:29]
	v_mfma_i32_16x16x64_i8 v[6:9], v[174:177], v[198:201], v[6:9]
	v_mfma_i32_16x16x64_i8 v[38:41], v[148:151], v[220:223], v[38:41]
	v_mfma_i32_16x16x64_i8 v[2:5], v[174:177], v[220:223], v[2:5]
	v_mfma_i32_16x16x64_i8 v[46:49], v[170:173], v[186:189], v[46:49]
	v_mfma_i32_16x16x64_i8 v[14:17], v[178:181], v[186:189], v[14:17]
	v_mfma_i32_16x16x64_i8 v[30:33], v[170:173], v[194:197], v[30:33]
	v_mfma_i32_16x16x64_i8 v[10:13], v[178:181], v[194:197], v[10:13]
	v_mfma_i32_16x16x64_i8 v[26:29], v[170:173], v[202:205], v[26:29]
	v_mfma_i32_16x16x64_i8 v[6:9], v[178:181], v[202:205], v[6:9]
	v_mfma_i32_16x16x64_i8 v[38:41], v[170:173], v[240:243], v[38:41]
	v_mfma_i32_16x16x64_i8 v[2:5], v[178:181], v[240:243], v[2:5]
	s_setprio 0
	s_barrier
	s_add_i32 vcc_hi, vcc_hi, 2
	s_add_u32 s54, s54, 0x100
	s_addc_u32 s55, s55, 0
	s_add_u32 s95, s95, 0x100
	s_addc_u32 vcc_lo, vcc_lo, 0
	s_cmp_gt_u32 vcc_hi, 13
	s_cbranch_scc0 .LBB0_1106
	s_and_b64 vcc, exec, s[36:37]
	s_cbranch_vccz .LBB0_1109
	s_barrier

.LBB0_1120:
	s_or_b64 exec, exec, s[78:79]
	v_lshlrev_b64 v[108:109], 2, v[170:171]
	s_waitcnt lgkmcnt(0)
	s_barrier
	v_lshl_add_u64 v[182:183], s[8:9], 0, v[108:109]
	v_lshl_add_u64 v[184:185], s[18:19], 0, v[108:109]
	global_load_dwordx4 v[146:149], v[182:183], off
	global_load_dwordx4 v[138:141], v[184:185], off
	v_lshl_add_u64 v[186:187], s[20:21], 0, v[108:109]
	global_load_dwordx4 v[142:145], v[186:187], off
	v_lshl_add_u64 v[188:189], s[10:11], 0, v[108:109]
	global_load_dwordx4 v[150:153], v[188:189], off
	v_cvt_f32_i32_e32 v119, v119
	v_cvt_f32_i32_e32 v118, v118
	v_cvt_f32_i32_e32 v117, v117
	v_cvt_f32_i32_e32 v116, v116
	v_cvt_f32_i32_e32 v109, v125
	v_cvt_f32_i32_e32 v108, v124
	v_cvt_f32_i32_e32 v125, v127
	v_cvt_f32_i32_e32 v124, v126
	v_cvt_f32_i32_e32 v127, v121
	v_cvt_f32_i32_e32 v126, v120
	v_mul_f32_e32 v136, 0x3c010204, v136
	v_mov_b32_e32 v120, v198
	v_mov_b32_e32 v121, v198
	v_mov_b32_e32 v199, v198
	v_pk_mul_f32 v[120:121], v[136:137], v[120:121] op_sel_hi:[0,1]
	v_mov_b32_e32 v191, v190
	v_cvt_f32_i32_e32 v203, v123
	v_cvt_f32_i32_e32 v202, v122
	v_pk_mul_f32 v[122:123], v[136:137], v[198:199] op_sel_hi:[0,1]
	v_pk_mul_f32 v[118:119], v[120:121], v[118:119]
	v_mov_b32_e32 v120, v190
	v_mov_b32_e32 v121, v190
	v_pk_mul_f32 v[116:117], v[122:123], v[116:117]
	v_pk_mul_f32 v[122:123], v[120:121], v[194:195] op_sel_hi:[1,0]
	v_pk_mul_f32 v[204:205], v[190:191], v[194:195] op_sel_hi:[1,0]
	v_pk_mul_f32 v[200:201], v[122:123], v[124:125]
	v_pk_mul_f32 v[204:205], v[204:205], v[108:109]
	v_pk_mul_f32 v[108:109], v[120:121], v[192:193] op_sel_hi:[1,0]
	ds_read_b128 v[120:123], v211
	v_pk_mul_f32 v[124:125], v[190:191], v[192:193] op_sel_hi:[1,0]
	v_pk_mul_f32 v[108:109], v[108:109], v[202:203]
	v_pk_mul_f32 v[202:203], v[124:125], v[126:127]
	ds_read_b128 v[124:127], v212 offset:1024
	s_waitcnt lgkmcnt(1)
	v_pk_mul_f32 v[220:221], v[122:123], 0 op_sel_hi:[1,0]
	v_pk_mul_f32 v[222:223], v[120:121], 0 op_sel_hi:[1,0]
	v_cndmask_b32_e64 v160, v123, v221, s[36:37]
	v_mov_b32_e32 v221, v115
	v_mov_b32_e32 v240, v115
	v_cndmask_b32_e64 v120, v120, v222, s[36:37]
	v_cndmask_b32_e64 v121, v121, v223, s[36:37]
	v_cndmask_b32_e64 v137, v122, v220, s[36:37]
	v_mov_b32_dpp v221, v132 row_ror:1 row_mask:0xf bank_mask:0xf
	v_mov_b32_e32 v122, v115
	v_mov_b32_e32 v224, v115
	v_mov_b32_dpp v240, v133 row_ror:1 row_mask:0xf bank_mask:0xf
	v_mov_b32_e32 v123, v115
	v_mov_b32_e32 v243, v115
	v_mov_b32_dpp v122, v132 row_ror:15 row_mask:0xf bank_mask:0xf
	v_mov_b32_dpp v224, v204 row_ror:15 row_mask:0xf bank_mask:0xf
	v_mov_b32_dpp v123, v133 row_ror:15 row_mask:0xf bank_mask:0xf
	v_mov_b32_dpp v243, v205 row_ror:15 row_mask:0xf bank_mask:0xf
	v_cndmask_b32_e64 v121, v240, v121, s[38:39]
	v_cndmask_b32_e64 v120, v221, v120, s[38:39]
	v_mov_b32_e32 v246, v115
	v_mov_b32_e32 v251, v115
	v_cndmask_b32_e64 v123, v123, v243, s[40:41]
	v_cndmask_b32_e64 v122, v122, v224, s[40:41]
	v_mov_b32_dpp v246, v134 row_ror:1 row_mask:0xf bank_mask:0xf
	v_mov_b32_e32 v249, v115
	v_mov_b32_dpp v251, v135 row_ror:1 row_mask:0xf bank_mask:0xf
	v_mov_b32_e32 v161, v115
	v_mov_b32_e32 v252, v115
	v_mov_b32_dpp v249, v200 row_ror:15 row_mask:0xf bank_mask:0xf
	v_mov_b32_dpp v161, v135 row_ror:15 row_mask:0xf bank_mask:0xf
	v_mov_b32_dpp v252, v201 row_ror:15 row_mask:0xf bank_mask:0xf
	v_cndmask_b32_e64 v161, v161, v252, s[40:41]
	s_mul_i32 s78, s76, 6
	v_mov_b32_e32 v107, v115
	v_mov_b32_e32 v114, v115
	v_mov_b32_e32 v173, v115
	v_mov_b32_e32 v193, v115
	v_mov_b32_e32 v220, v115
	v_mov_b32_e32 v175, v115
	v_mov_b32_e32 v222, v115
	v_mov_b32_e32 v223, v115
	s_waitcnt vmcnt(2)
	v_pk_mul_f32 v[230:231], v[132:133], v[138:139]
	v_pk_mul_f32 v[232:233], v[134:135], v[140:141]
	v_pk_fma_f32 v[120:121], v[146:147], v[120:121], v[230:231]
	v_mov_b32_e32 v231, v115
	s_waitcnt vmcnt(1)
	v_pk_fma_f32 v[120:121], v[142:143], v[122:123], v[120:121]
	v_cndmask_b32_e64 v123, v251, v160, s[38:39]
	v_mov_b32_dpp v231, v134 row_ror:15 row_mask:0xf bank_mask:0xf
	v_cndmask_b32_e64 v122, v246, v137, s[38:39]
	v_cndmask_b32_e64 v160, v231, v249, s[40:41]
	v_pk_fma_f32 v[122:123], v[148:149], v[122:123], v[232:233]
	v_mov_b32_e32 v195, v115
	v_mov_b32_e32 v225, v115
	v_mov_b32_e32 v239, v115
	v_mov_b32_e32 v241, v115
	v_mov_b32_e32 v242, v115
	v_mov_b32_e32 v230, v115
	v_mov_b32_e32 v245, v115
	v_mov_b32_e32 v244, v115
	v_mov_b32_e32 v247, v115
	v_mov_b32_e32 v248, v115
	v_mov_b32_e32 v236, v115
	v_mov_b32_e32 v250, v115
	v_pk_fma_f32 v[122:123], v[144:145], v[160:161], v[122:123]
	v_mov_b32_e32 v181, v180
	v_mov_b32_e32 v197, v196
	v_mov_b32_e32 v179, v178
	v_mov_b32_e32 v177, v176
	v_mov_b32_dpp v107, v204 row_ror:1 row_mask:0xf bank_mask:0xf
	v_mov_b32_dpp v114, v202 row_ror:1 row_mask:0xf bank_mask:0xf
	v_mov_b32_dpp v173, v202 row_ror:15 row_mask:0xf bank_mask:0xf
	v_mov_b32_dpp v193, v128 row_ror:1 row_mask:0xf bank_mask:0xf
	v_mov_b32_dpp v220, v128 row_ror:15 row_mask:0xf bank_mask:0xf
	v_mov_b32_dpp v175, v205 row_ror:1 row_mask:0xf bank_mask:0xf
	v_mov_b32_dpp v222, v203 row_ror:1 row_mask:0xf bank_mask:0xf
	v_mov_b32_dpp v223, v203 row_ror:15 row_mask:0xf bank_mask:0xf
	v_mov_b32_dpp v195, v129 row_ror:1 row_mask:0xf bank_mask:0xf
	v_mov_b32_dpp v225, v129 row_ror:15 row_mask:0xf bank_mask:0xf
	s_waitcnt vmcnt(0)
	v_pk_add_f32 v[120:121], v[150:151], v[120:121]
	v_mov_b32_dpp v239, v200 row_ror:1 row_mask:0xf bank_mask:0xf
	v_mov_b32_dpp v241, v108 row_ror:1 row_mask:0xf bank_mask:0xf
	v_mov_b32_dpp v242, v108 row_ror:15 row_mask:0xf bank_mask:0xf
	v_mov_b32_dpp v230, v130 row_ror:1 row_mask:0xf bank_mask:0xf
	v_mov_b32_dpp v245, v130 row_ror:15 row_mask:0xf bank_mask:0xf
	v_mov_b32_dpp v244, v201 row_ror:1 row_mask:0xf bank_mask:0xf
	v_mov_b32_dpp v247, v109 row_ror:1 row_mask:0xf bank_mask:0xf
	v_mov_b32_dpp v248, v109 row_ror:15 row_mask:0xf bank_mask:0xf
	v_mov_b32_dpp v236, v131 row_ror:1 row_mask:0xf bank_mask:0xf
	v_mov_b32_dpp v250, v131 row_ror:15 row_mask:0xf bank_mask:0xf
	v_pk_add_f32 v[122:123], v[152:153], v[122:123]
	s_mul_hi_i32 s23, s78, 0x5800
	s_mul_i32 s25, s78, 0x5800
	s_and_saveexec_b64 s[54:55], s[44:45]
	s_cbranch_execz .LBB0_1122
	s_add_u32 s68, s3, s25
	s_addc_u32 s69, s62, s23
	v_lshl_add_u64 v[160:161], v[170:171], 2, s[68:69]
	global_store_dwordx4 v[160:161], v[132:135], off nt
	s_nop 1
	v_add_co_u32_e32 v132, vcc, 0x5000, v160
	s_nop 1
	v_addc_co_u32_e32 v133, vcc, 0, v161, vcc
	global_store_dwordx4 v[132:133], v[120:123], off offset:2048 nt
	v_add_co_u32_e32 v132, vcc, 0xb000, v160
	s_nop 1
	v_addc_co_u32_e32 v133, vcc, 0, v161, vcc
	global_store_dwordx4 v[132:133], v[116:119], off nt
.LBB0_1122:
	s_or_b64 exec, exec, s[54:55]
	s_waitcnt lgkmcnt(0)
	v_pk_mul_f32 v[134:135], v[124:125], 0 op_sel_hi:[1,0]
	v_pk_mul_f32 v[132:133], v[126:127], 0 op_sel_hi:[1,0]
	v_cndmask_b32_e64 v134, v124, v134, s[42:43]
	v_cndmask_b32_e64 v135, v125, v135, s[42:43]
	v_cndmask_b32_e64 v160, v126, v132, s[42:43]
	v_cndmask_b32_e64 v161, v127, v133, s[42:43]
	v_cndmask_b32_e64 v124, v193, v114, s[38:39]
	v_cndmask_b32_e64 v125, v195, v222, s[38:39]
	v_cndmask_b32_e64 v127, v225, v135, s[40:41]
	v_cndmask_b32_e64 v126, v220, v134, s[40:41]
	v_pk_mul_f32 v[134:135], v[128:129], v[138:139]
	v_pk_mul_f32 v[132:133], v[130:131], v[140:141]
	v_pk_fma_f32 v[124:125], v[146:147], v[124:125], v[134:135]
	v_cvt_f32_i32_e32 v111, v111
	v_pk_fma_f32 v[124:125], v[142:143], v[126:127], v[124:125]
	v_cndmask_b32_e64 v126, v230, v241, s[38:39]
	v_cndmask_b32_e64 v127, v236, v247, s[38:39]
	v_cvt_f32_i32_e32 v110, v110
	v_cvt_f32_i32_e32 v113, v113
	v_cvt_f32_i32_e32 v112, v112
	v_cndmask_b32_e64 v135, v250, v161, s[40:41]
	v_cndmask_b32_e64 v134, v245, v160, s[40:41]
	v_pk_fma_f32 v[126:127], v[148:149], v[126:127], v[132:133]
	v_mov_b32_e32 v137, v136
	v_pk_fma_f32 v[126:127], v[144:145], v[134:135], v[126:127]
	v_mov_b32_e32 v134, v196
	v_mov_b32_e32 v135, v196
	v_mov_b32_e32 v132, v136
	v_mov_b32_e32 v133, v136
	s_add_i32 s79, s78, 3
	v_pk_mul_f32 v[134:135], v[132:133], v[134:135]
	v_pk_mul_f32 v[160:161], v[136:137], v[196:197]
	v_pk_add_f32 v[124:125], v[150:151], v[124:125]
	v_pk_add_f32 v[126:127], v[152:153], v[126:127]
	v_pk_mul_f32 v[112:113], v[134:135], v[112:113]
	v_pk_mul_f32 v[110:111], v[160:161], v[110:111]
	s_mul_hi_i32 s78, s79, 0x5800
	s_mulk_i32 s79, 0x5800
	s_and_saveexec_b64 s[54:55], s[14:15]
	s_cbranch_execz .LBB0_1124
	s_add_u32 s68, s3, s79
	s_addc_u32 s69, s62, s78
	v_lshl_add_u64 v[134:135], v[170:171], 2, s[68:69]
	global_store_dwordx4 v[134:135], v[128:131], off nt
	s_nop 1
	v_add_co_u32_e32 v128, vcc, 0x5000, v134
	s_nop 1
	v_addc_co_u32_e32 v129, vcc, 0, v135, vcc
	global_store_dwordx4 v[128:129], v[124:127], off offset:2048 nt
	v_add_co_u32_e32 v128, vcc, 0xb000, v134
	s_nop 1
	v_addc_co_u32_e32 v129, vcc, 0, v135, vcc
	global_store_dwordx4 v[128:129], v[110:113], off nt
.LBB0_1124:
	s_or_b64 exec, exec, s[54:55]
	v_cndmask_b32_e64 v128, v107, v221, s[38:39]
	v_mul_f32_e32 v128, v146, v128
	v_cndmask_b32_e64 v129, v224, v173, s[40:41]
	v_fmac_f32_e32 v128, v204, v138
	v_fmac_f32_e32 v128, v142, v129
	v_cndmask_b32_e64 v107, v114, v107, s[38:39]
	v_add_f32_e32 v160, v150, v128
	v_cndmask_b32_e64 v128, v175, v240, s[38:39]
	v_mul_f32_e32 v107, v146, v107
	v_mul_f32_e32 v128, v147, v128
	v_cndmask_b32_e64 v114, v173, v220, s[40:41]
	v_fmac_f32_e32 v107, v202, v138
	v_cndmask_b32_e64 v129, v243, v223, s[40:41]
	v_fmac_f32_e32 v128, v205, v139
	v_fmac_f32_e32 v107, v142, v114
	v_cndmask_b32_e64 v114, v222, v175, s[38:39]
	v_fmac_f32_e32 v128, v143, v129
	v_mul_f32_e32 v114, v147, v114
	v_add_f32_e32 v161, v151, v128
	v_cndmask_b32_e64 v128, v223, v225, s[40:41]
	v_fmac_f32_e32 v114, v203, v139
	v_fmac_f32_e32 v114, v143, v128
	v_cndmask_b32_e64 v128, v239, v246, s[38:39]
	v_mul_f32_e32 v128, v148, v128
	v_cndmask_b32_e64 v129, v249, v242, s[40:41]
	v_fmac_f32_e32 v128, v200, v140
	v_fmac_f32_e32 v128, v144, v129
	v_add_f32_e32 v138, v152, v128
	v_cndmask_b32_e64 v128, v244, v251, s[38:39]
	v_mul_f32_e32 v128, v149, v128
	v_cndmask_b32_e64 v129, v252, v248, s[40:41]
	v_fmac_f32_e32 v128, v201, v141
	v_fmac_f32_e32 v128, v145, v129
	v_add_f32_e32 v139, v153, v128
	v_cndmask_b32_e64 v128, v241, v239, s[38:39]
	v_mul_f32_e32 v128, v148, v128
	v_cndmask_b32_e64 v129, v242, v245, s[40:41]
	v_fmac_f32_e32 v128, v108, v140
	v_cndmask_b32_e64 v108, v247, v244, s[38:39]
	v_fmac_f32_e32 v128, v144, v129
	v_mul_f32_e32 v108, v149, v108
	v_cvt_f32_i32_e32 v101, v101
	v_cvt_f32_i32_e32 v100, v100
	v_add_f32_e32 v140, v152, v128
	v_cndmask_b32_e64 v128, v248, v250, s[40:41]
	v_fmac_f32_e32 v108, v109, v141
	v_fmac_f32_e32 v108, v145, v128
	v_mov_b32_e32 v130, v194
	v_mov_b32_e32 v131, v194
	v_add_f32_e32 v141, v153, v108
	v_pk_mul_f32 v[108:109], v[132:133], v[130:131]
	v_mov_b32_e32 v134, v192
	v_mov_b32_e32 v135, v192
	v_pk_mul_f32 v[100:101], v[108:109], v[100:101]
	v_pk_mul_f32 v[108:109], v[132:133], v[134:135]
	v_mul_f32_e32 v132, 0xbfb8aa3b, v120
	v_cvt_f32_i32_e32 v97, v97
	v_cvt_f32_i32_e32 v96, v96
	v_exp_f32_e32 v132, v132
	v_mul_f32_e32 v133, 0xbfb8aa3b, v121
	v_cvt_f32_i32_e32 v99, v99
	v_cvt_f32_i32_e32 v98, v98
	v_exp_f32_e32 v133, v133
	v_pk_mul_f32 v[96:97], v[108:109], v[96:97]
	v_add_f32_e32 v108, 1.0, v132
	v_cvt_f32_i32_e32 v95, v95
	v_cvt_f32_i32_e32 v94, v94
	v_rcp_f32_e32 v132, v108
	v_mov_b32_e32 v195, v194
	v_mov_b32_e32 v193, v192
	v_pk_mul_f32 v[128:129], v[136:137], v[194:195]
	v_add_f32_e32 v108, 1.0, v133
	v_pk_mul_f32 v[98:99], v[128:129], v[98:99]
	v_pk_mul_f32 v[128:129], v[136:137], v[192:193]
	v_rcp_f32_e32 v133, v108
	v_pk_mul_f32 v[108:109], v[128:129], v[94:95]
	v_mul_f32_e32 v94, v120, v132
	v_mul_f32_e32 v94, v116, v94
	v_mul_f32_e32 v116, 0xbfb8aa3b, v122
	v_mul_f32_e32 v120, 0xbfb8aa3b, v123
	v_exp_f32_e32 v116, v116
	v_exp_f32_e32 v120, v120
	v_mul_f32_e32 v95, v121, v133
	v_mul_f32_e32 v95, v117, v95
	v_add_f32_e32 v116, 1.0, v116
	v_add_f32_e32 v117, 1.0, v120
	v_rcp_f32_e32 v116, v116
	v_rcp_f32_e32 v117, v117
	v_cvt_pk_bf16_f32 v94, v94, v95
	v_add_f32_e32 v107, v150, v107
	v_mul_f32_e32 v95, v122, v116
	v_mul_f32_e32 v116, v123, v117
	v_mul_f32_e32 v117, 0xbfb8aa3b, v160
	v_exp_f32_e32 v117, v117
	v_mul_f32_e32 v95, v118, v95
	v_mul_f32_e32 v118, 0xbfb8aa3b, v161
	v_exp_f32_e32 v118, v118
	v_add_f32_e32 v117, 1.0, v117
	v_rcp_f32_e32 v117, v117
	v_mul_f32_e32 v116, v119, v116
	v_add_f32_e32 v118, 1.0, v118
	v_rcp_f32_e32 v118, v118
	v_cvt_pk_bf16_f32 v95, v95, v116
	v_mul_f32_e32 v116, v160, v117
	v_mul_f32_e32 v117, 0xbfb8aa3b, v138
	v_exp_f32_e32 v117, v117
	v_mul_f32_e32 v98, v98, v116
	v_mul_f32_e32 v116, v161, v118
	v_mul_f32_e32 v118, 0xbfb8aa3b, v139
	v_exp_f32_e32 v118, v118
	v_mul_f32_e32 v99, v99, v116
	v_add_f32_e32 v116, 1.0, v117
	v_rcp_f32_e32 v116, v116
	v_add_f32_e32 v117, 1.0, v118
	v_rcp_f32_e32 v117, v117
	v_cvt_pk_bf16_f32 v98, v98, v99
	v_mul_f32_e32 v99, v138, v116
	v_mul_f32_e32 v116, 0xbfb8aa3b, v107
	v_exp_f32_e32 v116, v116
	v_mul_f32_e32 v99, v100, v99
	v_mul_f32_e32 v100, v139, v117
	v_mul_f32_e32 v100, v101, v100
	v_add_f32_e32 v101, 1.0, v116
	v_rcp_f32_e32 v101, v101
	v_add_f32_e32 v114, v151, v114
	v_mul_f32_e32 v117, 0xbfb8aa3b, v114
	v_exp_f32_e32 v117, v117
	v_cvt_pk_bf16_f32 v99, v99, v100
	v_mul_f32_e32 v100, v107, v101
	v_mul_f32_e32 v107, 0xbfb8aa3b, v140
	v_exp_f32_e32 v107, v107
	v_add_f32_e32 v116, 1.0, v117
	v_rcp_f32_e32 v116, v116
	v_mul_f32_e32 v100, v108, v100
	v_mul_f32_e32 v108, 0xbfb8aa3b, v141
	v_exp_f32_e32 v108, v108
	v_add_f32_e32 v107, 1.0, v107
	v_rcp_f32_e32 v107, v107
	v_mul_f32_e32 v101, v114, v116
	v_mul_f32_e32 v101, v109, v101
	v_add_f32_e32 v108, 1.0, v108
	v_rcp_f32_e32 v109, v108
	v_cvt_pk_bf16_f32 v108, v100, v101
	v_mul_f32_e32 v100, v140, v107
	v_mul_f32_e32 v101, 0xbfb8aa3b, v124
	v_mul_f32_e32 v107, 0xbfb8aa3b, v125
	v_exp_f32_e32 v101, v101
	v_exp_f32_e32 v107, v107
	v_mul_f32_e32 v96, v96, v100
	v_mul_f32_e32 v100, v141, v109
	v_mul_f32_e32 v97, v97, v100
	v_add_f32_e32 v100, 1.0, v101
	v_add_f32_e32 v101, 1.0, v107
	v_rcp_f32_e32 v100, v100
	v_rcp_f32_e32 v101, v101
	v_cvt_pk_bf16_f32 v109, v96, v97
	v_cvt_f32_i32_e32 v81, v81
	v_mul_f32_e32 v96, v124, v100
	v_mul_f32_e32 v97, v125, v101
	v_mul_f32_e32 v100, 0xbfb8aa3b, v126
	v_mul_f32_e32 v101, 0xbfb8aa3b, v127
	v_exp_f32_e32 v100, v100
	v_exp_f32_e32 v101, v101
	v_mul_f32_e32 v96, v110, v96
	v_mul_f32_e32 v97, v111, v97
	v_add_f32_e32 v100, 1.0, v100
	v_add_f32_e32 v101, 1.0, v101
	v_rcp_f32_e32 v100, v100
	v_rcp_f32_e32 v101, v101
	v_cvt_pk_bf16_f32 v116, v96, v97
	v_cvt_f32_i32_e32 v80, v80
	v_mul_f32_e32 v96, v126, v100
	v_mul_f32_e32 v97, v127, v101
	v_mul_f32_e32 v96, v112, v96
	v_mul_f32_e32 v97, v113, v97
	v_cvt_pk_bf16_f32 v117, v96, v97
	global_load_dwordx4 v[110:113], v[184:185], off offset:16
	global_load_dwordx4 v[126:129], v[182:183], off offset:16
	global_load_dwordx4 v[118:121], v[186:187], off offset:16
	global_load_dwordx4 v[122:125], v[188:189], off offset:16
	v_cvt_f32_i32_e32 v79, v79
	v_cvt_f32_i32_e32 v78, v78
	v_cvt_f32_i32_e32 v87, v87
	v_cvt_f32_i32_e32 v86, v86
	v_cvt_f32_i32_e32 v89, v89
	v_cvt_f32_i32_e32 v88, v88
	v_mul_f32_e32 v106, 0x3c010204, v106
	v_mov_b32_e32 v96, v198
	v_mov_b32_e32 v97, v198
	v_pk_mul_f32 v[96:97], v[106:107], v[96:97] op_sel_hi:[0,1]
	v_pk_mul_f32 v[100:101], v[106:107], v[198:199] op_sel_hi:[0,1]
	v_pk_mul_f32 v[80:81], v[96:97], v[80:81]
	v_mov_b32_e32 v96, v180
	v_mov_b32_e32 v97, v180
	v_pk_mul_f32 v[78:79], v[100:101], v[78:79]
	v_pk_mul_f32 v[100:101], v[96:97], v[130:131]
	v_pk_mul_f32 v[130:131], v[180:181], v[194:195]
	v_pk_mul_f32 v[100:101], v[100:101], v[88:89]
	v_pk_mul_f32 v[132:133], v[130:131], v[86:87]
	ds_read_b128 v[86:89], v213
	v_cvt_f32_i32_e32 v83, v83
	v_cvt_f32_i32_e32 v82, v82
	v_cvt_f32_i32_e32 v85, v85
	v_cvt_f32_i32_e32 v84, v84
	v_pk_mul_f32 v[96:97], v[96:97], v[134:135]
	v_pk_mul_f32 v[130:131], v[180:181], v[192:193]
	v_mov_b32_e32 v140, v115
	v_pk_mul_f32 v[96:97], v[96:97], v[84:85]
	v_pk_mul_f32 v[130:131], v[130:131], v[82:83]
	ds_read_b128 v[82:85], v212 offset:1040
	s_waitcnt lgkmcnt(1)
	v_pk_mul_f32 v[134:135], v[88:89], 0 op_sel_hi:[1,0]
	v_pk_mul_f32 v[138:139], v[86:87], 0 op_sel_hi:[1,0]
	v_mov_b32_e32 v146, v115
	v_cndmask_b32_e64 v86, v86, v138, s[36:37]
	v_cndmask_b32_e64 v87, v87, v139, s[36:37]
	v_cndmask_b32_e64 v107, v88, v134, s[36:37]
	v_cndmask_b32_e64 v205, v89, v135, s[36:37]
	v_mov_b32_dpp v140, v102 row_ror:1 row_mask:0xf bank_mask:0xf
	v_mov_b32_e32 v88, v115
	v_mov_b32_e32 v143, v115
	v_mov_b32_dpp v146, v103 row_ror:1 row_mask:0xf bank_mask:0xf
	v_mov_b32_e32 v89, v115
	v_mov_b32_e32 v149, v115
	v_mov_b32_dpp v88, v102 row_ror:15 row_mask:0xf bank_mask:0xf
	v_mov_b32_dpp v143, v132 row_ror:15 row_mask:0xf bank_mask:0xf
	v_mov_b32_dpp v89, v103 row_ror:15 row_mask:0xf bank_mask:0xf
	v_mov_b32_dpp v149, v133 row_ror:15 row_mask:0xf bank_mask:0xf
	v_cndmask_b32_e64 v87, v146, v87, s[38:39]
	v_cndmask_b32_e64 v86, v140, v86, s[38:39]
	v_mov_b32_e32 v152, v115
	v_mov_b32_e32 v199, v115
	v_cndmask_b32_e64 v89, v89, v149, s[40:41]
	v_cndmask_b32_e64 v88, v88, v143, s[40:41]
	v_mov_b32_dpp v152, v104 row_ror:1 row_mask:0xf bank_mask:0xf
	v_mov_b32_e32 v220, v115
	v_mov_b32_e32 v175, v115
	v_mov_b32_dpp v199, v105 row_ror:1 row_mask:0xf bank_mask:0xf
	v_mov_b32_e32 v221, v115
	v_mov_b32_e32 v200, v115
	v_mov_b32_dpp v220, v104 row_ror:15 row_mask:0xf bank_mask:0xf
	v_mov_b32_dpp v175, v100 row_ror:15 row_mask:0xf bank_mask:0xf
	v_mov_b32_dpp v221, v105 row_ror:15 row_mask:0xf bank_mask:0xf
	v_mov_b32_dpp v200, v101 row_ror:15 row_mask:0xf bank_mask:0xf
	v_cndmask_b32_e64 v221, v221, v200, s[40:41]
	v_cndmask_b32_e64 v220, v220, v175, s[40:41]
	v_mov_b32_e32 v114, v115
	v_mov_b32_e32 v134, v115
	v_mov_b32_e32 v135, v115
	v_mov_b32_e32 v201, v115
	v_mov_b32_e32 v139, v115
	v_mov_b32_e32 v138, v115
	v_mov_b32_e32 v141, v115
	v_mov_b32_e32 v142, v115
	v_mov_b32_e32 v202, v115
	v_mov_b32_e32 v144, v115
	v_mov_b32_e32 v145, v115
	s_waitcnt vmcnt(3)
	v_pk_mul_f32 v[150:151], v[102:103], v[110:111]
	v_pk_mul_f32 v[160:161], v[104:105], v[112:113]
	s_waitcnt vmcnt(2)
	v_pk_fma_f32 v[86:87], v[126:127], v[86:87], v[150:151]
	v_mov_b32_e32 v147, v115
	s_waitcnt vmcnt(1)
	v_pk_fma_f32 v[86:87], v[118:119], v[88:89], v[86:87]
	v_cndmask_b32_e64 v89, v199, v205, s[38:39]
	v_cndmask_b32_e64 v88, v152, v107, s[38:39]
	v_pk_fma_f32 v[88:89], v[128:129], v[88:89], v[160:161]
	v_mov_b32_e32 v148, v115
	v_mov_b32_e32 v203, v115
	v_mov_b32_e32 v151, v115
	v_mov_b32_e32 v150, v115
	v_mov_b32_e32 v153, v115
	v_mov_b32_e32 v173, v115
	v_mov_b32_e32 v204, v115
	v_mov_b32_e32 v198, v115
	v_pk_fma_f32 v[88:89], v[120:121], v[220:221], v[88:89]
	v_mov_b32_dpp v114, v132 row_ror:1 row_mask:0xf bank_mask:0xf
	v_mov_b32_dpp v134, v130 row_ror:1 row_mask:0xf bank_mask:0xf
	v_mov_b32_dpp v135, v130 row_ror:15 row_mask:0xf bank_mask:0xf
	v_mov_b32_dpp v201, v90 row_ror:1 row_mask:0xf bank_mask:0xf
	v_mov_b32_dpp v139, v90 row_ror:15 row_mask:0xf bank_mask:0xf
	v_mov_b32_dpp v138, v133 row_ror:1 row_mask:0xf bank_mask:0xf
	v_mov_b32_dpp v141, v131 row_ror:1 row_mask:0xf bank_mask:0xf
	v_mov_b32_dpp v142, v131 row_ror:15 row_mask:0xf bank_mask:0xf
	v_mov_b32_dpp v202, v91 row_ror:1 row_mask:0xf bank_mask:0xf
	v_mov_b32_dpp v144, v91 row_ror:15 row_mask:0xf bank_mask:0xf
	s_waitcnt vmcnt(0)
	v_pk_add_f32 v[86:87], v[122:123], v[86:87]
	v_mov_b32_dpp v145, v100 row_ror:1 row_mask:0xf bank_mask:0xf
	v_mov_b32_dpp v147, v96 row_ror:1 row_mask:0xf bank_mask:0xf
	v_mov_b32_dpp v148, v96 row_ror:15 row_mask:0xf bank_mask:0xf
	v_mov_b32_dpp v203, v92 row_ror:1 row_mask:0xf bank_mask:0xf
	v_mov_b32_dpp v151, v92 row_ror:15 row_mask:0xf bank_mask:0xf
	v_mov_b32_dpp v150, v101 row_ror:1 row_mask:0xf bank_mask:0xf
	v_mov_b32_dpp v153, v97 row_ror:1 row_mask:0xf bank_mask:0xf
	v_mov_b32_dpp v173, v97 row_ror:15 row_mask:0xf bank_mask:0xf
	v_mov_b32_dpp v204, v93 row_ror:1 row_mask:0xf bank_mask:0xf
	v_mov_b32_dpp v198, v93 row_ror:15 row_mask:0xf bank_mask:0xf
	v_pk_add_f32 v[88:89], v[124:125], v[88:89]
	s_and_saveexec_b64 s[54:55], s[44:45]
	s_cbranch_execz .LBB0_1126
	s_add_u32 s68, s3, s25
	s_addc_u32 s69, s62, s23
	v_lshl_add_u64 v[160:161], v[170:171], 2, s[68:69]
	global_store_dwordx4 v[160:161], v[102:105], off offset:16 nt
	s_nop 1
	v_add_co_u32_e32 v102, vcc, 0x5000, v160
	s_nop 1
	v_addc_co_u32_e32 v103, vcc, 0, v161, vcc
	global_store_dwordx4 v[102:103], v[86:89], off offset:2064 nt
	v_add_co_u32_e32 v102, vcc, 0xb000, v160
	s_nop 1
	v_addc_co_u32_e32 v103, vcc, 0, v161, vcc
	global_store_dwordx4 v[102:103], v[78:81], off offset:16 nt
.LBB0_1126:
	s_or_b64 exec, exec, s[54:55]
	s_waitcnt lgkmcnt(0)
	v_pk_mul_f32 v[104:105], v[82:83], 0 op_sel_hi:[1,0]
	v_pk_mul_f32 v[102:103], v[84:85], 0 op_sel_hi:[1,0]
	v_cndmask_b32_e64 v104, v82, v104, s[42:43]
	v_cndmask_b32_e64 v105, v83, v105, s[42:43]
	v_cndmask_b32_e64 v160, v84, v102, s[42:43]
	v_cndmask_b32_e64 v161, v85, v103, s[42:43]
	v_cndmask_b32_e64 v82, v201, v134, s[38:39]
	v_cndmask_b32_e64 v83, v202, v141, s[38:39]
	v_cndmask_b32_e64 v85, v144, v105, s[40:41]
	v_cndmask_b32_e64 v84, v139, v104, s[40:41]
	v_pk_mul_f32 v[104:105], v[90:91], v[110:111]
	v_pk_mul_f32 v[102:103], v[92:93], v[112:113]
	v_pk_fma_f32 v[82:83], v[126:127], v[82:83], v[104:105]
	v_cvt_f32_i32_e32 v75, v75
	v_pk_fma_f32 v[82:83], v[118:119], v[84:85], v[82:83]
	v_cndmask_b32_e64 v84, v203, v147, s[38:39]
	v_cndmask_b32_e64 v85, v204, v153, s[38:39]
	v_cvt_f32_i32_e32 v74, v74
	v_cvt_f32_i32_e32 v77, v77
	v_cvt_f32_i32_e32 v76, v76
	v_cndmask_b32_e64 v105, v198, v161, s[40:41]
	v_cndmask_b32_e64 v104, v151, v160, s[40:41]
	v_pk_fma_f32 v[84:85], v[128:129], v[84:85], v[102:103]
	v_mov_b32_e32 v107, v106
	v_pk_fma_f32 v[84:85], v[120:121], v[104:105], v[84:85]
	v_mov_b32_e32 v104, v196
	v_mov_b32_e32 v105, v196
	v_mov_b32_e32 v102, v106
	v_mov_b32_e32 v103, v106
	v_pk_mul_f32 v[104:105], v[102:103], v[104:105]
	v_pk_mul_f32 v[160:161], v[106:107], v[196:197]
	v_pk_add_f32 v[82:83], v[122:123], v[82:83]
	v_pk_add_f32 v[84:85], v[124:125], v[84:85]
	v_pk_mul_f32 v[76:77], v[104:105], v[76:77]
	v_pk_mul_f32 v[74:75], v[160:161], v[74:75]
	s_and_saveexec_b64 s[54:55], s[14:15]
	s_cbranch_execz .LBB0_1128
	s_add_u32 s68, s3, s79
	s_addc_u32 s69, s62, s78
	v_lshl_add_u64 v[104:105], v[170:171], 2, s[68:69]
	global_store_dwordx4 v[104:105], v[90:93], off offset:16 nt
	s_nop 1
	v_add_co_u32_e32 v90, vcc, 0x5000, v104
	s_nop 1
	v_addc_co_u32_e32 v91, vcc, 0, v105, vcc
	global_store_dwordx4 v[90:91], v[82:85], off offset:2064 nt
	v_add_co_u32_e32 v90, vcc, 0xb000, v104
	s_nop 1
	v_addc_co_u32_e32 v91, vcc, 0, v105, vcc
	global_store_dwordx4 v[90:91], v[74:77], off offset:16 nt
.LBB0_1128:
	s_or_b64 exec, exec, s[54:55]
	v_cndmask_b32_e64 v90, v114, v140, s[38:39]
	v_mul_f32_e32 v90, v126, v90
	v_cndmask_b32_e64 v91, v143, v135, s[40:41]
	v_fmac_f32_e32 v90, v132, v110
	v_fmac_f32_e32 v90, v118, v91
	v_add_f32_e32 v104, v122, v90
	v_cndmask_b32_e64 v90, v138, v146, s[38:39]
	v_mul_f32_e32 v90, v127, v90
	v_cndmask_b32_e64 v91, v149, v142, s[40:41]
	v_fmac_f32_e32 v90, v133, v111
	v_fmac_f32_e32 v90, v119, v91
	v_add_f32_e32 v105, v123, v90
	v_cndmask_b32_e64 v90, v134, v114, s[38:39]
	v_mul_f32_e32 v90, v126, v90
	v_cndmask_b32_e64 v91, v135, v139, s[40:41]
	v_fmac_f32_e32 v90, v130, v110
	v_fmac_f32_e32 v90, v118, v91
	v_add_f32_e32 v110, v122, v90
	v_cndmask_b32_e64 v90, v141, v138, s[38:39]
	v_mul_f32_e32 v90, v127, v90
	v_cndmask_b32_e64 v91, v142, v144, s[40:41]
	v_fmac_f32_e32 v90, v131, v111
	v_cvt_f32_i32_e32 v69, v69
	v_cvt_f32_i32_e32 v68, v68
	v_fmac_f32_e32 v90, v119, v91
	v_add_f32_e32 v111, v123, v90
	v_cndmask_b32_e64 v90, v145, v152, s[38:39]
	v_mov_b32_e32 v92, v194
	v_mov_b32_e32 v93, v194
	v_mul_f32_e32 v90, v128, v90
	v_pk_mul_f32 v[92:93], v[102:103], v[92:93]
	v_fmac_f32_e32 v90, v100, v112
	v_pk_mul_f32 v[68:69], v[92:93], v[68:69]
	v_mov_b32_e32 v92, v192
	v_mov_b32_e32 v93, v192
	v_mul_f32_e32 v100, 0xbfb8aa3b, v86
	v_cvt_f32_i32_e32 v61, v61
	v_cvt_f32_i32_e32 v60, v60
	v_pk_mul_f32 v[92:93], v[102:103], v[92:93]
	v_exp_f32_e32 v100, v100
	v_mul_f32_e32 v102, 0xbfb8aa3b, v87
	v_exp_f32_e32 v102, v102
	v_pk_mul_f32 v[60:61], v[92:93], v[60:61]
	v_add_f32_e32 v92, 1.0, v100
	v_rcp_f32_e32 v92, v92
	v_add_f32_e32 v93, 1.0, v102
	v_cndmask_b32_e64 v91, v175, v148, s[40:41]
	v_rcp_f32_e32 v93, v93
	v_fmac_f32_e32 v90, v120, v91
	v_add_f32_e32 v118, v124, v90
	v_cndmask_b32_e64 v90, v150, v199, s[38:39]
	v_mul_f32_e32 v90, v129, v90
	v_mul_f32_e32 v86, v86, v92
	v_cndmask_b32_e64 v91, v200, v173, s[40:41]
	v_fmac_f32_e32 v90, v101, v113
	v_mul_f32_e32 v78, v78, v86
	v_mul_f32_e32 v86, v87, v93
	v_mul_f32_e32 v87, 0xbfb8aa3b, v88
	v_fmac_f32_e32 v90, v121, v91
	v_exp_f32_e32 v87, v87
	v_add_f32_e32 v101, v125, v90
	v_cndmask_b32_e64 v90, v147, v145, s[38:39]
	v_mul_f32_e32 v90, v128, v90
	v_cndmask_b32_e64 v91, v148, v151, s[40:41]
	v_fmac_f32_e32 v90, v96, v112
	v_fmac_f32_e32 v90, v120, v91
	v_cvt_f32_i32_e32 v67, v67
	v_cvt_f32_i32_e32 v66, v66
	v_mul_f32_e32 v79, v79, v86
	v_add_f32_e32 v86, 1.0, v87
	v_add_f32_e32 v112, v124, v90
	v_cndmask_b32_e64 v90, v153, v150, s[38:39]
	v_cvt_f32_i32_e32 v59, v59
	v_cvt_f32_i32_e32 v58, v58
	v_mul_f32_e32 v92, 0xbfb8aa3b, v89
	v_rcp_f32_e32 v86, v86
	v_mul_f32_e32 v90, v129, v90
	v_exp_f32_e32 v92, v92
	v_fmac_f32_e32 v90, v97, v113
	v_pk_mul_f32 v[96:97], v[106:107], v[194:195]
	v_cndmask_b32_e64 v91, v173, v198, s[40:41]
	v_pk_mul_f32 v[66:67], v[96:97], v[66:67]
	v_pk_mul_f32 v[96:97], v[106:107], v[192:193]
	v_add_f32_e32 v87, 1.0, v92
	v_pk_mul_f32 v[58:59], v[96:97], v[58:59]
	v_cvt_pk_bf16_f32 v96, v78, v79
	v_mul_f32_e32 v78, v88, v86
	v_mul_f32_e32 v78, v80, v78
	v_mul_f32_e32 v80, 0xbfb8aa3b, v104
	v_rcp_f32_e32 v87, v87
	v_exp_f32_e32 v80, v80
	v_mul_f32_e32 v86, 0xbfb8aa3b, v105
	v_exp_f32_e32 v86, v86
	v_mul_f32_e32 v79, v89, v87
	v_add_f32_e32 v80, 1.0, v80
	v_mul_f32_e32 v79, v81, v79
	v_rcp_f32_e32 v80, v80
	v_add_f32_e32 v81, 1.0, v86
	v_rcp_f32_e32 v81, v81
	v_cvt_pk_bf16_f32 v97, v78, v79
	v_mul_f32_e32 v79, 0xbfb8aa3b, v118
	v_exp_f32_e32 v79, v79
	v_mul_f32_e32 v78, v104, v80
	v_mul_f32_e32 v66, v66, v78
	v_mul_f32_e32 v78, v105, v81
	v_mul_f32_e32 v67, v67, v78
	v_add_f32_e32 v78, 1.0, v79
	v_mul_f32_e32 v80, 0xbfb8aa3b, v101
	v_rcp_f32_e32 v78, v78
	v_exp_f32_e32 v80, v80
	v_cvt_pk_bf16_f32 v100, v66, v67
	v_fmac_f32_e32 v90, v121, v91
	v_mul_f32_e32 v66, v118, v78
	v_add_f32_e32 v79, 1.0, v80
	v_mul_f32_e32 v66, v68, v66
	v_mul_f32_e32 v68, 0xbfb8aa3b, v110
	v_rcp_f32_e32 v79, v79
	v_exp_f32_e32 v68, v68
	v_mul_f32_e32 v78, 0xbfb8aa3b, v111
	v_exp_f32_e32 v78, v78
	v_mul_f32_e32 v67, v101, v79
	v_add_f32_e32 v68, 1.0, v68
	v_mul_f32_e32 v67, v69, v67
	v_rcp_f32_e32 v68, v68
	v_add_f32_e32 v69, 1.0, v78
	v_rcp_f32_e32 v69, v69
	v_cvt_pk_bf16_f32 v101, v66, v67
	v_mul_f32_e32 v67, 0xbfb8aa3b, v112
	v_exp_f32_e32 v67, v67
	v_mul_f32_e32 v66, v110, v68
	v_mul_f32_e32 v58, v58, v66
	v_mul_f32_e32 v66, v111, v69
	v_add_f32_e32 v113, v125, v90
	v_mul_f32_e32 v59, v59, v66
	v_add_f32_e32 v66, 1.0, v67
	v_mul_f32_e32 v68, 0xbfb8aa3b, v113
	v_rcp_f32_e32 v66, v66
	v_exp_f32_e32 v68, v68
	v_cvt_pk_bf16_f32 v110, v58, v59
	s_lshl_b32 s0, s76, 7
	v_mul_f32_e32 v58, v112, v66
	v_add_f32_e32 v67, 1.0, v68
	v_mul_f32_e32 v58, v60, v58
	v_mul_f32_e32 v60, 0xbfb8aa3b, v82
	v_rcp_f32_e32 v67, v67
	v_exp_f32_e32 v60, v60
	v_mul_f32_e32 v66, 0xbfb8aa3b, v83
	v_exp_f32_e32 v66, v66
	v_mul_f32_e32 v59, v113, v67
	v_add_f32_e32 v60, 1.0, v60
	v_mul_f32_e32 v59, v61, v59
	v_rcp_f32_e32 v60, v60
	v_add_f32_e32 v61, 1.0, v66
	v_rcp_f32_e32 v61, v61
	v_cvt_pk_bf16_f32 v111, v58, v59
	v_mul_f32_e32 v58, v82, v60
	v_mul_f32_e32 v60, 0xbfb8aa3b, v84
	v_mul_f32_e32 v59, v83, v61
	v_exp_f32_e32 v60, v60
	v_mul_f32_e32 v61, 0xbfb8aa3b, v85
	v_exp_f32_e32 v61, v61
	s_mul_i32 s1, s76, 0x2c0000
	v_add_f32_e32 v60, 1.0, v60
	v_rcp_f32_e32 v60, v60
	v_add_f32_e32 v61, 1.0, v61
	v_rcp_f32_e32 v61, v61
	s_mul_hi_i32 s0, s0, 0x5800
	s_add_u32 s54, s64, s1
	v_lshl_add_u32 v90, s74, 8, v217
	v_mul_f32_e32 v58, v74, v58
	s_addc_u32 s55, s57, s0
	v_or_b32_e32 v114, v90, v218
	v_mul_f32_e32 v59, v75, v59
	v_cvt_pk_bf16_f32 v118, v58, v59
	v_mul_f32_e32 v58, v84, v60
	v_lshl_add_u64 v[90:91], v[114:115], 1, s[54:55]
	v_mul_f32_e32 v58, v76, v58
	v_mul_f32_e32 v59, v85, v61
	s_mov_b32 s0, 0x2c000
	v_mul_f32_e32 v59, v77, v59
	v_cvt_pk_bf16_f32 v119, v58, v59
	v_add_co_u32_e32 v58, vcc, s0, v90
	s_mov_b32 s0, 0x58000
	s_nop 0
	v_addc_co_u32_e32 v59, vcc, 0, v91, vcc
	global_store_dwordx4 v[58:59], v[98:101], off nt
	v_add_co_u32_e32 v58, vcc, s0, v90
	s_mov_b32 s0, 0x84000
	s_nop 0
	v_addc_co_u32_e32 v59, vcc, 0, v91, vcc
	global_store_dwordx4 v[58:59], v[108:111], off nt
	v_add_co_u32_e32 v58, vcc, s0, v90
	global_store_dwordx4 v[90:91], v[94:97], off nt
	s_nop 0
	v_addc_co_u32_e32 v59, vcc, 0, v91, vcc
	global_store_dwordx4 v[58:59], v[116:119], off nt
	global_load_dwordx4 v[66:69], v[184:185], off
	global_load_dwordx4 v[82:85], v[182:183], off
	global_load_dwordx4 v[74:77], v[186:187], off
	global_load_dwordx4 v[78:81], v[188:189], off
	v_cvt_f32_i32_e32 v49, v49
	v_cvt_f32_i32_e32 v48, v48
	v_cvt_f32_i32_e32 v47, v47
	v_cvt_f32_i32_e32 v46, v46
	v_cvt_f32_i32_e32 v55, v55
	v_cvt_f32_i32_e32 v54, v54
	v_cvt_f32_i32_e32 v57, v57
	v_cvt_f32_i32_e32 v56, v56
	v_mov_b32_e32 v60, v178
	v_mov_b32_e32 v61, v178
	v_mov_b32_e32 v58, v136
	v_mov_b32_e32 v59, v136
	v_pk_mul_f32 v[60:61], v[58:59], v[60:61]
	v_pk_mul_f32 v[86:87], v[136:137], v[178:179]
	v_pk_mul_f32 v[48:49], v[60:61], v[48:49]
	v_mov_b32_e32 v60, v190
	v_mov_b32_e32 v61, v190
	v_pk_mul_f32 v[46:47], v[86:87], v[46:47]
	v_pk_mul_f32 v[86:87], v[60:61], v[174:175] op_sel_hi:[1,0]
	v_pk_mul_f32 v[92:93], v[190:191], v[174:175] op_sel_hi:[1,0]
	v_pk_mul_f32 v[88:89], v[86:87], v[56:57]
	v_pk_mul_f32 v[94:95], v[92:93], v[54:55]
	ds_read_b128 v[54:57], v214
	v_cvt_f32_i32_e32 v51, v51
	v_cvt_f32_i32_e32 v50, v50
	v_cvt_f32_i32_e32 v53, v53
	v_cvt_f32_i32_e32 v52, v52
	v_pk_mul_f32 v[60:61], v[60:61], v[172:173] op_sel_hi:[1,0]
	v_pk_mul_f32 v[92:93], v[190:191], v[172:173] op_sel_hi:[1,0]
	v_mov_b32_e32 v101, v115
	v_pk_mul_f32 v[86:87], v[60:61], v[52:53]
	v_pk_mul_f32 v[92:93], v[92:93], v[50:51]
	ds_read_b128 v[50:53], v215 offset:1024
	s_waitcnt lgkmcnt(1)
	v_pk_mul_f32 v[60:61], v[56:57], 0 op_sel_hi:[1,0]
	v_pk_mul_f32 v[96:97], v[54:55], 0 op_sel_hi:[1,0]
	v_mov_b32_e32 v109, v115
	v_cndmask_b32_e64 v54, v54, v96, s[46:47]
	v_cndmask_b32_e64 v55, v55, v97, s[46:47]
	v_cndmask_b32_e64 v125, v56, v60, s[46:47]
	v_cndmask_b32_e64 v128, v57, v61, s[46:47]
	v_mov_b32_dpp v101, v70 row_ror:1 row_mask:0xf bank_mask:0xf
	v_mov_b32_e32 v56, v115
	v_mov_b32_e32 v104, v115
	v_mov_b32_dpp v109, v71 row_ror:1 row_mask:0xf bank_mask:0xf
	v_mov_b32_e32 v57, v115
	v_mov_b32_e32 v112, v115
	v_mov_b32_dpp v56, v70 row_ror:15 row_mask:0xf bank_mask:0xf
	v_mov_b32_dpp v104, v94 row_ror:15 row_mask:0xf bank_mask:0xf
	v_mov_b32_dpp v57, v71 row_ror:15 row_mask:0xf bank_mask:0xf
	v_mov_b32_dpp v112, v95 row_ror:15 row_mask:0xf bank_mask:0xf
	v_cndmask_b32_e64 v55, v109, v55, s[38:39]
	v_cndmask_b32_e64 v54, v101, v54, s[38:39]
	v_mov_b32_e32 v116, v115
	v_mov_b32_e32 v121, v115
	v_cndmask_b32_e64 v57, v57, v112, s[40:41]
	v_cndmask_b32_e64 v56, v56, v104, s[40:41]
	v_mov_b32_dpp v116, v72 row_ror:1 row_mask:0xf bank_mask:0xf
	v_mov_b32_e32 v130, v115
	v_mov_b32_e32 v119, v115
	v_mov_b32_dpp v121, v73 row_ror:1 row_mask:0xf bank_mask:0xf
	v_mov_b32_e32 v129, v115
	v_mov_b32_e32 v122, v115
	v_mov_b32_dpp v130, v72 row_ror:15 row_mask:0xf bank_mask:0xf
	v_mov_b32_dpp v119, v88 row_ror:15 row_mask:0xf bank_mask:0xf
	v_mov_b32_dpp v129, v73 row_ror:15 row_mask:0xf bank_mask:0xf
	v_mov_b32_dpp v122, v89 row_ror:15 row_mask:0xf bank_mask:0xf
	v_cndmask_b32_e64 v129, v129, v122, s[40:41]
	v_mov_b32_e32 v96, v115
	v_mov_b32_e32 v97, v115
	v_mov_b32_e32 v98, v115
	v_mov_b32_e32 v60, v115
	v_mov_b32_e32 v100, v115
	v_mov_b32_e32 v99, v115
	v_mov_b32_e32 v102, v115
	v_mov_b32_e32 v103, v115
	v_mov_b32_e32 v61, v115
	s_waitcnt vmcnt(3)
	v_pk_mul_f32 v[110:111], v[70:71], v[66:67]
	v_pk_mul_f32 v[126:127], v[72:73], v[68:69]
	s_waitcnt vmcnt(2)
	v_pk_fma_f32 v[54:55], v[82:83], v[54:55], v[110:111]
	v_mov_b32_e32 v105, v115
	s_waitcnt vmcnt(1)
	v_pk_fma_f32 v[54:55], v[74:75], v[56:57], v[54:55]
	v_cndmask_b32_e64 v57, v121, v128, s[38:39]
	v_cndmask_b32_e64 v56, v116, v125, s[38:39]
	v_cndmask_b32_e64 v128, v130, v119, s[40:41]
	v_pk_fma_f32 v[56:57], v[84:85], v[56:57], v[126:127]
	v_mov_b32_e32 v108, v115
	v_mov_b32_e32 v110, v115
	v_mov_b32_e32 v111, v115
	v_mov_b32_e32 v123, v115
	v_mov_b32_e32 v114, v115
	v_mov_b32_e32 v113, v115
	v_mov_b32_e32 v117, v115
	v_mov_b32_e32 v118, v115
	v_mov_b32_e32 v124, v115
	v_mov_b32_e32 v120, v115
	v_pk_fma_f32 v[56:57], v[76:77], v[128:129], v[56:57]
	v_mov_b32_dpp v96, v94 row_ror:1 row_mask:0xf bank_mask:0xf
	v_mov_b32_dpp v97, v92 row_ror:1 row_mask:0xf bank_mask:0xf
	v_mov_b32_dpp v98, v92 row_ror:15 row_mask:0xf bank_mask:0xf
	v_mov_b32_dpp v60, v62 row_ror:1 row_mask:0xf bank_mask:0xf
	v_mov_b32_dpp v100, v62 row_ror:15 row_mask:0xf bank_mask:0xf
	v_mov_b32_dpp v99, v95 row_ror:1 row_mask:0xf bank_mask:0xf
	v_mov_b32_dpp v102, v93 row_ror:1 row_mask:0xf bank_mask:0xf
	v_mov_b32_dpp v103, v93 row_ror:15 row_mask:0xf bank_mask:0xf
	v_mov_b32_dpp v61, v63 row_ror:1 row_mask:0xf bank_mask:0xf
	v_mov_b32_dpp v105, v63 row_ror:15 row_mask:0xf bank_mask:0xf
	s_waitcnt vmcnt(0)
	v_pk_add_f32 v[54:55], v[78:79], v[54:55]
	v_mov_b32_dpp v108, v88 row_ror:1 row_mask:0xf bank_mask:0xf
	v_mov_b32_dpp v110, v86 row_ror:1 row_mask:0xf bank_mask:0xf
	v_mov_b32_dpp v111, v86 row_ror:15 row_mask:0xf bank_mask:0xf
	v_mov_b32_dpp v123, v64 row_ror:1 row_mask:0xf bank_mask:0xf
	v_mov_b32_dpp v114, v64 row_ror:15 row_mask:0xf bank_mask:0xf
	v_mov_b32_dpp v113, v89 row_ror:1 row_mask:0xf bank_mask:0xf
	v_mov_b32_dpp v117, v87 row_ror:1 row_mask:0xf bank_mask:0xf
	v_mov_b32_dpp v118, v87 row_ror:15 row_mask:0xf bank_mask:0xf
	v_mov_b32_dpp v124, v65 row_ror:1 row_mask:0xf bank_mask:0xf
	v_mov_b32_dpp v120, v65 row_ror:15 row_mask:0xf bank_mask:0xf
	v_pk_add_f32 v[56:57], v[80:81], v[56:57]
	s_and_saveexec_b64 s[54:55], s[50:51]
	s_cbranch_execz .LBB0_1130
	s_add_u32 s68, s3, s25
	s_addc_u32 s69, s62, s23
	v_lshl_add_u64 v[126:127], v[170:171], 2, s[68:69]
	global_store_dwordx4 v[126:127], v[70:73], off nt
	s_nop 1
	v_add_co_u32_e32 v70, vcc, 0x5000, v126
	s_nop 1
	v_addc_co_u32_e32 v71, vcc, 0, v127, vcc
	global_store_dwordx4 v[70:71], v[54:57], off offset:2048 nt
	v_add_co_u32_e32 v70, vcc, 0xb000, v126
	s_nop 1
	v_addc_co_u32_e32 v71, vcc, 0, v127, vcc
	global_store_dwordx4 v[70:71], v[46:49], off nt
.LBB0_1130:
	s_or_b64 exec, exec, s[54:55]
	s_waitcnt lgkmcnt(0)
	v_pk_mul_f32 v[70:71], v[52:53], 0 op_sel_hi:[1,0]
	v_pk_mul_f32 v[72:73], v[50:51], 0 op_sel_hi:[1,0]
	v_cndmask_b32_e64 v125, v52, v70, s[48:49]
	v_cndmask_b32_e64 v72, v50, v72, s[48:49]
	v_cndmask_b32_e64 v73, v51, v73, s[48:49]
	v_cndmask_b32_e64 v126, v53, v71, s[48:49]
	v_cndmask_b32_e64 v50, v60, v97, s[38:39]
	v_cndmask_b32_e64 v51, v61, v102, s[38:39]
	v_pk_mul_f32 v[70:71], v[62:63], v[66:67]
	v_cndmask_b32_e64 v53, v105, v73, s[40:41]
	v_cndmask_b32_e64 v52, v100, v72, s[40:41]
	v_pk_fma_f32 v[50:51], v[82:83], v[50:51], v[70:71]
	v_cvt_f32_i32_e32 v39, v39
	v_cvt_f32_i32_e32 v38, v38
	v_cvt_f32_i32_e32 v41, v41
	v_cvt_f32_i32_e32 v40, v40
	v_pk_mul_f32 v[60:61], v[64:65], v[68:69]
	v_pk_fma_f32 v[50:51], v[74:75], v[52:53], v[50:51]
	v_cndmask_b32_e64 v52, v123, v110, s[38:39]
	v_cndmask_b32_e64 v53, v124, v117, s[38:39]
	v_cndmask_b32_e64 v71, v120, v126, s[40:41]
	v_cndmask_b32_e64 v70, v114, v125, s[40:41]
	v_pk_fma_f32 v[52:53], v[84:85], v[52:53], v[60:61]
	v_mov_b32_e32 v60, v176
	v_mov_b32_e32 v61, v176
	v_pk_fma_f32 v[52:53], v[76:77], v[70:71], v[52:53]
	v_pk_mul_f32 v[58:59], v[58:59], v[60:61]
	v_pk_mul_f32 v[70:71], v[136:137], v[176:177]
	v_pk_add_f32 v[50:51], v[78:79], v[50:51]
	v_pk_add_f32 v[52:53], v[80:81], v[52:53]
	v_pk_mul_f32 v[60:61], v[58:59], v[40:41]
	v_pk_mul_f32 v[58:59], v[70:71], v[38:39]
	s_and_saveexec_b64 s[54:55], s[16:17]
	s_cbranch_execz .LBB0_1132
	s_add_u32 s68, s3, s79
	s_addc_u32 s69, s62, s78
	v_lshl_add_u64 v[38:39], v[170:171], 2, s[68:69]
	v_add_co_u32_e32 v40, vcc, 0x5000, v38
	global_store_dwordx4 v[38:39], v[62:65], off nt
	s_nop 0
	v_addc_co_u32_e32 v41, vcc, 0, v39, vcc
	v_add_co_u32_e32 v38, vcc, 0xb000, v38
	global_store_dwordx4 v[40:41], v[50:53], off offset:2048 nt
	s_nop 0
	v_addc_co_u32_e32 v39, vcc, 0, v39, vcc
	global_store_dwordx4 v[38:39], v[58:61], off nt
.LBB0_1132:
	s_or_b64 exec, exec, s[54:55]
	v_cndmask_b32_e64 v38, v96, v101, s[38:39]
	v_mul_f32_e32 v38, v82, v38
	v_cndmask_b32_e64 v39, v104, v98, s[40:41]
	v_fmac_f32_e32 v38, v94, v66
	v_fmac_f32_e32 v38, v74, v39
	v_add_f32_e32 v70, v78, v38
	v_cndmask_b32_e64 v38, v99, v109, s[38:39]
	v_mul_f32_e32 v38, v83, v38
	v_cndmask_b32_e64 v39, v112, v103, s[40:41]
	v_fmac_f32_e32 v38, v95, v67
	v_fmac_f32_e32 v38, v75, v39
	v_add_f32_e32 v71, v79, v38
	v_cndmask_b32_e64 v38, v97, v96, s[38:39]
	v_mul_f32_e32 v38, v82, v38
	v_cndmask_b32_e64 v39, v98, v100, s[40:41]
	v_fmac_f32_e32 v38, v92, v66
	v_fmac_f32_e32 v38, v74, v39
	v_add_f32_e32 v66, v78, v38
	v_cndmask_b32_e64 v38, v102, v99, s[38:39]
	v_mul_f32_e32 v38, v83, v38
	v_cndmask_b32_e64 v39, v103, v105, s[40:41]
	v_fmac_f32_e32 v38, v93, v67
	v_fmac_f32_e32 v38, v75, v39
	v_add_f32_e32 v67, v79, v38
	v_cndmask_b32_e64 v38, v108, v116, s[38:39]
	v_mul_f32_e32 v38, v84, v38
	v_cndmask_b32_e64 v39, v119, v111, s[40:41]
	v_fmac_f32_e32 v38, v88, v68
	v_fmac_f32_e32 v38, v76, v39
	v_add_f32_e32 v72, v80, v38
	v_cndmask_b32_e64 v38, v113, v121, s[38:39]
	v_mul_f32_e32 v38, v85, v38
	v_cndmask_b32_e64 v39, v122, v118, s[40:41]
	v_fmac_f32_e32 v38, v89, v69
	v_fmac_f32_e32 v38, v77, v39
	v_add_f32_e32 v73, v81, v38
	v_cndmask_b32_e64 v38, v110, v108, s[38:39]
	v_mul_f32_e32 v38, v84, v38
	v_cndmask_b32_e64 v39, v111, v114, s[40:41]
	v_fmac_f32_e32 v38, v86, v68
	v_fmac_f32_e32 v38, v76, v39
	v_add_f32_e32 v68, v80, v38
	v_cndmask_b32_e64 v38, v117, v113, s[38:39]
	v_cvt_f32_i32_e32 v31, v31
	v_cvt_f32_i32_e32 v30, v30
	v_mul_f32_e32 v38, v85, v38
	v_mul_f32_e32 v74, 0xbfb8aa3b, v54
	v_mov_b32_e32 v175, v174
	v_cndmask_b32_e64 v39, v118, v120, s[40:41]
	v_fmac_f32_e32 v38, v87, v69
	v_cvt_f32_i32_e32 v29, v29
	v_cvt_f32_i32_e32 v28, v28
	v_exp_f32_e32 v74, v74
	v_fmac_f32_e32 v38, v77, v39
	v_pk_mul_f32 v[64:65], v[136:137], v[174:175]
	v_add_f32_e32 v69, v81, v38
	v_mov_b32_e32 v40, v174
	v_mov_b32_e32 v41, v174
	v_mov_b32_e32 v38, v136
	v_mov_b32_e32 v39, v136
	v_pk_mul_f32 v[30:31], v[64:65], v[30:31]
	v_mov_b32_e32 v64, v172
	v_mov_b32_e32 v65, v172
	v_pk_mul_f32 v[62:63], v[38:39], v[40:41]
	v_pk_mul_f32 v[38:39], v[38:39], v[64:65]
	v_mul_f32_e32 v75, 0xbfb8aa3b, v55
	v_cvt_f32_i32_e32 v33, v33
	v_cvt_f32_i32_e32 v32, v32
	v_exp_f32_e32 v75, v75
	v_pk_mul_f32 v[28:29], v[38:39], v[28:29]
	v_add_f32_e32 v38, 1.0, v74
	v_cvt_f32_i32_e32 v27, v27
	v_cvt_f32_i32_e32 v26, v26
	v_rcp_f32_e32 v74, v38
	v_mov_b32_e32 v173, v172
	v_pk_mul_f32 v[32:33], v[62:63], v[32:33]
	v_pk_mul_f32 v[62:63], v[136:137], v[172:173]
	v_add_f32_e32 v38, 1.0, v75
	v_rcp_f32_e32 v75, v38
	v_pk_mul_f32 v[38:39], v[62:63], v[26:27]
	v_mul_f32_e32 v26, v54, v74
	v_mul_f32_e32 v26, v46, v26
	v_mul_f32_e32 v46, 0xbfb8aa3b, v56
	v_mul_f32_e32 v54, 0xbfb8aa3b, v57
	v_exp_f32_e32 v46, v46
	v_exp_f32_e32 v54, v54
	v_mul_f32_e32 v27, v55, v75
	v_mul_f32_e32 v27, v47, v27
	v_add_f32_e32 v46, 1.0, v46
	v_add_f32_e32 v47, 1.0, v54
	v_rcp_f32_e32 v46, v46
	v_rcp_f32_e32 v47, v47
	v_cvt_pk_bf16_f32 v26, v26, v27
	v_cvt_f32_i32_e32 v17, v17
	v_mul_f32_e32 v27, v56, v46
	v_mul_f32_e32 v46, v57, v47
	v_mul_f32_e32 v47, 0xbfb8aa3b, v70
	v_exp_f32_e32 v47, v47
	v_mul_f32_e32 v27, v48, v27
	v_mul_f32_e32 v48, 0xbfb8aa3b, v71
	v_exp_f32_e32 v48, v48
	v_add_f32_e32 v47, 1.0, v47
	v_rcp_f32_e32 v47, v47
	v_mul_f32_e32 v46, v49, v46
	v_add_f32_e32 v48, 1.0, v48
	v_rcp_f32_e32 v48, v48
	v_cvt_pk_bf16_f32 v27, v27, v46
	v_mul_f32_e32 v46, v70, v47
	v_mul_f32_e32 v47, 0xbfb8aa3b, v72
	v_exp_f32_e32 v47, v47
	v_mul_f32_e32 v30, v30, v46
	v_mul_f32_e32 v46, v71, v48
	v_mul_f32_e32 v48, 0xbfb8aa3b, v73
	v_exp_f32_e32 v48, v48
	v_mul_f32_e32 v31, v31, v46
	v_add_f32_e32 v46, 1.0, v47
	v_rcp_f32_e32 v46, v46
	v_add_f32_e32 v47, 1.0, v48
	v_rcp_f32_e32 v47, v47
	v_cvt_pk_bf16_f32 v30, v30, v31
	v_mul_f32_e32 v31, v72, v46
	v_mul_f32_e32 v46, 0xbfb8aa3b, v66
	v_exp_f32_e32 v46, v46
	v_mul_f32_e32 v31, v32, v31
	v_mul_f32_e32 v32, v73, v47
	v_mul_f32_e32 v47, 0xbfb8aa3b, v67
	v_mul_f32_e32 v32, v33, v32
	v_add_f32_e32 v33, 1.0, v46
	v_exp_f32_e32 v47, v47
	v_rcp_f32_e32 v33, v33
	v_cvt_pk_bf16_f32 v31, v31, v32
	v_cvt_f32_i32_e32 v16, v16
	v_add_f32_e32 v46, 1.0, v47
	v_mul_f32_e32 v32, v66, v33
	v_rcp_f32_e32 v46, v46
	v_mul_f32_e32 v32, v38, v32
	v_mul_f32_e32 v38, 0xbfb8aa3b, v68
	v_exp_f32_e32 v38, v38
	v_mul_f32_e32 v33, v67, v46
	v_mul_f32_e32 v46, 0xbfb8aa3b, v69
	v_exp_f32_e32 v46, v46
	v_add_f32_e32 v38, 1.0, v38
	v_mul_f32_e32 v33, v39, v33
	v_rcp_f32_e32 v39, v38
	v_add_f32_e32 v38, 1.0, v46
	v_rcp_f32_e32 v46, v38
	v_cvt_pk_bf16_f32 v38, v32, v33
	v_mul_f32_e32 v32, v68, v39
	v_mul_f32_e32 v33, 0xbfb8aa3b, v50
	v_mul_f32_e32 v39, 0xbfb8aa3b, v51
	v_exp_f32_e32 v33, v33
	v_exp_f32_e32 v39, v39
	v_mul_f32_e32 v28, v28, v32
	v_mul_f32_e32 v32, v69, v46
	v_mul_f32_e32 v29, v29, v32
	v_add_f32_e32 v32, 1.0, v33
	v_add_f32_e32 v33, 1.0, v39
	v_rcp_f32_e32 v32, v32
	v_rcp_f32_e32 v33, v33
	v_cvt_pk_bf16_f32 v39, v28, v29
	v_cvt_f32_i32_e32 v23, v23
	v_mul_f32_e32 v28, v50, v32
	v_mul_f32_e32 v29, v51, v33
	v_mul_f32_e32 v32, 0xbfb8aa3b, v52
	v_mul_f32_e32 v33, 0xbfb8aa3b, v53
	v_exp_f32_e32 v32, v32
	v_exp_f32_e32 v33, v33
	v_mul_f32_e32 v28, v58, v28
	v_mul_f32_e32 v29, v59, v29
	v_add_f32_e32 v32, 1.0, v32
	v_add_f32_e32 v33, 1.0, v33
	v_rcp_f32_e32 v32, v32
	v_rcp_f32_e32 v33, v33
	v_cvt_pk_bf16_f32 v46, v28, v29
	v_cvt_f32_i32_e32 v22, v22
	v_mul_f32_e32 v28, v52, v32
	v_mul_f32_e32 v29, v53, v33
	v_mul_f32_e32 v28, v60, v28
	v_mul_f32_e32 v29, v61, v29
	v_cvt_pk_bf16_f32 v47, v28, v29
	global_load_dwordx4 v[56:59], v[184:185], off offset:16
	global_load_dwordx4 v[60:63], v[182:183], off offset:16
	global_load_dwordx4 v[52:55], v[186:187], off offset:16
	global_load_dwordx4 v[48:51], v[188:189], off offset:16
	v_cvt_f32_i32_e32 v25, v25
	v_cvt_f32_i32_e32 v24, v24
	v_cvt_f32_i32_e32 v15, v15
	v_cvt_f32_i32_e32 v14, v14
	v_mov_b32_e32 v28, v178
	v_mov_b32_e32 v29, v178
	v_mov_b32_e32 v66, v106
	v_mov_b32_e32 v67, v106
	v_pk_mul_f32 v[28:29], v[66:67], v[28:29]
	v_mov_b32_e32 v68, v180
	v_mov_b32_e32 v69, v180
	v_pk_mul_f32 v[32:33], v[106:107], v[178:179]
	v_pk_mul_f32 v[16:17], v[28:29], v[16:17]
	v_pk_mul_f32 v[28:29], v[68:69], v[40:41]
	v_pk_mul_f32 v[40:41], v[180:181], v[174:175]
	v_pk_mul_f32 v[14:15], v[32:33], v[14:15]
	v_pk_mul_f32 v[32:33], v[28:29], v[24:25]
	v_pk_mul_f32 v[28:29], v[40:41], v[22:23]
	ds_read_b128 v[22:25], v216
	v_cvt_f32_i32_e32 v19, v19
	v_cvt_f32_i32_e32 v18, v18
	v_cvt_f32_i32_e32 v21, v21
	v_cvt_f32_i32_e32 v20, v20
	v_pk_mul_f32 v[40:41], v[68:69], v[64:65]
	v_pk_mul_f32 v[68:69], v[180:181], v[172:173]
	v_mov_b32_e32 v74, v115
	v_pk_mul_f32 v[64:65], v[40:41], v[20:21]
	v_pk_mul_f32 v[40:41], v[68:69], v[18:19]
	ds_read_b128 v[18:21], v215 offset:1040
	s_waitcnt lgkmcnt(1)
	v_pk_mul_f32 v[68:69], v[24:25], 0 op_sel_hi:[1,0]
	v_pk_mul_f32 v[70:71], v[22:23], 0 op_sel_hi:[1,0]
	v_cndmask_b32_e64 v100, v24, v68, s[46:47]
	v_mov_b32_e32 v68, v115
	v_cndmask_b32_e64 v22, v22, v70, s[46:47]
	v_cndmask_b32_e64 v23, v23, v71, s[46:47]
	v_mov_b32_dpp v68, v42 row_ror:1 row_mask:0xf bank_mask:0xf
	v_mov_b32_dpp v74, v43 row_ror:1 row_mask:0xf bank_mask:0xf
	v_cndmask_b32_e64 v101, v25, v69, s[46:47]
	v_mov_b32_e32 v24, v115
	v_mov_b32_e32 v70, v115
	v_mov_b32_e32 v25, v115
	v_mov_b32_e32 v76, v115
	v_cndmask_b32_e64 v23, v74, v23, s[38:39]
	v_cndmask_b32_e64 v22, v68, v22, s[38:39]
	v_mov_b32_dpp v24, v42 row_ror:15 row_mask:0xf bank_mask:0xf
	v_mov_b32_dpp v70, v28 row_ror:15 row_mask:0xf bank_mask:0xf
	v_mov_b32_dpp v25, v43 row_ror:15 row_mask:0xf bank_mask:0xf
	v_mov_b32_dpp v76, v29 row_ror:15 row_mask:0xf bank_mask:0xf
	v_mov_b32_e32 v86, v115
	v_cndmask_b32_e64 v25, v25, v76, s[40:41]
	v_cndmask_b32_e64 v24, v24, v70, s[40:41]
	v_mov_b32_e32 v102, v115
	v_mov_b32_e32 v82, v115
	v_mov_b32_dpp v86, v45 row_ror:1 row_mask:0xf bank_mask:0xf
	v_mov_b32_e32 v103, v115
	v_mov_b32_e32 v88, v115
	v_mov_b32_dpp v102, v44 row_ror:15 row_mask:0xf bank_mask:0xf
	v_mov_b32_dpp v82, v32 row_ror:15 row_mask:0xf bank_mask:0xf
	v_mov_b32_dpp v103, v45 row_ror:15 row_mask:0xf bank_mask:0xf
	v_mov_b32_dpp v88, v33 row_ror:15 row_mask:0xf bank_mask:0xf
	v_mov_b32_e32 v69, v115
	v_mov_b32_e32 v71, v115
	v_mov_b32_e32 v72, v115
	v_mov_b32_e32 v94, v115
	v_mov_b32_e32 v73, v115
	v_mov_b32_e32 v75, v115
	v_mov_b32_e32 v77, v115
	v_mov_b32_e32 v78, v115
	v_mov_b32_e32 v95, v115
	v_mov_b32_e32 v79, v115
	v_mov_b32_e32 v83, v115
	v_mov_b32_e32 v84, v115
	v_mov_b32_e32 v96, v115
	v_mov_b32_e32 v85, v115
	v_mov_b32_e32 v87, v115
	v_mov_b32_e32 v89, v115
	s_waitcnt vmcnt(3)
	v_pk_mul_f32 v[80:81], v[42:43], v[56:57]
	v_pk_mul_f32 v[98:99], v[44:45], v[58:59]
	s_waitcnt vmcnt(2)
	v_pk_fma_f32 v[22:23], v[60:61], v[22:23], v[80:81]
	v_mov_b32_e32 v80, v115
	s_waitcnt vmcnt(1)
	v_pk_fma_f32 v[22:23], v[52:53], v[24:25], v[22:23]
	v_cndmask_b32_e64 v25, v86, v101, s[38:39]
	v_mov_b32_dpp v80, v44 row_ror:1 row_mask:0xf bank_mask:0xf
	v_cndmask_b32_e64 v24, v80, v100, s[38:39]
	v_cndmask_b32_e64 v101, v103, v88, s[40:41]
	v_cndmask_b32_e64 v100, v102, v82, s[40:41]
	v_pk_fma_f32 v[24:25], v[62:63], v[24:25], v[98:99]
	v_mov_b32_e32 v81, v115
	v_mov_b32_e32 v92, v115
	v_mov_b32_e32 v97, v115
	v_mov_b32_e32 v93, v115
	v_pk_fma_f32 v[24:25], v[54:55], v[100:101], v[24:25]
	v_mov_b32_dpp v69, v28 row_ror:1 row_mask:0xf bank_mask:0xf
	v_mov_b32_dpp v71, v40 row_ror:1 row_mask:0xf bank_mask:0xf
	v_mov_b32_dpp v72, v40 row_ror:15 row_mask:0xf bank_mask:0xf
	v_mov_b32_dpp v94, v34 row_ror:1 row_mask:0xf bank_mask:0xf
	v_mov_b32_dpp v73, v34 row_ror:15 row_mask:0xf bank_mask:0xf
	v_mov_b32_dpp v75, v29 row_ror:1 row_mask:0xf bank_mask:0xf
	v_mov_b32_dpp v77, v41 row_ror:1 row_mask:0xf bank_mask:0xf
	v_mov_b32_dpp v78, v41 row_ror:15 row_mask:0xf bank_mask:0xf
	v_mov_b32_dpp v95, v35 row_ror:1 row_mask:0xf bank_mask:0xf
	v_mov_b32_dpp v79, v35 row_ror:15 row_mask:0xf bank_mask:0xf
	s_waitcnt vmcnt(0)
	v_pk_add_f32 v[22:23], v[48:49], v[22:23]
	v_mov_b32_dpp v81, v32 row_ror:1 row_mask:0xf bank_mask:0xf
	v_mov_b32_dpp v83, v64 row_ror:1 row_mask:0xf bank_mask:0xf
	v_mov_b32_dpp v84, v64 row_ror:15 row_mask:0xf bank_mask:0xf
	v_mov_b32_dpp v96, v36 row_ror:1 row_mask:0xf bank_mask:0xf
	v_mov_b32_dpp v85, v36 row_ror:15 row_mask:0xf bank_mask:0xf
	v_mov_b32_dpp v87, v33 row_ror:1 row_mask:0xf bank_mask:0xf
	v_mov_b32_dpp v89, v65 row_ror:1 row_mask:0xf bank_mask:0xf
	v_mov_b32_dpp v92, v65 row_ror:15 row_mask:0xf bank_mask:0xf
	v_mov_b32_dpp v97, v37 row_ror:1 row_mask:0xf bank_mask:0xf
	v_mov_b32_dpp v93, v37 row_ror:15 row_mask:0xf bank_mask:0xf
	v_pk_add_f32 v[24:25], v[50:51], v[24:25]
	s_and_saveexec_b64 s[54:55], s[50:51]
	s_cbranch_execz .LBB0_1134
	s_add_u32 s68, s3, s25
	s_addc_u32 s69, s62, s23
	v_lshl_add_u64 v[98:99], v[170:171], 2, s[68:69]
	global_store_dwordx4 v[98:99], v[42:45], off offset:16 nt
	s_nop 1
	v_add_co_u32_e32 v42, vcc, 0x5000, v98
	s_nop 1
	v_addc_co_u32_e32 v43, vcc, 0, v99, vcc
	global_store_dwordx4 v[42:43], v[22:25], off offset:2064 nt
	v_add_co_u32_e32 v42, vcc, 0xb000, v98
	s_nop 1
	v_addc_co_u32_e32 v43, vcc, 0, v99, vcc
	global_store_dwordx4 v[42:43], v[14:17], off offset:16 nt
.LBB0_1134:
	s_or_b64 exec, exec, s[54:55]
	s_waitcnt lgkmcnt(0)
	v_pk_mul_f32 v[44:45], v[18:19], 0 op_sel_hi:[1,0]
	v_pk_mul_f32 v[42:43], v[20:21], 0 op_sel_hi:[1,0]
	v_cndmask_b32_e64 v44, v18, v44, s[48:49]
	v_cndmask_b32_e64 v45, v19, v45, s[48:49]
	v_cndmask_b32_e64 v98, v20, v42, s[48:49]
	v_cndmask_b32_e64 v99, v21, v43, s[48:49]
	v_cndmask_b32_e64 v18, v94, v71, s[38:39]
	v_cndmask_b32_e64 v19, v95, v77, s[38:39]
	v_cndmask_b32_e64 v21, v79, v45, s[40:41]
	v_cndmask_b32_e64 v20, v73, v44, s[40:41]
	v_pk_mul_f32 v[44:45], v[34:35], v[56:57]
	v_cvt_f32_i32_e32 v3, v3
	v_pk_fma_f32 v[18:19], v[60:61], v[18:19], v[44:45]
	v_cvt_f32_i32_e32 v2, v2
	v_cvt_f32_i32_e32 v5, v5
	v_cvt_f32_i32_e32 v4, v4
	v_pk_mul_f32 v[42:43], v[36:37], v[58:59]
	v_pk_fma_f32 v[18:19], v[52:53], v[20:21], v[18:19]
	v_cndmask_b32_e64 v20, v96, v83, s[38:39]
	v_cndmask_b32_e64 v21, v97, v89, s[38:39]
	v_cndmask_b32_e64 v45, v93, v99, s[40:41]
	v_cndmask_b32_e64 v44, v85, v98, s[40:41]
	v_pk_fma_f32 v[20:21], v[62:63], v[20:21], v[42:43]
	v_mov_b32_e32 v42, v176
	v_mov_b32_e32 v43, v176
	v_pk_fma_f32 v[20:21], v[54:55], v[44:45], v[20:21]
	v_pk_mul_f32 v[42:43], v[66:67], v[42:43]
	v_pk_mul_f32 v[44:45], v[106:107], v[176:177]
	v_pk_add_f32 v[18:19], v[48:49], v[18:19]
	v_pk_add_f32 v[20:21], v[50:51], v[20:21]
	v_pk_mul_f32 v[4:5], v[42:43], v[4:5]
	v_pk_mul_f32 v[2:3], v[44:45], v[2:3]
	s_and_saveexec_b64 s[54:55], s[16:17]
	s_cbranch_execz .LBB0_1136
	s_add_u32 s68, s3, s79
	s_addc_u32 s69, s62, s78
	v_lshl_add_u64 v[42:43], v[170:171], 2, s[68:69]
	global_store_dwordx4 v[42:43], v[34:37], off offset:16 nt
	s_nop 1
	v_add_co_u32_e32 v34, vcc, 0x5000, v42
	s_nop 1
	v_addc_co_u32_e32 v35, vcc, 0, v43, vcc
	global_store_dwordx4 v[34:35], v[18:21], off offset:2064 nt
	v_add_co_u32_e32 v34, vcc, 0xb000, v42
	s_nop 1
	v_addc_co_u32_e32 v35, vcc, 0, v43, vcc
	global_store_dwordx4 v[34:35], v[2:5], off offset:16 nt
.LBB0_1136:
	s_or_b64 exec, exec, s[54:55]
	v_cvt_f32_i32_e32 v13, v13
	v_cvt_f32_i32_e32 v12, v12
	v_cvt_f32_i32_e32 v9, v9
	v_cvt_f32_i32_e32 v8, v8
	v_mov_b32_e32 v34, v174
	v_mov_b32_e32 v35, v174
	v_mov_b32_e32 v36, v106
	v_mov_b32_e32 v37, v106
	v_pk_mul_f32 v[34:35], v[36:37], v[34:35]
	v_cvt_f32_i32_e32 v7, v7
	v_cvt_f32_i32_e32 v6, v6
	v_pk_mul_f32 v[12:13], v[34:35], v[12:13]
	v_mov_b32_e32 v34, v172
	v_mov_b32_e32 v35, v172
	v_cvt_f32_i32_e32 v11, v11
	v_cvt_f32_i32_e32 v10, v10
	v_pk_mul_f32 v[34:35], v[36:37], v[34:35]
	v_cndmask_b32_e64 v67, v75, v74, s[38:39]
	v_pk_mul_f32 v[8:9], v[34:35], v[8:9]
	v_cndmask_b32_e64 v35, v89, v87, s[38:39]
	v_cndmask_b32_e64 v71, v71, v69, s[38:39]
	v_cndmask_b32_e64 v74, v69, v68, s[38:39]
	v_mov_b32_e32 v68, v65
	v_mov_b32_e32 v69, v63
	v_mov_b32_e32 v34, v59
	v_pk_mul_f32 v[36:37], v[106:107], v[172:173]
	v_pk_mul_f32 v[34:35], v[68:69], v[34:35]
	v_pk_mul_f32 v[42:43], v[106:107], v[174:175]
	v_pk_mul_f32 v[6:7], v[36:37], v[6:7]
	v_cndmask_b32_e64 v36, v92, v93, s[40:41]
	v_add_f32_e32 v34, v34, v35
	v_pk_mul_f32 v[10:11], v[42:43], v[10:11]
	v_cndmask_b32_e64 v43, v83, v81, s[38:39]
	v_fmac_f32_e32 v34, v55, v36
	v_mov_b32_e32 v65, v62
	v_mov_b32_e32 v42, v58
	v_add_f32_e32 v68, v51, v34
	v_pk_mul_f32 v[34:35], v[64:65], v[42:43]
	v_cndmask_b32_e64 v44, v84, v85, s[40:41]
	v_add_f32_e32 v34, v34, v35
	v_fmac_f32_e32 v34, v54, v44
	v_cndmask_b32_e64 v45, v77, v75, s[38:39]
	v_add_f32_e32 v42, v50, v34
	v_mov_b32_e32 v34, v41
	v_mov_b32_e32 v35, v61
	v_mov_b32_e32 v44, v57
	v_pk_mul_f32 v[34:35], v[34:35], v[44:45]
	v_cndmask_b32_e64 v79, v78, v79, s[40:41]
	v_add_f32_e32 v34, v34, v35
	v_cndmask_b32_e64 v73, v72, v73, s[40:41]
	v_cndmask_b32_e64 v72, v70, v72, s[40:41]
	v_fmac_f32_e32 v34, v53, v79
	v_mov_b32_e32 v41, v60
	v_mov_b32_e32 v70, v56
	v_add_f32_e32 v43, v49, v34
	v_pk_mul_f32 v[34:35], v[40:41], v[70:71]
	v_cndmask_b32_e64 v37, v87, v86, s[38:39]
	v_add_f32_e32 v34, v34, v35
	v_fmac_f32_e32 v34, v52, v73
	v_add_f32_e32 v40, v48, v34
	v_mov_b32_e32 v34, v33
	v_mov_b32_e32 v35, v63
	v_mov_b32_e32 v36, v59
	v_pk_mul_f32 v[34:35], v[34:35], v[36:37]
	v_cndmask_b32_e64 v66, v88, v92, s[40:41]
	v_add_f32_e32 v33, v34, v35
	v_cndmask_b32_e64 v80, v81, v80, s[38:39]
	v_fmac_f32_e32 v33, v55, v66
	v_add_f32_e32 v34, v51, v33
	v_mov_b32_e32 v33, v62
	v_mov_b32_e32 v59, v80
	v_pk_mul_f32 v[32:33], v[32:33], v[58:59]
	v_cndmask_b32_e64 v82, v82, v84, s[40:41]
	v_add_f32_e32 v32, v32, v33
	v_fmac_f32_e32 v32, v54, v82
	v_add_f32_e32 v35, v50, v32
	v_mov_b32_e32 v32, v29
	v_mov_b32_e32 v33, v61
	v_mov_b32_e32 v66, v57
	v_pk_mul_f32 v[32:33], v[32:33], v[66:67]
	v_cndmask_b32_e64 v76, v76, v78, s[40:41]
	v_add_f32_e32 v29, v32, v33
	v_fmac_f32_e32 v29, v53, v76
	v_add_f32_e32 v32, v49, v29
	v_mov_b32_e32 v29, v60
	v_mov_b32_e32 v57, v74
	v_pk_mul_f32 v[28:29], v[28:29], v[56:57]
	v_mul_f32_e32 v33, 0xbfb8aa3b, v23
	v_add_f32_e32 v28, v28, v29
	v_mul_f32_e32 v29, 0xbfb8aa3b, v22
	v_exp_f32_e32 v29, v29
	v_exp_f32_e32 v33, v33
	v_fmac_f32_e32 v28, v52, v72
	v_add_f32_e32 v36, v48, v28
	v_add_f32_e32 v29, 1.0, v29
	v_rcp_f32_e32 v29, v29
	v_add_f32_e32 v33, 1.0, v33
	v_rcp_f32_e32 v33, v33
	v_mul_f32_e32 v28, 0xbfb8aa3b, v25
	v_mul_f32_e32 v22, v22, v29
	v_mul_f32_e32 v14, v14, v22
	v_mul_f32_e32 v22, v23, v33
	v_mul_f32_e32 v23, 0xbfb8aa3b, v24
	v_exp_f32_e32 v23, v23
	v_mul_f32_e32 v15, v15, v22
	v_exp_f32_e32 v28, v28
	s_mov_b32 s0, 0x160000
	v_add_f32_e32 v22, 1.0, v23
	v_rcp_f32_e32 v22, v22
	v_add_f32_e32 v23, 1.0, v28
	v_cvt_pk_bf16_f32 v28, v14, v15
	v_rcp_f32_e32 v23, v23
	v_mul_f32_e32 v14, v24, v22
	v_mul_f32_e32 v14, v16, v14
	v_mul_f32_e32 v16, 0xbfb8aa3b, v36
	v_exp_f32_e32 v16, v16
	v_mul_f32_e32 v22, 0xbfb8aa3b, v32
	v_exp_f32_e32 v22, v22
	v_mul_f32_e32 v15, v25, v23
	v_add_f32_e32 v16, 1.0, v16
	v_mul_f32_e32 v15, v17, v15
	v_rcp_f32_e32 v16, v16
	v_add_f32_e32 v17, 1.0, v22
	v_rcp_f32_e32 v17, v17
	v_cvt_pk_bf16_f32 v29, v14, v15
	v_mul_f32_e32 v15, 0xbfb8aa3b, v35
	v_exp_f32_e32 v15, v15
	v_mul_f32_e32 v14, v36, v16
	v_mul_f32_e32 v10, v10, v14
	v_mul_f32_e32 v14, v32, v17
	v_mul_f32_e32 v11, v11, v14
	v_add_f32_e32 v14, 1.0, v15
	v_mul_f32_e32 v16, 0xbfb8aa3b, v34
	v_rcp_f32_e32 v14, v14
	v_exp_f32_e32 v16, v16
	v_cvt_pk_bf16_f32 v32, v10, v11
	v_mul_f32_e32 v10, v35, v14
	v_add_f32_e32 v15, 1.0, v16
	v_mul_f32_e32 v10, v12, v10
	v_mul_f32_e32 v12, 0xbfb8aa3b, v40
	v_rcp_f32_e32 v15, v15
	v_exp_f32_e32 v12, v12
	v_mul_f32_e32 v14, 0xbfb8aa3b, v43
	v_exp_f32_e32 v14, v14
	v_mul_f32_e32 v11, v34, v15
	v_add_f32_e32 v12, 1.0, v12
	v_mul_f32_e32 v11, v13, v11
	v_rcp_f32_e32 v12, v12
	v_add_f32_e32 v13, 1.0, v14
	v_rcp_f32_e32 v13, v13
	v_cvt_pk_bf16_f32 v33, v10, v11
	v_mul_f32_e32 v11, 0xbfb8aa3b, v42
	v_exp_f32_e32 v11, v11
	v_mul_f32_e32 v10, v40, v12
	v_mul_f32_e32 v6, v6, v10
	v_mul_f32_e32 v10, v43, v13
	v_mul_f32_e32 v7, v7, v10
	v_add_f32_e32 v10, 1.0, v11
	v_rcp_f32_e32 v10, v10
	v_mul_f32_e32 v12, 0xbfb8aa3b, v68
	v_exp_f32_e32 v12, v12
	v_cvt_pk_bf16_f32 v40, v6, v7
	v_mul_f32_e32 v6, v42, v10
	v_mul_f32_e32 v6, v8, v6
	v_mul_f32_e32 v8, 0xbfb8aa3b, v18
	v_exp_f32_e32 v8, v8
	v_add_f32_e32 v11, 1.0, v12
	v_rcp_f32_e32 v11, v11
	v_mul_f32_e32 v10, 0xbfb8aa3b, v19
	v_exp_f32_e32 v10, v10
	v_add_f32_e32 v8, 1.0, v8
	v_rcp_f32_e32 v8, v8
	v_mul_f32_e32 v7, v68, v11
	v_mul_f32_e32 v7, v9, v7
	v_add_f32_e32 v9, 1.0, v10
	v_rcp_f32_e32 v9, v9
	v_cvt_pk_bf16_f32 v41, v6, v7
	v_mul_f32_e32 v7, 0xbfb8aa3b, v20
	v_mul_f32_e32 v6, v18, v8
	v_exp_f32_e32 v7, v7
	v_mul_f32_e32 v8, 0xbfb8aa3b, v21
	v_exp_f32_e32 v8, v8
	v_mul_f32_e32 v2, v2, v6
	v_mul_f32_e32 v6, v19, v9
	v_mul_f32_e32 v3, v3, v6
	v_add_f32_e32 v6, 1.0, v7
	v_rcp_f32_e32 v6, v6
	v_add_f32_e32 v7, 1.0, v8
	v_rcp_f32_e32 v7, v7
	v_cvt_pk_bf16_f32 v48, v2, v3
	v_mul_f32_e32 v2, v20, v6
	v_mul_f32_e32 v2, v4, v2
	v_mul_f32_e32 v3, v21, v7
	v_mul_f32_e32 v3, v5, v3
	v_cvt_pk_bf16_f32 v49, v2, v3
	v_add_co_u32_e32 v2, vcc, s0, v90
	s_mov_b32 s0, 0x18c000
	s_nop 0
	v_addc_co_u32_e32 v3, vcc, 0, v91, vcc
	global_store_dwordx4 v[2:3], v[26:29], off nt
	v_add_co_u32_e32 v2, vcc, s0, v90
	s_nop 1
	v_addc_co_u32_e32 v3, vcc, 0, v91, vcc
	global_store_dwordx4 v[2:3], v[30:33], off nt
	v_add_co_u32_e32 v2, vcc, 0x1b8000, v90
	s_nop 1
	v_addc_co_u32_e32 v3, vcc, 0, v91, vcc
	global_store_dwordx4 v[2:3], v[38:41], off nt
	v_add_co_u32_e32 v2, vcc, 0x1e4000, v90
	s_nop 1
	v_addc_co_u32_e32 v3, vcc, 0, v91, vcc
	s_andn2_b64 vcc, exec, s[52:53]
	s_mov_b64 s[52:53], -1
	global_store_dwordx4 v[2:3], v[46:49], off nt
	s_cbranch_vccnz .LBB0_1102
	v_readlane_b32 s0, v255, 9
	v_readlane_b32 s1, v255, 10
	v_mov_b32_e32 v2, v115
	s_andn2_b64 vcc, exec, s[0:1]
	s_cbranch_vccnz .LBB0_1101
	s_barrier
	s_branch .LBB0_1101

.LBB0_1266:
	s_add_u32 s18, s16, 0xffea0100
	s_addc_u32 s19, s17, -1
	s_add_i32 s25, 0, 0x10000
	s_cmpk_eq_i32 s24, 0x54
	s_cselect_b32 s21, s13, s19
	s_cselect_b32 s20, s12, s18
	v_add_u32_e32 v160, s25, v179
	s_cselect_b32 s19, s15, s23
	s_cselect_b32 s18, s14, s22
	s_add_i32 s57, 0, 0x14000
	s_waitcnt lgkmcnt(0)
	ds_read_b128 v[132:135], v160
	ds_read_b128 v[136:139], v160 offset:1024
	ds_read_b128 v[174:177], v160 offset:2048
	ds_read_b128 v[182:185], v160 offset:3072
	v_add_u32_e32 v160, s57, v179
	ds_read_b128 v[186:189], v160
	ds_read_b128 v[190:193], v160 offset:1024
	ds_read_b128 v[194:197], v160 offset:2048
	ds_read_b128 v[198:201], v160 offset:3072
	v_lshl_add_u64 v[160:161], s[16:17], 0, v[170:171]
	s_add_i32 m0, s47, 0xc000
	ds_read_b128 v[202:205], v180
	ds_read_b128 v[206:209], v180 offset:1024
	ds_read_b128 v[210:213], v180 offset:2048
	ds_read_b128 v[214:217], v180 offset:3072
	ds_read_b128 v[218:221], v180 offset:4096
	ds_read_b128 v[222:225], v180 offset:5120
	ds_read_b128 v[240:243], v180 offset:6144
	ds_read_b128 v[244:247], v180 offset:7168
	global_load_lds_dwordx4 v[160:161], off
	v_lshl_add_u64 v[160:161], s[16:17], 0, v[172:173]
	s_add_i32 m0, s47, 0xe000
	s_nop 0
	global_load_lds_dwordx4 v[160:161], off
	s_waitcnt vmcnt(8)
	s_waitcnt lgkmcnt(0)
	s_barrier
	s_setprio 1
	s_waitcnt lgkmcnt(0)
	v_mfma_f32_16x16x32_bf16 v[128:131], v[132:135], v[202:205], v[128:131]
	v_mfma_f32_16x16x32_bf16 v[124:127], v[174:177], v[202:205], v[124:127]
	v_mfma_f32_16x16x32_bf16 v[110:113], v[132:135], v[210:213], v[110:113]
	v_mfma_f32_16x16x32_bf16 v[106:109], v[174:177], v[210:213], v[106:109]
	v_mfma_f32_16x16x32_bf16 v[94:97], v[132:135], v[218:221], v[94:97]
	v_mfma_f32_16x16x32_bf16 v[90:93], v[174:177], v[218:221], v[90:93]
	v_mfma_f32_16x16x32_bf16 v[78:81], v[132:135], v[240:243], v[78:81]
	v_mfma_f32_16x16x32_bf16 v[74:77], v[174:177], v[240:243], v[74:77]
	v_mfma_f32_16x16x32_bf16 v[128:131], v[136:139], v[206:209], v[128:131]
	v_mfma_f32_16x16x32_bf16 v[124:127], v[182:185], v[206:209], v[124:127]
	v_mfma_f32_16x16x32_bf16 v[110:113], v[136:139], v[214:217], v[110:113]
	v_mfma_f32_16x16x32_bf16 v[106:109], v[182:185], v[214:217], v[106:109]
	v_mfma_f32_16x16x32_bf16 v[94:97], v[136:139], v[222:225], v[94:97]
	v_mfma_f32_16x16x32_bf16 v[90:93], v[182:185], v[222:225], v[90:93]
	v_mfma_f32_16x16x32_bf16 v[78:81], v[136:139], v[244:247], v[78:81]
	v_mfma_f32_16x16x32_bf16 v[74:77], v[182:185], v[244:247], v[74:77]
	s_setprio 0
	s_setprio 1
	v_mfma_f32_16x16x32_bf16 v[120:123], v[186:189], v[202:205], v[120:123]
	v_mfma_f32_16x16x32_bf16 v[116:119], v[194:197], v[202:205], v[116:119]
	v_mfma_f32_16x16x32_bf16 v[102:105], v[186:189], v[210:213], v[102:105]
	v_mfma_f32_16x16x32_bf16 v[98:101], v[194:197], v[210:213], v[98:101]
	v_mfma_f32_16x16x32_bf16 v[86:89], v[186:189], v[218:221], v[86:89]
	v_mfma_f32_16x16x32_bf16 v[82:85], v[194:197], v[218:221], v[82:85]
	v_mfma_f32_16x16x32_bf16 v[70:73], v[186:189], v[240:243], v[70:73]
	v_mfma_f32_16x16x32_bf16 v[66:69], v[194:197], v[240:243], v[66:69]
	v_mfma_f32_16x16x32_bf16 v[120:123], v[190:193], v[206:209], v[120:123]
	v_mfma_f32_16x16x32_bf16 v[116:119], v[198:201], v[206:209], v[116:119]
	v_mfma_f32_16x16x32_bf16 v[102:105], v[190:193], v[214:217], v[102:105]
	v_mfma_f32_16x16x32_bf16 v[98:101], v[198:201], v[214:217], v[98:101]
	v_mfma_f32_16x16x32_bf16 v[86:89], v[190:193], v[222:225], v[86:89]
	v_mfma_f32_16x16x32_bf16 v[82:85], v[198:201], v[222:225], v[82:85]
	v_mfma_f32_16x16x32_bf16 v[70:73], v[190:193], v[244:247], v[70:73]
	v_mfma_f32_16x16x32_bf16 v[66:69], v[198:201], v[244:247], v[66:69]
	s_setprio 0
	s_barrier
	s_add_i32 s25, s25, s46
	v_lshl_add_u64 v[160:161], s[18:19], 0, v[114:115]
	s_mov_b32 m0, s25
	ds_read_b128 v[202:205], v180 offset:16384
	ds_read_b128 v[206:209], v180 offset:17408
	ds_read_b128 v[210:213], v180 offset:18432
	ds_read_b128 v[214:217], v180 offset:19456
	ds_read_b128 v[218:221], v180 offset:20480
	ds_read_b128 v[222:225], v180 offset:21504
	ds_read_b128 v[240:243], v180 offset:22528
	ds_read_b128 v[244:247], v180 offset:23552
	global_load_lds_dwordx4 v[160:161], off
	s_add_i32 m0, s25, 0x2000
	s_add_u32 s42, s18, 0x58000
	v_lshl_add_u64 v[230:231], s[18:19], 0, v[144:145]
	s_addc_u32 s43, s19, 0
	s_add_i32 s25, s57, s46
	global_load_lds_dwordx4 v[230:231], off
	v_lshl_add_u64 v[232:233], s[42:43], 0, v[114:115]
	s_mov_b32 m0, s25
	v_lshl_add_u64 v[236:237], s[20:21], 0, v[142:143]
	global_load_lds_dwordx4 v[232:233], off
	v_lshl_add_u64 v[232:233], s[42:43], 0, v[144:145]
	s_add_i32 m0, s25, 0x2000
	s_nop 0
	global_load_lds_dwordx4 v[232:233], off
	v_lshl_add_u64 v[232:233], s[20:21], 0, v[140:141]
	s_mov_b32 m0, s47
	s_nop 0
	global_load_lds_dwordx4 v[232:233], off
	s_mov_b32 m0, s48
	s_nop 0
	global_load_lds_dwordx4 v[236:237], off
	s_waitcnt vmcnt(8)
	s_waitcnt lgkmcnt(0)
	s_barrier
	s_setprio 1
	s_waitcnt lgkmcnt(0)
	v_mfma_f32_16x16x32_bf16 v[62:65], v[132:135], v[202:205], v[62:65]
	v_mfma_f32_16x16x32_bf16 v[58:61], v[174:177], v[202:205], v[58:61]
	v_mfma_f32_16x16x32_bf16 v[46:49], v[132:135], v[210:213], v[46:49]
	v_mfma_f32_16x16x32_bf16 v[42:45], v[174:177], v[210:213], v[42:45]
	v_mfma_f32_16x16x32_bf16 v[30:33], v[132:135], v[218:221], v[30:33]
	v_mfma_f32_16x16x32_bf16 v[26:29], v[174:177], v[218:221], v[26:29]
	v_mfma_f32_16x16x32_bf16 v[14:17], v[132:135], v[240:243], v[14:17]
	v_mfma_f32_16x16x32_bf16 v[10:13], v[174:177], v[240:243], v[10:13]
	v_mfma_f32_16x16x32_bf16 v[62:65], v[136:139], v[206:209], v[62:65]
	v_mfma_f32_16x16x32_bf16 v[58:61], v[182:185], v[206:209], v[58:61]
	v_mfma_f32_16x16x32_bf16 v[46:49], v[136:139], v[214:217], v[46:49]
	v_mfma_f32_16x16x32_bf16 v[42:45], v[182:185], v[214:217], v[42:45]
	v_mfma_f32_16x16x32_bf16 v[30:33], v[136:139], v[222:225], v[30:33]
	v_mfma_f32_16x16x32_bf16 v[26:29], v[182:185], v[222:225], v[26:29]
	v_mfma_f32_16x16x32_bf16 v[14:17], v[136:139], v[244:247], v[14:17]
	v_mfma_f32_16x16x32_bf16 v[10:13], v[182:185], v[244:247], v[10:13]
	s_setprio 0
	s_setprio 1
	v_mfma_f32_16x16x32_bf16 v[54:57], v[186:189], v[202:205], v[54:57]
	v_mfma_f32_16x16x32_bf16 v[50:53], v[194:197], v[202:205], v[50:53]
	v_mfma_f32_16x16x32_bf16 v[38:41], v[186:189], v[210:213], v[38:41]
	v_mfma_f32_16x16x32_bf16 v[34:37], v[194:197], v[210:213], v[34:37]
	v_mfma_f32_16x16x32_bf16 v[22:25], v[186:189], v[218:221], v[22:25]
	v_mfma_f32_16x16x32_bf16 v[18:21], v[194:197], v[218:221], v[18:21]
	v_mfma_f32_16x16x32_bf16 v[6:9], v[186:189], v[240:243], v[6:9]
	v_mfma_f32_16x16x32_bf16 v[2:5], v[194:197], v[240:243], v[2:5]
	v_mfma_f32_16x16x32_bf16 v[54:57], v[190:193], v[206:209], v[54:57]
	v_mfma_f32_16x16x32_bf16 v[50:53], v[198:201], v[206:209], v[50:53]
	v_mfma_f32_16x16x32_bf16 v[38:41], v[190:193], v[214:217], v[38:41]
	v_mfma_f32_16x16x32_bf16 v[34:37], v[198:201], v[214:217], v[34:37]
	v_mfma_f32_16x16x32_bf16 v[22:25], v[190:193], v[222:225], v[22:25]
	v_mfma_f32_16x16x32_bf16 v[18:21], v[198:201], v[222:225], v[18:21]
	v_mfma_f32_16x16x32_bf16 v[6:9], v[190:193], v[244:247], v[6:9]
	v_mfma_f32_16x16x32_bf16 v[2:5], v[198:201], v[244:247], v[2:5]
	s_setprio 0
	s_barrier
	s_add_i32 s25, 0, 0x18000
	v_add_u32_e32 v181, s25, v179
	s_add_i32 s42, 0, 0x1c000
	ds_read_b128 v[132:135], v181
	ds_read_b128 v[136:139], v181 offset:1024
	ds_read_b128 v[174:177], v181 offset:2048
	ds_read_b128 v[182:185], v181 offset:3072
	v_add_u32_e32 v181, s42, v179
	ds_read_b128 v[186:189], v181
	ds_read_b128 v[190:193], v181 offset:1024
	ds_read_b128 v[194:197], v181 offset:2048
	ds_read_b128 v[198:201], v181 offset:3072
	s_add_u32 s20, s20, 0x160000
	s_addc_u32 s21, s21, 0
	s_mov_b32 m0, s49
	v_lshl_add_u64 v[238:239], s[20:21], 0, v[140:141]
	ds_read_b128 v[202:205], v180 offset:32768
	ds_read_b128 v[206:209], v180 offset:33792
	ds_read_b128 v[210:213], v180 offset:34816
	ds_read_b128 v[214:217], v180 offset:35840
	ds_read_b128 v[218:221], v180 offset:36864
	ds_read_b128 v[222:225], v180 offset:37888
	ds_read_b128 v[240:243], v180 offset:38912
	ds_read_b128 v[244:247], v180 offset:39936
	global_load_lds_dwordx4 v[238:239], off
	v_lshl_add_u64 v[238:239], s[20:21], 0, v[142:143]
	s_mov_b32 m0, s50
	s_nop 0
	global_load_lds_dwordx4 v[238:239], off
	s_waitcnt vmcnt(8)
	s_waitcnt lgkmcnt(0)
	s_barrier
	s_setprio 1
	s_waitcnt lgkmcnt(0)
	v_mfma_f32_16x16x32_bf16 v[128:131], v[132:135], v[202:205], v[128:131]
	v_mfma_f32_16x16x32_bf16 v[124:127], v[174:177], v[202:205], v[124:127]
	v_mfma_f32_16x16x32_bf16 v[110:113], v[132:135], v[210:213], v[110:113]
	v_mfma_f32_16x16x32_bf16 v[106:109], v[174:177], v[210:213], v[106:109]
	v_mfma_f32_16x16x32_bf16 v[94:97], v[132:135], v[218:221], v[94:97]
	v_mfma_f32_16x16x32_bf16 v[90:93], v[174:177], v[218:221], v[90:93]
	v_mfma_f32_16x16x32_bf16 v[78:81], v[132:135], v[240:243], v[78:81]
	v_mfma_f32_16x16x32_bf16 v[74:77], v[174:177], v[240:243], v[74:77]
	v_mfma_f32_16x16x32_bf16 v[128:131], v[136:139], v[206:209], v[128:131]
	v_mfma_f32_16x16x32_bf16 v[124:127], v[182:185], v[206:209], v[124:127]
	v_mfma_f32_16x16x32_bf16 v[110:113], v[136:139], v[214:217], v[110:113]
	v_mfma_f32_16x16x32_bf16 v[106:109], v[182:185], v[214:217], v[106:109]
	v_mfma_f32_16x16x32_bf16 v[94:97], v[136:139], v[222:225], v[94:97]
	v_mfma_f32_16x16x32_bf16 v[90:93], v[182:185], v[222:225], v[90:93]
	v_mfma_f32_16x16x32_bf16 v[78:81], v[136:139], v[244:247], v[78:81]
	v_mfma_f32_16x16x32_bf16 v[74:77], v[182:185], v[244:247], v[74:77]
	s_setprio 0
	s_setprio 1
	v_mfma_f32_16x16x32_bf16 v[120:123], v[186:189], v[202:205], v[120:123]
	v_mfma_f32_16x16x32_bf16 v[116:119], v[194:197], v[202:205], v[116:119]
	v_mfma_f32_16x16x32_bf16 v[102:105], v[186:189], v[210:213], v[102:105]
	v_mfma_f32_16x16x32_bf16 v[98:101], v[194:197], v[210:213], v[98:101]
	v_mfma_f32_16x16x32_bf16 v[86:89], v[186:189], v[218:221], v[86:89]
	v_mfma_f32_16x16x32_bf16 v[82:85], v[194:197], v[218:221], v[82:85]
	v_mfma_f32_16x16x32_bf16 v[70:73], v[186:189], v[240:243], v[70:73]
	v_mfma_f32_16x16x32_bf16 v[66:69], v[194:197], v[240:243], v[66:69]
	v_mfma_f32_16x16x32_bf16 v[120:123], v[190:193], v[206:209], v[120:123]
	v_mfma_f32_16x16x32_bf16 v[116:119], v[198:201], v[206:209], v[116:119]
	v_mfma_f32_16x16x32_bf16 v[102:105], v[190:193], v[214:217], v[102:105]
	v_mfma_f32_16x16x32_bf16 v[98:101], v[198:201], v[214:217], v[98:101]
	v_mfma_f32_16x16x32_bf16 v[86:89], v[190:193], v[222:225], v[86:89]
	v_mfma_f32_16x16x32_bf16 v[82:85], v[198:201], v[222:225], v[82:85]
	v_mfma_f32_16x16x32_bf16 v[70:73], v[190:193], v[244:247], v[70:73]
	v_mfma_f32_16x16x32_bf16 v[66:69], v[198:201], v[244:247], v[66:69]
	s_setprio 0
	s_barrier
	s_add_i32 s20, s25, s46
	v_lshl_add_u64 v[160:161], v[160:161], 0, s[28:29]
	s_mov_b32 m0, s20
	ds_read_b128 v[202:205], v180 offset:49152
	ds_read_b128 v[206:209], v180 offset:50176
	ds_read_b128 v[210:213], v180 offset:51200
	ds_read_b128 v[214:217], v180 offset:52224
	ds_read_b128 v[218:221], v180 offset:53248
	ds_read_b128 v[222:225], v180 offset:54272
	ds_read_b128 v[240:243], v180 offset:55296
	ds_read_b128 v[244:247], v180 offset:56320
	global_load_lds_dwordx4 v[160:161], off
	s_add_i32 m0, s20, 0x2000
	s_add_u32 s18, s18, 0x58080
	v_lshl_add_u64 v[160:161], v[230:231], 0, s[28:29]
	s_addc_u32 s19, s19, 0
	s_add_i32 s20, s42, s46
	global_load_lds_dwordx4 v[160:161], off
	v_lshl_add_u64 v[160:161], s[18:19], 0, v[114:115]
	s_mov_b32 m0, s20
	s_nop 0
	global_load_lds_dwordx4 v[160:161], off
	v_lshl_add_u64 v[160:161], s[18:19], 0, v[144:145]
	s_add_i32 m0, s20, 0x2000
	s_nop 0
	global_load_lds_dwordx4 v[160:161], off
	v_lshl_add_u64 v[160:161], v[232:233], 0, s[30:31]
	s_mov_b32 m0, s54
	s_nop 0
	global_load_lds_dwordx4 v[160:161], off
	v_lshl_add_u64 v[160:161], v[236:237], 0, s[30:31]
	s_mov_b32 m0, s55
	s_nop 0
	global_load_lds_dwordx4 v[160:161], off
	s_waitcnt vmcnt(8)
	s_waitcnt lgkmcnt(0)
	s_barrier
	s_setprio 1
	s_waitcnt lgkmcnt(0)
	v_mfma_f32_16x16x32_bf16 v[62:65], v[132:135], v[202:205], v[62:65]
	v_mfma_f32_16x16x32_bf16 v[58:61], v[174:177], v[202:205], v[58:61]
	v_mfma_f32_16x16x32_bf16 v[46:49], v[132:135], v[210:213], v[46:49]
	v_mfma_f32_16x16x32_bf16 v[42:45], v[174:177], v[210:213], v[42:45]
	v_mfma_f32_16x16x32_bf16 v[30:33], v[132:135], v[218:221], v[30:33]
	v_mfma_f32_16x16x32_bf16 v[26:29], v[174:177], v[218:221], v[26:29]
	v_mfma_f32_16x16x32_bf16 v[14:17], v[132:135], v[240:243], v[14:17]
	v_mfma_f32_16x16x32_bf16 v[10:13], v[174:177], v[240:243], v[10:13]
	v_mfma_f32_16x16x32_bf16 v[62:65], v[136:139], v[206:209], v[62:65]
	v_mfma_f32_16x16x32_bf16 v[58:61], v[182:185], v[206:209], v[58:61]
	v_mfma_f32_16x16x32_bf16 v[46:49], v[136:139], v[214:217], v[46:49]
	v_mfma_f32_16x16x32_bf16 v[42:45], v[182:185], v[214:217], v[42:45]
	v_mfma_f32_16x16x32_bf16 v[30:33], v[136:139], v[222:225], v[30:33]
	v_mfma_f32_16x16x32_bf16 v[26:29], v[182:185], v[222:225], v[26:29]
	v_mfma_f32_16x16x32_bf16 v[14:17], v[136:139], v[244:247], v[14:17]
	v_mfma_f32_16x16x32_bf16 v[10:13], v[182:185], v[244:247], v[10:13]
	s_setprio 0
	s_setprio 1
	v_mfma_f32_16x16x32_bf16 v[54:57], v[186:189], v[202:205], v[54:57]
	v_mfma_f32_16x16x32_bf16 v[50:53], v[194:197], v[202:205], v[50:53]
	v_mfma_f32_16x16x32_bf16 v[38:41], v[186:189], v[210:213], v[38:41]
	v_mfma_f32_16x16x32_bf16 v[34:37], v[194:197], v[210:213], v[34:37]
	v_mfma_f32_16x16x32_bf16 v[22:25], v[186:189], v[218:221], v[22:25]
	v_mfma_f32_16x16x32_bf16 v[18:21], v[194:197], v[218:221], v[18:21]
	v_mfma_f32_16x16x32_bf16 v[6:9], v[186:189], v[240:243], v[6:9]
	v_mfma_f32_16x16x32_bf16 v[2:5], v[194:197], v[240:243], v[2:5]
	v_mfma_f32_16x16x32_bf16 v[54:57], v[190:193], v[206:209], v[54:57]
	v_mfma_f32_16x16x32_bf16 v[50:53], v[198:201], v[206:209], v[50:53]
	v_mfma_f32_16x16x32_bf16 v[38:41], v[190:193], v[214:217], v[38:41]
	v_mfma_f32_16x16x32_bf16 v[34:37], v[198:201], v[214:217], v[34:37]
	v_mfma_f32_16x16x32_bf16 v[22:25], v[190:193], v[222:225], v[22:25]
	v_mfma_f32_16x16x32_bf16 v[18:21], v[198:201], v[222:225], v[18:21]
	v_mfma_f32_16x16x32_bf16 v[6:9], v[190:193], v[244:247], v[6:9]
	v_mfma_f32_16x16x32_bf16 v[2:5], v[198:201], v[244:247], v[2:5]
	s_setprio 0
	s_barrier
	s_add_i32 s24, s24, 2
	s_add_u32 s22, s22, 0x100
	s_addc_u32 s23, s23, 0
	s_add_u32 s16, s16, 0x200
	s_addc_u32 s17, s17, 0
	s_cmpk_gt_u32 s24, 0x55
	s_cbranch_scc0 .LBB0_1266
	s_and_b64 vcc, exec, s[10:11]
	s_cbranch_vccz .LBB0_1269
	s_barrier

.LBB0_1272:
	global_load_dwordx4 v[182:185], v[174:175], off
	global_load_dwordx4 v[186:189], v[174:175], off offset:64
	v_add_co_u32_e32 v132, vcc, 0x10000, v174
	v_mov_b32_e32 v191, v115
	s_nop 0
	v_addc_co_u32_e32 v133, vcc, 0, v175, vcc
	global_load_dwordx4 v[136:139], v[132:133], off
	s_nop 0
	global_load_dwordx4 v[132:135], v[132:133], off offset:64
	v_mov_b32_e32 v177, v115
	s_add_u32 s20, s90, s20
	v_mov_b32_e32 v190, v115
	s_addc_u32 s21, s91, s21
	v_add_u32_e32 v176, s22, v178
	s_lshl_b32 s22, s3, 2
	s_ashr_i32 s23, s22, 31
	s_waitcnt vmcnt(0)
	v_lshlrev_b32_e32 v160, 16, v182
	v_and_b32_e32 v161, 0xffff0000, v182
	v_lshlrev_b32_e32 v181, 16, v183
	v_and_b32_e32 v182, 0xffff0000, v183
	v_lshlrev_b32_e32 v183, 16, v184
	v_and_b32_e32 v184, 0xffff0000, v184
	v_lshlrev_b32_e32 v192, 16, v185
	v_and_b32_e32 v185, 0xffff0000, v185
	v_lshlrev_b32_e32 v193, 16, v186
	v_and_b32_e32 v186, 0xffff0000, v186
	v_lshlrev_b32_e32 v194, 16, v187
	v_and_b32_e32 v187, 0xffff0000, v187
	v_lshlrev_b32_e32 v195, 16, v188
	v_and_b32_e32 v188, 0xffff0000, v188
	v_lshlrev_b32_e32 v196, 16, v189
	v_and_b32_e32 v189, 0xffff0000, v189
	v_add_f32_e32 v161, v129, v161
	v_add_f32_e32 v182, v131, v182
	v_add_f32_e32 v184, v125, v184
	v_add_f32_e32 v185, v127, v185
	v_add_f32_e32 v186, v121, v186
	v_add_f32_e32 v187, v123, v187
	v_add_f32_e32 v188, v117, v188
	v_add_f32_e32 v189, v119, v189
	v_add_f32_e32 v160, v128, v160
	v_add_f32_e32 v181, v130, v181
	v_add_f32_e32 v183, v124, v183
	v_add_f32_e32 v192, v126, v192
	v_add_f32_e32 v193, v120, v193
	v_add_f32_e32 v194, v122, v194
	v_add_f32_e32 v195, v116, v195
	v_add_f32_e32 v196, v118, v196
	v_cvt_pk_bf16_f32 v197, v160, v161
	v_cvt_pk_bf16_f32 v198, v181, v182
	v_cvt_pk_bf16_f32 v199, v183, v184
	v_cvt_pk_bf16_f32 v200, v192, v185
	v_mul_f32_e32 v161, v161, v161
	v_mul_f32_e32 v182, v182, v182
	v_mul_f32_e32 v184, v184, v184
	v_mul_f32_e32 v185, v185, v185
	v_cvt_pk_bf16_f32 v201, v193, v186
	v_cvt_pk_bf16_f32 v202, v194, v187
	v_cvt_pk_bf16_f32 v203, v195, v188
	v_cvt_pk_bf16_f32 v204, v196, v189
	v_mul_f32_e32 v186, v186, v186
	v_mul_f32_e32 v187, v187, v187
	v_mul_f32_e32 v188, v188, v188
	v_mul_f32_e32 v189, v189, v189
	v_fmac_f32_e32 v161, v160, v160
	v_fmac_f32_e32 v182, v181, v181
	v_fmac_f32_e32 v184, v183, v183
	v_fmac_f32_e32 v185, v192, v192
	v_fmac_f32_e32 v186, v193, v193
	v_fmac_f32_e32 v187, v194, v194
	v_fmac_f32_e32 v188, v195, v195
	v_fmac_f32_e32 v189, v196, v196
	v_cndmask_b32_e64 v181, v203, v199, s[36:37]
	v_add_f32_e32 v161, v161, v182
	v_add_f32_e32 v182, v184, v185
	v_add_f32_e32 v184, v186, v187
	v_add_f32_e32 v185, v188, v189
	v_mov_b32_dpp v191, v181 quad_perm:[1,0,3,2] row_mask:0xf bank_mask:0xf
	v_add_f32_e32 v161, v161, v182
	v_add_f32_e32 v181, v184, v185
	v_and_b32_e32 v186, 64, v234
	v_add_f32_e32 v189, v161, v181
	v_xor_b32_e32 v181, 16, v234
	v_add_u32_e32 v193, 64, v186
	v_cmp_lt_i32_e32 vcc, v181, v193
	v_cndmask_b32_e64 v192, v201, v197, s[36:37]
	v_cndmask_b32_e64 v160, v204, v200, s[36:37]
	v_cndmask_b32_e32 v181, v234, v181, vcc
	v_cndmask_b32_e64 v183, v202, v198, s[36:37]
	v_mov_b32_dpp v177, v192 quad_perm:[1,0,3,2] row_mask:0xf bank_mask:0xf
	v_mov_b32_e32 v192, v115
	v_lshlrev_b32_e32 v181, 2, v181
	v_mov_b32_dpp v190, v183 quad_perm:[1,0,3,2] row_mask:0xf bank_mask:0xf
	v_mov_b32_dpp v192, v160 quad_perm:[1,0,3,2] row_mask:0xf bank_mask:0xf
	ds_bpermute_b32 v194, v181, v189
	v_cndmask_b32_e64 v182, v197, v177, s[36:37]
	v_cndmask_b32_e64 v183, v198, v190, s[36:37]
	v_cndmask_b32_e64 v184, v199, v191, s[36:37]
	v_cndmask_b32_e64 v185, v200, v192, s[36:37]
	v_lshl_add_u64 v[160:161], v[148:149], 1, s[20:21]
	global_store_dwordx4 v[160:161], v[182:185], off nt
	v_xor_b32_e32 v160, 32, v234
	v_cmp_lt_i32_e32 vcc, v160, v193
	s_waitcnt lgkmcnt(0)
	v_add_f32_e32 v183, v189, v194
	v_cndmask_b32_e64 v186, v177, v201, s[36:37]
	v_cndmask_b32_e32 v160, v234, v160, vcc
	v_lshlrev_b32_e32 v182, 2, v160
	ds_bpermute_b32 v184, v182, v183
	v_cndmask_b32_e64 v187, v190, v202, s[36:37]
	v_cndmask_b32_e64 v188, v191, v203, s[36:37]
	v_cndmask_b32_e64 v189, v192, v204, s[36:37]
	v_lshl_add_u64 v[160:161], v[150:151], 1, s[20:21]
	v_ashrrev_i32_e32 v177, 31, v176
	global_store_dwordx4 v[160:161], v[186:189], off nt
	s_and_saveexec_b64 s[24:25], s[38:39]
	s_cbranch_execz .LBB0_1274
	v_lshlrev_b64 v[160:161], 7, v[176:177]
	v_lshl_add_u64 v[160:161], s[6:7], 0, v[160:161]
	v_lshl_add_u64 v[160:161], s[22:23], 2, v[160:161]
	s_lshl_b32 s4, s53, 2
	v_lshl_add_u64 v[160:161], v[160:161], 0, s[4:5]
	s_waitcnt lgkmcnt(0)
	v_add_f32_e32 v183, v183, v184
	global_store_dword v[160:161], v183, off nt
.LBB0_1274:
	s_or_b64 exec, exec, s[24:25]
	v_lshlrev_b32_e32 v160, 16, v136
	v_and_b32_e32 v136, 0xffff0000, v136
	v_lshlrev_b32_e32 v161, 16, v137
	v_and_b32_e32 v137, 0xffff0000, v137
	v_add_f32_e32 v136, v111, v136
	v_add_f32_e32 v137, v113, v137
	v_add_f32_e32 v160, v110, v160
	v_add_f32_e32 v161, v112, v161
	v_lshlrev_b32_e32 v183, 16, v138
	v_and_b32_e32 v138, 0xffff0000, v138
	s_waitcnt lgkmcnt(0)
	v_lshlrev_b32_e32 v184, 16, v139
	v_and_b32_e32 v139, 0xffff0000, v139
	v_cvt_pk_bf16_f32 v185, v160, v136
	v_cvt_pk_bf16_f32 v186, v161, v137
	v_mul_f32_e32 v136, v136, v136
	v_mul_f32_e32 v137, v137, v137
	v_add_f32_e32 v138, v107, v138
	v_add_f32_e32 v139, v109, v139
	v_fmac_f32_e32 v136, v160, v160
	v_fmac_f32_e32 v137, v161, v161
	v_add_f32_e32 v183, v106, v183
	v_add_f32_e32 v184, v108, v184
	v_cvt_pk_bf16_f32 v187, v183, v138
	v_add_f32_e32 v136, v136, v137
	v_mul_f32_e32 v137, v138, v138
	v_mul_f32_e32 v138, v139, v139
	v_fmac_f32_e32 v137, v183, v183
	v_fmac_f32_e32 v138, v184, v184
	v_add_f32_e32 v137, v137, v138
	v_add_f32_e32 v136, v136, v137
	v_lshlrev_b32_e32 v137, 16, v132
	v_and_b32_e32 v132, 0xffff0000, v132
	v_lshlrev_b32_e32 v138, 16, v133
	v_and_b32_e32 v133, 0xffff0000, v133
	v_add_f32_e32 v132, v103, v132
	v_add_f32_e32 v133, v105, v133
	v_cvt_pk_bf16_f32 v188, v184, v139
	v_add_f32_e32 v137, v102, v137
	v_add_f32_e32 v138, v104, v138
	v_lshlrev_b32_e32 v139, 16, v134
	v_and_b32_e32 v134, 0xffff0000, v134
	v_lshlrev_b32_e32 v160, 16, v135
	v_and_b32_e32 v135, 0xffff0000, v135
	v_cvt_pk_bf16_f32 v161, v137, v132
	v_cvt_pk_bf16_f32 v183, v138, v133
	v_mul_f32_e32 v132, v132, v132
	v_mul_f32_e32 v133, v133, v133
	v_add_f32_e32 v134, v99, v134
	v_add_f32_e32 v135, v101, v135
	v_fmac_f32_e32 v132, v137, v137
	v_fmac_f32_e32 v133, v138, v138
	v_add_f32_e32 v139, v98, v139
	v_add_f32_e32 v160, v100, v160
	v_cvt_pk_bf16_f32 v184, v139, v134
	v_add_f32_e32 v132, v132, v133
	v_mul_f32_e32 v133, v134, v134
	v_mul_f32_e32 v134, v135, v135
	v_fmac_f32_e32 v133, v139, v139
	v_fmac_f32_e32 v134, v160, v160
	v_add_f32_e32 v133, v133, v134
	v_cvt_pk_bf16_f32 v189, v160, v135
	v_add_f32_e32 v132, v132, v133
	v_cndmask_b32_e64 v135, v161, v185, s[36:37]
	v_mov_b32_e32 v139, v115
	v_add_f32_e32 v138, v136, v132
	v_cndmask_b32_e64 v132, v189, v188, s[36:37]
	v_mov_b32_dpp v139, v135 quad_perm:[1,0,3,2] row_mask:0xf bank_mask:0xf
	v_mov_b32_e32 v191, v115
	s_add_u32 s24, s20, 0x10000
	v_cndmask_b32_e64 v133, v184, v187, s[36:37]
	v_mov_b32_dpp v191, v132 quad_perm:[1,0,3,2] row_mask:0xf bank_mask:0xf
	v_cndmask_b32_e64 v132, v185, v139, s[36:37]
	ds_bpermute_b32 v185, v181, v138
	v_cndmask_b32_e64 v134, v183, v186, s[36:37]
	v_mov_b32_e32 v160, v115
	v_mov_b32_e32 v190, v115
	s_addc_u32 s25, s21, 0
	v_mov_b32_dpp v160, v134 quad_perm:[1,0,3,2] row_mask:0xf bank_mask:0xf
	v_mov_b32_dpp v190, v133 quad_perm:[1,0,3,2] row_mask:0xf bank_mask:0xf
	v_cndmask_b32_e64 v133, v186, v160, s[36:37]
	v_cndmask_b32_e64 v134, v187, v190, s[36:37]
	v_cndmask_b32_e64 v135, v188, v191, s[36:37]
	v_lshl_add_u64 v[136:137], v[148:149], 1, s[24:25]
	global_store_dwordx4 v[136:137], v[132:135], off nt
	v_cndmask_b32_e64 v136, v190, v184, s[36:37]
	v_cndmask_b32_e64 v137, v191, v189, s[36:37]
	s_waitcnt lgkmcnt(0)
	v_add_f32_e32 v132, v138, v185
	ds_bpermute_b32 v133, v182, v132
	v_cndmask_b32_e64 v134, v139, v161, s[36:37]
	v_cndmask_b32_e64 v135, v160, v183, s[36:37]
	v_lshl_add_u64 v[138:139], v[150:151], 1, s[24:25]
	global_store_dwordx4 v[138:139], v[134:137], off nt
	s_and_saveexec_b64 s[24:25], s[38:39]
	s_cbranch_execz .LBB0_1276
	s_waitcnt lgkmcnt(0)
	v_add_f32_e32 v134, v132, v133
	v_or_b32_e32 v132, 16, v176
	v_ashrrev_i32_e32 v133, 31, v132
	v_lshlrev_b64 v[132:133], 7, v[132:133]
	v_lshl_add_u64 v[132:133], s[6:7], 0, v[132:133]
	v_lshl_add_u64 v[132:133], s[22:23], 2, v[132:133]
	s_lshl_b32 s4, s53, 2
	v_lshl_add_u64 v[132:133], v[132:133], 0, s[4:5]
	global_store_dword v[132:133], v134, off nt
.LBB0_1276:
	s_or_b64 exec, exec, s[24:25]
	v_add_co_u32_e32 v132, vcc, 0x20000, v174
	s_add_u32 s24, s20, 0x20000
	s_waitcnt lgkmcnt(0)
	v_addc_co_u32_e32 v133, vcc, 0, v175, vcc
	global_load_dwordx4 v[184:187], v[132:133], off
	global_load_dwordx4 v[188:191], v[132:133], off offset:64
	v_add_co_u32_e32 v132, vcc, 0x30000, v174
	s_addc_u32 s25, s21, 0
	s_nop 0
	v_addc_co_u32_e32 v133, vcc, 0, v175, vcc
	global_load_dwordx4 v[136:139], v[132:133], off
	s_nop 0
	global_load_dwordx4 v[132:135], v[132:133], off offset:64
	s_waitcnt vmcnt(3)
	v_lshlrev_b32_e32 v160, 16, v184
	v_and_b32_e32 v161, 0xffff0000, v184
	v_and_b32_e32 v184, 0xffff0000, v185
	v_add_f32_e32 v192, v97, v184
	v_lshlrev_b32_e32 v184, 16, v186
	v_add_f32_e32 v193, v90, v184
	v_and_b32_e32 v184, 0xffff0000, v186
	v_add_f32_e32 v194, v91, v184
	v_lshlrev_b32_e32 v184, 16, v187
	v_add_f32_e32 v161, v95, v161
	v_add_f32_e32 v195, v92, v184
	v_and_b32_e32 v184, 0xffff0000, v187
	v_add_f32_e32 v160, v94, v160
	v_lshlrev_b32_e32 v183, 16, v185
	v_add_f32_e32 v196, v93, v184
	v_cvt_pk_bf16_f32 v184, v160, v161
	v_mul_f32_e32 v161, v161, v161
	v_add_f32_e32 v183, v96, v183
	v_fmac_f32_e32 v161, v160, v160
	v_mul_f32_e32 v160, v192, v192
	v_fmac_f32_e32 v160, v183, v183
	v_cvt_pk_bf16_f32 v185, v183, v192
	v_add_f32_e32 v160, v161, v160
	v_mul_f32_e32 v161, v194, v194
	v_mul_f32_e32 v183, v196, v196
	v_fmac_f32_e32 v161, v193, v193
	v_fmac_f32_e32 v183, v195, v195
	v_add_f32_e32 v161, v161, v183
	v_add_f32_e32 v160, v160, v161
	s_waitcnt vmcnt(2)
	v_lshlrev_b32_e32 v161, 16, v188
	v_and_b32_e32 v183, 0xffff0000, v188
	v_lshlrev_b32_e32 v188, 16, v189
	v_add_f32_e32 v192, v88, v188
	v_and_b32_e32 v188, 0xffff0000, v189
	v_cvt_pk_bf16_f32 v186, v193, v194
	v_add_f32_e32 v193, v89, v188
	v_lshlrev_b32_e32 v188, 16, v190
	v_add_f32_e32 v194, v82, v188
	v_and_b32_e32 v188, 0xffff0000, v190
	v_cvt_pk_bf16_f32 v187, v195, v196
	v_add_f32_e32 v195, v83, v188
	v_lshlrev_b32_e32 v188, 16, v191
	v_add_f32_e32 v183, v87, v183
	v_add_f32_e32 v196, v84, v188
	v_and_b32_e32 v188, 0xffff0000, v191
	v_add_f32_e32 v161, v86, v161
	v_add_f32_e32 v197, v85, v188
	v_cvt_pk_bf16_f32 v188, v161, v183
	v_mul_f32_e32 v183, v183, v183
	v_fmac_f32_e32 v183, v161, v161
	v_mul_f32_e32 v161, v193, v193
	v_fmac_f32_e32 v161, v192, v192
	v_cvt_pk_bf16_f32 v189, v192, v193
	v_add_f32_e32 v161, v183, v161
	v_mul_f32_e32 v183, v195, v195
	v_mul_f32_e32 v192, v197, v197
	v_fmac_f32_e32 v183, v194, v194
	v_fmac_f32_e32 v192, v196, v196
	v_cvt_pk_bf16_f32 v190, v194, v195
	v_add_f32_e32 v183, v183, v192
	v_cndmask_b32_e64 v193, v188, v184, s[36:37]
	v_mov_b32_e32 v194, v115
	v_add_f32_e32 v161, v161, v183
	v_cndmask_b32_e64 v192, v189, v185, s[36:37]
	v_mov_b32_dpp v194, v193 quad_perm:[1,0,3,2] row_mask:0xf bank_mask:0xf
	v_mov_b32_e32 v193, v115
	v_cvt_pk_bf16_f32 v191, v196, v197
	v_add_f32_e32 v183, v160, v161
	v_cndmask_b32_e64 v160, v191, v187, s[36:37]
	v_cndmask_b32_e64 v161, v190, v186, s[36:37]
	v_mov_b32_dpp v193, v192 quad_perm:[1,0,3,2] row_mask:0xf bank_mask:0xf
	v_mov_b32_e32 v192, v115
	v_mov_b32_e32 v195, v115
	v_cndmask_b32_e64 v184, v184, v194, s[36:37]
	v_mov_b32_dpp v192, v161 quad_perm:[1,0,3,2] row_mask:0xf bank_mask:0xf
	v_mov_b32_dpp v195, v160 quad_perm:[1,0,3,2] row_mask:0xf bank_mask:0xf
	v_cndmask_b32_e64 v185, v185, v193, s[36:37]
	v_cndmask_b32_e64 v186, v186, v192, s[36:37]
	v_cndmask_b32_e64 v187, v187, v195, s[36:37]
	v_lshl_add_u64 v[160:161], v[148:149], 1, s[24:25]
	global_store_dwordx4 v[160:161], v[184:187], off nt
	v_lshl_add_u64 v[160:161], v[150:151], 1, s[24:25]
	s_nop 0
	v_cndmask_b32_e64 v184, v194, v188, s[36:37]
	v_cndmask_b32_e64 v185, v193, v189, s[36:37]
	v_cndmask_b32_e64 v186, v192, v190, s[36:37]
	v_cndmask_b32_e64 v187, v195, v191, s[36:37]
	global_store_dwordx4 v[160:161], v[184:187], off nt
	ds_bpermute_b32 v160, v181, v183
	s_waitcnt lgkmcnt(0)
	v_add_f32_e32 v183, v183, v160
	ds_bpermute_b32 v184, v182, v183
	s_and_saveexec_b64 s[24:25], s[38:39]
	s_cbranch_execz .LBB0_1278
	v_or_b32_e32 v160, 32, v176
	v_ashrrev_i32_e32 v161, 31, v160
	v_lshlrev_b64 v[160:161], 7, v[160:161]
	v_lshl_add_u64 v[160:161], s[6:7], 0, v[160:161]
	v_lshl_add_u64 v[160:161], s[22:23], 2, v[160:161]
	s_lshl_b32 s4, s53, 2
	s_waitcnt lgkmcnt(0)
	v_add_f32_e32 v183, v183, v184
	v_lshl_add_u64 v[160:161], v[160:161], 0, s[4:5]
	global_store_dword v[160:161], v183, off nt
.LBB0_1278:
	s_or_b64 exec, exec, s[24:25]
	s_waitcnt vmcnt(3)
	v_lshlrev_b32_e32 v160, 16, v136
	v_and_b32_e32 v136, 0xffff0000, v136
	v_lshlrev_b32_e32 v161, 16, v137
	v_and_b32_e32 v137, 0xffff0000, v137
	v_add_f32_e32 v136, v79, v136
	v_add_f32_e32 v137, v81, v137
	v_add_f32_e32 v160, v78, v160
	v_add_f32_e32 v161, v80, v161
	v_lshlrev_b32_e32 v183, 16, v138
	v_and_b32_e32 v138, 0xffff0000, v138
	s_waitcnt lgkmcnt(0)
	v_lshlrev_b32_e32 v184, 16, v139
	v_and_b32_e32 v139, 0xffff0000, v139
	v_cvt_pk_bf16_f32 v185, v160, v136
	v_cvt_pk_bf16_f32 v186, v161, v137
	v_mul_f32_e32 v136, v136, v136
	v_mul_f32_e32 v137, v137, v137
	v_add_f32_e32 v138, v75, v138
	v_add_f32_e32 v139, v77, v139
	v_fmac_f32_e32 v136, v160, v160
	v_fmac_f32_e32 v137, v161, v161
	v_add_f32_e32 v183, v74, v183
	v_add_f32_e32 v184, v76, v184
	v_cvt_pk_bf16_f32 v187, v183, v138
	v_add_f32_e32 v136, v136, v137
	v_mul_f32_e32 v137, v138, v138
	v_mul_f32_e32 v138, v139, v139
	v_fmac_f32_e32 v137, v183, v183
	v_fmac_f32_e32 v138, v184, v184
	v_add_f32_e32 v137, v137, v138
	v_add_f32_e32 v136, v136, v137
	s_waitcnt vmcnt(2)
	v_lshlrev_b32_e32 v137, 16, v132
	v_and_b32_e32 v132, 0xffff0000, v132
	v_lshlrev_b32_e32 v138, 16, v133
	v_and_b32_e32 v133, 0xffff0000, v133
	v_add_f32_e32 v132, v71, v132
	v_add_f32_e32 v133, v73, v133
	v_cvt_pk_bf16_f32 v188, v184, v139
	v_add_f32_e32 v137, v70, v137
	v_add_f32_e32 v138, v72, v138
	v_lshlrev_b32_e32 v139, 16, v134
	v_and_b32_e32 v134, 0xffff0000, v134
	v_lshlrev_b32_e32 v160, 16, v135
	v_and_b32_e32 v135, 0xffff0000, v135
	v_cvt_pk_bf16_f32 v161, v137, v132
	v_cvt_pk_bf16_f32 v183, v138, v133
	v_mul_f32_e32 v132, v132, v132
	v_mul_f32_e32 v133, v133, v133
	v_add_f32_e32 v134, v67, v134
	v_add_f32_e32 v135, v69, v135
	v_fmac_f32_e32 v132, v137, v137
	v_fmac_f32_e32 v133, v138, v138
	v_add_f32_e32 v139, v66, v139
	v_add_f32_e32 v160, v68, v160
	v_cvt_pk_bf16_f32 v184, v139, v134
	v_add_f32_e32 v132, v132, v133
	v_mul_f32_e32 v133, v134, v134
	v_mul_f32_e32 v134, v135, v135
	v_fmac_f32_e32 v133, v139, v139
	v_fmac_f32_e32 v134, v160, v160
	v_add_f32_e32 v133, v133, v134
	v_cvt_pk_bf16_f32 v189, v160, v135
	v_add_f32_e32 v132, v132, v133
	v_cndmask_b32_e64 v135, v161, v185, s[36:37]
	v_mov_b32_e32 v139, v115
	v_add_f32_e32 v138, v136, v132
	v_cndmask_b32_e64 v132, v189, v188, s[36:37]
	v_mov_b32_dpp v139, v135 quad_perm:[1,0,3,2] row_mask:0xf bank_mask:0xf
	v_mov_b32_e32 v191, v115
	s_add_u32 s24, s20, 0x30000
	v_cndmask_b32_e64 v133, v184, v187, s[36:37]
	v_mov_b32_dpp v191, v132 quad_perm:[1,0,3,2] row_mask:0xf bank_mask:0xf
	v_cndmask_b32_e64 v132, v185, v139, s[36:37]
	ds_bpermute_b32 v185, v181, v138
	v_cndmask_b32_e64 v134, v183, v186, s[36:37]
	v_mov_b32_e32 v160, v115
	v_mov_b32_e32 v190, v115
	s_addc_u32 s25, s21, 0
	v_mov_b32_dpp v160, v134 quad_perm:[1,0,3,2] row_mask:0xf bank_mask:0xf
	v_mov_b32_dpp v190, v133 quad_perm:[1,0,3,2] row_mask:0xf bank_mask:0xf
	v_cndmask_b32_e64 v133, v186, v160, s[36:37]
	v_cndmask_b32_e64 v134, v187, v190, s[36:37]
	v_cndmask_b32_e64 v135, v188, v191, s[36:37]
	v_lshl_add_u64 v[136:137], v[148:149], 1, s[24:25]
	global_store_dwordx4 v[136:137], v[132:135], off nt
	v_cndmask_b32_e64 v136, v190, v184, s[36:37]
	v_cndmask_b32_e64 v137, v191, v189, s[36:37]
	s_waitcnt lgkmcnt(0)
	v_add_f32_e32 v132, v138, v185
	ds_bpermute_b32 v133, v182, v132
	v_cndmask_b32_e64 v134, v139, v161, s[36:37]
	v_cndmask_b32_e64 v135, v160, v183, s[36:37]
	v_lshl_add_u64 v[138:139], v[150:151], 1, s[24:25]
	global_store_dwordx4 v[138:139], v[134:137], off nt
	s_and_saveexec_b64 s[24:25], s[38:39]
	s_cbranch_execz .LBB0_1280
	s_waitcnt lgkmcnt(0)
	v_add_f32_e32 v134, v132, v133
	v_or_b32_e32 v132, 48, v176
	v_ashrrev_i32_e32 v133, 31, v132
	v_lshlrev_b64 v[132:133], 7, v[132:133]
	v_lshl_add_u64 v[132:133], s[6:7], 0, v[132:133]
	v_lshl_add_u64 v[132:133], s[22:23], 2, v[132:133]
	s_lshl_b32 s4, s53, 2
	v_lshl_add_u64 v[132:133], v[132:133], 0, s[4:5]
	global_store_dword v[132:133], v134, off nt
.LBB0_1280:
	s_or_b64 exec, exec, s[24:25]
	v_add_co_u32_e32 v132, vcc, 0x80000, v174
	s_add_u32 s24, s20, 0x80000
	s_waitcnt lgkmcnt(0)
	v_addc_co_u32_e32 v133, vcc, 0, v175, vcc
	global_load_dwordx4 v[184:187], v[132:133], off
	global_load_dwordx4 v[188:191], v[132:133], off offset:64
	v_add_co_u32_e32 v132, vcc, 0x90000, v174
	s_addc_u32 s25, s21, 0
	s_nop 0
	v_addc_co_u32_e32 v133, vcc, 0, v175, vcc
	global_load_dwordx4 v[136:139], v[132:133], off
	s_nop 0
	global_load_dwordx4 v[132:135], v[132:133], off offset:64
	s_waitcnt vmcnt(3)
	v_lshlrev_b32_e32 v160, 16, v184
	v_and_b32_e32 v161, 0xffff0000, v184
	v_and_b32_e32 v184, 0xffff0000, v185
	v_add_f32_e32 v192, v65, v184
	v_lshlrev_b32_e32 v184, 16, v186
	v_add_f32_e32 v193, v58, v184
	v_and_b32_e32 v184, 0xffff0000, v186
	v_add_f32_e32 v194, v59, v184
	v_lshlrev_b32_e32 v184, 16, v187
	v_add_f32_e32 v161, v63, v161
	v_add_f32_e32 v195, v60, v184
	v_and_b32_e32 v184, 0xffff0000, v187
	v_add_f32_e32 v160, v62, v160
	v_lshlrev_b32_e32 v183, 16, v185
	v_add_f32_e32 v196, v61, v184
	v_cvt_pk_bf16_f32 v184, v160, v161
	v_mul_f32_e32 v161, v161, v161
	v_add_f32_e32 v183, v64, v183
	v_fmac_f32_e32 v161, v160, v160
	v_mul_f32_e32 v160, v192, v192
	v_fmac_f32_e32 v160, v183, v183
	v_cvt_pk_bf16_f32 v185, v183, v192
	v_add_f32_e32 v160, v161, v160
	v_mul_f32_e32 v161, v194, v194
	v_mul_f32_e32 v183, v196, v196
	v_fmac_f32_e32 v161, v193, v193
	v_fmac_f32_e32 v183, v195, v195
	v_add_f32_e32 v161, v161, v183
	v_add_f32_e32 v160, v160, v161
	s_waitcnt vmcnt(2)
	v_lshlrev_b32_e32 v161, 16, v188
	v_and_b32_e32 v183, 0xffff0000, v188
	v_lshlrev_b32_e32 v188, 16, v189
	v_add_f32_e32 v192, v56, v188
	v_and_b32_e32 v188, 0xffff0000, v189
	v_cvt_pk_bf16_f32 v186, v193, v194
	v_add_f32_e32 v193, v57, v188
	v_lshlrev_b32_e32 v188, 16, v190
	v_add_f32_e32 v194, v50, v188
	v_and_b32_e32 v188, 0xffff0000, v190
	v_cvt_pk_bf16_f32 v187, v195, v196
	v_add_f32_e32 v195, v51, v188
	v_lshlrev_b32_e32 v188, 16, v191
	v_add_f32_e32 v183, v55, v183
	v_add_f32_e32 v196, v52, v188
	v_and_b32_e32 v188, 0xffff0000, v191
	v_add_f32_e32 v161, v54, v161
	v_add_f32_e32 v197, v53, v188
	v_cvt_pk_bf16_f32 v188, v161, v183
	v_mul_f32_e32 v183, v183, v183
	v_fmac_f32_e32 v183, v161, v161
	v_mul_f32_e32 v161, v193, v193
	v_fmac_f32_e32 v161, v192, v192
	v_cvt_pk_bf16_f32 v189, v192, v193
	v_add_f32_e32 v161, v183, v161
	v_mul_f32_e32 v183, v195, v195
	v_mul_f32_e32 v192, v197, v197
	v_fmac_f32_e32 v183, v194, v194
	v_fmac_f32_e32 v192, v196, v196
	v_cvt_pk_bf16_f32 v190, v194, v195
	v_add_f32_e32 v183, v183, v192
	v_cndmask_b32_e64 v193, v188, v184, s[36:37]
	v_mov_b32_e32 v194, v115
	v_add_f32_e32 v161, v161, v183
	v_cndmask_b32_e64 v192, v189, v185, s[36:37]
	v_mov_b32_dpp v194, v193 quad_perm:[1,0,3,2] row_mask:0xf bank_mask:0xf
	v_mov_b32_e32 v193, v115
	v_cvt_pk_bf16_f32 v191, v196, v197
	v_add_f32_e32 v183, v160, v161
	v_cndmask_b32_e64 v160, v191, v187, s[36:37]
	v_cndmask_b32_e64 v161, v190, v186, s[36:37]
	v_mov_b32_dpp v193, v192 quad_perm:[1,0,3,2] row_mask:0xf bank_mask:0xf
	v_mov_b32_e32 v192, v115
	v_mov_b32_e32 v195, v115
	v_cndmask_b32_e64 v184, v184, v194, s[36:37]
	v_mov_b32_dpp v192, v161 quad_perm:[1,0,3,2] row_mask:0xf bank_mask:0xf
	v_mov_b32_dpp v195, v160 quad_perm:[1,0,3,2] row_mask:0xf bank_mask:0xf
	v_cndmask_b32_e64 v185, v185, v193, s[36:37]
	v_cndmask_b32_e64 v186, v186, v192, s[36:37]
	v_cndmask_b32_e64 v187, v187, v195, s[36:37]
	v_lshl_add_u64 v[160:161], v[148:149], 1, s[24:25]
	global_store_dwordx4 v[160:161], v[184:187], off nt
	v_lshl_add_u64 v[160:161], v[150:151], 1, s[24:25]
	s_nop 0
	v_cndmask_b32_e64 v184, v194, v188, s[36:37]
	v_cndmask_b32_e64 v185, v193, v189, s[36:37]
	v_cndmask_b32_e64 v186, v192, v190, s[36:37]
	v_cndmask_b32_e64 v187, v195, v191, s[36:37]
	global_store_dwordx4 v[160:161], v[184:187], off nt
	ds_bpermute_b32 v160, v181, v183
	s_waitcnt lgkmcnt(0)
	v_add_f32_e32 v183, v183, v160
	ds_bpermute_b32 v184, v182, v183
	s_and_saveexec_b64 s[24:25], s[38:39]
	s_cbranch_execz .LBB0_1282
	v_lshlrev_b64 v[160:161], 7, v[176:177]
	v_lshl_add_u64 v[160:161], s[6:7], 0, v[160:161]
	v_lshl_add_u64 v[160:161], s[22:23], 2, v[160:161]
	s_lshl_b32 s4, s53, 2
	v_lshl_add_u64 v[160:161], v[160:161], 0, s[4:5]
	v_add_co_u32_e32 v160, vcc, 0x4000, v160
	s_waitcnt lgkmcnt(0)
	v_add_f32_e32 v183, v183, v184
	v_addc_co_u32_e32 v161, vcc, 0, v161, vcc
	global_store_dword v[160:161], v183, off nt
.LBB0_1282:
	s_or_b64 exec, exec, s[24:25]
	s_waitcnt vmcnt(3)
	v_lshlrev_b32_e32 v160, 16, v136
	v_and_b32_e32 v136, 0xffff0000, v136
	v_lshlrev_b32_e32 v161, 16, v137
	v_and_b32_e32 v137, 0xffff0000, v137
	v_add_f32_e32 v136, v47, v136
	v_add_f32_e32 v137, v49, v137
	v_add_f32_e32 v160, v46, v160
	v_add_f32_e32 v161, v48, v161
	v_lshlrev_b32_e32 v183, 16, v138
	v_and_b32_e32 v138, 0xffff0000, v138
	s_waitcnt lgkmcnt(0)
	v_lshlrev_b32_e32 v184, 16, v139
	v_and_b32_e32 v139, 0xffff0000, v139
	v_cvt_pk_bf16_f32 v185, v160, v136
	v_cvt_pk_bf16_f32 v186, v161, v137
	v_mul_f32_e32 v136, v136, v136
	v_mul_f32_e32 v137, v137, v137
	v_add_f32_e32 v138, v43, v138
	v_add_f32_e32 v139, v45, v139
	v_fmac_f32_e32 v136, v160, v160
	v_fmac_f32_e32 v137, v161, v161
	v_add_f32_e32 v183, v42, v183
	v_add_f32_e32 v184, v44, v184
	v_cvt_pk_bf16_f32 v187, v183, v138
	v_add_f32_e32 v136, v136, v137
	v_mul_f32_e32 v137, v138, v138
	v_mul_f32_e32 v138, v139, v139
	v_fmac_f32_e32 v137, v183, v183
	v_fmac_f32_e32 v138, v184, v184
	v_add_f32_e32 v137, v137, v138
	v_add_f32_e32 v136, v136, v137
	s_waitcnt vmcnt(2)
	v_lshlrev_b32_e32 v137, 16, v132
	v_and_b32_e32 v132, 0xffff0000, v132
	v_lshlrev_b32_e32 v138, 16, v133
	v_and_b32_e32 v133, 0xffff0000, v133
	v_add_f32_e32 v132, v39, v132
	v_add_f32_e32 v133, v41, v133
	v_cvt_pk_bf16_f32 v188, v184, v139
	v_add_f32_e32 v137, v38, v137
	v_add_f32_e32 v138, v40, v138
	v_lshlrev_b32_e32 v139, 16, v134
	v_and_b32_e32 v134, 0xffff0000, v134
	v_lshlrev_b32_e32 v160, 16, v135
	v_and_b32_e32 v135, 0xffff0000, v135
	v_cvt_pk_bf16_f32 v161, v137, v132
	v_cvt_pk_bf16_f32 v183, v138, v133
	v_mul_f32_e32 v132, v132, v132
	v_mul_f32_e32 v133, v133, v133
	v_add_f32_e32 v134, v35, v134
	v_add_f32_e32 v135, v37, v135
	v_fmac_f32_e32 v132, v137, v137
	v_fmac_f32_e32 v133, v138, v138
	v_add_f32_e32 v139, v34, v139
	v_add_f32_e32 v160, v36, v160
	v_cvt_pk_bf16_f32 v184, v139, v134
	v_add_f32_e32 v132, v132, v133
	v_mul_f32_e32 v133, v134, v134
	v_mul_f32_e32 v134, v135, v135
	v_fmac_f32_e32 v133, v139, v139
	v_fmac_f32_e32 v134, v160, v160
	v_add_f32_e32 v133, v133, v134
	v_cvt_pk_bf16_f32 v189, v160, v135
	v_add_f32_e32 v132, v132, v133
	v_cndmask_b32_e64 v135, v161, v185, s[36:37]
	v_mov_b32_e32 v139, v115
	v_add_f32_e32 v138, v136, v132
	v_cndmask_b32_e64 v132, v189, v188, s[36:37]
	v_mov_b32_dpp v139, v135 quad_perm:[1,0,3,2] row_mask:0xf bank_mask:0xf
	v_mov_b32_e32 v191, v115
	s_add_u32 s24, s20, 0x90000
	v_cndmask_b32_e64 v133, v184, v187, s[36:37]
	v_mov_b32_dpp v191, v132 quad_perm:[1,0,3,2] row_mask:0xf bank_mask:0xf
	v_cndmask_b32_e64 v132, v185, v139, s[36:37]
	ds_bpermute_b32 v185, v181, v138
	v_cndmask_b32_e64 v134, v183, v186, s[36:37]
	v_mov_b32_e32 v160, v115
	v_mov_b32_e32 v190, v115
	s_addc_u32 s25, s21, 0
	v_mov_b32_dpp v160, v134 quad_perm:[1,0,3,2] row_mask:0xf bank_mask:0xf
	v_mov_b32_dpp v190, v133 quad_perm:[1,0,3,2] row_mask:0xf bank_mask:0xf
	v_cndmask_b32_e64 v133, v186, v160, s[36:37]
	v_cndmask_b32_e64 v134, v187, v190, s[36:37]
	v_cndmask_b32_e64 v135, v188, v191, s[36:37]
	v_lshl_add_u64 v[136:137], v[148:149], 1, s[24:25]
	global_store_dwordx4 v[136:137], v[132:135], off nt
	v_cndmask_b32_e64 v136, v190, v184, s[36:37]
	v_cndmask_b32_e64 v137, v191, v189, s[36:37]
	s_waitcnt lgkmcnt(0)
	v_add_f32_e32 v132, v138, v185
	ds_bpermute_b32 v133, v182, v132
	v_cndmask_b32_e64 v134, v139, v161, s[36:37]
	v_cndmask_b32_e64 v135, v160, v183, s[36:37]
	v_lshl_add_u64 v[138:139], v[150:151], 1, s[24:25]
	global_store_dwordx4 v[138:139], v[134:137], off nt
	s_and_saveexec_b64 s[24:25], s[38:39]
	s_cbranch_execz .LBB0_1284
	s_waitcnt lgkmcnt(0)
	v_add_f32_e32 v134, v132, v133
	v_lshlrev_b64 v[132:133], 7, v[176:177]
	v_lshl_add_u64 v[132:133], s[6:7], 0, v[132:133]
	v_lshl_add_u64 v[132:133], s[22:23], 2, v[132:133]
	s_lshl_b32 s4, s53, 2
	v_lshl_add_u64 v[132:133], v[132:133], 0, s[4:5]
	v_add_co_u32_e32 v132, vcc, 0x4000, v132
	s_nop 1
	v_addc_co_u32_e32 v133, vcc, 0, v133, vcc
	global_store_dword v[132:133], v134, off offset:2048 nt
.LBB0_1284:
	s_or_b64 exec, exec, s[24:25]
	v_add_co_u32_e32 v132, vcc, 0xa0000, v174
	s_add_u32 s24, s20, 0xa0000
	s_waitcnt lgkmcnt(0)
	v_addc_co_u32_e32 v133, vcc, 0, v175, vcc
	global_load_dwordx4 v[184:187], v[132:133], off
	global_load_dwordx4 v[188:191], v[132:133], off offset:64
	v_add_co_u32_e32 v132, vcc, 0xb0000, v174
	s_addc_u32 s25, s21, 0
	s_nop 0
	v_addc_co_u32_e32 v133, vcc, 0, v175, vcc
	global_load_dwordx4 v[136:139], v[132:133], off
	s_nop 0
	global_load_dwordx4 v[132:135], v[132:133], off offset:64
	s_waitcnt vmcnt(3)
	v_lshlrev_b32_e32 v160, 16, v184
	v_and_b32_e32 v161, 0xffff0000, v184
	v_and_b32_e32 v184, 0xffff0000, v185
	v_add_f32_e32 v192, v33, v184
	v_lshlrev_b32_e32 v184, 16, v186
	v_add_f32_e32 v193, v26, v184
	v_and_b32_e32 v184, 0xffff0000, v186
	v_add_f32_e32 v194, v27, v184
	v_lshlrev_b32_e32 v184, 16, v187
	v_add_f32_e32 v161, v31, v161
	v_add_f32_e32 v195, v28, v184
	v_and_b32_e32 v184, 0xffff0000, v187
	v_add_f32_e32 v160, v30, v160
	v_lshlrev_b32_e32 v183, 16, v185
	v_add_f32_e32 v196, v29, v184
	v_cvt_pk_bf16_f32 v184, v160, v161
	v_mul_f32_e32 v161, v161, v161
	v_add_f32_e32 v183, v32, v183
	v_fmac_f32_e32 v161, v160, v160
	v_mul_f32_e32 v160, v192, v192
	v_fmac_f32_e32 v160, v183, v183
	v_cvt_pk_bf16_f32 v185, v183, v192
	v_add_f32_e32 v160, v161, v160
	v_mul_f32_e32 v161, v194, v194
	v_mul_f32_e32 v183, v196, v196
	v_fmac_f32_e32 v161, v193, v193
	v_fmac_f32_e32 v183, v195, v195
	v_add_f32_e32 v161, v161, v183
	v_add_f32_e32 v160, v160, v161
	s_waitcnt vmcnt(2)
	v_lshlrev_b32_e32 v161, 16, v188
	v_and_b32_e32 v183, 0xffff0000, v188
	v_lshlrev_b32_e32 v188, 16, v189
	v_add_f32_e32 v192, v24, v188
	v_and_b32_e32 v188, 0xffff0000, v189
	v_cvt_pk_bf16_f32 v186, v193, v194
	v_add_f32_e32 v193, v25, v188
	v_lshlrev_b32_e32 v188, 16, v190
	v_add_f32_e32 v194, v18, v188
	v_and_b32_e32 v188, 0xffff0000, v190
	v_cvt_pk_bf16_f32 v187, v195, v196
	v_add_f32_e32 v195, v19, v188
	v_lshlrev_b32_e32 v188, 16, v191
	v_add_f32_e32 v183, v23, v183
	v_add_f32_e32 v196, v20, v188
	v_and_b32_e32 v188, 0xffff0000, v191
	v_add_f32_e32 v161, v22, v161
	v_add_f32_e32 v197, v21, v188
	v_cvt_pk_bf16_f32 v188, v161, v183
	v_mul_f32_e32 v183, v183, v183
	v_fmac_f32_e32 v183, v161, v161
	v_mul_f32_e32 v161, v193, v193
	v_fmac_f32_e32 v161, v192, v192
	v_cvt_pk_bf16_f32 v189, v192, v193
	v_add_f32_e32 v161, v183, v161
	v_mul_f32_e32 v183, v195, v195
	v_mul_f32_e32 v192, v197, v197
	v_fmac_f32_e32 v183, v194, v194
	v_fmac_f32_e32 v192, v196, v196
	v_cvt_pk_bf16_f32 v190, v194, v195
	v_add_f32_e32 v183, v183, v192
	v_cndmask_b32_e64 v193, v188, v184, s[36:37]
	v_mov_b32_e32 v194, v115
	v_add_f32_e32 v161, v161, v183
	v_cndmask_b32_e64 v192, v189, v185, s[36:37]
	v_mov_b32_dpp v194, v193 quad_perm:[1,0,3,2] row_mask:0xf bank_mask:0xf
	v_mov_b32_e32 v193, v115
	v_cvt_pk_bf16_f32 v191, v196, v197
	v_add_f32_e32 v183, v160, v161
	v_cndmask_b32_e64 v160, v191, v187, s[36:37]
	v_cndmask_b32_e64 v161, v190, v186, s[36:37]
	v_mov_b32_dpp v193, v192 quad_perm:[1,0,3,2] row_mask:0xf bank_mask:0xf
	v_mov_b32_e32 v192, v115
	v_mov_b32_e32 v195, v115
	v_cndmask_b32_e64 v184, v184, v194, s[36:37]
	v_mov_b32_dpp v192, v161 quad_perm:[1,0,3,2] row_mask:0xf bank_mask:0xf
	v_mov_b32_dpp v195, v160 quad_perm:[1,0,3,2] row_mask:0xf bank_mask:0xf
	v_cndmask_b32_e64 v185, v185, v193, s[36:37]
	v_cndmask_b32_e64 v186, v186, v192, s[36:37]
	v_cndmask_b32_e64 v187, v187, v195, s[36:37]
	v_lshl_add_u64 v[160:161], v[148:149], 1, s[24:25]
	global_store_dwordx4 v[160:161], v[184:187], off nt
	v_lshl_add_u64 v[160:161], v[150:151], 1, s[24:25]
	s_nop 0
	v_cndmask_b32_e64 v184, v194, v188, s[36:37]
	v_cndmask_b32_e64 v185, v193, v189, s[36:37]
	v_cndmask_b32_e64 v186, v192, v190, s[36:37]
	v_cndmask_b32_e64 v187, v195, v191, s[36:37]
	global_store_dwordx4 v[160:161], v[184:187], off nt
	ds_bpermute_b32 v160, v181, v183
	s_waitcnt lgkmcnt(0)
	v_add_f32_e32 v183, v183, v160
	ds_bpermute_b32 v184, v182, v183
	s_and_saveexec_b64 s[24:25], s[38:39]
	s_cbranch_execz .LBB0_1286
	v_lshlrev_b64 v[160:161], 7, v[176:177]
	v_lshl_add_u64 v[160:161], s[6:7], 0, v[160:161]
	v_lshl_add_u64 v[160:161], s[22:23], 2, v[160:161]
	s_lshl_b32 s4, s53, 2
	v_lshl_add_u64 v[160:161], v[160:161], 0, s[4:5]
	v_add_co_u32_e32 v160, vcc, 0x5000, v160
	s_waitcnt lgkmcnt(0)
	v_add_f32_e32 v183, v183, v184
	v_addc_co_u32_e32 v161, vcc, 0, v161, vcc
	global_store_dword v[160:161], v183, off nt
.LBB0_1286:
	s_or_b64 exec, exec, s[24:25]
	s_waitcnt vmcnt(3)
	v_lshlrev_b32_e32 v160, 16, v136
	v_and_b32_e32 v136, 0xffff0000, v136
	v_lshlrev_b32_e32 v161, 16, v137
	v_and_b32_e32 v137, 0xffff0000, v137
	v_add_f32_e32 v136, v15, v136
	v_add_f32_e32 v137, v17, v137
	v_add_f32_e32 v160, v14, v160
	v_add_f32_e32 v161, v16, v161
	v_lshlrev_b32_e32 v183, 16, v138
	v_and_b32_e32 v138, 0xffff0000, v138
	s_waitcnt lgkmcnt(0)
	v_lshlrev_b32_e32 v184, 16, v139
	v_and_b32_e32 v139, 0xffff0000, v139
	v_cvt_pk_bf16_f32 v185, v160, v136
	v_cvt_pk_bf16_f32 v186, v161, v137
	v_mul_f32_e32 v136, v136, v136
	v_mul_f32_e32 v137, v137, v137
	v_add_f32_e32 v138, v11, v138
	v_add_f32_e32 v139, v13, v139
	v_fmac_f32_e32 v136, v160, v160
	v_fmac_f32_e32 v137, v161, v161
	v_add_f32_e32 v183, v10, v183
	v_add_f32_e32 v184, v12, v184
	v_cvt_pk_bf16_f32 v187, v183, v138
	v_add_f32_e32 v136, v136, v137
	v_mul_f32_e32 v137, v138, v138
	v_mul_f32_e32 v138, v139, v139
	v_fmac_f32_e32 v137, v183, v183
	v_fmac_f32_e32 v138, v184, v184
	v_add_f32_e32 v137, v137, v138
	v_add_f32_e32 v136, v136, v137
	s_waitcnt vmcnt(2)
	v_lshlrev_b32_e32 v137, 16, v132
	v_and_b32_e32 v132, 0xffff0000, v132
	v_lshlrev_b32_e32 v138, 16, v133
	v_and_b32_e32 v133, 0xffff0000, v133
	v_add_f32_e32 v132, v7, v132
	v_add_f32_e32 v133, v9, v133
	v_cvt_pk_bf16_f32 v188, v184, v139
	v_add_f32_e32 v137, v6, v137
	v_add_f32_e32 v138, v8, v138
	v_lshlrev_b32_e32 v139, 16, v134
	v_and_b32_e32 v134, 0xffff0000, v134
	v_lshlrev_b32_e32 v160, 16, v135
	v_and_b32_e32 v135, 0xffff0000, v135
	v_cvt_pk_bf16_f32 v161, v137, v132
	v_cvt_pk_bf16_f32 v183, v138, v133
	v_mul_f32_e32 v132, v132, v132
	v_mul_f32_e32 v133, v133, v133
	v_add_f32_e32 v134, v3, v134
	v_add_f32_e32 v135, v5, v135
	v_fmac_f32_e32 v132, v137, v137
	v_fmac_f32_e32 v133, v138, v138
	v_add_f32_e32 v139, v2, v139
	v_add_f32_e32 v160, v4, v160
	v_cvt_pk_bf16_f32 v184, v139, v134
	v_add_f32_e32 v132, v132, v133
	v_mul_f32_e32 v133, v134, v134
	v_mul_f32_e32 v134, v135, v135
	v_fmac_f32_e32 v133, v139, v139
	v_fmac_f32_e32 v134, v160, v160
	v_add_f32_e32 v133, v133, v134
	v_add_f32_e32 v132, v132, v133
	v_add_f32_e32 v138, v136, v132
	ds_bpermute_b32 v181, v181, v138
	v_cvt_pk_bf16_f32 v189, v160, v135
	s_add_u32 s20, s20, 0xb0000
	v_cndmask_b32_e64 v132, v189, v188, s[36:37]
	v_cndmask_b32_e64 v133, v184, v187, s[36:37]
	v_cndmask_b32_e64 v134, v183, v186, s[36:37]
	v_cndmask_b32_e64 v135, v161, v185, s[36:37]
	v_mov_b32_e32 v139, v115
	v_mov_b32_e32 v160, v115
	v_mov_b32_e32 v190, v115
	v_mov_b32_e32 v191, v115
	s_addc_u32 s21, s21, 0
	v_mov_b32_dpp v139, v135 quad_perm:[1,0,3,2] row_mask:0xf bank_mask:0xf
	v_mov_b32_dpp v160, v134 quad_perm:[1,0,3,2] row_mask:0xf bank_mask:0xf
	v_mov_b32_dpp v190, v133 quad_perm:[1,0,3,2] row_mask:0xf bank_mask:0xf
	v_mov_b32_dpp v191, v132 quad_perm:[1,0,3,2] row_mask:0xf bank_mask:0xf
	v_cndmask_b32_e64 v132, v185, v139, s[36:37]
	v_cndmask_b32_e64 v133, v186, v160, s[36:37]
	v_cndmask_b32_e64 v134, v187, v190, s[36:37]
	v_cndmask_b32_e64 v135, v188, v191, s[36:37]
	v_lshl_add_u64 v[136:137], v[148:149], 1, s[20:21]
	global_store_dwordx4 v[136:137], v[132:135], off nt
	v_cndmask_b32_e64 v136, v190, v184, s[36:37]
	v_cndmask_b32_e64 v137, v191, v189, s[36:37]
	s_waitcnt lgkmcnt(0)
	v_add_f32_e32 v132, v138, v181
	ds_bpermute_b32 v133, v182, v132
	v_cndmask_b32_e64 v134, v139, v161, s[36:37]
	v_cndmask_b32_e64 v135, v160, v183, s[36:37]
	v_lshl_add_u64 v[138:139], v[150:151], 1, s[20:21]
	global_store_dwordx4 v[138:139], v[134:137], off nt
	s_and_saveexec_b64 s[20:21], s[38:39]
	s_cbranch_execz .LBB0_1288
	s_waitcnt lgkmcnt(0)
	v_add_f32_e32 v134, v132, v133
	v_lshlrev_b64 v[132:133], 7, v[176:177]
	v_lshl_add_u64 v[132:133], s[6:7], 0, v[132:133]
	v_lshl_add_u64 v[132:133], s[22:23], 2, v[132:133]
	s_lshl_b32 s4, s53, 2
	v_lshl_add_u64 v[132:133], v[132:133], 0, s[4:5]
	v_add_co_u32_e32 v132, vcc, 0x5000, v132
	s_nop 1
	v_addc_co_u32_e32 v133, vcc, 0, v133, vcc
	global_store_dword v[132:133], v134, off offset:2048 nt

.LBB0_1289:
	s_waitcnt lgkmcnt(0)
	global_load_dwordx4 v[132:135], v[174:175], off
	s_lshl_b64 s[18:19], s[18:19], 2
	s_add_u32 s18, s90, s18
	s_addc_u32 s19, s91, s19
	v_lshl_add_u64 v[136:137], v[146:147], 2, s[18:19]
	s_waitcnt vmcnt(0)
	v_lshlrev_b32_e32 v138, 16, v132
	v_and_b32_e32 v139, 0xffff0000, v132
	v_lshlrev_b32_e32 v132, 16, v133
	v_and_b32_e32 v133, 0xffff0000, v133
	v_pk_add_f32 v[130:131], v[130:131], v[132:133]
	v_lshlrev_b32_e32 v132, 16, v134
	v_and_b32_e32 v133, 0xffff0000, v134
	v_pk_add_f32 v[128:129], v[128:129], v[138:139]
	v_pk_add_f32 v[124:125], v[124:125], v[132:133]
	v_lshlrev_b32_e32 v132, 16, v135
	v_and_b32_e32 v133, 0xffff0000, v135
	v_pk_add_f32 v[126:127], v[126:127], v[132:133]
	global_store_dwordx4 v[136:137], v[128:131], off nt
	global_store_dwordx4 v[136:137], v[124:127], off offset:16 nt
	global_load_dwordx4 v[124:127], v[174:175], off offset:64
	s_waitcnt vmcnt(0)
	v_lshlrev_b32_e32 v128, 16, v124
	v_and_b32_e32 v129, 0xffff0000, v124
	v_lshlrev_b32_e32 v124, 16, v125
	v_and_b32_e32 v125, 0xffff0000, v125
	v_pk_add_f32 v[122:123], v[122:123], v[124:125]
	v_lshlrev_b32_e32 v124, 16, v126
	v_and_b32_e32 v125, 0xffff0000, v126
	v_pk_add_f32 v[120:121], v[120:121], v[128:129]
	v_pk_add_f32 v[116:117], v[116:117], v[124:125]
	v_lshlrev_b32_e32 v124, 16, v127
	v_and_b32_e32 v125, 0xffff0000, v127
	v_pk_add_f32 v[118:119], v[118:119], v[124:125]
	global_store_dwordx4 v[136:137], v[120:123], off offset:128 nt
	global_store_dwordx4 v[136:137], v[116:119], off offset:144 nt
	s_nop 0
	v_lshl_add_u64 v[120:121], v[152:153], 1, s[16:17]
	global_load_dwordx4 v[116:119], v[120:121], off
	v_lshl_add_u64 v[122:123], v[152:153], 2, s[18:19]
	s_waitcnt vmcnt(0)
	v_lshlrev_b32_e32 v124, 16, v116
	v_and_b32_e32 v125, 0xffff0000, v116
	v_lshlrev_b32_e32 v116, 16, v117
	v_and_b32_e32 v117, 0xffff0000, v117
	v_pk_add_f32 v[112:113], v[112:113], v[116:117]
	v_lshlrev_b32_e32 v116, 16, v118
	v_and_b32_e32 v117, 0xffff0000, v118
	v_pk_add_f32 v[110:111], v[110:111], v[124:125]
	v_pk_add_f32 v[106:107], v[106:107], v[116:117]
	v_lshlrev_b32_e32 v116, 16, v119
	v_and_b32_e32 v117, 0xffff0000, v119
	v_pk_add_f32 v[108:109], v[108:109], v[116:117]
	global_store_dwordx4 v[122:123], v[110:113], off nt
	global_store_dwordx4 v[122:123], v[106:109], off offset:16 nt
	global_load_dwordx4 v[106:109], v[120:121], off offset:64
	s_waitcnt vmcnt(0)
	v_lshlrev_b32_e32 v110, 16, v106
	v_and_b32_e32 v111, 0xffff0000, v106
	v_lshlrev_b32_e32 v106, 16, v107
	v_and_b32_e32 v107, 0xffff0000, v107
	v_pk_add_f32 v[104:105], v[104:105], v[106:107]
	v_lshlrev_b32_e32 v106, 16, v108
	v_and_b32_e32 v107, 0xffff0000, v108
	v_pk_add_f32 v[102:103], v[102:103], v[110:111]
	v_pk_add_f32 v[98:99], v[98:99], v[106:107]
	v_lshlrev_b32_e32 v106, 16, v109
	v_and_b32_e32 v107, 0xffff0000, v109
	v_pk_add_f32 v[100:101], v[100:101], v[106:107]
	global_store_dwordx4 v[122:123], v[102:105], off offset:128 nt
	global_store_dwordx4 v[122:123], v[98:101], off offset:144 nt
	s_nop 0
	v_lshl_add_u64 v[102:103], v[154:155], 1, s[16:17]
	global_load_dwordx4 v[98:101], v[102:103], off
	v_lshl_add_u64 v[104:105], v[154:155], 2, s[18:19]
	s_waitcnt vmcnt(0)
	v_lshlrev_b32_e32 v106, 16, v98
	v_and_b32_e32 v107, 0xffff0000, v98
	v_lshlrev_b32_e32 v98, 16, v99
	v_and_b32_e32 v99, 0xffff0000, v99
	v_pk_add_f32 v[96:97], v[96:97], v[98:99]
	v_lshlrev_b32_e32 v98, 16, v100
	v_and_b32_e32 v99, 0xffff0000, v100
	v_pk_add_f32 v[94:95], v[94:95], v[106:107]
	v_pk_add_f32 v[90:91], v[90:91], v[98:99]
	v_lshlrev_b32_e32 v98, 16, v101
	v_and_b32_e32 v99, 0xffff0000, v101
	v_pk_add_f32 v[92:93], v[92:93], v[98:99]
	global_store_dwordx4 v[104:105], v[94:97], off nt
	global_store_dwordx4 v[104:105], v[90:93], off offset:16 nt
	global_load_dwordx4 v[90:93], v[102:103], off offset:64
	s_waitcnt vmcnt(0)
	v_lshlrev_b32_e32 v94, 16, v90
	v_and_b32_e32 v95, 0xffff0000, v90
	v_lshlrev_b32_e32 v90, 16, v91
	v_and_b32_e32 v91, 0xffff0000, v91
	v_pk_add_f32 v[88:89], v[88:89], v[90:91]
	v_lshlrev_b32_e32 v90, 16, v92
	v_and_b32_e32 v91, 0xffff0000, v92
	v_pk_add_f32 v[86:87], v[86:87], v[94:95]
	v_pk_add_f32 v[82:83], v[82:83], v[90:91]
	v_lshlrev_b32_e32 v90, 16, v93
	v_and_b32_e32 v91, 0xffff0000, v93
	v_pk_add_f32 v[84:85], v[84:85], v[90:91]
	global_store_dwordx4 v[104:105], v[86:89], off offset:128 nt
	global_store_dwordx4 v[104:105], v[82:85], off offset:144 nt
	s_nop 0
	v_lshl_add_u64 v[86:87], v[156:157], 1, s[16:17]
	global_load_dwordx4 v[82:85], v[86:87], off
	v_lshl_add_u64 v[88:89], v[156:157], 2, s[18:19]
	s_waitcnt vmcnt(0)
	v_lshlrev_b32_e32 v90, 16, v82
	v_and_b32_e32 v91, 0xffff0000, v82
	v_lshlrev_b32_e32 v82, 16, v83
	v_and_b32_e32 v83, 0xffff0000, v83
	v_pk_add_f32 v[80:81], v[80:81], v[82:83]
	v_lshlrev_b32_e32 v82, 16, v84
	v_and_b32_e32 v83, 0xffff0000, v84
	v_pk_add_f32 v[78:79], v[78:79], v[90:91]
	v_pk_add_f32 v[74:75], v[74:75], v[82:83]
	v_lshlrev_b32_e32 v82, 16, v85
	v_and_b32_e32 v83, 0xffff0000, v85
	v_pk_add_f32 v[76:77], v[76:77], v[82:83]
	global_store_dwordx4 v[88:89], v[78:81], off nt
	global_store_dwordx4 v[88:89], v[74:77], off offset:16 nt
	global_load_dwordx4 v[74:77], v[86:87], off offset:64
	s_waitcnt vmcnt(0)
	v_lshlrev_b32_e32 v78, 16, v74
	v_and_b32_e32 v79, 0xffff0000, v74
	v_lshlrev_b32_e32 v74, 16, v75
	v_and_b32_e32 v75, 0xffff0000, v75
	v_pk_add_f32 v[72:73], v[72:73], v[74:75]
	v_lshlrev_b32_e32 v74, 16, v76
	v_and_b32_e32 v75, 0xffff0000, v76
	v_pk_add_f32 v[70:71], v[70:71], v[78:79]
	v_pk_add_f32 v[66:67], v[66:67], v[74:75]
	v_lshlrev_b32_e32 v74, 16, v77
	v_and_b32_e32 v75, 0xffff0000, v77
	v_pk_add_f32 v[68:69], v[68:69], v[74:75]
	global_store_dwordx4 v[88:89], v[70:73], off offset:128 nt
	global_store_dwordx4 v[88:89], v[66:69], off offset:144 nt
	s_nop 0
	v_lshl_add_u64 v[70:71], v[158:159], 1, s[16:17]
	global_load_dwordx4 v[66:69], v[70:71], off
	v_lshl_add_u64 v[72:73], v[158:159], 2, s[18:19]
	s_waitcnt vmcnt(0)
	v_lshlrev_b32_e32 v74, 16, v66
	v_and_b32_e32 v75, 0xffff0000, v66
	v_lshlrev_b32_e32 v66, 16, v67
	v_and_b32_e32 v67, 0xffff0000, v67
	v_pk_add_f32 v[64:65], v[64:65], v[66:67]
	v_lshlrev_b32_e32 v66, 16, v68
	v_and_b32_e32 v67, 0xffff0000, v68
	v_pk_add_f32 v[62:63], v[62:63], v[74:75]
	v_pk_add_f32 v[58:59], v[58:59], v[66:67]
	v_lshlrev_b32_e32 v66, 16, v69
	v_and_b32_e32 v67, 0xffff0000, v69
	v_pk_add_f32 v[60:61], v[60:61], v[66:67]
	global_store_dwordx4 v[72:73], v[62:65], off nt
	global_store_dwordx4 v[72:73], v[58:61], off offset:16 nt
	global_load_dwordx4 v[58:61], v[70:71], off offset:64
	s_waitcnt vmcnt(0)
	v_lshlrev_b32_e32 v62, 16, v58
	v_and_b32_e32 v63, 0xffff0000, v58
	v_lshlrev_b32_e32 v58, 16, v59
	v_and_b32_e32 v59, 0xffff0000, v59
	v_pk_add_f32 v[56:57], v[56:57], v[58:59]
	v_lshlrev_b32_e32 v58, 16, v60
	v_and_b32_e32 v59, 0xffff0000, v60
	v_pk_add_f32 v[54:55], v[54:55], v[62:63]
	v_pk_add_f32 v[50:51], v[50:51], v[58:59]
	v_lshlrev_b32_e32 v58, 16, v61
	v_and_b32_e32 v59, 0xffff0000, v61
	v_pk_add_f32 v[52:53], v[52:53], v[58:59]
	global_store_dwordx4 v[72:73], v[54:57], off offset:128 nt
	global_store_dwordx4 v[72:73], v[50:53], off offset:144 nt
	s_nop 0
	v_lshl_add_u64 v[54:55], v[164:165], 1, s[16:17]
	global_load_dwordx4 v[50:53], v[54:55], off
	v_lshl_add_u64 v[56:57], v[164:165], 2, s[18:19]
	s_waitcnt vmcnt(0)
	v_lshlrev_b32_e32 v58, 16, v50
	v_and_b32_e32 v59, 0xffff0000, v50
	v_lshlrev_b32_e32 v50, 16, v51
	v_and_b32_e32 v51, 0xffff0000, v51
	v_pk_add_f32 v[48:49], v[48:49], v[50:51]
	v_lshlrev_b32_e32 v50, 16, v52
	v_and_b32_e32 v51, 0xffff0000, v52
	v_pk_add_f32 v[46:47], v[46:47], v[58:59]
	v_pk_add_f32 v[42:43], v[42:43], v[50:51]
	v_lshlrev_b32_e32 v50, 16, v53
	v_and_b32_e32 v51, 0xffff0000, v53
	v_pk_add_f32 v[44:45], v[44:45], v[50:51]
	global_store_dwordx4 v[56:57], v[46:49], off nt
	global_store_dwordx4 v[56:57], v[42:45], off offset:16 nt
	global_load_dwordx4 v[42:45], v[54:55], off offset:64
	s_waitcnt vmcnt(0)
	v_lshlrev_b32_e32 v46, 16, v42
	v_and_b32_e32 v47, 0xffff0000, v42
	v_lshlrev_b32_e32 v42, 16, v43
	v_and_b32_e32 v43, 0xffff0000, v43
	v_pk_add_f32 v[40:41], v[40:41], v[42:43]
	v_lshlrev_b32_e32 v42, 16, v44
	v_and_b32_e32 v43, 0xffff0000, v44
	v_pk_add_f32 v[38:39], v[38:39], v[46:47]
	v_pk_add_f32 v[34:35], v[34:35], v[42:43]
	v_lshlrev_b32_e32 v42, 16, v45
	v_and_b32_e32 v43, 0xffff0000, v45
	v_pk_add_f32 v[36:37], v[36:37], v[42:43]
	global_store_dwordx4 v[56:57], v[38:41], off offset:128 nt
	global_store_dwordx4 v[56:57], v[34:37], off offset:144 nt
	s_nop 0
	v_lshl_add_u64 v[38:39], v[166:167], 1, s[16:17]
	global_load_dwordx4 v[34:37], v[38:39], off
	v_lshl_add_u64 v[40:41], v[166:167], 2, s[18:19]
	s_waitcnt vmcnt(0)
	v_lshlrev_b32_e32 v42, 16, v34
	v_and_b32_e32 v43, 0xffff0000, v34
	v_lshlrev_b32_e32 v34, 16, v35
	v_and_b32_e32 v35, 0xffff0000, v35
	v_pk_add_f32 v[32:33], v[32:33], v[34:35]
	v_lshlrev_b32_e32 v34, 16, v36
	v_and_b32_e32 v35, 0xffff0000, v36
	v_pk_add_f32 v[30:31], v[30:31], v[42:43]
	v_pk_add_f32 v[26:27], v[26:27], v[34:35]
	v_lshlrev_b32_e32 v34, 16, v37
	v_and_b32_e32 v35, 0xffff0000, v37
	v_pk_add_f32 v[28:29], v[28:29], v[34:35]
	global_store_dwordx4 v[40:41], v[30:33], off nt
	global_store_dwordx4 v[40:41], v[26:29], off offset:16 nt
	global_load_dwordx4 v[26:29], v[38:39], off offset:64
	s_waitcnt vmcnt(0)
	v_lshlrev_b32_e32 v30, 16, v26
	v_and_b32_e32 v31, 0xffff0000, v26
	v_lshlrev_b32_e32 v26, 16, v27
	v_and_b32_e32 v27, 0xffff0000, v27
	v_pk_add_f32 v[24:25], v[24:25], v[26:27]
	v_lshlrev_b32_e32 v26, 16, v28
	v_and_b32_e32 v27, 0xffff0000, v28
	v_pk_add_f32 v[22:23], v[22:23], v[30:31]
	v_pk_add_f32 v[18:19], v[18:19], v[26:27]
	v_lshlrev_b32_e32 v26, 16, v29
	v_and_b32_e32 v27, 0xffff0000, v29
	v_pk_add_f32 v[20:21], v[20:21], v[26:27]
	global_store_dwordx4 v[40:41], v[22:25], off offset:128 nt
	global_store_dwordx4 v[40:41], v[18:21], off offset:144 nt
	s_nop 0
	v_lshl_add_u64 v[22:23], v[168:169], 1, s[16:17]
	global_load_dwordx4 v[18:21], v[22:23], off
	v_lshl_add_u64 v[24:25], v[168:169], 2, s[18:19]
	s_waitcnt vmcnt(0)
	v_lshlrev_b32_e32 v26, 16, v18
	v_and_b32_e32 v27, 0xffff0000, v18
	v_lshlrev_b32_e32 v18, 16, v19
	v_and_b32_e32 v19, 0xffff0000, v19
	v_pk_add_f32 v[16:17], v[16:17], v[18:19]
	v_lshlrev_b32_e32 v18, 16, v20
	v_and_b32_e32 v19, 0xffff0000, v20
	v_pk_add_f32 v[14:15], v[14:15], v[26:27]
	v_pk_add_f32 v[10:11], v[10:11], v[18:19]
	v_lshlrev_b32_e32 v18, 16, v21
	v_and_b32_e32 v19, 0xffff0000, v21
	v_pk_add_f32 v[12:13], v[12:13], v[18:19]
	global_store_dwordx4 v[24:25], v[14:17], off nt
	global_store_dwordx4 v[24:25], v[10:13], off offset:16 nt
	global_load_dwordx4 v[10:13], v[22:23], off offset:64
	s_waitcnt vmcnt(0)
	v_lshlrev_b32_e32 v14, 16, v10
	v_and_b32_e32 v15, 0xffff0000, v10
	v_lshlrev_b32_e32 v10, 16, v11
	v_and_b32_e32 v11, 0xffff0000, v11
	v_pk_add_f32 v[8:9], v[8:9], v[10:11]
	v_lshlrev_b32_e32 v10, 16, v12
	v_and_b32_e32 v11, 0xffff0000, v12
	v_pk_add_f32 v[6:7], v[6:7], v[14:15]
	v_pk_add_f32 v[2:3], v[2:3], v[10:11]
	v_lshlrev_b32_e32 v10, 16, v13
	v_and_b32_e32 v11, 0xffff0000, v13
	v_pk_add_f32 v[4:5], v[4:5], v[10:11]
	global_store_dwordx4 v[24:25], v[6:9], off offset:128 nt
	global_store_dwordx4 v[24:25], v[2:5], off offset:144 nt
	s_and_b64 vcc, exec, s[40:41]
	s_mov_b64 s[16:17], -1
	s_cbranch_vccnz .LBB0_1258

	.amdhsa_kernel _Z3fwd4Args
		.amdhsa_group_segment_fixed_size 0
		.amdhsa_private_segment_fixed_size 0
		.amdhsa_kernarg_size 512
		.amdhsa_user_sgpr_count 2
		.amdhsa_user_sgpr_dispatch_ptr 0
		.amdhsa_user_sgpr_queue_ptr 0
		.amdhsa_user_sgpr_kernarg_segment_ptr 1
		.amdhsa_user_sgpr_dispatch_id 0
		.amdhsa_user_sgpr_kernarg_preload_length 0
		.amdhsa_user_sgpr_kernarg_preload_offset 0
		.amdhsa_user_sgpr_private_segment_size 0
		.amdhsa_uses_dynamic_stack 0
		.amdhsa_enable_private_segment 0
		.amdhsa_system_sgpr_workgroup_id_x 1
		.amdhsa_system_sgpr_workgroup_id_y 0
		.amdhsa_system_sgpr_workgroup_id_z 0
		.amdhsa_system_sgpr_workgroup_info 0
		.amdhsa_system_vgpr_workitem_id 0
		.amdhsa_next_free_vgpr 256
		.amdhsa_next_free_sgpr 100
		.amdhsa_accum_offset 256
		.amdhsa_reserve_vcc 1
		.amdhsa_float_round_mode_32 0
		.amdhsa_float_round_mode_16_64 0
		.amdhsa_float_denorm_mode_32 3
		.amdhsa_float_denorm_mode_16_64 3
		.amdhsa_dx10_clamp 1
		.amdhsa_ieee_mode 1
		.amdhsa_fp16_overflow 0
		.amdhsa_tg_split 0
		.amdhsa_exception_fp_ieee_invalid_op 0
		.amdhsa_exception_fp_denorm_src 0
		.amdhsa_exception_fp_ieee_div_zero 0
		.amdhsa_exception_fp_ieee_overflow 0
		.amdhsa_exception_fp_ieee_underflow 0
		.amdhsa_exception_fp_ieee_inexact 0
		.amdhsa_exception_int_div_zero 0
	.end_amdhsa_kernel

amdhsa.kernels:
  - .agpr_count:     0
    .args:
      - .offset:         0
        .size:           256
        .value_kind:     by_value
      - .offset:         256
        .size:           4
        .value_kind:     hidden_block_count_x
      - .offset:         260
        .size:           4
        .value_kind:     hidden_block_count_y
      - .offset:         264
        .size:           4
        .value_kind:     hidden_block_count_z
      - .offset:         268
        .size:           2
        .value_kind:     hidden_group_size_x
      - .offset:         270
        .size:           2
        .value_kind:     hidden_group_size_y
      - .offset:         272
        .size:           2
        .value_kind:     hidden_group_size_z
      - .offset:         274
        .size:           2
        .value_kind:     hidden_remainder_x
      - .offset:         276
        .size:           2
        .value_kind:     hidden_remainder_y
      - .offset:         278
        .size:           2
        .value_kind:     hidden_remainder_z
      - .offset:         296
        .size:           8
        .value_kind:     hidden_global_offset_x
      - .offset:         304
        .size:           8
        .value_kind:     hidden_global_offset_y
      - .offset:         312
        .size:           8
        .value_kind:     hidden_global_offset_z
      - .offset:         320
        .size:           2
        .value_kind:     hidden_grid_dims
      - .offset:         376
        .size:           4
        .value_kind:     hidden_dynamic_lds_size
    .group_segment_fixed_size: 0
    .kernarg_segment_align: 8
    .kernarg_segment_size: 512
    .language:       OpenCL C
    .language_version:
      - 2
      - 0
    .max_flat_workgroup_size: 512
    .name:           _Z3fwd4Args
    .private_segment_fixed_size: 0
    .sgpr_count:     106
    .sgpr_spill_count: 144
    .symbol:         _Z3fwd4Args.kd
    .uniform_work_group_size: 1
    .uses_dynamic_stack: false
    .vgpr_count:     256
    .vgpr_spill_count: 0
    .wavefront_size: 64
